# GEMM loop counter/pointer bumps and exit compare moved from behind the last MFMA (compute wave critical path) to the end of the preceding load segment
# speedup vs baseline: 1.0144x; 1.0144x over previous
.Lm4bp_31:
	s_waitcnt lgkmcnt(0)
	s_mov_b32 s100, 0
	s_barrier
	v_mfma_f32_16x16x32_bf16 v[60:63], v[128:131], v[162:165], 0
	v_mfma_f32_16x16x32_bf16 v[56:59], v[136:139], v[162:165], 0
	v_mfma_f32_16x16x32_bf16 v[48:51], v[128:131], v[170:173], 0
	v_mfma_f32_16x16x32_bf16 v[40:43], v[136:139], v[170:173], 0
	v_mfma_f32_16x16x32_bf16 v[32:35], v[128:131], v[178:181], 0
	v_mfma_f32_16x16x32_bf16 v[24:27], v[136:139], v[178:181], 0
	v_mfma_f32_16x16x32_bf16 v[16:19], v[128:131], v[194:197], 0
	v_mfma_f32_16x16x32_bf16 v[8:11], v[136:139], v[194:197], 0
	v_mfma_f32_16x16x32_bf16 v[60:63], v[132:135], v[166:169], v[60:63]
	v_mfma_f32_16x16x32_bf16 v[56:59], v[146:149], v[166:169], v[56:59]
	v_mfma_f32_16x16x32_bf16 v[48:51], v[132:135], v[174:177], v[48:51]
	v_mfma_f32_16x16x32_bf16 v[40:43], v[146:149], v[174:177], v[40:43]
	v_mfma_f32_16x16x32_bf16 v[32:35], v[132:135], v[182:185], v[32:35]
	v_mfma_f32_16x16x32_bf16 v[24:27], v[146:149], v[182:185], v[24:27]
	v_mfma_f32_16x16x32_bf16 v[16:19], v[132:135], v[210:213], v[16:19]
	v_mfma_f32_16x16x32_bf16 v[8:11], v[146:149], v[210:213], v[8:11]
	v_mfma_f32_16x16x32_bf16 v[52:55], v[214:217], v[162:165], 0
	v_mfma_f32_16x16x32_bf16 v[44:47], v[222:225], v[162:165], 0
	v_mfma_f32_16x16x32_bf16 v[36:39], v[214:217], v[170:173], 0
	v_mfma_f32_16x16x32_bf16 v[28:31], v[222:225], v[170:173], 0
	v_mfma_f32_16x16x32_bf16 v[20:23], v[214:217], v[178:181], 0
	v_mfma_f32_16x16x32_bf16 v[12:15], v[222:225], v[178:181], 0
	v_mfma_f32_16x16x32_bf16 v[4:7], v[214:217], v[194:197], 0
	v_mfma_f32_16x16x32_bf16 v[0:3], v[222:225], v[194:197], 0
	v_mfma_f32_16x16x32_bf16 v[52:55], v[218:221], v[166:169], v[52:55]
	v_mfma_f32_16x16x32_bf16 v[44:47], v[226:229], v[166:169], v[44:47]
	v_mfma_f32_16x16x32_bf16 v[36:39], v[218:221], v[174:177], v[36:39]
	v_mfma_f32_16x16x32_bf16 v[28:31], v[226:229], v[174:177], v[28:31]
	v_mfma_f32_16x16x32_bf16 v[20:23], v[218:221], v[182:185], v[20:23]
	v_mfma_f32_16x16x32_bf16 v[12:15], v[226:229], v[182:185], v[12:15]
	v_mfma_f32_16x16x32_bf16 v[4:7], v[218:221], v[210:213], v[4:7]
	v_mfma_f32_16x16x32_bf16 v[0:3], v[226:229], v[210:213], v[0:3]
	s_barrier
	s_add_i32 s6, 0, 0x18000
	v_add_u32_e32 v146, s6, v206
	ds_read_b128 v[128:131], v146
	ds_read_b128 v[132:135], v146 offset:1024
	ds_read_b128 v[136:139], v146 offset:2048
	ds_read_b128 v[146:149], v146 offset:3072
	s_add_u32 s50, s52, 0xb0000
	s_addc_u32 s51, s53, 0
	s_mov_b32 m0, s68
	v_lshl_add_u64 v[214:215], s[50:51], 0, v[154:155]
	ds_read_b128 v[162:165], v208 offset:32768
	ds_read_b128 v[166:169], v208 offset:33792
	ds_read_b128 v[170:173], v208 offset:34816
	ds_read_b128 v[174:177], v208 offset:35840
	ds_read_b128 v[178:181], v208 offset:36864
	ds_read_b128 v[182:185], v208 offset:37888
	ds_read_b128 v[194:197], v208 offset:38912
	ds_read_b128 v[210:213], v208 offset:39936
	global_load_lds_dwordx4 v[214:215], off
	v_lshl_add_u64 v[214:215], s[50:51], 0, v[152:153]
	s_mov_b32 m0, s69
	s_nop 0
	global_load_lds_dwordx4 v[214:215], off
	s_add_i32 s19, 0, 0x1c000
	v_add_u32_e32 v192, s19, v206
	ds_read_b128 v[214:217], v192
	ds_read_b128 v[218:221], v192 offset:1024
	ds_read_b128 v[222:225], v192 offset:2048
	ds_read_b128 v[226:229], v192 offset:3072
	s_waitcnt vmcnt(8)
	s_waitcnt lgkmcnt(0)
	s_barrier
	v_mfma_f32_16x16x32_bf16 v[124:127], v[128:131], v[162:165], v[124:127]
	v_mfma_f32_16x16x32_bf16 v[120:123], v[136:139], v[162:165], v[120:123]
	v_mfma_f32_16x16x32_bf16 v[108:111], v[128:131], v[170:173], v[108:111]
	v_mfma_f32_16x16x32_bf16 v[104:107], v[136:139], v[170:173], v[104:107]
	v_mfma_f32_16x16x32_bf16 v[96:99], v[128:131], v[178:181], v[96:99]
	v_mfma_f32_16x16x32_bf16 v[88:91], v[136:139], v[178:181], v[88:91]
	v_mfma_f32_16x16x32_bf16 v[84:87], v[128:131], v[194:197], v[84:87]
	v_mfma_f32_16x16x32_bf16 v[80:83], v[136:139], v[194:197], v[80:83]
	v_mfma_f32_16x16x32_bf16 v[124:127], v[132:135], v[166:169], v[124:127]
	v_mfma_f32_16x16x32_bf16 v[120:123], v[146:149], v[166:169], v[120:123]
	v_mfma_f32_16x16x32_bf16 v[108:111], v[132:135], v[174:177], v[108:111]
	v_mfma_f32_16x16x32_bf16 v[104:107], v[146:149], v[174:177], v[104:107]
	v_mfma_f32_16x16x32_bf16 v[96:99], v[132:135], v[182:185], v[96:99]
	v_mfma_f32_16x16x32_bf16 v[88:91], v[146:149], v[182:185], v[88:91]
	v_mfma_f32_16x16x32_bf16 v[84:87], v[132:135], v[210:213], v[84:87]
	v_mfma_f32_16x16x32_bf16 v[80:83], v[146:149], v[210:213], v[80:83]
	v_mfma_f32_16x16x32_bf16 v[116:119], v[214:217], v[162:165], v[116:119]
	v_mfma_f32_16x16x32_bf16 v[112:115], v[222:225], v[162:165], v[112:115]
	v_mfma_f32_16x16x32_bf16 v[100:103], v[214:217], v[170:173], v[100:103]
	v_mfma_f32_16x16x32_bf16 v[92:95], v[222:225], v[170:173], v[92:95]
	v_mfma_f32_16x16x32_bf16 v[76:79], v[214:217], v[178:181], v[76:79]
	v_mfma_f32_16x16x32_bf16 v[72:75], v[222:225], v[178:181], v[72:75]
	v_mfma_f32_16x16x32_bf16 v[68:71], v[214:217], v[194:197], v[68:71]
	v_mfma_f32_16x16x32_bf16 v[64:67], v[222:225], v[194:197], v[64:67]
	v_mfma_f32_16x16x32_bf16 v[116:119], v[218:221], v[166:169], v[116:119]
	v_mfma_f32_16x16x32_bf16 v[112:115], v[226:229], v[166:169], v[112:115]
	v_mfma_f32_16x16x32_bf16 v[100:103], v[218:221], v[174:177], v[100:103]
	v_mfma_f32_16x16x32_bf16 v[92:95], v[226:229], v[174:177], v[92:95]
	v_mfma_f32_16x16x32_bf16 v[76:79], v[218:221], v[182:185], v[76:79]
	v_mfma_f32_16x16x32_bf16 v[72:75], v[226:229], v[182:185], v[72:75]
	v_mfma_f32_16x16x32_bf16 v[68:71], v[218:221], v[210:213], v[68:71]
	v_mfma_f32_16x16x32_bf16 v[64:67], v[226:229], v[210:213], v[64:67]
	s_barrier
	s_add_i32 s6, s6, s57
	v_lshl_add_u64 v[230:231], v[230:231], 0, s[36:37]
	s_mov_b32 m0, s6
	s_nop 0
	global_load_lds_dwordx4 v[230:231], off
	v_lshl_add_u64 v[230:231], v[232:233], 0, s[36:37]
	s_add_i32 m0, s6, 0x2000
	s_nop 0
	global_load_lds_dwordx4 v[230:231], off
	s_mov_b32 m0, s70
	v_lshl_add_u64 v[230:231], v[234:235], 0, s[36:37]
	ds_read_b128 v[162:165], v208 offset:49152
	ds_read_b128 v[166:169], v208 offset:50176
	ds_read_b128 v[170:173], v208 offset:51200
	ds_read_b128 v[174:177], v208 offset:52224
	ds_read_b128 v[178:181], v208 offset:53248
	ds_read_b128 v[182:185], v208 offset:54272
	ds_read_b128 v[194:197], v208 offset:55296
	ds_read_b128 v[210:213], v208 offset:56320
	global_load_lds_dwordx4 v[230:231], off
	v_lshl_add_u64 v[230:231], v[236:237], 0, s[36:37]
	s_mov_b32 m0, s71
	s_nop 0
	global_load_lds_dwordx4 v[230:231], off
	s_add_u32 s48, s48, 0xb0080
	s_addc_u32 s49, s49, 0
	s_add_i32 s6, s19, s57
	v_lshl_add_u64 v[250:251], s[48:49], 0, v[140:141]
	s_mov_b32 m0, s6
	s_nop 0
	global_load_lds_dwordx4 v[250:251], off
	v_lshl_add_u64 v[250:251], s[48:49], 0, v[150:151]
	s_add_i32 m0, s6, 0x2000
	s_nop 0
	global_load_lds_dwordx4 v[250:251], off
	s_add_i32 s12, s12, 2
	s_add_u32 s10, s10, 0x100
	s_addc_u32 s11, s11, 0
	s_cmp_gt_u32 s12, 41
	s_mov_b64 s[50:51], s[46:47]
	s_waitcnt vmcnt(8)
	s_waitcnt lgkmcnt(0)
	s_barrier
	v_mfma_f32_16x16x32_bf16 v[60:63], v[128:131], v[162:165], v[60:63]
	v_mfma_f32_16x16x32_bf16 v[56:59], v[136:139], v[162:165], v[56:59]
	v_mfma_f32_16x16x32_bf16 v[48:51], v[128:131], v[170:173], v[48:51]
	v_mfma_f32_16x16x32_bf16 v[40:43], v[136:139], v[170:173], v[40:43]
	v_mfma_f32_16x16x32_bf16 v[32:35], v[128:131], v[178:181], v[32:35]
	v_mfma_f32_16x16x32_bf16 v[24:27], v[136:139], v[178:181], v[24:27]
	v_mfma_f32_16x16x32_bf16 v[16:19], v[128:131], v[194:197], v[16:19]
	v_mfma_f32_16x16x32_bf16 v[8:11], v[136:139], v[194:197], v[8:11]
	v_mfma_f32_16x16x32_bf16 v[60:63], v[132:135], v[166:169], v[60:63]
	v_mfma_f32_16x16x32_bf16 v[56:59], v[146:149], v[166:169], v[56:59]
	v_mfma_f32_16x16x32_bf16 v[48:51], v[132:135], v[174:177], v[48:51]
	v_mfma_f32_16x16x32_bf16 v[40:43], v[146:149], v[174:177], v[40:43]
	v_mfma_f32_16x16x32_bf16 v[32:35], v[132:135], v[182:185], v[32:35]
	v_mfma_f32_16x16x32_bf16 v[24:27], v[146:149], v[182:185], v[24:27]
	v_mfma_f32_16x16x32_bf16 v[16:19], v[132:135], v[210:213], v[16:19]
	v_mfma_f32_16x16x32_bf16 v[8:11], v[146:149], v[210:213], v[8:11]
	v_mfma_f32_16x16x32_bf16 v[52:55], v[214:217], v[162:165], v[52:55]
	v_mfma_f32_16x16x32_bf16 v[44:47], v[222:225], v[162:165], v[44:47]
	v_mfma_f32_16x16x32_bf16 v[36:39], v[214:217], v[170:173], v[36:39]
	v_mfma_f32_16x16x32_bf16 v[28:31], v[222:225], v[170:173], v[28:31]
	v_mfma_f32_16x16x32_bf16 v[20:23], v[214:217], v[178:181], v[20:23]
	v_mfma_f32_16x16x32_bf16 v[12:15], v[222:225], v[178:181], v[12:15]
	v_mfma_f32_16x16x32_bf16 v[4:7], v[214:217], v[194:197], v[4:7]
	v_mfma_f32_16x16x32_bf16 v[0:3], v[222:225], v[194:197], v[0:3]
	v_mfma_f32_16x16x32_bf16 v[52:55], v[218:221], v[166:169], v[52:55]
	v_mfma_f32_16x16x32_bf16 v[44:47], v[226:229], v[166:169], v[44:47]
	v_mfma_f32_16x16x32_bf16 v[36:39], v[218:221], v[174:177], v[36:39]
	v_mfma_f32_16x16x32_bf16 v[28:31], v[226:229], v[174:177], v[28:31]
	v_mfma_f32_16x16x32_bf16 v[20:23], v[218:221], v[182:185], v[20:23]
	v_mfma_f32_16x16x32_bf16 v[12:15], v[226:229], v[182:185], v[12:15]
	v_mfma_f32_16x16x32_bf16 v[4:7], v[218:221], v[210:213], v[4:7]
	v_mfma_f32_16x16x32_bf16 v[0:3], v[226:229], v[210:213], v[0:3]
	s_barrier
.LBB0_31:
	s_add_u32 s46, s50, 0x100
	s_addc_u32 s47, s51, 0
	s_add_i32 s6, 0, 0x10000
	v_add_u32_e32 v146, s6, v206
	ds_read_b128 v[128:131], v146
	ds_read_b128 v[132:135], v146 offset:1024
	ds_read_b128 v[136:139], v146 offset:2048
	ds_read_b128 v[146:149], v146 offset:3072
	s_cmp_eq_u32 s12, 40
	s_cselect_b32 s53, s31, s47
	s_cselect_b32 s52, s30, s46
	s_cselect_b32 s49, s35, s11
	s_cselect_b32 s48, s34, s10
	v_lshl_add_u64 v[214:215], s[50:51], 0, v[158:159]
	s_add_i32 m0, s58, 0xc000
	ds_read_b128 v[162:165], v208
	ds_read_b128 v[166:169], v208 offset:1024
	ds_read_b128 v[170:173], v208 offset:2048
	ds_read_b128 v[174:177], v208 offset:3072
	ds_read_b128 v[178:181], v208 offset:4096
	ds_read_b128 v[182:185], v208 offset:5120
	ds_read_b128 v[194:197], v208 offset:6144
	ds_read_b128 v[210:213], v208 offset:7168
	global_load_lds_dwordx4 v[214:215], off
	v_lshl_add_u64 v[214:215], s[50:51], 0, v[160:161]
	s_add_i32 m0, s58, 0xe000
	s_nop 0
	global_load_lds_dwordx4 v[214:215], off
	s_add_i32 s19, 0, 0x14000
	v_add_u32_e32 v192, s19, v206
	ds_read_b128 v[214:217], v192
	ds_read_b128 v[218:221], v192 offset:1024
	ds_read_b128 v[222:225], v192 offset:2048
	ds_read_b128 v[226:229], v192 offset:3072
	s_nop 0
	s_waitcnt vmcnt(8)
	s_waitcnt lgkmcnt(0)
	s_barrier
	v_mfma_f32_16x16x32_bf16 v[124:127], v[128:131], v[162:165], v[124:127]
	v_mfma_f32_16x16x32_bf16 v[120:123], v[136:139], v[162:165], v[120:123]
	v_mfma_f32_16x16x32_bf16 v[108:111], v[128:131], v[170:173], v[108:111]
	v_mfma_f32_16x16x32_bf16 v[104:107], v[136:139], v[170:173], v[104:107]
	v_mfma_f32_16x16x32_bf16 v[96:99], v[128:131], v[178:181], v[96:99]
	v_mfma_f32_16x16x32_bf16 v[88:91], v[136:139], v[178:181], v[88:91]
	v_mfma_f32_16x16x32_bf16 v[84:87], v[128:131], v[194:197], v[84:87]
	v_mfma_f32_16x16x32_bf16 v[80:83], v[136:139], v[194:197], v[80:83]
	v_mfma_f32_16x16x32_bf16 v[124:127], v[132:135], v[166:169], v[124:127]
	v_mfma_f32_16x16x32_bf16 v[120:123], v[146:149], v[166:169], v[120:123]
	v_mfma_f32_16x16x32_bf16 v[108:111], v[132:135], v[174:177], v[108:111]
	v_mfma_f32_16x16x32_bf16 v[104:107], v[146:149], v[174:177], v[104:107]
	v_mfma_f32_16x16x32_bf16 v[96:99], v[132:135], v[182:185], v[96:99]
	v_mfma_f32_16x16x32_bf16 v[88:91], v[146:149], v[182:185], v[88:91]
	v_mfma_f32_16x16x32_bf16 v[84:87], v[132:135], v[210:213], v[84:87]
	v_mfma_f32_16x16x32_bf16 v[80:83], v[146:149], v[210:213], v[80:83]
	v_mfma_f32_16x16x32_bf16 v[116:119], v[214:217], v[162:165], v[116:119]
	v_mfma_f32_16x16x32_bf16 v[112:115], v[222:225], v[162:165], v[112:115]
	v_mfma_f32_16x16x32_bf16 v[100:103], v[214:217], v[170:173], v[100:103]
	v_mfma_f32_16x16x32_bf16 v[92:95], v[222:225], v[170:173], v[92:95]
	v_mfma_f32_16x16x32_bf16 v[76:79], v[214:217], v[178:181], v[76:79]
	v_mfma_f32_16x16x32_bf16 v[72:75], v[222:225], v[178:181], v[72:75]
	v_mfma_f32_16x16x32_bf16 v[68:71], v[214:217], v[194:197], v[68:71]
	v_mfma_f32_16x16x32_bf16 v[64:67], v[222:225], v[194:197], v[64:67]
	v_mfma_f32_16x16x32_bf16 v[116:119], v[218:221], v[166:169], v[116:119]
	v_mfma_f32_16x16x32_bf16 v[112:115], v[226:229], v[166:169], v[112:115]
	v_mfma_f32_16x16x32_bf16 v[100:103], v[218:221], v[174:177], v[100:103]
	v_mfma_f32_16x16x32_bf16 v[92:95], v[226:229], v[174:177], v[92:95]
	v_mfma_f32_16x16x32_bf16 v[76:79], v[218:221], v[182:185], v[76:79]
	v_mfma_f32_16x16x32_bf16 v[72:75], v[226:229], v[182:185], v[72:75]
	v_mfma_f32_16x16x32_bf16 v[68:71], v[218:221], v[210:213], v[68:71]
	v_mfma_f32_16x16x32_bf16 v[64:67], v[226:229], v[210:213], v[64:67]
	s_barrier
	s_add_i32 s6, s6, s57
	v_lshl_add_u64 v[230:231], s[48:49], 0, v[140:141]
	s_mov_b32 m0, s6
	s_nop 0
	global_load_lds_dwordx4 v[230:231], off
	v_lshl_add_u64 v[232:233], s[48:49], 0, v[150:151]
	s_add_i32 m0, s6, 0x2000
	s_nop 0
	global_load_lds_dwordx4 v[232:233], off
	s_mov_b32 m0, s58
	v_lshl_add_u64 v[234:235], s[52:53], 0, v[154:155]
	ds_read_b128 v[162:165], v208 offset:16384
	ds_read_b128 v[166:169], v208 offset:17408
	ds_read_b128 v[170:173], v208 offset:18432
	ds_read_b128 v[174:177], v208 offset:19456
	ds_read_b128 v[178:181], v208 offset:20480
	ds_read_b128 v[182:185], v208 offset:21504
	ds_read_b128 v[194:197], v208 offset:22528
	ds_read_b128 v[210:213], v208 offset:23552
	global_load_lds_dwordx4 v[234:235], off
	v_lshl_add_u64 v[236:237], s[52:53], 0, v[152:153]
	s_mov_b32 m0, s59
	s_nop 0
	global_load_lds_dwordx4 v[236:237], off
	s_add_u32 s50, s48, 0xb0000
	s_addc_u32 s51, s49, 0
	s_add_i32 s6, s19, s57
	v_lshl_add_u64 v[250:251], s[50:51], 0, v[140:141]
	s_mov_b32 m0, s6
	s_nop 0
	global_load_lds_dwordx4 v[250:251], off
	v_lshl_add_u64 v[250:251], s[50:51], 0, v[150:151]
	s_add_i32 m0, s6, 0x2000
	s_nop 0
	global_load_lds_dwordx4 v[250:251], off
	s_waitcnt vmcnt(8)
	s_waitcnt lgkmcnt(0)
	s_barrier
	v_mfma_f32_16x16x32_bf16 v[60:63], v[128:131], v[162:165], v[60:63]
	v_mfma_f32_16x16x32_bf16 v[56:59], v[136:139], v[162:165], v[56:59]
	v_mfma_f32_16x16x32_bf16 v[48:51], v[128:131], v[170:173], v[48:51]
	v_mfma_f32_16x16x32_bf16 v[40:43], v[136:139], v[170:173], v[40:43]
	v_mfma_f32_16x16x32_bf16 v[32:35], v[128:131], v[178:181], v[32:35]
	v_mfma_f32_16x16x32_bf16 v[24:27], v[136:139], v[178:181], v[24:27]
	v_mfma_f32_16x16x32_bf16 v[16:19], v[128:131], v[194:197], v[16:19]
	v_mfma_f32_16x16x32_bf16 v[8:11], v[136:139], v[194:197], v[8:11]
	v_mfma_f32_16x16x32_bf16 v[60:63], v[132:135], v[166:169], v[60:63]
	v_mfma_f32_16x16x32_bf16 v[56:59], v[146:149], v[166:169], v[56:59]
	v_mfma_f32_16x16x32_bf16 v[48:51], v[132:135], v[174:177], v[48:51]
	v_mfma_f32_16x16x32_bf16 v[40:43], v[146:149], v[174:177], v[40:43]
	v_mfma_f32_16x16x32_bf16 v[32:35], v[132:135], v[182:185], v[32:35]
	v_mfma_f32_16x16x32_bf16 v[24:27], v[146:149], v[182:185], v[24:27]
	v_mfma_f32_16x16x32_bf16 v[16:19], v[132:135], v[210:213], v[16:19]
	v_mfma_f32_16x16x32_bf16 v[8:11], v[146:149], v[210:213], v[8:11]
	v_mfma_f32_16x16x32_bf16 v[52:55], v[214:217], v[162:165], v[52:55]
	v_mfma_f32_16x16x32_bf16 v[44:47], v[222:225], v[162:165], v[44:47]
	v_mfma_f32_16x16x32_bf16 v[36:39], v[214:217], v[170:173], v[36:39]
	v_mfma_f32_16x16x32_bf16 v[28:31], v[222:225], v[170:173], v[28:31]
	v_mfma_f32_16x16x32_bf16 v[20:23], v[214:217], v[178:181], v[20:23]
	v_mfma_f32_16x16x32_bf16 v[12:15], v[222:225], v[178:181], v[12:15]
	v_mfma_f32_16x16x32_bf16 v[4:7], v[214:217], v[194:197], v[4:7]
	v_mfma_f32_16x16x32_bf16 v[0:3], v[222:225], v[194:197], v[0:3]
	v_mfma_f32_16x16x32_bf16 v[52:55], v[218:221], v[166:169], v[52:55]
	v_mfma_f32_16x16x32_bf16 v[44:47], v[226:229], v[166:169], v[44:47]
	v_mfma_f32_16x16x32_bf16 v[36:39], v[218:221], v[174:177], v[36:39]
	v_mfma_f32_16x16x32_bf16 v[28:31], v[226:229], v[174:177], v[28:31]
	v_mfma_f32_16x16x32_bf16 v[20:23], v[218:221], v[182:185], v[20:23]
	v_mfma_f32_16x16x32_bf16 v[12:15], v[226:229], v[182:185], v[12:15]
	v_mfma_f32_16x16x32_bf16 v[4:7], v[218:221], v[210:213], v[4:7]
	v_mfma_f32_16x16x32_bf16 v[0:3], v[226:229], v[210:213], v[0:3]
	s_barrier
	s_add_i32 s6, 0, 0x18000
	v_add_u32_e32 v146, s6, v206
	ds_read_b128 v[128:131], v146
	ds_read_b128 v[132:135], v146 offset:1024
	ds_read_b128 v[136:139], v146 offset:2048
	ds_read_b128 v[146:149], v146 offset:3072
	s_add_u32 s50, s52, 0xb0000
	s_addc_u32 s51, s53, 0
	s_mov_b32 m0, s68
	v_lshl_add_u64 v[214:215], s[50:51], 0, v[154:155]
	ds_read_b128 v[162:165], v208 offset:32768
	ds_read_b128 v[166:169], v208 offset:33792
	ds_read_b128 v[170:173], v208 offset:34816
	ds_read_b128 v[174:177], v208 offset:35840
	ds_read_b128 v[178:181], v208 offset:36864
	ds_read_b128 v[182:185], v208 offset:37888
	ds_read_b128 v[194:197], v208 offset:38912
	ds_read_b128 v[210:213], v208 offset:39936
	global_load_lds_dwordx4 v[214:215], off
	v_lshl_add_u64 v[214:215], s[50:51], 0, v[152:153]
	s_mov_b32 m0, s69
	s_nop 0
	global_load_lds_dwordx4 v[214:215], off
	s_add_i32 s19, 0, 0x1c000
	v_add_u32_e32 v192, s19, v206
	ds_read_b128 v[214:217], v192
	ds_read_b128 v[218:221], v192 offset:1024
	ds_read_b128 v[222:225], v192 offset:2048
	ds_read_b128 v[226:229], v192 offset:3072
	s_waitcnt vmcnt(8)
	s_waitcnt lgkmcnt(0)
	s_barrier
	v_mfma_f32_16x16x32_bf16 v[124:127], v[128:131], v[162:165], v[124:127]
	v_mfma_f32_16x16x32_bf16 v[120:123], v[136:139], v[162:165], v[120:123]
	v_mfma_f32_16x16x32_bf16 v[108:111], v[128:131], v[170:173], v[108:111]
	v_mfma_f32_16x16x32_bf16 v[104:107], v[136:139], v[170:173], v[104:107]
	v_mfma_f32_16x16x32_bf16 v[96:99], v[128:131], v[178:181], v[96:99]
	v_mfma_f32_16x16x32_bf16 v[88:91], v[136:139], v[178:181], v[88:91]
	v_mfma_f32_16x16x32_bf16 v[84:87], v[128:131], v[194:197], v[84:87]
	v_mfma_f32_16x16x32_bf16 v[80:83], v[136:139], v[194:197], v[80:83]
	v_mfma_f32_16x16x32_bf16 v[124:127], v[132:135], v[166:169], v[124:127]
	v_mfma_f32_16x16x32_bf16 v[120:123], v[146:149], v[166:169], v[120:123]
	v_mfma_f32_16x16x32_bf16 v[108:111], v[132:135], v[174:177], v[108:111]
	v_mfma_f32_16x16x32_bf16 v[104:107], v[146:149], v[174:177], v[104:107]
	v_mfma_f32_16x16x32_bf16 v[96:99], v[132:135], v[182:185], v[96:99]
	v_mfma_f32_16x16x32_bf16 v[88:91], v[146:149], v[182:185], v[88:91]
	v_mfma_f32_16x16x32_bf16 v[84:87], v[132:135], v[210:213], v[84:87]
	v_mfma_f32_16x16x32_bf16 v[80:83], v[146:149], v[210:213], v[80:83]
	v_mfma_f32_16x16x32_bf16 v[116:119], v[214:217], v[162:165], v[116:119]
	v_mfma_f32_16x16x32_bf16 v[112:115], v[222:225], v[162:165], v[112:115]
	v_mfma_f32_16x16x32_bf16 v[100:103], v[214:217], v[170:173], v[100:103]
	v_mfma_f32_16x16x32_bf16 v[92:95], v[222:225], v[170:173], v[92:95]
	v_mfma_f32_16x16x32_bf16 v[76:79], v[214:217], v[178:181], v[76:79]
	v_mfma_f32_16x16x32_bf16 v[72:75], v[222:225], v[178:181], v[72:75]
	v_mfma_f32_16x16x32_bf16 v[68:71], v[214:217], v[194:197], v[68:71]
	v_mfma_f32_16x16x32_bf16 v[64:67], v[222:225], v[194:197], v[64:67]
	v_mfma_f32_16x16x32_bf16 v[116:119], v[218:221], v[166:169], v[116:119]
	v_mfma_f32_16x16x32_bf16 v[112:115], v[226:229], v[166:169], v[112:115]
	v_mfma_f32_16x16x32_bf16 v[100:103], v[218:221], v[174:177], v[100:103]
	v_mfma_f32_16x16x32_bf16 v[92:95], v[226:229], v[174:177], v[92:95]
	v_mfma_f32_16x16x32_bf16 v[76:79], v[218:221], v[182:185], v[76:79]
	v_mfma_f32_16x16x32_bf16 v[72:75], v[226:229], v[182:185], v[72:75]
	v_mfma_f32_16x16x32_bf16 v[68:71], v[218:221], v[210:213], v[68:71]
	v_mfma_f32_16x16x32_bf16 v[64:67], v[226:229], v[210:213], v[64:67]
	s_barrier
	s_add_i32 s6, s6, s57
	v_lshl_add_u64 v[230:231], v[230:231], 0, s[36:37]
	s_mov_b32 m0, s6
	s_nop 0
	global_load_lds_dwordx4 v[230:231], off
	v_lshl_add_u64 v[230:231], v[232:233], 0, s[36:37]
	s_add_i32 m0, s6, 0x2000
	s_nop 0
	global_load_lds_dwordx4 v[230:231], off
	s_mov_b32 m0, s70
	v_lshl_add_u64 v[230:231], v[234:235], 0, s[36:37]
	ds_read_b128 v[162:165], v208 offset:49152
	ds_read_b128 v[166:169], v208 offset:50176
	ds_read_b128 v[170:173], v208 offset:51200
	ds_read_b128 v[174:177], v208 offset:52224
	ds_read_b128 v[178:181], v208 offset:53248
	ds_read_b128 v[182:185], v208 offset:54272
	ds_read_b128 v[194:197], v208 offset:55296
	ds_read_b128 v[210:213], v208 offset:56320
	global_load_lds_dwordx4 v[230:231], off
	v_lshl_add_u64 v[230:231], v[236:237], 0, s[36:37]
	s_mov_b32 m0, s71
	s_nop 0
	global_load_lds_dwordx4 v[230:231], off
	s_add_u32 s48, s48, 0xb0080
	s_addc_u32 s49, s49, 0
	s_add_i32 s6, s19, s57
	v_lshl_add_u64 v[250:251], s[48:49], 0, v[140:141]
	s_mov_b32 m0, s6
	s_nop 0
	global_load_lds_dwordx4 v[250:251], off
	v_lshl_add_u64 v[250:251], s[48:49], 0, v[150:151]
	s_add_i32 m0, s6, 0x2000
	s_nop 0
	global_load_lds_dwordx4 v[250:251], off
	s_add_i32 s12, s12, 2
	s_add_u32 s10, s10, 0x100
	s_addc_u32 s11, s11, 0
	s_cmp_gt_u32 s12, 41
	s_mov_b64 s[50:51], s[46:47]
	s_waitcnt vmcnt(8)
	s_waitcnt lgkmcnt(0)
	s_barrier
	v_mfma_f32_16x16x32_bf16 v[60:63], v[128:131], v[162:165], v[60:63]
	v_mfma_f32_16x16x32_bf16 v[56:59], v[136:139], v[162:165], v[56:59]
	v_mfma_f32_16x16x32_bf16 v[48:51], v[128:131], v[170:173], v[48:51]
	v_mfma_f32_16x16x32_bf16 v[40:43], v[136:139], v[170:173], v[40:43]
	v_mfma_f32_16x16x32_bf16 v[32:35], v[128:131], v[178:181], v[32:35]
	v_mfma_f32_16x16x32_bf16 v[24:27], v[136:139], v[178:181], v[24:27]
	v_mfma_f32_16x16x32_bf16 v[16:19], v[128:131], v[194:197], v[16:19]
	v_mfma_f32_16x16x32_bf16 v[8:11], v[136:139], v[194:197], v[8:11]
	v_mfma_f32_16x16x32_bf16 v[60:63], v[132:135], v[166:169], v[60:63]
	v_mfma_f32_16x16x32_bf16 v[56:59], v[146:149], v[166:169], v[56:59]
	v_mfma_f32_16x16x32_bf16 v[48:51], v[132:135], v[174:177], v[48:51]
	v_mfma_f32_16x16x32_bf16 v[40:43], v[146:149], v[174:177], v[40:43]
	v_mfma_f32_16x16x32_bf16 v[32:35], v[132:135], v[182:185], v[32:35]
	v_mfma_f32_16x16x32_bf16 v[24:27], v[146:149], v[182:185], v[24:27]
	v_mfma_f32_16x16x32_bf16 v[16:19], v[132:135], v[210:213], v[16:19]
	v_mfma_f32_16x16x32_bf16 v[8:11], v[146:149], v[210:213], v[8:11]
	v_mfma_f32_16x16x32_bf16 v[52:55], v[214:217], v[162:165], v[52:55]
	v_mfma_f32_16x16x32_bf16 v[44:47], v[222:225], v[162:165], v[44:47]
	v_mfma_f32_16x16x32_bf16 v[36:39], v[214:217], v[170:173], v[36:39]
	v_mfma_f32_16x16x32_bf16 v[28:31], v[222:225], v[170:173], v[28:31]
	v_mfma_f32_16x16x32_bf16 v[20:23], v[214:217], v[178:181], v[20:23]
	v_mfma_f32_16x16x32_bf16 v[12:15], v[222:225], v[178:181], v[12:15]
	v_mfma_f32_16x16x32_bf16 v[4:7], v[214:217], v[194:197], v[4:7]
	v_mfma_f32_16x16x32_bf16 v[0:3], v[222:225], v[194:197], v[0:3]
	v_mfma_f32_16x16x32_bf16 v[52:55], v[218:221], v[166:169], v[52:55]
	v_mfma_f32_16x16x32_bf16 v[44:47], v[226:229], v[166:169], v[44:47]
	v_mfma_f32_16x16x32_bf16 v[36:39], v[218:221], v[174:177], v[36:39]
	v_mfma_f32_16x16x32_bf16 v[28:31], v[226:229], v[174:177], v[28:31]
	v_mfma_f32_16x16x32_bf16 v[20:23], v[218:221], v[182:185], v[20:23]
	v_mfma_f32_16x16x32_bf16 v[12:15], v[226:229], v[182:185], v[12:15]
	v_mfma_f32_16x16x32_bf16 v[4:7], v[218:221], v[210:213], v[4:7]
	v_mfma_f32_16x16x32_bf16 v[0:3], v[226:229], v[210:213], v[0:3]
	s_barrier
	s_cbranch_scc0 .LBB0_31
	s_mov_b32 s100, 1
	s_ashr_i32 s39, s38, 31
	v_lshl_or_b32 v128, s81, 8, v207
	s_lshl_b64 s[10:11], s[38:39], 8
	v_ashrrev_i32_e32 v129, 31, v128
	v_lshl_add_u64 v[168:169], s[10:11], 0, v[156:157]
	v_lshlrev_b64 v[170:171], 1, v[128:129]
	v_lshl_add_u64 v[174:175], s[4:5], 0, v[170:171]
	v_lshlrev_b64 v[172:173], 11, v[168:169]
	v_lshl_add_u64 v[128:129], v[174:175], 0, v[172:173]
	global_load_dwordx4 v[146:149], v[128:129], off
	global_load_dwordx4 v[182:185], v[128:129], off offset:256
	v_or_b32_e32 v166, 16, v168
	v_mov_b32_e32 v167, v169
	v_lshlrev_b64 v[176:177], 11, v[166:167]
	v_lshl_add_u64 v[128:129], v[174:175], 0, v[176:177]
	global_load_dwordx4 v[194:197], v[128:129], off
	global_load_dwordx4 v[210:213], v[128:129], off offset:256
	v_or_b32_e32 v164, 32, v168
	v_mov_b32_e32 v165, v169
	v_or_b32_e32 v162, 48, v168
	v_mov_b32_e32 v163, v169
	v_lshlrev_b64 v[180:181], 11, v[164:165]
	v_lshlrev_b64 v[178:179], 11, v[162:163]
	v_lshl_add_u64 v[128:129], v[174:175], 0, v[180:181]
	v_lshl_add_u64 v[130:131], v[174:175], 0, v[178:179]
	global_load_dwordx4 v[214:217], v[128:129], off
	global_load_dwordx4 v[136:139], v[128:129], off offset:256
	global_load_dwordx4 v[132:135], v[130:131], off
	s_nop 0
	global_load_dwordx4 v[128:131], v[130:131], off offset:256
	s_mov_b64 s[10:11], 0x90
	v_lshl_add_u64 v[172:173], s[28:29], 0, v[172:173]
	v_lshl_add_u64 v[172:173], v[172:173], 0, v[170:171]
	s_waitcnt vmcnt(0)
	v_lshlrev_b32_e32 v218, 16, v146
	v_and_b32_e32 v219, 0xffff0000, v146
	v_lshlrev_b32_e32 v220, 16, v148
	v_and_b32_e32 v221, 0xffff0000, v148
	v_lshlrev_b32_e32 v146, 16, v147
	v_and_b32_e32 v147, 0xffff0000, v147
	v_lshlrev_b32_e32 v222, 16, v182
	v_and_b32_e32 v223, 0xffff0000, v182
	v_lshlrev_b32_e32 v224, 16, v184
	v_and_b32_e32 v225, 0xffff0000, v184
	v_lshlrev_b32_e32 v182, 16, v183
	v_and_b32_e32 v183, 0xffff0000, v183
	v_pk_fma_f32 v[124:125], v[124:125], 0.5, v[218:219] op_sel_hi:[1,0,1]
	v_pk_fma_f32 v[120:121], v[120:121], 0.5, v[220:221] op_sel_hi:[1,0,1]
	v_pk_fma_f32 v[126:127], v[126:127], 0.5, v[146:147] op_sel_hi:[1,0,1]
	v_pk_fma_f32 v[116:117], v[116:117], 0.5, v[222:223] op_sel_hi:[1,0,1]
	v_pk_fma_f32 v[146:147], v[112:113], 0.5, v[224:225] op_sel_hi:[1,0,1]
	v_pk_fma_f32 v[118:119], v[118:119], 0.5, v[182:183] op_sel_hi:[1,0,1]
	v_pk_mul_f32 v[220:221], v[124:125], v[124:125]
	v_pk_mul_f32 v[222:223], v[126:127], v[126:127]
	v_cvt_pk_bf16_f32 v112, v124, v125
	v_cvt_pk_bf16_f32 v113, v126, v127
	v_pk_mul_f32 v[124:125], v[116:117], v[116:117]
	v_pk_mul_f32 v[126:127], v[118:119], v[118:119]
	v_pk_mul_f32 v[228:229], v[146:147], v[146:147]
	v_cvt_pk_bf16_f32 v116, v116, v117
	v_cvt_pk_bf16_f32 v117, v118, v119
	v_cvt_pk_bf16_f32 v118, v146, v147
	v_add_f32_e32 v146, v220, v221
	v_add_f32_e32 v146, v222, v146
	v_lshlrev_b32_e32 v148, 16, v149
	v_and_b32_e32 v149, 0xffff0000, v149
	v_pk_mul_f32 v[224:225], v[120:121], v[120:121]
	v_add_f32_e32 v146, v223, v146
	v_pk_fma_f32 v[122:123], v[122:123], 0.5, v[148:149] op_sel_hi:[1,0,1]
	v_add_f32_e32 v146, v224, v146
	v_pk_mul_f32 v[226:227], v[122:123], v[122:123]
	v_add_f32_e32 v146, v225, v146
	v_add_f32_e32 v146, v226, v146
	v_add_f32_e32 v146, v227, v146
	v_add_f32_e32 v124, v124, v146
	v_add_f32_e32 v124, v125, v124
	v_add_f32_e32 v124, v126, v124
	v_lshlrev_b32_e32 v184, 16, v185
	v_and_b32_e32 v185, 0xffff0000, v185
	v_add_f32_e32 v124, v127, v124
	v_pk_fma_f32 v[148:149], v[114:115], 0.5, v[184:185] op_sel_hi:[1,0,1]
	v_add_f32_e32 v124, v228, v124
	v_pk_mul_f32 v[230:231], v[148:149], v[148:149]
	v_add_f32_e32 v124, v229, v124
	v_add_f32_e32 v124, v230, v124
	v_add_f32_e32 v209, v231, v124
	v_lshlrev_b32_e32 v124, 16, v212
	v_and_b32_e32 v125, 0xffff0000, v212
	v_pk_fma_f32 v[124:125], v[92:93], 0.5, v[124:125] op_sel_hi:[1,0,1]
	v_lshlrev_b32_e32 v92, 16, v211
	v_and_b32_e32 v93, 0xffff0000, v211
	v_pk_fma_f32 v[102:103], v[102:103], 0.5, v[92:93] op_sel_hi:[1,0,1]
	v_lshlrev_b32_e32 v92, 16, v213
	v_and_b32_e32 v93, 0xffff0000, v213
	v_pk_fma_f32 v[126:127], v[94:95], 0.5, v[92:93] op_sel_hi:[1,0,1]
	v_lshlrev_b32_e32 v92, 16, v214
	v_and_b32_e32 v93, 0xffff0000, v214
	v_pk_fma_f32 v[92:93], v[96:97], 0.5, v[92:93] op_sel_hi:[1,0,1]
	v_lshlrev_b32_e32 v96, 16, v217
	v_and_b32_e32 v97, 0xffff0000, v217
	v_lshlrev_b32_e32 v94, 16, v216
	v_and_b32_e32 v95, 0xffff0000, v216
	v_pk_fma_f32 v[90:91], v[90:91], 0.5, v[96:97] op_sel_hi:[1,0,1]
	v_lshlrev_b32_e32 v96, 16, v136
	v_and_b32_e32 v97, 0xffff0000, v136
	v_lshlrev_b32_e32 v182, 16, v194
	v_and_b32_e32 v183, 0xffff0000, v194
	v_pk_fma_f32 v[88:89], v[88:89], 0.5, v[94:95] op_sel_hi:[1,0,1]
	v_lshlrev_b32_e32 v94, 16, v215
	v_and_b32_e32 v95, 0xffff0000, v215
	v_pk_fma_f32 v[96:97], v[76:77], 0.5, v[96:97] op_sel_hi:[1,0,1]
	v_lshl_add_u64 v[76:77], v[168:169], 0, s[36:37]
	v_lshlrev_b32_e32 v184, 16, v196
	v_and_b32_e32 v185, 0xffff0000, v196
	v_cvt_pk_bf16_f32 v114, v120, v121
	v_pk_fma_f32 v[120:121], v[108:109], 0.5, v[182:183] op_sel_hi:[1,0,1]
	v_pk_fma_f32 v[94:95], v[98:99], 0.5, v[94:95] op_sel_hi:[1,0,1]
	v_lshlrev_b64 v[182:183], 11, v[76:77]
	v_lshlrev_b32_e32 v98, 16, v138
	v_and_b32_e32 v99, 0xffff0000, v138
	v_pk_fma_f32 v[108:109], v[104:105], 0.5, v[184:185] op_sel_hi:[1,0,1]
	v_lshl_add_u64 v[184:185], v[174:175], 0, v[182:183]
	v_pk_fma_f32 v[98:99], v[72:73], 0.5, v[98:99] op_sel_hi:[1,0,1]
	v_lshlrev_b32_e32 v72, 16, v137
	v_and_b32_e32 v73, 0xffff0000, v137
	v_lshlrev_b32_e32 v218, 16, v210
	v_and_b32_e32 v219, 0xffff0000, v210
	global_load_dwordx4 v[210:213], v[184:185], off
	v_pk_fma_f32 v[136:137], v[78:79], 0.5, v[72:73] op_sel_hi:[1,0,1]
	v_lshlrev_b32_e32 v72, 16, v139
	v_and_b32_e32 v73, 0xffff0000, v139
	v_pk_fma_f32 v[138:139], v[74:75], 0.5, v[72:73] op_sel_hi:[1,0,1]
	v_lshlrev_b32_e32 v72, 16, v132
	v_and_b32_e32 v73, 0xffff0000, v132
	v_pk_fma_f32 v[74:75], v[84:85], 0.5, v[72:73] op_sel_hi:[1,0,1]
	v_lshlrev_b32_e32 v72, 16, v134
	v_and_b32_e32 v73, 0xffff0000, v134
	v_pk_fma_f32 v[78:79], v[80:81], 0.5, v[72:73] op_sel_hi:[1,0,1]
	v_lshlrev_b32_e32 v72, 16, v133
	v_and_b32_e32 v73, 0xffff0000, v133
	v_pk_fma_f32 v[100:101], v[100:101], 0.5, v[218:219] op_sel_hi:[1,0,1]
	global_load_dwordx4 v[218:221], v[184:185], off offset:256
	v_pk_fma_f32 v[80:81], v[86:87], 0.5, v[72:73] op_sel_hi:[1,0,1]
	v_lshlrev_b32_e32 v72, 16, v135
	v_and_b32_e32 v73, 0xffff0000, v135
	v_pk_fma_f32 v[82:83], v[82:83], 0.5, v[72:73] op_sel_hi:[1,0,1]
	v_lshl_add_u64 v[72:73], v[168:169], 0, s[10:11]
	v_lshlrev_b64 v[132:133], 11, v[72:73]
	v_lshl_add_u64 v[134:135], v[174:175], 0, v[132:133]
	v_lshlrev_b32_e32 v84, 16, v128
	v_and_b32_e32 v85, 0xffff0000, v128
	global_load_dwordx4 v[226:229], v[134:135], off
	global_load_dwordx4 v[234:237], v[134:135], off offset:256
	v_pk_fma_f32 v[84:85], v[68:69], 0.5, v[84:85] op_sel_hi:[1,0,1]
	v_lshlrev_b32_e32 v68, 16, v130
	v_and_b32_e32 v69, 0xffff0000, v130
	v_pk_fma_f32 v[86:87], v[64:65], 0.5, v[68:69] op_sel_hi:[1,0,1]
	v_lshlrev_b32_e32 v64, 16, v129
	v_and_b32_e32 v65, 0xffff0000, v129
	s_mov_b64 s[10:11], 0xa0
	v_pk_fma_f32 v[128:129], v[70:71], 0.5, v[64:65] op_sel_hi:[1,0,1]
	v_lshl_add_u64 v[70:71], v[168:169], 0, s[10:11]
	s_mov_b64 s[10:11], 0xb0
	v_lshlrev_b32_e32 v64, 16, v131
	v_and_b32_e32 v65, 0xffff0000, v131
	v_lshlrev_b64 v[134:135], 11, v[70:71]
	v_lshl_add_u64 v[68:69], v[168:169], 0, s[10:11]
	v_pk_fma_f32 v[130:131], v[66:67], 0.5, v[64:65] op_sel_hi:[1,0,1]
	v_lshl_add_u64 v[64:65], v[174:175], 0, v[134:135]
	v_lshlrev_b64 v[184:185], 11, v[68:69]
	global_load_dwordx4 v[238:241], v[64:65], off
	global_load_dwordx4 v[242:245], v[64:65], off offset:256
	v_lshl_add_u64 v[64:65], v[174:175], 0, v[184:185]
	global_load_dwordx4 v[246:249], v[64:65], off
	s_nop 0
	global_load_dwordx4 v[64:67], v[64:65], off offset:256
	v_lshlrev_b32_e32 v194, 16, v195
	v_and_b32_e32 v195, 0xffff0000, v195
	v_lshlrev_b32_e32 v196, 16, v197
	v_and_b32_e32 v197, 0xffff0000, v197
	v_cvt_pk_bf16_f32 v115, v122, v123
	v_cvt_pk_bf16_f32 v119, v148, v149
	v_pk_fma_f32 v[122:123], v[110:111], 0.5, v[194:195] op_sel_hi:[1,0,1]
	v_pk_fma_f32 v[110:111], v[106:107], 0.5, v[196:197] op_sel_hi:[1,0,1]
	global_store_dwordx4 v[172:173], v[112:115], off
	global_store_dwordx4 v[172:173], v[116:119], off offset:256
	v_cvt_pk_bf16_f32 v104, v120, v121
	v_lshl_add_u64 v[112:113], s[28:29], 0, v[176:177]
	v_cvt_pk_bf16_f32 v105, v122, v123
	v_cvt_pk_bf16_f32 v106, v108, v109
	v_cvt_pk_bf16_f32 v107, v110, v111
	v_lshl_add_u64 v[112:113], v[112:113], 0, v[170:171]
	v_cvt_pk_bf16_f32 v146, v100, v101
	v_cvt_pk_bf16_f32 v147, v102, v103
	v_cvt_pk_bf16_f32 v148, v124, v125
	v_cvt_pk_bf16_f32 v149, v126, v127
	global_store_dwordx4 v[112:113], v[104:107], off
	global_store_dwordx4 v[112:113], v[146:149], off offset:256
	v_cvt_pk_bf16_f32 v194, v92, v93
	v_lshl_add_u64 v[104:105], s[28:29], 0, v[180:181]
	v_cvt_pk_bf16_f32 v195, v94, v95
	v_cvt_pk_bf16_f32 v196, v88, v89
	v_cvt_pk_bf16_f32 v197, v90, v91
	v_lshl_add_u64 v[104:105], v[104:105], 0, v[170:171]
	v_cvt_pk_bf16_f32 v214, v96, v97
	v_cvt_pk_bf16_f32 v215, v136, v137
	v_cvt_pk_bf16_f32 v216, v98, v99
	v_cvt_pk_bf16_f32 v217, v138, v139
	global_store_dwordx4 v[104:105], v[194:197], off
	global_store_dwordx4 v[104:105], v[214:217], off offset:256
	v_lshl_add_u64 v[104:105], s[28:29], 0, v[178:179]
	v_cvt_pk_bf16_f32 v222, v74, v75
	v_cvt_pk_bf16_f32 v223, v80, v81
	v_cvt_pk_bf16_f32 v224, v78, v79
	v_cvt_pk_bf16_f32 v225, v82, v83
	v_lshl_add_u64 v[104:105], v[104:105], 0, v[170:171]
	v_cvt_pk_bf16_f32 v230, v84, v85
	v_cvt_pk_bf16_f32 v231, v128, v129
	v_cvt_pk_bf16_f32 v232, v86, v87
	v_cvt_pk_bf16_f32 v233, v130, v131
	global_store_dwordx4 v[104:105], v[222:225], off
	global_store_dwordx4 v[104:105], v[230:233], off offset:256
	s_waitcnt vmcnt(0)
	v_lshlrev_b32_e32 v104, 16, v210
	v_and_b32_e32 v105, 0xffff0000, v210
	v_pk_fma_f32 v[60:61], v[60:61], 0.5, v[104:105] op_sel_hi:[1,0,1]
	v_lshlrev_b32_e32 v104, 16, v212
	v_and_b32_e32 v105, 0xffff0000, v212
	v_pk_fma_f32 v[56:57], v[56:57], 0.5, v[104:105] op_sel_hi:[1,0,1]
	v_lshlrev_b32_e32 v104, 16, v211
	v_and_b32_e32 v105, 0xffff0000, v211
	v_pk_fma_f32 v[62:63], v[62:63], 0.5, v[104:105] op_sel_hi:[1,0,1]
	v_lshlrev_b32_e32 v104, 16, v213
	v_and_b32_e32 v105, 0xffff0000, v213
	v_pk_fma_f32 v[58:59], v[58:59], 0.5, v[104:105] op_sel_hi:[1,0,1]
	v_lshlrev_b32_e32 v104, 16, v218
	v_and_b32_e32 v105, 0xffff0000, v218
	v_pk_fma_f32 v[52:53], v[52:53], 0.5, v[104:105] op_sel_hi:[1,0,1]
	v_lshlrev_b32_e32 v104, 16, v220
	v_and_b32_e32 v105, 0xffff0000, v220
	v_pk_fma_f32 v[104:105], v[44:45], 0.5, v[104:105] op_sel_hi:[1,0,1]
	v_lshlrev_b32_e32 v44, 16, v219
	v_and_b32_e32 v45, 0xffff0000, v219
	v_pk_fma_f32 v[54:55], v[54:55], 0.5, v[44:45] op_sel_hi:[1,0,1]
	v_lshlrev_b32_e32 v44, 16, v221
	v_and_b32_e32 v45, 0xffff0000, v221
	v_pk_fma_f32 v[106:107], v[46:47], 0.5, v[44:45] op_sel_hi:[1,0,1]
	v_lshlrev_b32_e32 v44, 16, v226
	v_and_b32_e32 v45, 0xffff0000, v226
	v_pk_fma_f32 v[44:45], v[48:49], 0.5, v[44:45] op_sel_hi:[1,0,1]
	v_lshlrev_b32_e32 v48, 16, v229
	v_and_b32_e32 v49, 0xffff0000, v229
	v_pk_fma_f32 v[42:43], v[42:43], 0.5, v[48:49] op_sel_hi:[1,0,1]
	v_lshlrev_b32_e32 v48, 16, v234
	v_and_b32_e32 v49, 0xffff0000, v234
	v_pk_fma_f32 v[36:37], v[36:37], 0.5, v[48:49] op_sel_hi:[1,0,1]
	v_lshlrev_b32_e32 v48, 16, v236
	v_and_b32_e32 v49, 0xffff0000, v236
	v_lshlrev_b32_e32 v46, 16, v228
	v_and_b32_e32 v47, 0xffff0000, v228
	v_pk_fma_f32 v[48:49], v[28:29], 0.5, v[48:49] op_sel_hi:[1,0,1]
	v_lshlrev_b32_e32 v28, 16, v235
	v_and_b32_e32 v29, 0xffff0000, v235
	v_pk_fma_f32 v[40:41], v[40:41], 0.5, v[46:47] op_sel_hi:[1,0,1]
	v_lshlrev_b32_e32 v46, 16, v227
	v_and_b32_e32 v47, 0xffff0000, v227
	v_pk_fma_f32 v[38:39], v[38:39], 0.5, v[28:29] op_sel_hi:[1,0,1]
	v_lshlrev_b32_e32 v28, 16, v237
	v_and_b32_e32 v29, 0xffff0000, v237
	v_pk_fma_f32 v[46:47], v[50:51], 0.5, v[46:47] op_sel_hi:[1,0,1]
	v_pk_fma_f32 v[50:51], v[30:31], 0.5, v[28:29] op_sel_hi:[1,0,1]
	v_lshlrev_b32_e32 v28, 16, v238
	v_and_b32_e32 v29, 0xffff0000, v238
	v_lshlrev_b32_e32 v180, 16, v64
	v_and_b32_e32 v181, 0xffff0000, v64
	v_pk_fma_f32 v[28:29], v[32:33], 0.5, v[28:29] op_sel_hi:[1,0,1]
	v_lshlrev_b32_e32 v32, 16, v241
	v_and_b32_e32 v33, 0xffff0000, v241
	v_pk_fma_f32 v[4:5], v[4:5], 0.5, v[180:181] op_sel_hi:[1,0,1]
	v_lshlrev_b32_e32 v180, 16, v66
	v_and_b32_e32 v181, 0xffff0000, v66
	v_pk_fma_f32 v[26:27], v[26:27], 0.5, v[32:33] op_sel_hi:[1,0,1]
	v_lshlrev_b32_e32 v32, 16, v242
	v_and_b32_e32 v33, 0xffff0000, v242
	v_pk_fma_f32 v[0:1], v[0:1], 0.5, v[180:181] op_sel_hi:[1,0,1]
	v_lshl_add_u64 v[180:181], s[28:29], 0, v[182:183]
	v_cvt_pk_bf16_f32 v112, v60, v61
	v_cvt_pk_bf16_f32 v113, v62, v63
	v_cvt_pk_bf16_f32 v114, v56, v57
	v_cvt_pk_bf16_f32 v115, v58, v59
	v_pk_fma_f32 v[20:21], v[20:21], 0.5, v[32:33] op_sel_hi:[1,0,1]
	v_lshlrev_b32_e32 v32, 16, v244
	v_and_b32_e32 v33, 0xffff0000, v244
	v_lshl_add_u64 v[180:181], v[180:181], 0, v[170:171]
	v_cvt_pk_bf16_f32 v116, v52, v53
	v_cvt_pk_bf16_f32 v117, v54, v55
	v_cvt_pk_bf16_f32 v118, v104, v105
	v_cvt_pk_bf16_f32 v119, v106, v107
	v_lshlrev_b32_e32 v30, 16, v240
	v_and_b32_e32 v31, 0xffff0000, v240
	v_pk_fma_f32 v[32:33], v[12:13], 0.5, v[32:33] op_sel_hi:[1,0,1]
	v_lshlrev_b32_e32 v12, 16, v243
	v_and_b32_e32 v13, 0xffff0000, v243
	global_store_dwordx4 v[180:181], v[112:115], off
	global_store_dwordx4 v[180:181], v[116:119], off offset:256
	v_cvt_pk_bf16_f32 v146, v44, v45
	v_lshl_add_u64 v[112:113], s[28:29], 0, v[132:133]
	v_cvt_pk_bf16_f32 v147, v46, v47
	v_cvt_pk_bf16_f32 v148, v40, v41
	v_cvt_pk_bf16_f32 v149, v42, v43
	v_pk_fma_f32 v[24:25], v[24:25], 0.5, v[30:31] op_sel_hi:[1,0,1]
	v_lshlrev_b32_e32 v30, 16, v239
	v_and_b32_e32 v31, 0xffff0000, v239
	v_pk_fma_f32 v[22:23], v[22:23], 0.5, v[12:13] op_sel_hi:[1,0,1]
	v_lshlrev_b32_e32 v12, 16, v245
	v_and_b32_e32 v13, 0xffff0000, v245
	v_lshl_add_u64 v[112:113], v[112:113], 0, v[170:171]
	v_cvt_pk_bf16_f32 v172, v36, v37
	v_cvt_pk_bf16_f32 v173, v38, v39
	v_cvt_pk_bf16_f32 v174, v48, v49
	v_cvt_pk_bf16_f32 v175, v50, v51
	v_pk_fma_f32 v[30:31], v[34:35], 0.5, v[30:31] op_sel_hi:[1,0,1]
	v_pk_fma_f32 v[34:35], v[14:15], 0.5, v[12:13] op_sel_hi:[1,0,1]
	v_lshlrev_b32_e32 v12, 16, v246
	v_and_b32_e32 v13, 0xffff0000, v246
	v_lshlrev_b32_e32 v14, 16, v248
	v_and_b32_e32 v15, 0xffff0000, v248
	global_store_dwordx4 v[112:113], v[146:149], off
	global_store_dwordx4 v[112:113], v[172:175], off offset:256
	v_lshl_add_u64 v[112:113], s[28:29], 0, v[134:135]
	v_cvt_pk_bf16_f32 v176, v28, v29
	v_cvt_pk_bf16_f32 v177, v30, v31
	v_cvt_pk_bf16_f32 v178, v24, v25
	v_cvt_pk_bf16_f32 v179, v26, v27
	v_pk_fma_f32 v[12:13], v[16:17], 0.5, v[12:13] op_sel_hi:[1,0,1]
	v_pk_fma_f32 v[8:9], v[8:9], 0.5, v[14:15] op_sel_hi:[1,0,1]
	v_lshlrev_b32_e32 v14, 16, v247
	v_and_b32_e32 v15, 0xffff0000, v247
	v_lshlrev_b32_e32 v16, 16, v249
	v_and_b32_e32 v17, 0xffff0000, v249
	v_lshlrev_b32_e32 v64, 16, v65
	v_and_b32_e32 v65, 0xffff0000, v65
	v_lshl_add_u64 v[112:113], v[112:113], 0, v[170:171]
	v_cvt_pk_bf16_f32 v194, v20, v21
	v_cvt_pk_bf16_f32 v195, v22, v23
	v_cvt_pk_bf16_f32 v196, v32, v33
	v_cvt_pk_bf16_f32 v197, v34, v35
	v_pk_fma_f32 v[14:15], v[18:19], 0.5, v[14:15] op_sel_hi:[1,0,1]
	v_pk_fma_f32 v[10:11], v[10:11], 0.5, v[16:17] op_sel_hi:[1,0,1]
	v_pk_fma_f32 v[6:7], v[6:7], 0.5, v[64:65] op_sel_hi:[1,0,1]
	v_lshlrev_b32_e32 v64, 16, v67
	v_and_b32_e32 v65, 0xffff0000, v67
	global_store_dwordx4 v[112:113], v[176:179], off
	global_store_dwordx4 v[112:113], v[194:197], off offset:256
	v_lshl_add_u64 v[112:113], s[28:29], 0, v[184:185]
	v_cvt_pk_bf16_f32 v16, v12, v13
	v_cvt_pk_bf16_f32 v17, v14, v15
	v_cvt_pk_bf16_f32 v18, v8, v9
	v_cvt_pk_bf16_f32 v19, v10, v11
	v_pk_fma_f32 v[2:3], v[2:3], 0.5, v[64:65] op_sel_hi:[1,0,1]
	v_lshl_add_u64 v[112:113], v[112:113], 0, v[170:171]
	v_cvt_pk_bf16_f32 v64, v4, v5
	v_cvt_pk_bf16_f32 v65, v6, v7
	v_cvt_pk_bf16_f32 v66, v0, v1
	v_cvt_pk_bf16_f32 v67, v2, v3
	global_store_dwordx4 v[112:113], v[16:19], off
	global_store_dwordx4 v[112:113], v[64:67], off offset:256
	s_lshl_b32 s10, s81, 2
	v_and_b32_e32 v17, 64, v188
	v_xor_b32_e32 v16, 16, v188
	v_add_u32_e32 v17, 64, v17
	v_cmp_lt_i32_e32 vcc, v16, v17
	v_xor_b32_e32 v18, 32, v188
	s_ashr_i32 s11, s10, 31
	v_cndmask_b32_e32 v16, v188, v16, vcc
	v_lshlrev_b32_e32 v16, 2, v16
	ds_bpermute_b32 v19, v16, v209
	v_cmp_lt_i32_e32 vcc, v18, v17
	s_lshl_b64 s[10:11], s[10:11], 2
	s_add_u32 s38, s73, s10
	v_cndmask_b32_e32 v17, v188, v18, vcc
	v_lshlrev_b32_e32 v17, 2, v17
	s_waitcnt lgkmcnt(0)
	v_add_f32_e32 v18, v209, v19
	ds_bpermute_b32 v19, v17, v18
	s_addc_u32 s39, s74, s11
	s_and_saveexec_b64 s[46:47], s[42:43]
	s_cbranch_execz .LBB0_34
	s_waitcnt lgkmcnt(0)
	v_add_f32_e32 v64, v18, v19
	v_lshlrev_b64 v[18:19], 6, v[168:169]
	v_lshl_add_u64 v[18:19], s[38:39], 0, v[18:19]
	global_store_dword v[18:19], v64, off

.Lm4bp_77:
	s_waitcnt lgkmcnt(0)
	s_mov_b32 s100, 0
	s_barrier
	s_nop 0
	v_mfma_f32_16x16x32_bf16 v[60:63], v[158:161], v[174:177], 0
	v_mfma_f32_16x16x32_bf16 v[56:59], v[166:169], v[174:177], 0
	v_mfma_f32_16x16x32_bf16 v[52:55], v[158:161], v[182:185], 0
	v_mfma_f32_16x16x32_bf16 v[48:51], v[166:169], v[182:185], 0
	v_mfma_f32_16x16x32_bf16 v[44:47], v[158:161], v[210:213], 0
	v_mfma_f32_16x16x32_bf16 v[40:43], v[166:169], v[210:213], 0
	v_mfma_f32_16x16x32_bf16 v[36:39], v[158:161], v[218:221], 0
	v_mfma_f32_16x16x32_bf16 v[32:35], v[166:169], v[218:221], 0
	v_mfma_f32_16x16x32_bf16 v[60:63], v[162:165], v[178:181], v[60:63]
	v_mfma_f32_16x16x32_bf16 v[56:59], v[170:173], v[178:181], v[56:59]
	v_mfma_f32_16x16x32_bf16 v[52:55], v[162:165], v[206:209], v[52:55]
	v_mfma_f32_16x16x32_bf16 v[48:51], v[170:173], v[206:209], v[48:51]
	v_mfma_f32_16x16x32_bf16 v[44:47], v[162:165], v[214:217], v[44:47]
	v_mfma_f32_16x16x32_bf16 v[40:43], v[170:173], v[214:217], v[40:43]
	v_mfma_f32_16x16x32_bf16 v[36:39], v[162:165], v[222:225], v[36:39]
	v_mfma_f32_16x16x32_bf16 v[32:35], v[170:173], v[222:225], v[32:35]
	v_mfma_f32_16x16x32_bf16 v[28:31], v[226:229], v[174:177], 0
	v_mfma_f32_16x16x32_bf16 v[24:27], v[234:237], v[174:177], 0
	v_mfma_f32_16x16x32_bf16 v[20:23], v[226:229], v[182:185], 0
	v_mfma_f32_16x16x32_bf16 v[16:19], v[234:237], v[182:185], 0
	v_mfma_f32_16x16x32_bf16 v[12:15], v[226:229], v[210:213], 0
	v_mfma_f32_16x16x32_bf16 v[8:11], v[234:237], v[210:213], 0
	v_mfma_f32_16x16x32_bf16 v[4:7], v[226:229], v[218:221], 0
	v_mfma_f32_16x16x32_bf16 v[0:3], v[234:237], v[218:221], 0
	v_mfma_f32_16x16x32_bf16 v[28:31], v[230:233], v[178:181], v[28:31]
	v_mfma_f32_16x16x32_bf16 v[24:27], v[238:241], v[178:181], v[24:27]
	v_mfma_f32_16x16x32_bf16 v[20:23], v[230:233], v[206:209], v[20:23]
	v_mfma_f32_16x16x32_bf16 v[16:19], v[238:241], v[206:209], v[16:19]
	v_mfma_f32_16x16x32_bf16 v[12:15], v[230:233], v[214:217], v[12:15]
	v_mfma_f32_16x16x32_bf16 v[8:11], v[238:241], v[214:217], v[8:11]
	v_mfma_f32_16x16x32_bf16 v[4:7], v[230:233], v[222:225], v[4:7]
	v_mfma_f32_16x16x32_bf16 v[0:3], v[238:241], v[222:225], v[0:3]
	s_barrier
	s_add_i32 s6, 0, 0x18000
	v_add_u32_e32 v170, s6, v154
	ds_read_b128 v[158:161], v170
	ds_read_b128 v[162:165], v170 offset:1024
	ds_read_b128 v[166:169], v170 offset:2048
	ds_read_b128 v[170:173], v170 offset:3072
	s_add_u32 s54, s54, 0x40000
	s_addc_u32 s55, s55, 0
	s_mov_b32 m0, s70
	v_lshl_add_u64 v[226:227], s[54:55], 0, v[128:129]
	ds_read_b128 v[174:177], v157 offset:32768
	ds_read_b128 v[178:181], v157 offset:33792
	ds_read_b128 v[182:185], v157 offset:34816
	ds_read_b128 v[206:209], v157 offset:35840
	ds_read_b128 v[210:213], v157 offset:36864
	ds_read_b128 v[214:217], v157 offset:37888
	ds_read_b128 v[218:221], v157 offset:38912
	ds_read_b128 v[222:225], v157 offset:39936
	global_load_lds_dwordx4 v[226:227], off
	v_lshl_add_u64 v[226:227], s[54:55], 0, v[130:131]
	s_mov_b32 m0, s71
	s_nop 0
	global_load_lds_dwordx4 v[226:227], off
	s_add_i32 s19, 0, 0x1c000
	v_add_u32_e32 v192, s19, v154
	ds_read_b128 v[226:229], v192
	ds_read_b128 v[230:233], v192 offset:1024
	ds_read_b128 v[234:237], v192 offset:2048
	ds_read_b128 v[238:241], v192 offset:3072
	s_waitcnt vmcnt(8)
	s_waitcnt lgkmcnt(0)
	s_barrier
	v_mfma_f32_16x16x32_bf16 v[124:127], v[158:161], v[174:177], v[124:127]
	v_mfma_f32_16x16x32_bf16 v[120:123], v[166:169], v[174:177], v[120:123]
	v_mfma_f32_16x16x32_bf16 v[116:119], v[158:161], v[182:185], v[116:119]
	v_mfma_f32_16x16x32_bf16 v[112:115], v[166:169], v[182:185], v[112:115]
	v_mfma_f32_16x16x32_bf16 v[108:111], v[158:161], v[210:213], v[108:111]
	v_mfma_f32_16x16x32_bf16 v[104:107], v[166:169], v[210:213], v[104:107]
	v_mfma_f32_16x16x32_bf16 v[100:103], v[158:161], v[218:221], v[100:103]
	v_mfma_f32_16x16x32_bf16 v[96:99], v[166:169], v[218:221], v[96:99]
	v_mfma_f32_16x16x32_bf16 v[124:127], v[162:165], v[178:181], v[124:127]
	v_mfma_f32_16x16x32_bf16 v[120:123], v[170:173], v[178:181], v[120:123]
	v_mfma_f32_16x16x32_bf16 v[116:119], v[162:165], v[206:209], v[116:119]
	v_mfma_f32_16x16x32_bf16 v[112:115], v[170:173], v[206:209], v[112:115]
	v_mfma_f32_16x16x32_bf16 v[108:111], v[162:165], v[214:217], v[108:111]
	v_mfma_f32_16x16x32_bf16 v[104:107], v[170:173], v[214:217], v[104:107]
	v_mfma_f32_16x16x32_bf16 v[100:103], v[162:165], v[222:225], v[100:103]
	v_mfma_f32_16x16x32_bf16 v[96:99], v[170:173], v[222:225], v[96:99]
	v_mfma_f32_16x16x32_bf16 v[92:95], v[226:229], v[174:177], v[92:95]
	v_mfma_f32_16x16x32_bf16 v[88:91], v[234:237], v[174:177], v[88:91]
	v_mfma_f32_16x16x32_bf16 v[84:87], v[226:229], v[182:185], v[84:87]
	v_mfma_f32_16x16x32_bf16 v[80:83], v[234:237], v[182:185], v[80:83]
	v_mfma_f32_16x16x32_bf16 v[76:79], v[226:229], v[210:213], v[76:79]
	v_mfma_f32_16x16x32_bf16 v[72:75], v[234:237], v[210:213], v[72:75]
	v_mfma_f32_16x16x32_bf16 v[68:71], v[226:229], v[218:221], v[68:71]
	v_mfma_f32_16x16x32_bf16 v[64:67], v[234:237], v[218:221], v[64:67]
	v_mfma_f32_16x16x32_bf16 v[92:95], v[230:233], v[178:181], v[92:95]
	v_mfma_f32_16x16x32_bf16 v[88:91], v[238:241], v[178:181], v[88:91]
	v_mfma_f32_16x16x32_bf16 v[84:87], v[230:233], v[206:209], v[84:87]
	v_mfma_f32_16x16x32_bf16 v[80:83], v[238:241], v[206:209], v[80:83]
	v_mfma_f32_16x16x32_bf16 v[76:79], v[230:233], v[214:217], v[76:79]
	v_mfma_f32_16x16x32_bf16 v[72:75], v[238:241], v[214:217], v[72:75]
	v_mfma_f32_16x16x32_bf16 v[68:71], v[230:233], v[222:225], v[68:71]
	v_mfma_f32_16x16x32_bf16 v[64:67], v[238:241], v[222:225], v[64:67]
	s_barrier
	s_add_i32 s6, s6, s59
	v_lshl_add_u64 v[146:147], v[146:147], 0, s[36:37]
	s_mov_b32 m0, s6
	s_nop 0
	global_load_lds_dwordx4 v[146:147], off
	v_lshl_add_u64 v[146:147], v[148:149], 0, s[36:37]
	s_add_i32 m0, s6, 0x2000
	s_nop 0
	global_load_lds_dwordx4 v[146:147], off
	s_mov_b32 m0, s72
	v_lshl_add_u64 v[146:147], v[194:195], 0, s[36:37]
	ds_read_b128 v[174:177], v157 offset:49152
	ds_read_b128 v[178:181], v157 offset:50176
	ds_read_b128 v[182:185], v157 offset:51200
	ds_read_b128 v[206:209], v157 offset:52224
	ds_read_b128 v[210:213], v157 offset:53248
	ds_read_b128 v[214:217], v157 offset:54272
	ds_read_b128 v[218:221], v157 offset:55296
	ds_read_b128 v[222:225], v157 offset:56320
	global_load_lds_dwordx4 v[146:147], off
	v_lshl_add_u64 v[146:147], v[196:197], 0, s[36:37]
	s_mov_b32 m0, s73
	s_nop 0
	global_load_lds_dwordx4 v[146:147], off
	s_add_u32 s52, s52, 0x40080
	s_addc_u32 s53, s53, 0
	s_add_i32 s6, s19, s59
	v_lshl_add_u64 v[146:147], s[52:53], 0, v[140:141]
	s_mov_b32 m0, s6
	s_nop 0
	global_load_lds_dwordx4 v[146:147], off
	v_lshl_add_u64 v[146:147], s[52:53], 0, v[132:133]
	s_add_i32 m0, s6, 0x2000
	s_nop 0
	global_load_lds_dwordx4 v[146:147], off
	s_add_i32 s81, s81, 2
	s_add_u32 s50, s50, 0x100
	s_addc_u32 s51, s51, 0
	s_cmp_gt_u32 s81, 13
	s_nop 0
	s_waitcnt vmcnt(8)
	s_waitcnt lgkmcnt(0)
	s_barrier
	v_mfma_f32_16x16x32_bf16 v[60:63], v[158:161], v[174:177], v[60:63]
	v_mfma_f32_16x16x32_bf16 v[56:59], v[166:169], v[174:177], v[56:59]
	v_mfma_f32_16x16x32_bf16 v[52:55], v[158:161], v[182:185], v[52:55]
	v_mfma_f32_16x16x32_bf16 v[48:51], v[166:169], v[182:185], v[48:51]
	v_mfma_f32_16x16x32_bf16 v[44:47], v[158:161], v[210:213], v[44:47]
	v_mfma_f32_16x16x32_bf16 v[40:43], v[166:169], v[210:213], v[40:43]
	v_mfma_f32_16x16x32_bf16 v[36:39], v[158:161], v[218:221], v[36:39]
	v_mfma_f32_16x16x32_bf16 v[32:35], v[166:169], v[218:221], v[32:35]
	v_mfma_f32_16x16x32_bf16 v[60:63], v[162:165], v[178:181], v[60:63]
	v_mfma_f32_16x16x32_bf16 v[56:59], v[170:173], v[178:181], v[56:59]
	v_mfma_f32_16x16x32_bf16 v[52:55], v[162:165], v[206:209], v[52:55]
	v_mfma_f32_16x16x32_bf16 v[48:51], v[170:173], v[206:209], v[48:51]
	v_mfma_f32_16x16x32_bf16 v[44:47], v[162:165], v[214:217], v[44:47]
	v_mfma_f32_16x16x32_bf16 v[40:43], v[170:173], v[214:217], v[40:43]
	v_mfma_f32_16x16x32_bf16 v[36:39], v[162:165], v[222:225], v[36:39]
	v_mfma_f32_16x16x32_bf16 v[32:35], v[170:173], v[222:225], v[32:35]
	v_mfma_f32_16x16x32_bf16 v[28:31], v[226:229], v[174:177], v[28:31]
	v_mfma_f32_16x16x32_bf16 v[24:27], v[234:237], v[174:177], v[24:27]
	v_mfma_f32_16x16x32_bf16 v[20:23], v[226:229], v[182:185], v[20:23]
	v_mfma_f32_16x16x32_bf16 v[16:19], v[234:237], v[182:185], v[16:19]
	v_mfma_f32_16x16x32_bf16 v[12:15], v[226:229], v[210:213], v[12:15]
	v_mfma_f32_16x16x32_bf16 v[8:11], v[234:237], v[210:213], v[8:11]
	v_mfma_f32_16x16x32_bf16 v[4:7], v[226:229], v[218:221], v[4:7]
	v_mfma_f32_16x16x32_bf16 v[0:3], v[234:237], v[218:221], v[0:3]
	v_mfma_f32_16x16x32_bf16 v[28:31], v[230:233], v[178:181], v[28:31]
	v_mfma_f32_16x16x32_bf16 v[24:27], v[238:241], v[178:181], v[24:27]
	v_mfma_f32_16x16x32_bf16 v[20:23], v[230:233], v[206:209], v[20:23]
	v_mfma_f32_16x16x32_bf16 v[16:19], v[238:241], v[206:209], v[16:19]
	v_mfma_f32_16x16x32_bf16 v[12:15], v[230:233], v[214:217], v[12:15]
	v_mfma_f32_16x16x32_bf16 v[8:11], v[238:241], v[214:217], v[8:11]
	v_mfma_f32_16x16x32_bf16 v[4:7], v[230:233], v[222:225], v[4:7]
	v_mfma_f32_16x16x32_bf16 v[0:3], v[238:241], v[222:225], v[0:3]
	s_barrier
.LBB0_77:
	s_add_u32 s6, s26, s50
	s_addc_u32 s19, s27, s51
	s_add_u32 s6, s6, 0x100
	s_addc_u32 s19, s19, 0
	s_add_u32 s23, s10, s50
	s_addc_u32 s52, s11, s51
	s_add_i32 s82, 0, 0x10000
	v_add_u32_e32 v146, s82, v154
	ds_read_b128 v[158:161], v146
	ds_read_b128 v[162:165], v146 offset:1024
	ds_read_b128 v[166:169], v146 offset:2048
	ds_read_b128 v[170:173], v146 offset:3072
	s_cmpk_eq_i32 s50, 0x700
	s_cselect_b32 s55, s12, s19
	s_cselect_b32 s54, s31, s6
	s_cselect_b32 s53, s35, s52
	s_cselect_b32 s52, s39, s23
	v_lshl_add_u64 v[146:147], v[150:151], 0, s[50:51]
	s_add_i32 m0, s68, 0xc000
	ds_read_b128 v[174:177], v157
	ds_read_b128 v[178:181], v157 offset:1024
	ds_read_b128 v[182:185], v157 offset:2048
	ds_read_b128 v[206:209], v157 offset:3072
	ds_read_b128 v[210:213], v157 offset:4096
	ds_read_b128 v[214:217], v157 offset:5120
	ds_read_b128 v[218:221], v157 offset:6144
	ds_read_b128 v[222:225], v157 offset:7168
	global_load_lds_dwordx4 v[146:147], off
	v_lshl_add_u64 v[146:147], v[152:153], 0, s[50:51]
	s_add_i32 m0, s68, 0xe000
	s_nop 0
	global_load_lds_dwordx4 v[146:147], off
	s_add_i32 s6, 0, 0x14000
	v_add_u32_e32 v146, s6, v154
	ds_read_b128 v[226:229], v146
	ds_read_b128 v[230:233], v146 offset:1024
	ds_read_b128 v[234:237], v146 offset:2048
	ds_read_b128 v[238:241], v146 offset:3072
	s_nop 0
	s_waitcnt vmcnt(8)
	s_waitcnt lgkmcnt(0)
	s_barrier
	v_mfma_f32_16x16x32_bf16 v[124:127], v[158:161], v[174:177], v[124:127]
	v_mfma_f32_16x16x32_bf16 v[120:123], v[166:169], v[174:177], v[120:123]
	v_mfma_f32_16x16x32_bf16 v[116:119], v[158:161], v[182:185], v[116:119]
	v_mfma_f32_16x16x32_bf16 v[112:115], v[166:169], v[182:185], v[112:115]
	v_mfma_f32_16x16x32_bf16 v[108:111], v[158:161], v[210:213], v[108:111]
	v_mfma_f32_16x16x32_bf16 v[104:107], v[166:169], v[210:213], v[104:107]
	v_mfma_f32_16x16x32_bf16 v[100:103], v[158:161], v[218:221], v[100:103]
	v_mfma_f32_16x16x32_bf16 v[96:99], v[166:169], v[218:221], v[96:99]
	v_mfma_f32_16x16x32_bf16 v[124:127], v[162:165], v[178:181], v[124:127]
	v_mfma_f32_16x16x32_bf16 v[120:123], v[170:173], v[178:181], v[120:123]
	v_mfma_f32_16x16x32_bf16 v[116:119], v[162:165], v[206:209], v[116:119]
	v_mfma_f32_16x16x32_bf16 v[112:115], v[170:173], v[206:209], v[112:115]
	v_mfma_f32_16x16x32_bf16 v[108:111], v[162:165], v[214:217], v[108:111]
	v_mfma_f32_16x16x32_bf16 v[104:107], v[170:173], v[214:217], v[104:107]
	v_mfma_f32_16x16x32_bf16 v[100:103], v[162:165], v[222:225], v[100:103]
	v_mfma_f32_16x16x32_bf16 v[96:99], v[170:173], v[222:225], v[96:99]
	v_mfma_f32_16x16x32_bf16 v[92:95], v[226:229], v[174:177], v[92:95]
	v_mfma_f32_16x16x32_bf16 v[88:91], v[234:237], v[174:177], v[88:91]
	v_mfma_f32_16x16x32_bf16 v[84:87], v[226:229], v[182:185], v[84:87]
	v_mfma_f32_16x16x32_bf16 v[80:83], v[234:237], v[182:185], v[80:83]
	v_mfma_f32_16x16x32_bf16 v[76:79], v[226:229], v[210:213], v[76:79]
	v_mfma_f32_16x16x32_bf16 v[72:75], v[234:237], v[210:213], v[72:75]
	v_mfma_f32_16x16x32_bf16 v[68:71], v[226:229], v[218:221], v[68:71]
	v_mfma_f32_16x16x32_bf16 v[64:67], v[234:237], v[218:221], v[64:67]
	v_mfma_f32_16x16x32_bf16 v[92:95], v[230:233], v[178:181], v[92:95]
	v_mfma_f32_16x16x32_bf16 v[88:91], v[238:241], v[178:181], v[88:91]
	v_mfma_f32_16x16x32_bf16 v[84:87], v[230:233], v[206:209], v[84:87]
	v_mfma_f32_16x16x32_bf16 v[80:83], v[238:241], v[206:209], v[80:83]
	v_mfma_f32_16x16x32_bf16 v[76:79], v[230:233], v[214:217], v[76:79]
	v_mfma_f32_16x16x32_bf16 v[72:75], v[238:241], v[214:217], v[72:75]
	v_mfma_f32_16x16x32_bf16 v[68:71], v[230:233], v[222:225], v[68:71]
	v_mfma_f32_16x16x32_bf16 v[64:67], v[238:241], v[222:225], v[64:67]
	s_barrier
	s_add_i32 s19, s82, s59
	v_lshl_add_u64 v[146:147], s[52:53], 0, v[140:141]
	s_mov_b32 m0, s19
	v_lshl_add_u64 v[148:149], s[52:53], 0, v[132:133]
	global_load_lds_dwordx4 v[146:147], off
	s_add_i32 m0, s19, 0x2000
	s_nop 0
	global_load_lds_dwordx4 v[148:149], off
	s_mov_b32 m0, s68
	v_lshl_add_u64 v[194:195], s[54:55], 0, v[128:129]
	ds_read_b128 v[174:177], v157 offset:16384
	ds_read_b128 v[178:181], v157 offset:17408
	ds_read_b128 v[182:185], v157 offset:18432
	ds_read_b128 v[206:209], v157 offset:19456
	ds_read_b128 v[210:213], v157 offset:20480
	ds_read_b128 v[214:217], v157 offset:21504
	ds_read_b128 v[218:221], v157 offset:22528
	ds_read_b128 v[222:225], v157 offset:23552
	global_load_lds_dwordx4 v[194:195], off
	v_lshl_add_u64 v[196:197], s[54:55], 0, v[130:131]
	s_mov_b32 m0, s69
	s_nop 0
	global_load_lds_dwordx4 v[196:197], off
	s_add_u32 s82, s52, 0x40000
	s_addc_u32 s83, s53, 0
	s_add_i32 s6, s6, s59
	v_lshl_add_u64 v[250:251], s[82:83], 0, v[140:141]
	s_mov_b32 m0, s6
	s_nop 0
	global_load_lds_dwordx4 v[250:251], off
	v_lshl_add_u64 v[250:251], s[82:83], 0, v[132:133]
	s_add_i32 m0, s6, 0x2000
	s_nop 0
	global_load_lds_dwordx4 v[250:251], off
	s_nop 0
	s_waitcnt vmcnt(8)
	s_waitcnt lgkmcnt(0)
	s_barrier
	v_mfma_f32_16x16x32_bf16 v[60:63], v[158:161], v[174:177], v[60:63]
	v_mfma_f32_16x16x32_bf16 v[56:59], v[166:169], v[174:177], v[56:59]
	v_mfma_f32_16x16x32_bf16 v[52:55], v[158:161], v[182:185], v[52:55]
	v_mfma_f32_16x16x32_bf16 v[48:51], v[166:169], v[182:185], v[48:51]
	v_mfma_f32_16x16x32_bf16 v[44:47], v[158:161], v[210:213], v[44:47]
	v_mfma_f32_16x16x32_bf16 v[40:43], v[166:169], v[210:213], v[40:43]
	v_mfma_f32_16x16x32_bf16 v[36:39], v[158:161], v[218:221], v[36:39]
	v_mfma_f32_16x16x32_bf16 v[32:35], v[166:169], v[218:221], v[32:35]
	v_mfma_f32_16x16x32_bf16 v[60:63], v[162:165], v[178:181], v[60:63]
	v_mfma_f32_16x16x32_bf16 v[56:59], v[170:173], v[178:181], v[56:59]
	v_mfma_f32_16x16x32_bf16 v[52:55], v[162:165], v[206:209], v[52:55]
	v_mfma_f32_16x16x32_bf16 v[48:51], v[170:173], v[206:209], v[48:51]
	v_mfma_f32_16x16x32_bf16 v[44:47], v[162:165], v[214:217], v[44:47]
	v_mfma_f32_16x16x32_bf16 v[40:43], v[170:173], v[214:217], v[40:43]
	v_mfma_f32_16x16x32_bf16 v[36:39], v[162:165], v[222:225], v[36:39]
	v_mfma_f32_16x16x32_bf16 v[32:35], v[170:173], v[222:225], v[32:35]
	v_mfma_f32_16x16x32_bf16 v[28:31], v[226:229], v[174:177], v[28:31]
	v_mfma_f32_16x16x32_bf16 v[24:27], v[234:237], v[174:177], v[24:27]
	v_mfma_f32_16x16x32_bf16 v[20:23], v[226:229], v[182:185], v[20:23]
	v_mfma_f32_16x16x32_bf16 v[16:19], v[234:237], v[182:185], v[16:19]
	v_mfma_f32_16x16x32_bf16 v[12:15], v[226:229], v[210:213], v[12:15]
	v_mfma_f32_16x16x32_bf16 v[8:11], v[234:237], v[210:213], v[8:11]
	v_mfma_f32_16x16x32_bf16 v[4:7], v[226:229], v[218:221], v[4:7]
	v_mfma_f32_16x16x32_bf16 v[0:3], v[234:237], v[218:221], v[0:3]
	v_mfma_f32_16x16x32_bf16 v[28:31], v[230:233], v[178:181], v[28:31]
	v_mfma_f32_16x16x32_bf16 v[24:27], v[238:241], v[178:181], v[24:27]
	v_mfma_f32_16x16x32_bf16 v[20:23], v[230:233], v[206:209], v[20:23]
	v_mfma_f32_16x16x32_bf16 v[16:19], v[238:241], v[206:209], v[16:19]
	v_mfma_f32_16x16x32_bf16 v[12:15], v[230:233], v[214:217], v[12:15]
	v_mfma_f32_16x16x32_bf16 v[8:11], v[238:241], v[214:217], v[8:11]
	v_mfma_f32_16x16x32_bf16 v[4:7], v[230:233], v[222:225], v[4:7]
	v_mfma_f32_16x16x32_bf16 v[0:3], v[238:241], v[222:225], v[0:3]
	s_barrier
	s_add_i32 s6, 0, 0x18000
	v_add_u32_e32 v170, s6, v154
	ds_read_b128 v[158:161], v170
	ds_read_b128 v[162:165], v170 offset:1024
	ds_read_b128 v[166:169], v170 offset:2048
	ds_read_b128 v[170:173], v170 offset:3072
	s_add_u32 s54, s54, 0x40000
	s_addc_u32 s55, s55, 0
	s_mov_b32 m0, s70
	v_lshl_add_u64 v[226:227], s[54:55], 0, v[128:129]
	ds_read_b128 v[174:177], v157 offset:32768
	ds_read_b128 v[178:181], v157 offset:33792
	ds_read_b128 v[182:185], v157 offset:34816
	ds_read_b128 v[206:209], v157 offset:35840
	ds_read_b128 v[210:213], v157 offset:36864
	ds_read_b128 v[214:217], v157 offset:37888
	ds_read_b128 v[218:221], v157 offset:38912
	ds_read_b128 v[222:225], v157 offset:39936
	global_load_lds_dwordx4 v[226:227], off
	v_lshl_add_u64 v[226:227], s[54:55], 0, v[130:131]
	s_mov_b32 m0, s71
	s_nop 0
	global_load_lds_dwordx4 v[226:227], off
	s_add_i32 s19, 0, 0x1c000
	v_add_u32_e32 v192, s19, v154
	ds_read_b128 v[226:229], v192
	ds_read_b128 v[230:233], v192 offset:1024
	ds_read_b128 v[234:237], v192 offset:2048
	ds_read_b128 v[238:241], v192 offset:3072
	s_waitcnt vmcnt(8)
	s_waitcnt lgkmcnt(0)
	s_barrier
	v_mfma_f32_16x16x32_bf16 v[124:127], v[158:161], v[174:177], v[124:127]
	v_mfma_f32_16x16x32_bf16 v[120:123], v[166:169], v[174:177], v[120:123]
	v_mfma_f32_16x16x32_bf16 v[116:119], v[158:161], v[182:185], v[116:119]
	v_mfma_f32_16x16x32_bf16 v[112:115], v[166:169], v[182:185], v[112:115]
	v_mfma_f32_16x16x32_bf16 v[108:111], v[158:161], v[210:213], v[108:111]
	v_mfma_f32_16x16x32_bf16 v[104:107], v[166:169], v[210:213], v[104:107]
	v_mfma_f32_16x16x32_bf16 v[100:103], v[158:161], v[218:221], v[100:103]
	v_mfma_f32_16x16x32_bf16 v[96:99], v[166:169], v[218:221], v[96:99]
	v_mfma_f32_16x16x32_bf16 v[124:127], v[162:165], v[178:181], v[124:127]
	v_mfma_f32_16x16x32_bf16 v[120:123], v[170:173], v[178:181], v[120:123]
	v_mfma_f32_16x16x32_bf16 v[116:119], v[162:165], v[206:209], v[116:119]
	v_mfma_f32_16x16x32_bf16 v[112:115], v[170:173], v[206:209], v[112:115]
	v_mfma_f32_16x16x32_bf16 v[108:111], v[162:165], v[214:217], v[108:111]
	v_mfma_f32_16x16x32_bf16 v[104:107], v[170:173], v[214:217], v[104:107]
	v_mfma_f32_16x16x32_bf16 v[100:103], v[162:165], v[222:225], v[100:103]
	v_mfma_f32_16x16x32_bf16 v[96:99], v[170:173], v[222:225], v[96:99]
	v_mfma_f32_16x16x32_bf16 v[92:95], v[226:229], v[174:177], v[92:95]
	v_mfma_f32_16x16x32_bf16 v[88:91], v[234:237], v[174:177], v[88:91]
	v_mfma_f32_16x16x32_bf16 v[84:87], v[226:229], v[182:185], v[84:87]
	v_mfma_f32_16x16x32_bf16 v[80:83], v[234:237], v[182:185], v[80:83]
	v_mfma_f32_16x16x32_bf16 v[76:79], v[226:229], v[210:213], v[76:79]
	v_mfma_f32_16x16x32_bf16 v[72:75], v[234:237], v[210:213], v[72:75]
	v_mfma_f32_16x16x32_bf16 v[68:71], v[226:229], v[218:221], v[68:71]
	v_mfma_f32_16x16x32_bf16 v[64:67], v[234:237], v[218:221], v[64:67]
	v_mfma_f32_16x16x32_bf16 v[92:95], v[230:233], v[178:181], v[92:95]
	v_mfma_f32_16x16x32_bf16 v[88:91], v[238:241], v[178:181], v[88:91]
	v_mfma_f32_16x16x32_bf16 v[84:87], v[230:233], v[206:209], v[84:87]
	v_mfma_f32_16x16x32_bf16 v[80:83], v[238:241], v[206:209], v[80:83]
	v_mfma_f32_16x16x32_bf16 v[76:79], v[230:233], v[214:217], v[76:79]
	v_mfma_f32_16x16x32_bf16 v[72:75], v[238:241], v[214:217], v[72:75]
	v_mfma_f32_16x16x32_bf16 v[68:71], v[230:233], v[222:225], v[68:71]
	v_mfma_f32_16x16x32_bf16 v[64:67], v[238:241], v[222:225], v[64:67]
	s_barrier
	s_add_i32 s6, s6, s59
	v_lshl_add_u64 v[146:147], v[146:147], 0, s[36:37]
	s_mov_b32 m0, s6
	s_nop 0
	global_load_lds_dwordx4 v[146:147], off
	v_lshl_add_u64 v[146:147], v[148:149], 0, s[36:37]
	s_add_i32 m0, s6, 0x2000
	s_nop 0
	global_load_lds_dwordx4 v[146:147], off
	s_mov_b32 m0, s72
	v_lshl_add_u64 v[146:147], v[194:195], 0, s[36:37]
	ds_read_b128 v[174:177], v157 offset:49152
	ds_read_b128 v[178:181], v157 offset:50176
	ds_read_b128 v[182:185], v157 offset:51200
	ds_read_b128 v[206:209], v157 offset:52224
	ds_read_b128 v[210:213], v157 offset:53248
	ds_read_b128 v[214:217], v157 offset:54272
	ds_read_b128 v[218:221], v157 offset:55296
	ds_read_b128 v[222:225], v157 offset:56320
	global_load_lds_dwordx4 v[146:147], off
	v_lshl_add_u64 v[146:147], v[196:197], 0, s[36:37]
	s_mov_b32 m0, s73
	s_nop 0
	global_load_lds_dwordx4 v[146:147], off
	s_add_u32 s52, s52, 0x40080
	s_addc_u32 s53, s53, 0
	s_add_i32 s6, s19, s59
	v_lshl_add_u64 v[146:147], s[52:53], 0, v[140:141]
	s_mov_b32 m0, s6
	s_nop 0
	global_load_lds_dwordx4 v[146:147], off
	v_lshl_add_u64 v[146:147], s[52:53], 0, v[132:133]
	s_add_i32 m0, s6, 0x2000
	s_nop 0
	global_load_lds_dwordx4 v[146:147], off
	s_add_i32 s81, s81, 2
	s_add_u32 s50, s50, 0x100
	s_addc_u32 s51, s51, 0
	s_cmp_gt_u32 s81, 13
	s_nop 0
	s_waitcnt vmcnt(8)
	s_waitcnt lgkmcnt(0)
	s_barrier
	v_mfma_f32_16x16x32_bf16 v[60:63], v[158:161], v[174:177], v[60:63]
	v_mfma_f32_16x16x32_bf16 v[56:59], v[166:169], v[174:177], v[56:59]
	v_mfma_f32_16x16x32_bf16 v[52:55], v[158:161], v[182:185], v[52:55]
	v_mfma_f32_16x16x32_bf16 v[48:51], v[166:169], v[182:185], v[48:51]
	v_mfma_f32_16x16x32_bf16 v[44:47], v[158:161], v[210:213], v[44:47]
	v_mfma_f32_16x16x32_bf16 v[40:43], v[166:169], v[210:213], v[40:43]
	v_mfma_f32_16x16x32_bf16 v[36:39], v[158:161], v[218:221], v[36:39]
	v_mfma_f32_16x16x32_bf16 v[32:35], v[166:169], v[218:221], v[32:35]
	v_mfma_f32_16x16x32_bf16 v[60:63], v[162:165], v[178:181], v[60:63]
	v_mfma_f32_16x16x32_bf16 v[56:59], v[170:173], v[178:181], v[56:59]
	v_mfma_f32_16x16x32_bf16 v[52:55], v[162:165], v[206:209], v[52:55]
	v_mfma_f32_16x16x32_bf16 v[48:51], v[170:173], v[206:209], v[48:51]
	v_mfma_f32_16x16x32_bf16 v[44:47], v[162:165], v[214:217], v[44:47]
	v_mfma_f32_16x16x32_bf16 v[40:43], v[170:173], v[214:217], v[40:43]
	v_mfma_f32_16x16x32_bf16 v[36:39], v[162:165], v[222:225], v[36:39]
	v_mfma_f32_16x16x32_bf16 v[32:35], v[170:173], v[222:225], v[32:35]
	v_mfma_f32_16x16x32_bf16 v[28:31], v[226:229], v[174:177], v[28:31]
	v_mfma_f32_16x16x32_bf16 v[24:27], v[234:237], v[174:177], v[24:27]
	v_mfma_f32_16x16x32_bf16 v[20:23], v[226:229], v[182:185], v[20:23]
	v_mfma_f32_16x16x32_bf16 v[16:19], v[234:237], v[182:185], v[16:19]
	v_mfma_f32_16x16x32_bf16 v[12:15], v[226:229], v[210:213], v[12:15]
	v_mfma_f32_16x16x32_bf16 v[8:11], v[234:237], v[210:213], v[8:11]
	v_mfma_f32_16x16x32_bf16 v[4:7], v[226:229], v[218:221], v[4:7]
	v_mfma_f32_16x16x32_bf16 v[0:3], v[234:237], v[218:221], v[0:3]
	v_mfma_f32_16x16x32_bf16 v[28:31], v[230:233], v[178:181], v[28:31]
	v_mfma_f32_16x16x32_bf16 v[24:27], v[238:241], v[178:181], v[24:27]
	v_mfma_f32_16x16x32_bf16 v[20:23], v[230:233], v[206:209], v[20:23]
	v_mfma_f32_16x16x32_bf16 v[16:19], v[238:241], v[206:209], v[16:19]
	v_mfma_f32_16x16x32_bf16 v[12:15], v[230:233], v[214:217], v[12:15]
	v_mfma_f32_16x16x32_bf16 v[8:11], v[238:241], v[214:217], v[8:11]
	v_mfma_f32_16x16x32_bf16 v[4:7], v[230:233], v[222:225], v[4:7]
	v_mfma_f32_16x16x32_bf16 v[0:3], v[238:241], v[222:225], v[0:3]
	s_barrier
	s_cbranch_scc0 .LBB0_77
	s_mov_b32 s100, 1
	v_lshl_add_u32 v158, s75, 10, v155
	ds_read2_b32 v[146:147], v158 offset1:16
	s_add_u32 s50, s10, 0xffffff00
	s_addc_u32 s51, s11, -1
	s_ashr_i32 s31, s30, 31
	s_lshl_b64 s[10:11], s[30:31], 8
	s_waitcnt lgkmcnt(0)
	v_mul_f32_e32 v184, 0xbfb8aa3b, v146
	v_mul_f32_e32 v206, v146, v146
	v_pk_mul_f32 v[168:169], v[124:125], v[184:185] op_sel_hi:[1,0]
	v_pk_mul_f32 v[170:171], v[126:127], v[184:185] op_sel_hi:[1,0]
	v_pk_mul_f32 v[172:173], v[120:121], v[184:185] op_sel_hi:[1,0]
	v_pk_mul_f32 v[174:175], v[122:123], v[184:185] op_sel_hi:[1,0]
	v_exp_f32_e32 v168, v168
	v_exp_f32_e32 v169, v169
	v_exp_f32_e32 v170, v170
	v_exp_f32_e32 v171, v171
	v_exp_f32_e32 v172, v172
	v_exp_f32_e32 v173, v173
	v_exp_f32_e32 v174, v174
	v_exp_f32_e32 v175, v175
	v_pk_mul_f32 v[176:177], v[124:125], v[92:93]
	v_pk_mul_f32 v[178:179], v[126:127], v[94:95]
	v_pk_mul_f32 v[180:181], v[120:121], v[88:89]
	v_pk_mul_f32 v[182:183], v[122:123], v[90:91]
	v_pk_add_f32 v[168:169], v[168:169], 1.0 op_sel_hi:[1,0]
	v_pk_add_f32 v[170:171], v[170:171], 1.0 op_sel_hi:[1,0]
	v_pk_add_f32 v[172:173], v[172:173], 1.0 op_sel_hi:[1,0]
	v_pk_add_f32 v[174:175], v[174:175], 1.0 op_sel_hi:[1,0]
	v_rcp_f32_e32 v168, v168
	v_rcp_f32_e32 v169, v169
	v_rcp_f32_e32 v170, v170
	v_rcp_f32_e32 v171, v171
	v_rcp_f32_e32 v172, v172
	v_rcp_f32_e32 v173, v173
	v_rcp_f32_e32 v174, v174
	v_rcp_f32_e32 v175, v175
	v_pk_mul_f32 v[176:177], v[176:177], v[206:207] op_sel_hi:[1,0]
	v_pk_mul_f32 v[178:179], v[178:179], v[206:207] op_sel_hi:[1,0]
	v_pk_mul_f32 v[180:181], v[180:181], v[206:207] op_sel_hi:[1,0]
	v_pk_mul_f32 v[182:183], v[182:183], v[206:207] op_sel_hi:[1,0]
	v_pk_mul_f32 v[176:177], v[176:177], v[168:169]
	v_pk_mul_f32 v[178:179], v[178:179], v[170:171]
	v_pk_mul_f32 v[180:181], v[180:181], v[172:173]
	v_pk_mul_f32 v[182:183], v[182:183], v[174:175]
	v_cvt_pk_bf16_f32 v160, v176, v177
	v_cvt_pk_bf16_f32 v161, v178, v179
	v_cvt_pk_bf16_f32 v162, v180, v181
	v_cvt_pk_bf16_f32 v163, v182, v183
	v_lshl_add_u64 v[152:153], v[134:135], 0, s[10:11]
	s_movk_i32 s6, 0x1600
	v_lshl_or_b32 v150, s74, 7, v156
	v_ashrrev_i32_e32 v151, 31, v150
	s_nop 1
	v_mov_b64_e32 v[148:149], s[28:29]
	v_mad_u64_u32 v[148:149], s[10:11], v152, s6, v[148:149]
	v_mov_b32_e32 v146, v149
	v_mad_u64_u32 v[152:153], s[10:11], v153, s6, v[146:147]
	v_mov_b32_e32 v149, v152
	v_mov_b32_e32 v146, v147
	v_lshl_add_u64 v[150:151], v[150:151], 1, v[148:149]
	global_store_dwordx4 v[150:151], v[160:163], off
	v_mul_f32_e32 v184, 0xbfb8aa3b, v146
	v_mul_f32_e32 v206, v146, v146
	v_pk_mul_f32 v[168:169], v[116:117], v[184:185] op_sel_hi:[1,0]
	v_pk_mul_f32 v[170:171], v[118:119], v[184:185] op_sel_hi:[1,0]
	v_pk_mul_f32 v[172:173], v[112:113], v[184:185] op_sel_hi:[1,0]
	v_pk_mul_f32 v[174:175], v[114:115], v[184:185] op_sel_hi:[1,0]
	v_exp_f32_e32 v168, v168
	v_exp_f32_e32 v169, v169
	v_exp_f32_e32 v170, v170
	v_exp_f32_e32 v171, v171
	v_exp_f32_e32 v172, v172
	v_exp_f32_e32 v173, v173
	v_exp_f32_e32 v174, v174
	v_exp_f32_e32 v175, v175
	v_pk_mul_f32 v[176:177], v[116:117], v[84:85]
	v_pk_mul_f32 v[178:179], v[118:119], v[86:87]
	v_pk_mul_f32 v[180:181], v[112:113], v[80:81]
	v_pk_mul_f32 v[182:183], v[114:115], v[82:83]
	v_pk_add_f32 v[168:169], v[168:169], 1.0 op_sel_hi:[1,0]
	v_pk_add_f32 v[170:171], v[170:171], 1.0 op_sel_hi:[1,0]
	v_pk_add_f32 v[172:173], v[172:173], 1.0 op_sel_hi:[1,0]
	v_pk_add_f32 v[174:175], v[174:175], 1.0 op_sel_hi:[1,0]
	v_rcp_f32_e32 v168, v168
	v_rcp_f32_e32 v169, v169
	v_rcp_f32_e32 v170, v170
	v_rcp_f32_e32 v171, v171
	v_rcp_f32_e32 v172, v172
	v_rcp_f32_e32 v173, v173
	v_rcp_f32_e32 v174, v174
	v_rcp_f32_e32 v175, v175
	v_pk_mul_f32 v[176:177], v[176:177], v[206:207] op_sel_hi:[1,0]
	v_pk_mul_f32 v[178:179], v[178:179], v[206:207] op_sel_hi:[1,0]
	v_pk_mul_f32 v[180:181], v[180:181], v[206:207] op_sel_hi:[1,0]
	v_pk_mul_f32 v[182:183], v[182:183], v[206:207] op_sel_hi:[1,0]
	v_pk_mul_f32 v[176:177], v[176:177], v[168:169]
	v_pk_mul_f32 v[178:179], v[178:179], v[170:171]
	v_pk_mul_f32 v[180:181], v[180:181], v[172:173]
	v_pk_mul_f32 v[182:183], v[182:183], v[174:175]
	v_cvt_pk_bf16_f32 v160, v176, v177
	v_cvt_pk_bf16_f32 v161, v178, v179
	v_cvt_pk_bf16_f32 v162, v180, v181
	v_cvt_pk_bf16_f32 v163, v182, v183
	s_mov_b32 s6, 0x16000
	s_nop 1
	v_add_co_u32_e32 v146, vcc, s6, v150
	s_nop 0
	v_addc_co_u32_e32 v147, vcc, 0, v151, vcc
	global_store_dwordx4 v[146:147], v[160:163], off
	ds_read2_b32 v[146:147], v158 offset0:32 offset1:48
	s_mov_b32 s6, 0x2c000
	s_waitcnt lgkmcnt(0)
	v_mul_f32_e32 v184, 0xbfb8aa3b, v146
	v_mul_f32_e32 v206, v146, v146
	v_pk_mul_f32 v[168:169], v[108:109], v[184:185] op_sel_hi:[1,0]
	v_pk_mul_f32 v[170:171], v[110:111], v[184:185] op_sel_hi:[1,0]
	v_pk_mul_f32 v[172:173], v[104:105], v[184:185] op_sel_hi:[1,0]
	v_pk_mul_f32 v[174:175], v[106:107], v[184:185] op_sel_hi:[1,0]
	v_exp_f32_e32 v168, v168
	v_exp_f32_e32 v169, v169
	v_exp_f32_e32 v170, v170
	v_exp_f32_e32 v171, v171
	v_exp_f32_e32 v172, v172
	v_exp_f32_e32 v173, v173
	v_exp_f32_e32 v174, v174
	v_exp_f32_e32 v175, v175
	v_pk_mul_f32 v[176:177], v[108:109], v[76:77]
	v_pk_mul_f32 v[178:179], v[110:111], v[78:79]
	v_pk_mul_f32 v[180:181], v[104:105], v[72:73]
	v_pk_mul_f32 v[182:183], v[106:107], v[74:75]
	v_pk_add_f32 v[168:169], v[168:169], 1.0 op_sel_hi:[1,0]
	v_pk_add_f32 v[170:171], v[170:171], 1.0 op_sel_hi:[1,0]
	v_pk_add_f32 v[172:173], v[172:173], 1.0 op_sel_hi:[1,0]
	v_pk_add_f32 v[174:175], v[174:175], 1.0 op_sel_hi:[1,0]
	v_rcp_f32_e32 v168, v168
	v_rcp_f32_e32 v169, v169
	v_rcp_f32_e32 v170, v170
	v_rcp_f32_e32 v171, v171
	v_rcp_f32_e32 v172, v172
	v_rcp_f32_e32 v173, v173
	v_rcp_f32_e32 v174, v174
	v_rcp_f32_e32 v175, v175
	v_pk_mul_f32 v[176:177], v[176:177], v[206:207] op_sel_hi:[1,0]
	v_pk_mul_f32 v[178:179], v[178:179], v[206:207] op_sel_hi:[1,0]
	v_pk_mul_f32 v[180:181], v[180:181], v[206:207] op_sel_hi:[1,0]
	v_pk_mul_f32 v[182:183], v[182:183], v[206:207] op_sel_hi:[1,0]
	v_pk_mul_f32 v[176:177], v[176:177], v[168:169]
	v_pk_mul_f32 v[178:179], v[178:179], v[170:171]
	v_pk_mul_f32 v[180:181], v[180:181], v[172:173]
	v_pk_mul_f32 v[182:183], v[182:183], v[174:175]
	v_cvt_pk_bf16_f32 v160, v176, v177
	v_cvt_pk_bf16_f32 v161, v178, v179
	v_cvt_pk_bf16_f32 v162, v180, v181
	v_cvt_pk_bf16_f32 v163, v182, v183
	s_nop 1
	v_mov_b32_e32 v146, v147
	v_add_co_u32_e32 v148, vcc, s6, v150
	v_addc_co_u32_e32 v149, vcc, 0, v151, vcc
	global_store_dwordx4 v[148:149], v[160:163], off
	v_mul_f32_e32 v184, 0xbfb8aa3b, v146
	v_mul_f32_e32 v206, v146, v146
	v_pk_mul_f32 v[168:169], v[100:101], v[184:185] op_sel_hi:[1,0]
	v_pk_mul_f32 v[170:171], v[102:103], v[184:185] op_sel_hi:[1,0]
	v_pk_mul_f32 v[172:173], v[96:97], v[184:185] op_sel_hi:[1,0]
	v_pk_mul_f32 v[174:175], v[98:99], v[184:185] op_sel_hi:[1,0]
	v_exp_f32_e32 v168, v168
	v_exp_f32_e32 v169, v169
	v_exp_f32_e32 v170, v170
	v_exp_f32_e32 v171, v171
	v_exp_f32_e32 v172, v172
	v_exp_f32_e32 v173, v173
	v_exp_f32_e32 v174, v174
	v_exp_f32_e32 v175, v175
	v_pk_mul_f32 v[176:177], v[100:101], v[68:69]
	v_pk_mul_f32 v[178:179], v[102:103], v[70:71]
	v_pk_mul_f32 v[180:181], v[96:97], v[64:65]
	v_pk_mul_f32 v[182:183], v[98:99], v[66:67]
	v_pk_add_f32 v[168:169], v[168:169], 1.0 op_sel_hi:[1,0]
	v_pk_add_f32 v[170:171], v[170:171], 1.0 op_sel_hi:[1,0]
	v_pk_add_f32 v[172:173], v[172:173], 1.0 op_sel_hi:[1,0]
	v_pk_add_f32 v[174:175], v[174:175], 1.0 op_sel_hi:[1,0]
	v_rcp_f32_e32 v168, v168
	v_rcp_f32_e32 v169, v169
	v_rcp_f32_e32 v170, v170
	v_rcp_f32_e32 v171, v171
	v_rcp_f32_e32 v172, v172
	v_rcp_f32_e32 v173, v173
	v_rcp_f32_e32 v174, v174
	v_rcp_f32_e32 v175, v175
	v_pk_mul_f32 v[176:177], v[176:177], v[206:207] op_sel_hi:[1,0]
	v_pk_mul_f32 v[178:179], v[178:179], v[206:207] op_sel_hi:[1,0]
	v_pk_mul_f32 v[180:181], v[180:181], v[206:207] op_sel_hi:[1,0]
	v_pk_mul_f32 v[182:183], v[182:183], v[206:207] op_sel_hi:[1,0]
	v_pk_mul_f32 v[176:177], v[176:177], v[168:169]
	v_pk_mul_f32 v[178:179], v[178:179], v[170:171]
	v_pk_mul_f32 v[180:181], v[180:181], v[172:173]
	v_pk_mul_f32 v[182:183], v[182:183], v[174:175]
	v_cvt_pk_bf16_f32 v160, v176, v177
	v_cvt_pk_bf16_f32 v161, v178, v179
	v_cvt_pk_bf16_f32 v162, v180, v181
	v_cvt_pk_bf16_f32 v163, v182, v183
	s_mov_b32 s6, 0x42000
	s_nop 1
	v_add_co_u32_e32 v146, vcc, s6, v150
	s_nop 0
	v_addc_co_u32_e32 v147, vcc, 0, v151, vcc
	global_store_dwordx4 v[146:147], v[160:163], off
	ds_read2_b32 v[146:147], v158 offset0:128 offset1:144
	s_mov_b32 s6, 0xb0000
	s_waitcnt lgkmcnt(0)
	v_mul_f32_e32 v184, 0xbfb8aa3b, v146
	v_mul_f32_e32 v206, v146, v146
	v_pk_mul_f32 v[168:169], v[60:61], v[184:185] op_sel_hi:[1,0]
	v_pk_mul_f32 v[170:171], v[62:63], v[184:185] op_sel_hi:[1,0]
	v_pk_mul_f32 v[172:173], v[56:57], v[184:185] op_sel_hi:[1,0]
	v_pk_mul_f32 v[174:175], v[58:59], v[184:185] op_sel_hi:[1,0]
	v_exp_f32_e32 v168, v168
	v_exp_f32_e32 v169, v169
	v_exp_f32_e32 v170, v170
	v_exp_f32_e32 v171, v171
	v_exp_f32_e32 v172, v172
	v_exp_f32_e32 v173, v173
	v_exp_f32_e32 v174, v174
	v_exp_f32_e32 v175, v175
	v_pk_mul_f32 v[176:177], v[60:61], v[28:29]
	v_pk_mul_f32 v[178:179], v[62:63], v[30:31]
	v_pk_mul_f32 v[180:181], v[56:57], v[24:25]
	v_pk_mul_f32 v[182:183], v[58:59], v[26:27]
	v_pk_add_f32 v[168:169], v[168:169], 1.0 op_sel_hi:[1,0]
	v_pk_add_f32 v[170:171], v[170:171], 1.0 op_sel_hi:[1,0]
	v_pk_add_f32 v[172:173], v[172:173], 1.0 op_sel_hi:[1,0]
	v_pk_add_f32 v[174:175], v[174:175], 1.0 op_sel_hi:[1,0]
	v_rcp_f32_e32 v168, v168
	v_rcp_f32_e32 v169, v169
	v_rcp_f32_e32 v170, v170
	v_rcp_f32_e32 v171, v171
	v_rcp_f32_e32 v172, v172
	v_rcp_f32_e32 v173, v173
	v_rcp_f32_e32 v174, v174
	v_rcp_f32_e32 v175, v175
	v_pk_mul_f32 v[176:177], v[176:177], v[206:207] op_sel_hi:[1,0]
	v_pk_mul_f32 v[178:179], v[178:179], v[206:207] op_sel_hi:[1,0]
	v_pk_mul_f32 v[180:181], v[180:181], v[206:207] op_sel_hi:[1,0]
	v_pk_mul_f32 v[182:183], v[182:183], v[206:207] op_sel_hi:[1,0]
	v_pk_mul_f32 v[176:177], v[176:177], v[168:169]
	v_pk_mul_f32 v[178:179], v[178:179], v[170:171]
	v_pk_mul_f32 v[180:181], v[180:181], v[172:173]
	v_pk_mul_f32 v[182:183], v[182:183], v[174:175]
	v_cvt_pk_bf16_f32 v160, v176, v177
	v_cvt_pk_bf16_f32 v161, v178, v179
	v_cvt_pk_bf16_f32 v162, v180, v181
	v_cvt_pk_bf16_f32 v163, v182, v183
	s_nop 1
	v_mov_b32_e32 v146, v147
	v_add_co_u32_e32 v148, vcc, s6, v150
	v_addc_co_u32_e32 v149, vcc, 0, v151, vcc
	global_store_dwordx4 v[148:149], v[160:163], off
	v_mul_f32_e32 v184, 0xbfb8aa3b, v146
	v_mul_f32_e32 v206, v146, v146
	v_pk_mul_f32 v[168:169], v[52:53], v[184:185] op_sel_hi:[1,0]
	v_pk_mul_f32 v[170:171], v[54:55], v[184:185] op_sel_hi:[1,0]
	v_pk_mul_f32 v[172:173], v[48:49], v[184:185] op_sel_hi:[1,0]
	v_pk_mul_f32 v[174:175], v[50:51], v[184:185] op_sel_hi:[1,0]
	v_exp_f32_e32 v168, v168
	v_exp_f32_e32 v169, v169
	v_exp_f32_e32 v170, v170
	v_exp_f32_e32 v171, v171
	v_exp_f32_e32 v172, v172
	v_exp_f32_e32 v173, v173
	v_exp_f32_e32 v174, v174
	v_exp_f32_e32 v175, v175
	v_pk_mul_f32 v[176:177], v[52:53], v[20:21]
	v_pk_mul_f32 v[178:179], v[54:55], v[22:23]
	v_pk_mul_f32 v[180:181], v[48:49], v[16:17]
	v_pk_mul_f32 v[182:183], v[50:51], v[18:19]
	v_pk_add_f32 v[168:169], v[168:169], 1.0 op_sel_hi:[1,0]
	v_pk_add_f32 v[170:171], v[170:171], 1.0 op_sel_hi:[1,0]
	v_pk_add_f32 v[172:173], v[172:173], 1.0 op_sel_hi:[1,0]
	v_pk_add_f32 v[174:175], v[174:175], 1.0 op_sel_hi:[1,0]
	v_rcp_f32_e32 v168, v168
	v_rcp_f32_e32 v169, v169
	v_rcp_f32_e32 v170, v170
	v_rcp_f32_e32 v171, v171
	v_rcp_f32_e32 v172, v172
	v_rcp_f32_e32 v173, v173
	v_rcp_f32_e32 v174, v174
	v_rcp_f32_e32 v175, v175
	v_pk_mul_f32 v[176:177], v[176:177], v[206:207] op_sel_hi:[1,0]
	v_pk_mul_f32 v[178:179], v[178:179], v[206:207] op_sel_hi:[1,0]
	v_pk_mul_f32 v[180:181], v[180:181], v[206:207] op_sel_hi:[1,0]
	v_pk_mul_f32 v[182:183], v[182:183], v[206:207] op_sel_hi:[1,0]
	v_pk_mul_f32 v[176:177], v[176:177], v[168:169]
	v_pk_mul_f32 v[178:179], v[178:179], v[170:171]
	v_pk_mul_f32 v[180:181], v[180:181], v[172:173]
	v_pk_mul_f32 v[182:183], v[182:183], v[174:175]
	v_cvt_pk_bf16_f32 v160, v176, v177
	v_cvt_pk_bf16_f32 v161, v178, v179
	v_cvt_pk_bf16_f32 v162, v180, v181
	v_cvt_pk_bf16_f32 v163, v182, v183
	s_mov_b32 s6, 0xc6000
	s_nop 1
	v_add_co_u32_e32 v146, vcc, s6, v150
	s_nop 0
	v_addc_co_u32_e32 v147, vcc, 0, v151, vcc
	global_store_dwordx4 v[146:147], v[160:163], off
	ds_read2_b32 v[146:147], v158 offset0:160 offset1:176
	s_mov_b32 s6, 0xdc000
	s_waitcnt lgkmcnt(0)
	v_mul_f32_e32 v184, 0xbfb8aa3b, v146
	v_mul_f32_e32 v206, v146, v146
	v_pk_mul_f32 v[168:169], v[44:45], v[184:185] op_sel_hi:[1,0]
	v_pk_mul_f32 v[170:171], v[46:47], v[184:185] op_sel_hi:[1,0]
	v_pk_mul_f32 v[172:173], v[40:41], v[184:185] op_sel_hi:[1,0]
	v_pk_mul_f32 v[174:175], v[42:43], v[184:185] op_sel_hi:[1,0]
	v_exp_f32_e32 v168, v168
	v_exp_f32_e32 v169, v169
	v_exp_f32_e32 v170, v170
	v_exp_f32_e32 v171, v171
	v_exp_f32_e32 v172, v172
	v_exp_f32_e32 v173, v173
	v_exp_f32_e32 v174, v174
	v_exp_f32_e32 v175, v175
	v_pk_mul_f32 v[176:177], v[44:45], v[12:13]
	v_pk_mul_f32 v[178:179], v[46:47], v[14:15]
	v_pk_mul_f32 v[180:181], v[40:41], v[8:9]
	v_pk_mul_f32 v[182:183], v[42:43], v[10:11]
	v_pk_add_f32 v[168:169], v[168:169], 1.0 op_sel_hi:[1,0]
	v_pk_add_f32 v[170:171], v[170:171], 1.0 op_sel_hi:[1,0]
	v_pk_add_f32 v[172:173], v[172:173], 1.0 op_sel_hi:[1,0]
	v_pk_add_f32 v[174:175], v[174:175], 1.0 op_sel_hi:[1,0]
	v_rcp_f32_e32 v168, v168
	v_rcp_f32_e32 v169, v169
	v_rcp_f32_e32 v170, v170
	v_rcp_f32_e32 v171, v171
	v_rcp_f32_e32 v172, v172
	v_rcp_f32_e32 v173, v173
	v_rcp_f32_e32 v174, v174
	v_rcp_f32_e32 v175, v175
	v_pk_mul_f32 v[176:177], v[176:177], v[206:207] op_sel_hi:[1,0]
	v_pk_mul_f32 v[178:179], v[178:179], v[206:207] op_sel_hi:[1,0]
	v_pk_mul_f32 v[180:181], v[180:181], v[206:207] op_sel_hi:[1,0]
	v_pk_mul_f32 v[182:183], v[182:183], v[206:207] op_sel_hi:[1,0]
	v_pk_mul_f32 v[176:177], v[176:177], v[168:169]
	v_pk_mul_f32 v[178:179], v[178:179], v[170:171]
	v_pk_mul_f32 v[180:181], v[180:181], v[172:173]
	v_pk_mul_f32 v[182:183], v[182:183], v[174:175]
	v_cvt_pk_bf16_f32 v158, v176, v177
	v_cvt_pk_bf16_f32 v159, v178, v179
	v_cvt_pk_bf16_f32 v160, v180, v181
	v_cvt_pk_bf16_f32 v161, v182, v183
	s_nop 1
	v_mov_b32_e32 v146, v147
	v_add_co_u32_e32 v148, vcc, s6, v150
	v_addc_co_u32_e32 v149, vcc, 0, v151, vcc
	global_store_dwordx4 v[148:149], v[158:161], off
	v_mul_f32_e32 v184, 0xbfb8aa3b, v146
	v_mul_f32_e32 v206, v146, v146
	v_pk_mul_f32 v[168:169], v[36:37], v[184:185] op_sel_hi:[1,0]
	v_pk_mul_f32 v[170:171], v[38:39], v[184:185] op_sel_hi:[1,0]
	v_pk_mul_f32 v[172:173], v[32:33], v[184:185] op_sel_hi:[1,0]
	v_pk_mul_f32 v[174:175], v[34:35], v[184:185] op_sel_hi:[1,0]
	v_exp_f32_e32 v168, v168
	v_exp_f32_e32 v169, v169
	v_exp_f32_e32 v170, v170
	v_exp_f32_e32 v171, v171
	v_exp_f32_e32 v172, v172
	v_exp_f32_e32 v173, v173
	v_exp_f32_e32 v174, v174
	v_exp_f32_e32 v175, v175
	v_pk_mul_f32 v[176:177], v[36:37], v[4:5]
	v_pk_mul_f32 v[178:179], v[38:39], v[6:7]
	v_pk_mul_f32 v[180:181], v[32:33], v[0:1]
	v_pk_mul_f32 v[182:183], v[34:35], v[2:3]
	v_pk_add_f32 v[168:169], v[168:169], 1.0 op_sel_hi:[1,0]
	v_pk_add_f32 v[170:171], v[170:171], 1.0 op_sel_hi:[1,0]
	v_pk_add_f32 v[172:173], v[172:173], 1.0 op_sel_hi:[1,0]
	v_pk_add_f32 v[174:175], v[174:175], 1.0 op_sel_hi:[1,0]
	v_rcp_f32_e32 v168, v168
	v_rcp_f32_e32 v169, v169
	v_rcp_f32_e32 v170, v170
	v_rcp_f32_e32 v171, v171
	v_rcp_f32_e32 v172, v172
	v_rcp_f32_e32 v173, v173
	v_rcp_f32_e32 v174, v174
	v_rcp_f32_e32 v175, v175
	v_pk_mul_f32 v[176:177], v[176:177], v[206:207] op_sel_hi:[1,0]
	v_pk_mul_f32 v[178:179], v[178:179], v[206:207] op_sel_hi:[1,0]
	v_pk_mul_f32 v[180:181], v[180:181], v[206:207] op_sel_hi:[1,0]
	v_pk_mul_f32 v[182:183], v[182:183], v[206:207] op_sel_hi:[1,0]
	v_pk_mul_f32 v[176:177], v[176:177], v[168:169]
	v_pk_mul_f32 v[178:179], v[178:179], v[170:171]
	v_pk_mul_f32 v[180:181], v[180:181], v[172:173]
	v_pk_mul_f32 v[182:183], v[182:183], v[174:175]
	v_cvt_pk_bf16_f32 v158, v176, v177
	v_cvt_pk_bf16_f32 v159, v178, v179
	v_cvt_pk_bf16_f32 v160, v180, v181
	v_cvt_pk_bf16_f32 v161, v182, v183
	s_nop 1
	v_add_co_u32_e32 v146, vcc, 0xf2000, v150
	s_nop 0
	v_addc_co_u32_e32 v147, vcc, 0, v151, vcc
	s_andn2_b64 vcc, exec, s[44:45]
	global_store_dwordx4 v[146:147], v[158:161], off
	s_cbranch_vccz .LBB0_73
	s_mov_b64 s[46:47], s[50:51]
	s_andn2_b64 vcc, exec, s[42:43]
	s_mov_b64 s[50:51], s[46:47]
	s_cbranch_vccnz .LBB0_74

.Lm4bp_103:
	s_waitcnt lgkmcnt(0)
	s_mov_b32 s100, 0
	s_barrier
	s_nop 0
	v_mfma_f32_16x16x32_bf16 v[60:63], v[128:131], v[162:165], 0
	v_mfma_f32_16x16x32_bf16 v[56:59], v[136:139], v[162:165], 0
	v_mfma_f32_16x16x32_bf16 v[48:51], v[128:131], v[170:173], 0
	v_mfma_f32_16x16x32_bf16 v[40:43], v[136:139], v[170:173], 0
	v_mfma_f32_16x16x32_bf16 v[32:35], v[128:131], v[178:181], 0
	v_mfma_f32_16x16x32_bf16 v[24:27], v[136:139], v[178:181], 0
	v_mfma_f32_16x16x32_bf16 v[16:19], v[128:131], v[194:197], 0
	v_mfma_f32_16x16x32_bf16 v[8:11], v[136:139], v[194:197], 0
	v_mfma_f32_16x16x32_bf16 v[60:63], v[132:135], v[166:169], v[60:63]
	v_mfma_f32_16x16x32_bf16 v[56:59], v[146:149], v[166:169], v[56:59]
	v_mfma_f32_16x16x32_bf16 v[48:51], v[132:135], v[174:177], v[48:51]
	v_mfma_f32_16x16x32_bf16 v[40:43], v[146:149], v[174:177], v[40:43]
	v_mfma_f32_16x16x32_bf16 v[32:35], v[132:135], v[182:185], v[32:35]
	v_mfma_f32_16x16x32_bf16 v[24:27], v[146:149], v[182:185], v[24:27]
	v_mfma_f32_16x16x32_bf16 v[16:19], v[132:135], v[210:213], v[16:19]
	v_mfma_f32_16x16x32_bf16 v[8:11], v[146:149], v[210:213], v[8:11]
	v_mfma_f32_16x16x32_bf16 v[52:55], v[214:217], v[162:165], 0
	v_mfma_f32_16x16x32_bf16 v[44:47], v[222:225], v[162:165], 0
	v_mfma_f32_16x16x32_bf16 v[36:39], v[214:217], v[170:173], 0
	v_mfma_f32_16x16x32_bf16 v[28:31], v[222:225], v[170:173], 0
	v_mfma_f32_16x16x32_bf16 v[20:23], v[214:217], v[178:181], 0
	v_mfma_f32_16x16x32_bf16 v[12:15], v[222:225], v[178:181], 0
	v_mfma_f32_16x16x32_bf16 v[4:7], v[214:217], v[194:197], 0
	v_mfma_f32_16x16x32_bf16 v[0:3], v[222:225], v[194:197], 0
	v_mfma_f32_16x16x32_bf16 v[52:55], v[218:221], v[166:169], v[52:55]
	v_mfma_f32_16x16x32_bf16 v[44:47], v[226:229], v[166:169], v[44:47]
	v_mfma_f32_16x16x32_bf16 v[36:39], v[218:221], v[174:177], v[36:39]
	v_mfma_f32_16x16x32_bf16 v[28:31], v[226:229], v[174:177], v[28:31]
	v_mfma_f32_16x16x32_bf16 v[20:23], v[218:221], v[182:185], v[20:23]
	v_mfma_f32_16x16x32_bf16 v[12:15], v[226:229], v[182:185], v[12:15]
	v_mfma_f32_16x16x32_bf16 v[4:7], v[218:221], v[210:213], v[4:7]
	v_mfma_f32_16x16x32_bf16 v[0:3], v[226:229], v[210:213], v[0:3]
	s_barrier
	s_add_i32 s6, 0, 0x18000
	v_add_u32_e32 v146, s6, v206
	ds_read_b128 v[128:131], v146
	ds_read_b128 v[132:135], v146 offset:1024
	ds_read_b128 v[136:139], v146 offset:2048
	ds_read_b128 v[146:149], v146 offset:3072
	s_add_u32 s68, s68, 0x40000
	s_addc_u32 s69, s69, 0
	s_mov_b32 m0, s74
	v_lshl_add_u64 v[214:215], s[68:69], 0, v[154:155]
	ds_read_b128 v[162:165], v208 offset:32768
	ds_read_b128 v[166:169], v208 offset:33792
	ds_read_b128 v[170:173], v208 offset:34816
	ds_read_b128 v[174:177], v208 offset:35840
	ds_read_b128 v[178:181], v208 offset:36864
	ds_read_b128 v[182:185], v208 offset:37888
	ds_read_b128 v[194:197], v208 offset:38912
	ds_read_b128 v[210:213], v208 offset:39936
	global_load_lds_dwordx4 v[214:215], off
	v_lshl_add_u64 v[214:215], s[68:69], 0, v[152:153]
	s_mov_b32 m0, s75
	s_nop 0
	global_load_lds_dwordx4 v[214:215], off
	s_add_i32 s19, 0, 0x1c000
	v_add_u32_e32 v209, s19, v206
	ds_read_b128 v[214:217], v209
	ds_read_b128 v[218:221], v209 offset:1024
	ds_read_b128 v[222:225], v209 offset:2048
	ds_read_b128 v[226:229], v209 offset:3072
	s_waitcnt vmcnt(8)
	s_waitcnt lgkmcnt(0)
	s_barrier
	v_mfma_f32_16x16x32_bf16 v[124:127], v[128:131], v[162:165], v[124:127]
	v_mfma_f32_16x16x32_bf16 v[120:123], v[136:139], v[162:165], v[120:123]
	v_mfma_f32_16x16x32_bf16 v[108:111], v[128:131], v[170:173], v[108:111]
	v_mfma_f32_16x16x32_bf16 v[104:107], v[136:139], v[170:173], v[104:107]
	v_mfma_f32_16x16x32_bf16 v[96:99], v[128:131], v[178:181], v[96:99]
	v_mfma_f32_16x16x32_bf16 v[88:91], v[136:139], v[178:181], v[88:91]
	v_mfma_f32_16x16x32_bf16 v[84:87], v[128:131], v[194:197], v[84:87]
	v_mfma_f32_16x16x32_bf16 v[80:83], v[136:139], v[194:197], v[80:83]
	v_mfma_f32_16x16x32_bf16 v[124:127], v[132:135], v[166:169], v[124:127]
	v_mfma_f32_16x16x32_bf16 v[120:123], v[146:149], v[166:169], v[120:123]
	v_mfma_f32_16x16x32_bf16 v[108:111], v[132:135], v[174:177], v[108:111]
	v_mfma_f32_16x16x32_bf16 v[104:107], v[146:149], v[174:177], v[104:107]
	v_mfma_f32_16x16x32_bf16 v[96:99], v[132:135], v[182:185], v[96:99]
	v_mfma_f32_16x16x32_bf16 v[88:91], v[146:149], v[182:185], v[88:91]
	v_mfma_f32_16x16x32_bf16 v[84:87], v[132:135], v[210:213], v[84:87]
	v_mfma_f32_16x16x32_bf16 v[80:83], v[146:149], v[210:213], v[80:83]
	v_mfma_f32_16x16x32_bf16 v[116:119], v[214:217], v[162:165], v[116:119]
	v_mfma_f32_16x16x32_bf16 v[112:115], v[222:225], v[162:165], v[112:115]
	v_mfma_f32_16x16x32_bf16 v[100:103], v[214:217], v[170:173], v[100:103]
	v_mfma_f32_16x16x32_bf16 v[92:95], v[222:225], v[170:173], v[92:95]
	v_mfma_f32_16x16x32_bf16 v[76:79], v[214:217], v[178:181], v[76:79]
	v_mfma_f32_16x16x32_bf16 v[72:75], v[222:225], v[178:181], v[72:75]
	v_mfma_f32_16x16x32_bf16 v[68:71], v[214:217], v[194:197], v[68:71]
	v_mfma_f32_16x16x32_bf16 v[64:67], v[222:225], v[194:197], v[64:67]
	v_mfma_f32_16x16x32_bf16 v[116:119], v[218:221], v[166:169], v[116:119]
	v_mfma_f32_16x16x32_bf16 v[112:115], v[226:229], v[166:169], v[112:115]
	v_mfma_f32_16x16x32_bf16 v[100:103], v[218:221], v[174:177], v[100:103]
	v_mfma_f32_16x16x32_bf16 v[92:95], v[226:229], v[174:177], v[92:95]
	v_mfma_f32_16x16x32_bf16 v[76:79], v[218:221], v[182:185], v[76:79]
	v_mfma_f32_16x16x32_bf16 v[72:75], v[226:229], v[182:185], v[72:75]
	v_mfma_f32_16x16x32_bf16 v[68:71], v[218:221], v[210:213], v[68:71]
	v_mfma_f32_16x16x32_bf16 v[64:67], v[226:229], v[210:213], v[64:67]
	s_barrier
	s_add_i32 s6, s6, s71
	v_lshl_add_u64 v[192:193], v[192:193], 0, s[36:37]
	s_mov_b32 m0, s6
	s_nop 0
	global_load_lds_dwordx4 v[192:193], off
	v_lshl_add_u64 v[192:193], v[230:231], 0, s[36:37]
	s_add_i32 m0, s6, 0x2000
	s_nop 0
	global_load_lds_dwordx4 v[192:193], off
	s_mov_b32 m0, s80
	v_lshl_add_u64 v[192:193], v[232:233], 0, s[36:37]
	ds_read_b128 v[162:165], v208 offset:49152
	ds_read_b128 v[166:169], v208 offset:50176
	ds_read_b128 v[170:173], v208 offset:51200
	ds_read_b128 v[174:177], v208 offset:52224
	ds_read_b128 v[178:181], v208 offset:53248
	ds_read_b128 v[182:185], v208 offset:54272
	ds_read_b128 v[194:197], v208 offset:55296
	ds_read_b128 v[210:213], v208 offset:56320
	global_load_lds_dwordx4 v[192:193], off
	v_lshl_add_u64 v[192:193], v[234:235], 0, s[36:37]
	s_mov_b32 m0, s81
	s_nop 0
	global_load_lds_dwordx4 v[192:193], off
	s_add_u32 s58, s58, 0x40080
	s_addc_u32 s59, s59, 0
	s_add_i32 s6, s19, s71
	v_lshl_add_u64 v[250:251], s[58:59], 0, v[140:141]
	s_mov_b32 m0, s6
	s_nop 0
	global_load_lds_dwordx4 v[250:251], off
	v_lshl_add_u64 v[250:251], s[58:59], 0, v[150:151]
	s_add_i32 m0, s6, 0x2000
	s_nop 0
	global_load_lds_dwordx4 v[250:251], off
	s_add_i32 s12, s12, 2
	s_add_u32 s54, s54, 0x100
	s_addc_u32 s55, s55, 0
	s_add_u32 s10, s10, 0x100
	s_addc_u32 s11, s11, 0
	s_cmp_gt_u32 s12, 13
	s_waitcnt vmcnt(8)
	s_waitcnt lgkmcnt(0)
	s_barrier
	v_mfma_f32_16x16x32_bf16 v[60:63], v[128:131], v[162:165], v[60:63]
	v_mfma_f32_16x16x32_bf16 v[56:59], v[136:139], v[162:165], v[56:59]
	v_mfma_f32_16x16x32_bf16 v[48:51], v[128:131], v[170:173], v[48:51]
	v_mfma_f32_16x16x32_bf16 v[40:43], v[136:139], v[170:173], v[40:43]
	v_mfma_f32_16x16x32_bf16 v[32:35], v[128:131], v[178:181], v[32:35]
	v_mfma_f32_16x16x32_bf16 v[24:27], v[136:139], v[178:181], v[24:27]
	v_mfma_f32_16x16x32_bf16 v[16:19], v[128:131], v[194:197], v[16:19]
	v_mfma_f32_16x16x32_bf16 v[8:11], v[136:139], v[194:197], v[8:11]
	v_mfma_f32_16x16x32_bf16 v[60:63], v[132:135], v[166:169], v[60:63]
	v_mfma_f32_16x16x32_bf16 v[56:59], v[146:149], v[166:169], v[56:59]
	v_mfma_f32_16x16x32_bf16 v[48:51], v[132:135], v[174:177], v[48:51]
	v_mfma_f32_16x16x32_bf16 v[40:43], v[146:149], v[174:177], v[40:43]
	v_mfma_f32_16x16x32_bf16 v[32:35], v[132:135], v[182:185], v[32:35]
	v_mfma_f32_16x16x32_bf16 v[24:27], v[146:149], v[182:185], v[24:27]
	v_mfma_f32_16x16x32_bf16 v[16:19], v[132:135], v[210:213], v[16:19]
	v_mfma_f32_16x16x32_bf16 v[8:11], v[146:149], v[210:213], v[8:11]
	v_mfma_f32_16x16x32_bf16 v[52:55], v[214:217], v[162:165], v[52:55]
	v_mfma_f32_16x16x32_bf16 v[44:47], v[222:225], v[162:165], v[44:47]
	v_mfma_f32_16x16x32_bf16 v[36:39], v[214:217], v[170:173], v[36:39]
	v_mfma_f32_16x16x32_bf16 v[28:31], v[222:225], v[170:173], v[28:31]
	v_mfma_f32_16x16x32_bf16 v[20:23], v[214:217], v[178:181], v[20:23]
	v_mfma_f32_16x16x32_bf16 v[12:15], v[222:225], v[178:181], v[12:15]
	v_mfma_f32_16x16x32_bf16 v[4:7], v[214:217], v[194:197], v[4:7]
	v_mfma_f32_16x16x32_bf16 v[0:3], v[222:225], v[194:197], v[0:3]
	v_mfma_f32_16x16x32_bf16 v[52:55], v[218:221], v[166:169], v[52:55]
	v_mfma_f32_16x16x32_bf16 v[44:47], v[226:229], v[166:169], v[44:47]
	v_mfma_f32_16x16x32_bf16 v[36:39], v[218:221], v[174:177], v[36:39]
	v_mfma_f32_16x16x32_bf16 v[28:31], v[226:229], v[174:177], v[28:31]
	v_mfma_f32_16x16x32_bf16 v[20:23], v[218:221], v[182:185], v[20:23]
	v_mfma_f32_16x16x32_bf16 v[12:15], v[226:229], v[182:185], v[12:15]
	v_mfma_f32_16x16x32_bf16 v[4:7], v[218:221], v[210:213], v[4:7]
	v_mfma_f32_16x16x32_bf16 v[0:3], v[226:229], v[210:213], v[0:3]
	s_barrier
.LBB0_103:
	s_add_u32 s6, s54, 0xfffc0080
	s_addc_u32 s19, s55, -1
	s_add_i32 s23, 0, 0x10000
	v_add_u32_e32 v146, s23, v206
	ds_read_b128 v[128:131], v146
	ds_read_b128 v[132:135], v146 offset:1024
	ds_read_b128 v[136:139], v146 offset:2048
	ds_read_b128 v[146:149], v146 offset:3072
	s_cmp_eq_u32 s12, 12
	s_cselect_b32 s69, s47, s19
	s_cselect_b32 s68, s46, s6
	s_cselect_b32 s59, s49, s11
	s_cselect_b32 s58, s48, s10
	v_lshl_add_u64 v[192:193], s[54:55], 0, v[158:159]
	s_add_i32 m0, s72, 0xc000
	ds_read_b128 v[162:165], v208
	ds_read_b128 v[166:169], v208 offset:1024
	ds_read_b128 v[170:173], v208 offset:2048
	ds_read_b128 v[174:177], v208 offset:3072
	ds_read_b128 v[178:181], v208 offset:4096
	ds_read_b128 v[182:185], v208 offset:5120
	ds_read_b128 v[194:197], v208 offset:6144
	ds_read_b128 v[210:213], v208 offset:7168
	global_load_lds_dwordx4 v[192:193], off
	v_lshl_add_u64 v[192:193], s[54:55], 0, v[160:161]
	s_add_i32 m0, s72, 0xe000
	s_nop 0
	global_load_lds_dwordx4 v[192:193], off
	s_add_i32 s6, 0, 0x14000
	v_add_u32_e32 v192, s6, v206
	ds_read_b128 v[214:217], v192
	ds_read_b128 v[218:221], v192 offset:1024
	ds_read_b128 v[222:225], v192 offset:2048
	ds_read_b128 v[226:229], v192 offset:3072
	s_nop 0
	s_waitcnt vmcnt(8)
	s_waitcnt lgkmcnt(0)
	s_barrier
	v_mfma_f32_16x16x32_bf16 v[124:127], v[128:131], v[162:165], v[124:127]
	v_mfma_f32_16x16x32_bf16 v[120:123], v[136:139], v[162:165], v[120:123]
	v_mfma_f32_16x16x32_bf16 v[108:111], v[128:131], v[170:173], v[108:111]
	v_mfma_f32_16x16x32_bf16 v[104:107], v[136:139], v[170:173], v[104:107]
	v_mfma_f32_16x16x32_bf16 v[96:99], v[128:131], v[178:181], v[96:99]
	v_mfma_f32_16x16x32_bf16 v[88:91], v[136:139], v[178:181], v[88:91]
	v_mfma_f32_16x16x32_bf16 v[84:87], v[128:131], v[194:197], v[84:87]
	v_mfma_f32_16x16x32_bf16 v[80:83], v[136:139], v[194:197], v[80:83]
	v_mfma_f32_16x16x32_bf16 v[124:127], v[132:135], v[166:169], v[124:127]
	v_mfma_f32_16x16x32_bf16 v[120:123], v[146:149], v[166:169], v[120:123]
	v_mfma_f32_16x16x32_bf16 v[108:111], v[132:135], v[174:177], v[108:111]
	v_mfma_f32_16x16x32_bf16 v[104:107], v[146:149], v[174:177], v[104:107]
	v_mfma_f32_16x16x32_bf16 v[96:99], v[132:135], v[182:185], v[96:99]
	v_mfma_f32_16x16x32_bf16 v[88:91], v[146:149], v[182:185], v[88:91]
	v_mfma_f32_16x16x32_bf16 v[84:87], v[132:135], v[210:213], v[84:87]
	v_mfma_f32_16x16x32_bf16 v[80:83], v[146:149], v[210:213], v[80:83]
	v_mfma_f32_16x16x32_bf16 v[116:119], v[214:217], v[162:165], v[116:119]
	v_mfma_f32_16x16x32_bf16 v[112:115], v[222:225], v[162:165], v[112:115]
	v_mfma_f32_16x16x32_bf16 v[100:103], v[214:217], v[170:173], v[100:103]
	v_mfma_f32_16x16x32_bf16 v[92:95], v[222:225], v[170:173], v[92:95]
	v_mfma_f32_16x16x32_bf16 v[76:79], v[214:217], v[178:181], v[76:79]
	v_mfma_f32_16x16x32_bf16 v[72:75], v[222:225], v[178:181], v[72:75]
	v_mfma_f32_16x16x32_bf16 v[68:71], v[214:217], v[194:197], v[68:71]
	v_mfma_f32_16x16x32_bf16 v[64:67], v[222:225], v[194:197], v[64:67]
	v_mfma_f32_16x16x32_bf16 v[116:119], v[218:221], v[166:169], v[116:119]
	v_mfma_f32_16x16x32_bf16 v[112:115], v[226:229], v[166:169], v[112:115]
	v_mfma_f32_16x16x32_bf16 v[100:103], v[218:221], v[174:177], v[100:103]
	v_mfma_f32_16x16x32_bf16 v[92:95], v[226:229], v[174:177], v[92:95]
	v_mfma_f32_16x16x32_bf16 v[76:79], v[218:221], v[182:185], v[76:79]
	v_mfma_f32_16x16x32_bf16 v[72:75], v[226:229], v[182:185], v[72:75]
	v_mfma_f32_16x16x32_bf16 v[68:71], v[218:221], v[210:213], v[68:71]
	v_mfma_f32_16x16x32_bf16 v[64:67], v[226:229], v[210:213], v[64:67]
	s_barrier
	s_add_i32 s19, s23, s71
	v_lshl_add_u64 v[192:193], s[58:59], 0, v[140:141]
	s_mov_b32 m0, s19
	v_lshl_add_u64 v[230:231], s[58:59], 0, v[150:151]
	global_load_lds_dwordx4 v[192:193], off
	s_add_i32 m0, s19, 0x2000
	s_nop 0
	global_load_lds_dwordx4 v[230:231], off
	s_mov_b32 m0, s72
	v_lshl_add_u64 v[232:233], s[68:69], 0, v[154:155]
	ds_read_b128 v[162:165], v208 offset:16384
	ds_read_b128 v[166:169], v208 offset:17408
	ds_read_b128 v[170:173], v208 offset:18432
	ds_read_b128 v[174:177], v208 offset:19456
	ds_read_b128 v[178:181], v208 offset:20480
	ds_read_b128 v[182:185], v208 offset:21504
	ds_read_b128 v[194:197], v208 offset:22528
	ds_read_b128 v[210:213], v208 offset:23552
	global_load_lds_dwordx4 v[232:233], off
	v_lshl_add_u64 v[234:235], s[68:69], 0, v[152:153]
	s_mov_b32 m0, s73
	s_nop 0
	global_load_lds_dwordx4 v[234:235], off
	s_add_u32 s86, s58, 0x40000
	s_addc_u32 s87, s59, 0
	s_add_i32 s6, s6, s71
	v_lshl_add_u64 v[250:251], s[86:87], 0, v[140:141]
	s_mov_b32 m0, s6
	s_nop 0
	global_load_lds_dwordx4 v[250:251], off
	v_lshl_add_u64 v[250:251], s[86:87], 0, v[150:151]
	s_add_i32 m0, s6, 0x2000
	s_nop 0
	global_load_lds_dwordx4 v[250:251], off
	s_nop 0
	s_waitcnt vmcnt(8)
	s_waitcnt lgkmcnt(0)
	s_barrier
	v_mfma_f32_16x16x32_bf16 v[60:63], v[128:131], v[162:165], v[60:63]
	v_mfma_f32_16x16x32_bf16 v[56:59], v[136:139], v[162:165], v[56:59]
	v_mfma_f32_16x16x32_bf16 v[48:51], v[128:131], v[170:173], v[48:51]
	v_mfma_f32_16x16x32_bf16 v[40:43], v[136:139], v[170:173], v[40:43]
	v_mfma_f32_16x16x32_bf16 v[32:35], v[128:131], v[178:181], v[32:35]
	v_mfma_f32_16x16x32_bf16 v[24:27], v[136:139], v[178:181], v[24:27]
	v_mfma_f32_16x16x32_bf16 v[16:19], v[128:131], v[194:197], v[16:19]
	v_mfma_f32_16x16x32_bf16 v[8:11], v[136:139], v[194:197], v[8:11]
	v_mfma_f32_16x16x32_bf16 v[60:63], v[132:135], v[166:169], v[60:63]
	v_mfma_f32_16x16x32_bf16 v[56:59], v[146:149], v[166:169], v[56:59]
	v_mfma_f32_16x16x32_bf16 v[48:51], v[132:135], v[174:177], v[48:51]
	v_mfma_f32_16x16x32_bf16 v[40:43], v[146:149], v[174:177], v[40:43]
	v_mfma_f32_16x16x32_bf16 v[32:35], v[132:135], v[182:185], v[32:35]
	v_mfma_f32_16x16x32_bf16 v[24:27], v[146:149], v[182:185], v[24:27]
	v_mfma_f32_16x16x32_bf16 v[16:19], v[132:135], v[210:213], v[16:19]
	v_mfma_f32_16x16x32_bf16 v[8:11], v[146:149], v[210:213], v[8:11]
	v_mfma_f32_16x16x32_bf16 v[52:55], v[214:217], v[162:165], v[52:55]
	v_mfma_f32_16x16x32_bf16 v[44:47], v[222:225], v[162:165], v[44:47]
	v_mfma_f32_16x16x32_bf16 v[36:39], v[214:217], v[170:173], v[36:39]
	v_mfma_f32_16x16x32_bf16 v[28:31], v[222:225], v[170:173], v[28:31]
	v_mfma_f32_16x16x32_bf16 v[20:23], v[214:217], v[178:181], v[20:23]
	v_mfma_f32_16x16x32_bf16 v[12:15], v[222:225], v[178:181], v[12:15]
	v_mfma_f32_16x16x32_bf16 v[4:7], v[214:217], v[194:197], v[4:7]
	v_mfma_f32_16x16x32_bf16 v[0:3], v[222:225], v[194:197], v[0:3]
	v_mfma_f32_16x16x32_bf16 v[52:55], v[218:221], v[166:169], v[52:55]
	v_mfma_f32_16x16x32_bf16 v[44:47], v[226:229], v[166:169], v[44:47]
	v_mfma_f32_16x16x32_bf16 v[36:39], v[218:221], v[174:177], v[36:39]
	v_mfma_f32_16x16x32_bf16 v[28:31], v[226:229], v[174:177], v[28:31]
	v_mfma_f32_16x16x32_bf16 v[20:23], v[218:221], v[182:185], v[20:23]
	v_mfma_f32_16x16x32_bf16 v[12:15], v[226:229], v[182:185], v[12:15]
	v_mfma_f32_16x16x32_bf16 v[4:7], v[218:221], v[210:213], v[4:7]
	v_mfma_f32_16x16x32_bf16 v[0:3], v[226:229], v[210:213], v[0:3]
	s_barrier
	s_add_i32 s6, 0, 0x18000
	v_add_u32_e32 v146, s6, v206
	ds_read_b128 v[128:131], v146
	ds_read_b128 v[132:135], v146 offset:1024
	ds_read_b128 v[136:139], v146 offset:2048
	ds_read_b128 v[146:149], v146 offset:3072
	s_add_u32 s68, s68, 0x40000
	s_addc_u32 s69, s69, 0
	s_mov_b32 m0, s74
	v_lshl_add_u64 v[214:215], s[68:69], 0, v[154:155]
	ds_read_b128 v[162:165], v208 offset:32768
	ds_read_b128 v[166:169], v208 offset:33792
	ds_read_b128 v[170:173], v208 offset:34816
	ds_read_b128 v[174:177], v208 offset:35840
	ds_read_b128 v[178:181], v208 offset:36864
	ds_read_b128 v[182:185], v208 offset:37888
	ds_read_b128 v[194:197], v208 offset:38912
	ds_read_b128 v[210:213], v208 offset:39936
	global_load_lds_dwordx4 v[214:215], off
	v_lshl_add_u64 v[214:215], s[68:69], 0, v[152:153]
	s_mov_b32 m0, s75
	s_nop 0
	global_load_lds_dwordx4 v[214:215], off
	s_add_i32 s19, 0, 0x1c000
	v_add_u32_e32 v209, s19, v206
	ds_read_b128 v[214:217], v209
	ds_read_b128 v[218:221], v209 offset:1024
	ds_read_b128 v[222:225], v209 offset:2048
	ds_read_b128 v[226:229], v209 offset:3072
	s_waitcnt vmcnt(8)
	s_waitcnt lgkmcnt(0)
	s_barrier
	v_mfma_f32_16x16x32_bf16 v[124:127], v[128:131], v[162:165], v[124:127]
	v_mfma_f32_16x16x32_bf16 v[120:123], v[136:139], v[162:165], v[120:123]
	v_mfma_f32_16x16x32_bf16 v[108:111], v[128:131], v[170:173], v[108:111]
	v_mfma_f32_16x16x32_bf16 v[104:107], v[136:139], v[170:173], v[104:107]
	v_mfma_f32_16x16x32_bf16 v[96:99], v[128:131], v[178:181], v[96:99]
	v_mfma_f32_16x16x32_bf16 v[88:91], v[136:139], v[178:181], v[88:91]
	v_mfma_f32_16x16x32_bf16 v[84:87], v[128:131], v[194:197], v[84:87]
	v_mfma_f32_16x16x32_bf16 v[80:83], v[136:139], v[194:197], v[80:83]
	v_mfma_f32_16x16x32_bf16 v[124:127], v[132:135], v[166:169], v[124:127]
	v_mfma_f32_16x16x32_bf16 v[120:123], v[146:149], v[166:169], v[120:123]
	v_mfma_f32_16x16x32_bf16 v[108:111], v[132:135], v[174:177], v[108:111]
	v_mfma_f32_16x16x32_bf16 v[104:107], v[146:149], v[174:177], v[104:107]
	v_mfma_f32_16x16x32_bf16 v[96:99], v[132:135], v[182:185], v[96:99]
	v_mfma_f32_16x16x32_bf16 v[88:91], v[146:149], v[182:185], v[88:91]
	v_mfma_f32_16x16x32_bf16 v[84:87], v[132:135], v[210:213], v[84:87]
	v_mfma_f32_16x16x32_bf16 v[80:83], v[146:149], v[210:213], v[80:83]
	v_mfma_f32_16x16x32_bf16 v[116:119], v[214:217], v[162:165], v[116:119]
	v_mfma_f32_16x16x32_bf16 v[112:115], v[222:225], v[162:165], v[112:115]
	v_mfma_f32_16x16x32_bf16 v[100:103], v[214:217], v[170:173], v[100:103]
	v_mfma_f32_16x16x32_bf16 v[92:95], v[222:225], v[170:173], v[92:95]
	v_mfma_f32_16x16x32_bf16 v[76:79], v[214:217], v[178:181], v[76:79]
	v_mfma_f32_16x16x32_bf16 v[72:75], v[222:225], v[178:181], v[72:75]
	v_mfma_f32_16x16x32_bf16 v[68:71], v[214:217], v[194:197], v[68:71]
	v_mfma_f32_16x16x32_bf16 v[64:67], v[222:225], v[194:197], v[64:67]
	v_mfma_f32_16x16x32_bf16 v[116:119], v[218:221], v[166:169], v[116:119]
	v_mfma_f32_16x16x32_bf16 v[112:115], v[226:229], v[166:169], v[112:115]
	v_mfma_f32_16x16x32_bf16 v[100:103], v[218:221], v[174:177], v[100:103]
	v_mfma_f32_16x16x32_bf16 v[92:95], v[226:229], v[174:177], v[92:95]
	v_mfma_f32_16x16x32_bf16 v[76:79], v[218:221], v[182:185], v[76:79]
	v_mfma_f32_16x16x32_bf16 v[72:75], v[226:229], v[182:185], v[72:75]
	v_mfma_f32_16x16x32_bf16 v[68:71], v[218:221], v[210:213], v[68:71]
	v_mfma_f32_16x16x32_bf16 v[64:67], v[226:229], v[210:213], v[64:67]
	s_barrier
	s_add_i32 s6, s6, s71
	v_lshl_add_u64 v[192:193], v[192:193], 0, s[36:37]
	s_mov_b32 m0, s6
	s_nop 0
	global_load_lds_dwordx4 v[192:193], off
	v_lshl_add_u64 v[192:193], v[230:231], 0, s[36:37]
	s_add_i32 m0, s6, 0x2000
	s_nop 0
	global_load_lds_dwordx4 v[192:193], off
	s_mov_b32 m0, s80
	v_lshl_add_u64 v[192:193], v[232:233], 0, s[36:37]
	ds_read_b128 v[162:165], v208 offset:49152
	ds_read_b128 v[166:169], v208 offset:50176
	ds_read_b128 v[170:173], v208 offset:51200
	ds_read_b128 v[174:177], v208 offset:52224
	ds_read_b128 v[178:181], v208 offset:53248
	ds_read_b128 v[182:185], v208 offset:54272
	ds_read_b128 v[194:197], v208 offset:55296
	ds_read_b128 v[210:213], v208 offset:56320
	global_load_lds_dwordx4 v[192:193], off
	v_lshl_add_u64 v[192:193], v[234:235], 0, s[36:37]
	s_mov_b32 m0, s81
	s_nop 0
	global_load_lds_dwordx4 v[192:193], off
	s_add_u32 s58, s58, 0x40080
	s_addc_u32 s59, s59, 0
	s_add_i32 s6, s19, s71
	v_lshl_add_u64 v[250:251], s[58:59], 0, v[140:141]
	s_mov_b32 m0, s6
	s_nop 0
	global_load_lds_dwordx4 v[250:251], off
	v_lshl_add_u64 v[250:251], s[58:59], 0, v[150:151]
	s_add_i32 m0, s6, 0x2000
	s_nop 0
	global_load_lds_dwordx4 v[250:251], off
	s_add_i32 s12, s12, 2
	s_add_u32 s54, s54, 0x100
	s_addc_u32 s55, s55, 0
	s_add_u32 s10, s10, 0x100
	s_addc_u32 s11, s11, 0
	s_cmp_gt_u32 s12, 13
	s_waitcnt vmcnt(8)
	s_waitcnt lgkmcnt(0)
	s_barrier
	v_mfma_f32_16x16x32_bf16 v[60:63], v[128:131], v[162:165], v[60:63]
	v_mfma_f32_16x16x32_bf16 v[56:59], v[136:139], v[162:165], v[56:59]
	v_mfma_f32_16x16x32_bf16 v[48:51], v[128:131], v[170:173], v[48:51]
	v_mfma_f32_16x16x32_bf16 v[40:43], v[136:139], v[170:173], v[40:43]
	v_mfma_f32_16x16x32_bf16 v[32:35], v[128:131], v[178:181], v[32:35]
	v_mfma_f32_16x16x32_bf16 v[24:27], v[136:139], v[178:181], v[24:27]
	v_mfma_f32_16x16x32_bf16 v[16:19], v[128:131], v[194:197], v[16:19]
	v_mfma_f32_16x16x32_bf16 v[8:11], v[136:139], v[194:197], v[8:11]
	v_mfma_f32_16x16x32_bf16 v[60:63], v[132:135], v[166:169], v[60:63]
	v_mfma_f32_16x16x32_bf16 v[56:59], v[146:149], v[166:169], v[56:59]
	v_mfma_f32_16x16x32_bf16 v[48:51], v[132:135], v[174:177], v[48:51]
	v_mfma_f32_16x16x32_bf16 v[40:43], v[146:149], v[174:177], v[40:43]
	v_mfma_f32_16x16x32_bf16 v[32:35], v[132:135], v[182:185], v[32:35]
	v_mfma_f32_16x16x32_bf16 v[24:27], v[146:149], v[182:185], v[24:27]
	v_mfma_f32_16x16x32_bf16 v[16:19], v[132:135], v[210:213], v[16:19]
	v_mfma_f32_16x16x32_bf16 v[8:11], v[146:149], v[210:213], v[8:11]
	v_mfma_f32_16x16x32_bf16 v[52:55], v[214:217], v[162:165], v[52:55]
	v_mfma_f32_16x16x32_bf16 v[44:47], v[222:225], v[162:165], v[44:47]
	v_mfma_f32_16x16x32_bf16 v[36:39], v[214:217], v[170:173], v[36:39]
	v_mfma_f32_16x16x32_bf16 v[28:31], v[222:225], v[170:173], v[28:31]
	v_mfma_f32_16x16x32_bf16 v[20:23], v[214:217], v[178:181], v[20:23]
	v_mfma_f32_16x16x32_bf16 v[12:15], v[222:225], v[178:181], v[12:15]
	v_mfma_f32_16x16x32_bf16 v[4:7], v[214:217], v[194:197], v[4:7]
	v_mfma_f32_16x16x32_bf16 v[0:3], v[222:225], v[194:197], v[0:3]
	v_mfma_f32_16x16x32_bf16 v[52:55], v[218:221], v[166:169], v[52:55]
	v_mfma_f32_16x16x32_bf16 v[44:47], v[226:229], v[166:169], v[44:47]
	v_mfma_f32_16x16x32_bf16 v[36:39], v[218:221], v[174:177], v[36:39]
	v_mfma_f32_16x16x32_bf16 v[28:31], v[226:229], v[174:177], v[28:31]
	v_mfma_f32_16x16x32_bf16 v[20:23], v[218:221], v[182:185], v[20:23]
	v_mfma_f32_16x16x32_bf16 v[12:15], v[226:229], v[182:185], v[12:15]
	v_mfma_f32_16x16x32_bf16 v[4:7], v[218:221], v[210:213], v[4:7]
	v_mfma_f32_16x16x32_bf16 v[0:3], v[226:229], v[210:213], v[0:3]
	s_barrier
	s_cbranch_scc0 .LBB0_103
	s_mov_b32 s100, 1
	s_ashr_i32 s51, s50, 31
	s_ashr_i32 s53, s52, 31
	s_lshl_b64 s[10:11], s[50:51], 13
	s_lshl_b64 s[50:51], s[52:53], 8
	s_add_u32 s10, s50, s10
	v_lshl_or_b32 v128, s85, 8, v207
	s_addc_u32 s11, s51, s11
	v_ashrrev_i32_e32 v129, 31, v128
	v_lshl_add_u64 v[168:169], s[10:11], 0, v[156:157]
	v_lshlrev_b64 v[170:171], 1, v[128:129]
	v_lshl_add_u64 v[174:175], s[26:27], 0, v[170:171]
	v_lshlrev_b64 v[172:173], 11, v[168:169]
	v_or_b32_e32 v166, 16, v168
	v_mov_b32_e32 v167, v169
	v_lshl_add_u64 v[128:129], v[174:175], 0, v[172:173]
	v_lshlrev_b64 v[176:177], 11, v[166:167]
	global_load_dwordx4 v[146:149], v[128:129], off
	global_load_dwordx4 v[182:185], v[128:129], off offset:256
	v_lshl_add_u64 v[128:129], v[174:175], 0, v[176:177]
	global_load_dwordx4 v[194:197], v[128:129], off
	global_load_dwordx4 v[210:213], v[128:129], off offset:256
	v_or_b32_e32 v164, 32, v168
	v_mov_b32_e32 v165, v169
	v_or_b32_e32 v162, 48, v168
	v_mov_b32_e32 v163, v169
	v_lshlrev_b64 v[180:181], 11, v[164:165]
	v_lshlrev_b64 v[178:179], 11, v[162:163]
	v_lshl_add_u64 v[128:129], v[174:175], 0, v[180:181]
	v_lshl_add_u64 v[130:131], v[174:175], 0, v[178:179]
	global_load_dwordx4 v[214:217], v[128:129], off
	global_load_dwordx4 v[136:139], v[128:129], off offset:256
	global_load_dwordx4 v[132:135], v[130:131], off
	s_nop 0
	global_load_dwordx4 v[128:131], v[130:131], off offset:256
	s_mov_b64 s[10:11], 0x90
	v_lshl_add_u64 v[172:173], s[28:29], 0, v[172:173]
	v_lshl_add_u64 v[172:173], v[172:173], 0, v[170:171]
	s_waitcnt vmcnt(0)
	v_lshlrev_b32_e32 v192, 16, v146
	v_and_b32_e32 v193, 0xffff0000, v146
	v_lshlrev_b32_e32 v218, 16, v148
	v_and_b32_e32 v219, 0xffff0000, v148
	v_lshlrev_b32_e32 v146, 16, v147
	v_and_b32_e32 v147, 0xffff0000, v147
	v_lshlrev_b32_e32 v148, 16, v149
	v_and_b32_e32 v149, 0xffff0000, v149
	v_lshlrev_b32_e32 v220, 16, v182
	v_and_b32_e32 v221, 0xffff0000, v182
	v_lshlrev_b32_e32 v222, 16, v184
	v_and_b32_e32 v223, 0xffff0000, v184
	v_lshlrev_b32_e32 v182, 16, v183
	v_and_b32_e32 v183, 0xffff0000, v183
	v_lshlrev_b32_e32 v184, 16, v185
	v_and_b32_e32 v185, 0xffff0000, v185
	v_pk_add_f32 v[124:125], v[124:125], v[192:193]
	v_pk_add_f32 v[126:127], v[126:127], v[146:147]
	v_pk_add_f32 v[122:123], v[122:123], v[148:149]
	v_pk_add_f32 v[116:117], v[116:117], v[220:221]
	v_pk_add_f32 v[146:147], v[112:113], v[222:223]
	v_pk_add_f32 v[118:119], v[118:119], v[182:183]
	v_pk_add_f32 v[148:149], v[114:115], v[184:185]
	v_lshlrev_b32_e32 v182, 16, v194
	v_and_b32_e32 v183, 0xffff0000, v194
	v_lshlrev_b32_e32 v184, 16, v196
	v_and_b32_e32 v185, 0xffff0000, v196
	v_lshlrev_b32_e32 v192, 16, v195
	v_and_b32_e32 v193, 0xffff0000, v195
	v_lshlrev_b32_e32 v194, 16, v197
	v_and_b32_e32 v195, 0xffff0000, v197
	v_pk_mul_f32 v[196:197], v[124:125], v[124:125]
	v_pk_add_f32 v[120:121], v[120:121], v[218:219]
	v_pk_mul_f32 v[218:219], v[126:127], v[126:127]
	v_cvt_pk_bf16_f32 v112, v124, v125
	v_cvt_pk_bf16_f32 v113, v126, v127
	v_pk_mul_f32 v[124:125], v[116:117], v[116:117]
	v_pk_mul_f32 v[126:127], v[118:119], v[118:119]
	v_pk_mul_f32 v[224:225], v[146:147], v[146:147]
	v_cvt_pk_bf16_f32 v116, v116, v117
	v_cvt_pk_bf16_f32 v117, v118, v119
	v_cvt_pk_bf16_f32 v118, v146, v147
	v_add_f32_e32 v146, v196, v197
	v_add_f32_e32 v146, v218, v146
	v_pk_mul_f32 v[220:221], v[120:121], v[120:121]
	v_add_f32_e32 v146, v219, v146
	v_add_f32_e32 v146, v220, v146
	v_pk_mul_f32 v[222:223], v[122:123], v[122:123]
	v_add_f32_e32 v146, v221, v146
	v_add_f32_e32 v146, v222, v146
	v_add_f32_e32 v146, v223, v146
	v_add_f32_e32 v124, v124, v146
	v_add_f32_e32 v124, v125, v124
	v_add_f32_e32 v124, v126, v124
	v_add_f32_e32 v124, v127, v124
	v_add_f32_e32 v124, v224, v124
	v_pk_mul_f32 v[226:227], v[148:149], v[148:149]
	v_add_f32_e32 v124, v225, v124
	v_add_f32_e32 v124, v226, v124
	v_add_f32_e32 v209, v227, v124
	v_lshlrev_b32_e32 v124, 16, v210
	v_and_b32_e32 v125, 0xffff0000, v210
	v_pk_add_f32 v[100:101], v[100:101], v[124:125]
	v_lshlrev_b32_e32 v124, 16, v212
	v_and_b32_e32 v125, 0xffff0000, v212
	v_pk_add_f32 v[124:125], v[92:93], v[124:125]
	v_lshlrev_b32_e32 v92, 16, v211
	v_and_b32_e32 v93, 0xffff0000, v211
	v_pk_add_f32 v[102:103], v[102:103], v[92:93]
	v_lshlrev_b32_e32 v92, 16, v213
	v_and_b32_e32 v93, 0xffff0000, v213
	v_pk_add_f32 v[126:127], v[94:95], v[92:93]
	v_lshlrev_b32_e32 v92, 16, v214
	v_and_b32_e32 v93, 0xffff0000, v214
	v_pk_add_f32 v[92:93], v[96:97], v[92:93]
	v_lshlrev_b32_e32 v96, 16, v217
	v_and_b32_e32 v97, 0xffff0000, v217
	v_lshlrev_b32_e32 v94, 16, v216
	v_and_b32_e32 v95, 0xffff0000, v216
	v_pk_add_f32 v[90:91], v[90:91], v[96:97]
	v_lshlrev_b32_e32 v96, 16, v136
	v_and_b32_e32 v97, 0xffff0000, v136
	v_pk_add_f32 v[88:89], v[88:89], v[94:95]
	v_lshlrev_b32_e32 v94, 16, v215
	v_and_b32_e32 v95, 0xffff0000, v215
	v_pk_add_f32 v[96:97], v[76:77], v[96:97]
	v_lshl_add_u64 v[76:77], v[168:169], 0, s[36:37]
	v_cvt_pk_bf16_f32 v114, v120, v121
	v_pk_add_f32 v[120:121], v[108:109], v[182:183]
	v_pk_add_f32 v[94:95], v[98:99], v[94:95]
	v_lshlrev_b64 v[182:183], 11, v[76:77]
	v_lshlrev_b32_e32 v98, 16, v138
	v_and_b32_e32 v99, 0xffff0000, v138
	v_pk_add_f32 v[108:109], v[104:105], v[184:185]
	v_lshl_add_u64 v[184:185], v[174:175], 0, v[182:183]
	v_pk_add_f32 v[98:99], v[72:73], v[98:99]
	v_lshlrev_b32_e32 v72, 16, v137
	v_and_b32_e32 v73, 0xffff0000, v137
	global_load_dwordx4 v[210:213], v[184:185], off
	global_load_dwordx4 v[218:221], v[184:185], off offset:256
	v_pk_add_f32 v[136:137], v[78:79], v[72:73]
	v_lshlrev_b32_e32 v72, 16, v139
	v_and_b32_e32 v73, 0xffff0000, v139
	v_pk_add_f32 v[138:139], v[74:75], v[72:73]
	v_lshlrev_b32_e32 v72, 16, v132
	v_and_b32_e32 v73, 0xffff0000, v132
	v_pk_add_f32 v[74:75], v[84:85], v[72:73]
	v_lshlrev_b32_e32 v72, 16, v134
	v_and_b32_e32 v73, 0xffff0000, v134
	v_pk_add_f32 v[78:79], v[80:81], v[72:73]
	v_lshlrev_b32_e32 v72, 16, v133
	v_and_b32_e32 v73, 0xffff0000, v133
	v_pk_add_f32 v[80:81], v[86:87], v[72:73]
	v_lshlrev_b32_e32 v72, 16, v135
	v_and_b32_e32 v73, 0xffff0000, v135
	v_pk_add_f32 v[82:83], v[82:83], v[72:73]
	v_lshl_add_u64 v[72:73], v[168:169], 0, s[10:11]
	v_lshlrev_b64 v[132:133], 11, v[72:73]
	v_lshl_add_u64 v[134:135], v[174:175], 0, v[132:133]
	v_lshlrev_b32_e32 v84, 16, v128
	v_and_b32_e32 v85, 0xffff0000, v128
	global_load_dwordx4 v[226:229], v[134:135], off
	global_load_dwordx4 v[234:237], v[134:135], off offset:256
	v_pk_add_f32 v[84:85], v[68:69], v[84:85]
	v_lshlrev_b32_e32 v68, 16, v130
	v_and_b32_e32 v69, 0xffff0000, v130
	v_pk_add_f32 v[86:87], v[64:65], v[68:69]
	v_lshlrev_b32_e32 v64, 16, v129
	v_and_b32_e32 v65, 0xffff0000, v129
	s_mov_b64 s[10:11], 0xa0
	v_pk_add_f32 v[128:129], v[70:71], v[64:65]
	v_lshl_add_u64 v[70:71], v[168:169], 0, s[10:11]
	s_mov_b64 s[10:11], 0xb0
	v_lshlrev_b32_e32 v64, 16, v131
	v_and_b32_e32 v65, 0xffff0000, v131
	v_lshlrev_b64 v[134:135], 11, v[70:71]
	v_lshl_add_u64 v[68:69], v[168:169], 0, s[10:11]
	v_pk_add_f32 v[130:131], v[66:67], v[64:65]
	v_lshl_add_u64 v[64:65], v[174:175], 0, v[134:135]
	v_lshlrev_b64 v[184:185], 11, v[68:69]
	global_load_dwordx4 v[238:241], v[64:65], off
	global_load_dwordx4 v[242:245], v[64:65], off offset:256
	v_lshl_add_u64 v[64:65], v[174:175], 0, v[184:185]
	global_load_dwordx4 v[246:249], v[64:65], off
	s_nop 0
	global_load_dwordx4 v[64:67], v[64:65], off offset:256
	v_cvt_pk_bf16_f32 v115, v122, v123
	v_cvt_pk_bf16_f32 v119, v148, v149
	v_pk_add_f32 v[110:111], v[110:111], v[192:193]
	v_pk_add_f32 v[122:123], v[106:107], v[194:195]
	global_store_dwordx4 v[172:173], v[112:115], off
	global_store_dwordx4 v[172:173], v[116:119], off offset:256
	v_cvt_pk_bf16_f32 v104, v120, v121
	v_lshl_add_u64 v[112:113], s[28:29], 0, v[176:177]
	v_cvt_pk_bf16_f32 v105, v110, v111
	v_cvt_pk_bf16_f32 v106, v108, v109
	v_cvt_pk_bf16_f32 v107, v122, v123
	v_lshl_add_u64 v[112:113], v[112:113], 0, v[170:171]
	v_cvt_pk_bf16_f32 v146, v100, v101
	v_cvt_pk_bf16_f32 v147, v102, v103
	v_cvt_pk_bf16_f32 v148, v124, v125
	v_cvt_pk_bf16_f32 v149, v126, v127
	global_store_dwordx4 v[112:113], v[104:107], off
	global_store_dwordx4 v[112:113], v[146:149], off offset:256
	v_cvt_pk_bf16_f32 v194, v92, v93
	v_lshl_add_u64 v[104:105], s[28:29], 0, v[180:181]
	v_cvt_pk_bf16_f32 v195, v94, v95
	v_cvt_pk_bf16_f32 v196, v88, v89
	v_cvt_pk_bf16_f32 v197, v90, v91
	v_lshl_add_u64 v[104:105], v[104:105], 0, v[170:171]
	v_cvt_pk_bf16_f32 v214, v96, v97
	v_cvt_pk_bf16_f32 v215, v136, v137
	v_cvt_pk_bf16_f32 v216, v98, v99
	v_cvt_pk_bf16_f32 v217, v138, v139
	global_store_dwordx4 v[104:105], v[194:197], off
	global_store_dwordx4 v[104:105], v[214:217], off offset:256
	v_lshl_add_u64 v[104:105], s[28:29], 0, v[178:179]
	v_cvt_pk_bf16_f32 v222, v74, v75
	v_cvt_pk_bf16_f32 v223, v80, v81
	v_cvt_pk_bf16_f32 v224, v78, v79
	v_cvt_pk_bf16_f32 v225, v82, v83
	v_lshl_add_u64 v[104:105], v[104:105], 0, v[170:171]
	v_cvt_pk_bf16_f32 v230, v84, v85
	v_cvt_pk_bf16_f32 v231, v128, v129
	v_cvt_pk_bf16_f32 v232, v86, v87
	v_cvt_pk_bf16_f32 v233, v130, v131
	global_store_dwordx4 v[104:105], v[222:225], off
	global_store_dwordx4 v[104:105], v[230:233], off offset:256
	s_waitcnt vmcnt(0)
	v_lshlrev_b32_e32 v104, 16, v210
	v_and_b32_e32 v105, 0xffff0000, v210
	v_pk_add_f32 v[60:61], v[60:61], v[104:105]
	v_lshlrev_b32_e32 v104, 16, v212
	v_and_b32_e32 v105, 0xffff0000, v212
	v_pk_add_f32 v[56:57], v[56:57], v[104:105]
	v_lshlrev_b32_e32 v104, 16, v211
	v_and_b32_e32 v105, 0xffff0000, v211
	v_pk_add_f32 v[62:63], v[62:63], v[104:105]
	v_lshlrev_b32_e32 v104, 16, v213
	v_and_b32_e32 v105, 0xffff0000, v213
	v_pk_add_f32 v[58:59], v[58:59], v[104:105]
	v_lshlrev_b32_e32 v104, 16, v218
	v_and_b32_e32 v105, 0xffff0000, v218
	v_pk_add_f32 v[52:53], v[52:53], v[104:105]
	v_lshlrev_b32_e32 v104, 16, v220
	v_and_b32_e32 v105, 0xffff0000, v220
	v_pk_add_f32 v[104:105], v[44:45], v[104:105]
	v_lshlrev_b32_e32 v44, 16, v219
	v_and_b32_e32 v45, 0xffff0000, v219
	v_pk_add_f32 v[54:55], v[54:55], v[44:45]
	v_lshlrev_b32_e32 v44, 16, v221
	v_and_b32_e32 v45, 0xffff0000, v221
	v_pk_add_f32 v[106:107], v[46:47], v[44:45]
	v_lshlrev_b32_e32 v44, 16, v226
	v_and_b32_e32 v45, 0xffff0000, v226
	v_pk_add_f32 v[44:45], v[48:49], v[44:45]
	v_lshlrev_b32_e32 v48, 16, v229
	v_and_b32_e32 v49, 0xffff0000, v229
	v_pk_add_f32 v[42:43], v[42:43], v[48:49]
	v_lshlrev_b32_e32 v48, 16, v234
	v_and_b32_e32 v49, 0xffff0000, v234
	v_pk_add_f32 v[36:37], v[36:37], v[48:49]
	v_lshlrev_b32_e32 v48, 16, v236
	v_and_b32_e32 v49, 0xffff0000, v236
	v_lshlrev_b32_e32 v46, 16, v228
	v_and_b32_e32 v47, 0xffff0000, v228
	v_pk_add_f32 v[48:49], v[28:29], v[48:49]
	v_lshlrev_b32_e32 v28, 16, v235
	v_and_b32_e32 v29, 0xffff0000, v235
	v_pk_add_f32 v[40:41], v[40:41], v[46:47]
	v_lshlrev_b32_e32 v46, 16, v227
	v_and_b32_e32 v47, 0xffff0000, v227
	v_pk_add_f32 v[38:39], v[38:39], v[28:29]
	v_lshlrev_b32_e32 v28, 16, v237
	v_and_b32_e32 v29, 0xffff0000, v237
	v_pk_add_f32 v[46:47], v[50:51], v[46:47]
	v_pk_add_f32 v[50:51], v[30:31], v[28:29]
	v_lshlrev_b32_e32 v28, 16, v238
	v_and_b32_e32 v29, 0xffff0000, v238
	v_lshlrev_b32_e32 v180, 16, v64
	v_and_b32_e32 v181, 0xffff0000, v64
	v_pk_add_f32 v[28:29], v[32:33], v[28:29]
	v_lshlrev_b32_e32 v32, 16, v241
	v_and_b32_e32 v33, 0xffff0000, v241
	v_pk_add_f32 v[4:5], v[4:5], v[180:181]
	v_lshlrev_b32_e32 v180, 16, v66
	v_and_b32_e32 v181, 0xffff0000, v66
	v_pk_add_f32 v[26:27], v[26:27], v[32:33]
	v_lshlrev_b32_e32 v32, 16, v242
	v_and_b32_e32 v33, 0xffff0000, v242
	v_pk_add_f32 v[0:1], v[0:1], v[180:181]
	v_lshl_add_u64 v[180:181], s[28:29], 0, v[182:183]
	v_cvt_pk_bf16_f32 v112, v60, v61
	v_cvt_pk_bf16_f32 v113, v62, v63
	v_cvt_pk_bf16_f32 v114, v56, v57
	v_cvt_pk_bf16_f32 v115, v58, v59
	v_pk_add_f32 v[20:21], v[20:21], v[32:33]
	v_lshlrev_b32_e32 v32, 16, v244
	v_and_b32_e32 v33, 0xffff0000, v244
	v_lshl_add_u64 v[180:181], v[180:181], 0, v[170:171]
	v_cvt_pk_bf16_f32 v116, v52, v53
	v_cvt_pk_bf16_f32 v117, v54, v55
	v_cvt_pk_bf16_f32 v118, v104, v105
	v_cvt_pk_bf16_f32 v119, v106, v107
	v_lshlrev_b32_e32 v30, 16, v240
	v_and_b32_e32 v31, 0xffff0000, v240
	v_pk_add_f32 v[32:33], v[12:13], v[32:33]
	v_lshlrev_b32_e32 v12, 16, v243
	v_and_b32_e32 v13, 0xffff0000, v243
	global_store_dwordx4 v[180:181], v[112:115], off
	global_store_dwordx4 v[180:181], v[116:119], off offset:256
	v_cvt_pk_bf16_f32 v146, v44, v45
	v_lshl_add_u64 v[112:113], s[28:29], 0, v[132:133]
	v_cvt_pk_bf16_f32 v147, v46, v47
	v_cvt_pk_bf16_f32 v148, v40, v41
	v_cvt_pk_bf16_f32 v149, v42, v43
	v_pk_add_f32 v[24:25], v[24:25], v[30:31]
	v_lshlrev_b32_e32 v30, 16, v239
	v_and_b32_e32 v31, 0xffff0000, v239
	v_pk_add_f32 v[22:23], v[22:23], v[12:13]
	v_lshlrev_b32_e32 v12, 16, v245
	v_and_b32_e32 v13, 0xffff0000, v245
	v_lshl_add_u64 v[112:113], v[112:113], 0, v[170:171]
	v_cvt_pk_bf16_f32 v172, v36, v37
	v_cvt_pk_bf16_f32 v173, v38, v39
	v_cvt_pk_bf16_f32 v174, v48, v49
	v_cvt_pk_bf16_f32 v175, v50, v51
	v_pk_add_f32 v[30:31], v[34:35], v[30:31]
	v_pk_add_f32 v[34:35], v[14:15], v[12:13]
	v_lshlrev_b32_e32 v12, 16, v246
	v_and_b32_e32 v13, 0xffff0000, v246
	v_lshlrev_b32_e32 v14, 16, v248
	v_and_b32_e32 v15, 0xffff0000, v248
	global_store_dwordx4 v[112:113], v[146:149], off
	global_store_dwordx4 v[112:113], v[172:175], off offset:256
	v_lshl_add_u64 v[112:113], s[28:29], 0, v[134:135]
	v_cvt_pk_bf16_f32 v176, v28, v29
	v_cvt_pk_bf16_f32 v177, v30, v31
	v_cvt_pk_bf16_f32 v178, v24, v25
	v_cvt_pk_bf16_f32 v179, v26, v27
	v_pk_add_f32 v[12:13], v[16:17], v[12:13]
	v_pk_add_f32 v[8:9], v[8:9], v[14:15]
	v_lshlrev_b32_e32 v14, 16, v247
	v_and_b32_e32 v15, 0xffff0000, v247
	v_lshlrev_b32_e32 v16, 16, v249
	v_and_b32_e32 v17, 0xffff0000, v249
	v_lshlrev_b32_e32 v64, 16, v65
	v_and_b32_e32 v65, 0xffff0000, v65
	v_lshl_add_u64 v[112:113], v[112:113], 0, v[170:171]
	v_cvt_pk_bf16_f32 v194, v20, v21
	v_cvt_pk_bf16_f32 v195, v22, v23
	v_cvt_pk_bf16_f32 v196, v32, v33
	v_cvt_pk_bf16_f32 v197, v34, v35
	v_pk_add_f32 v[14:15], v[18:19], v[14:15]
	v_pk_add_f32 v[10:11], v[10:11], v[16:17]
	v_pk_add_f32 v[6:7], v[6:7], v[64:65]
	v_lshlrev_b32_e32 v64, 16, v67
	v_and_b32_e32 v65, 0xffff0000, v67
	global_store_dwordx4 v[112:113], v[176:179], off
	global_store_dwordx4 v[112:113], v[194:197], off offset:256
	v_lshl_add_u64 v[112:113], s[28:29], 0, v[184:185]
	v_cvt_pk_bf16_f32 v16, v12, v13
	v_cvt_pk_bf16_f32 v17, v14, v15
	v_cvt_pk_bf16_f32 v18, v8, v9
	v_cvt_pk_bf16_f32 v19, v10, v11
	v_pk_add_f32 v[2:3], v[2:3], v[64:65]
	v_lshl_add_u64 v[112:113], v[112:113], 0, v[170:171]
	v_cvt_pk_bf16_f32 v64, v4, v5
	v_cvt_pk_bf16_f32 v65, v6, v7
	v_cvt_pk_bf16_f32 v66, v0, v1
	v_cvt_pk_bf16_f32 v67, v2, v3
	global_store_dwordx4 v[112:113], v[16:19], off
	global_store_dwordx4 v[112:113], v[64:67], off offset:256
	s_lshl_b32 s10, s85, 2
	v_and_b32_e32 v17, 64, v188
	v_xor_b32_e32 v16, 16, v188
	v_add_u32_e32 v17, 64, v17
	v_cmp_lt_i32_e32 vcc, v16, v17
	v_xor_b32_e32 v18, 32, v188
	s_ashr_i32 s11, s10, 31
	v_cndmask_b32_e32 v16, v188, v16, vcc
	v_lshlrev_b32_e32 v16, 2, v16
	ds_bpermute_b32 v19, v16, v209
	v_cmp_lt_i32_e32 vcc, v18, v17
	s_lshl_b64 s[10:11], s[10:11], 2
	s_add_u32 s50, s83, s10
	v_cndmask_b32_e32 v17, v188, v18, vcc
	v_lshlrev_b32_e32 v17, 2, v17
	s_waitcnt lgkmcnt(0)
	v_add_f32_e32 v18, v209, v19
	ds_bpermute_b32 v19, v17, v18
	s_addc_u32 s51, s84, s11
	s_and_saveexec_b64 s[52:53], s[42:43]
	s_cbranch_execz .LBB0_106
	s_waitcnt lgkmcnt(0)
	v_add_f32_e32 v64, v18, v19
	v_lshlrev_b64 v[18:19], 6, v[168:169]
	v_lshl_add_u64 v[18:19], s[50:51], 0, v[18:19]
	global_store_dword v[18:19], v64, off

.Lm4bp_248:
	s_waitcnt lgkmcnt(0)
	s_mov_b32 s100, 0
	s_barrier
	v_mfma_f32_16x16x32_bf16 v[60:63], v[128:131], v[162:165], 0
	v_mfma_f32_16x16x32_bf16 v[56:59], v[136:139], v[162:165], 0
	v_mfma_f32_16x16x32_bf16 v[48:51], v[128:131], v[170:173], 0
	v_mfma_f32_16x16x32_bf16 v[40:43], v[136:139], v[170:173], 0
	v_mfma_f32_16x16x32_bf16 v[32:35], v[128:131], v[178:181], 0
	v_mfma_f32_16x16x32_bf16 v[24:27], v[136:139], v[178:181], 0
	v_mfma_f32_16x16x32_bf16 v[16:19], v[128:131], v[194:197], 0
	v_mfma_f32_16x16x32_bf16 v[8:11], v[136:139], v[194:197], 0
	v_mfma_f32_16x16x32_bf16 v[60:63], v[132:135], v[166:169], v[60:63]
	v_mfma_f32_16x16x32_bf16 v[56:59], v[146:149], v[166:169], v[56:59]
	v_mfma_f32_16x16x32_bf16 v[48:51], v[132:135], v[174:177], v[48:51]
	v_mfma_f32_16x16x32_bf16 v[40:43], v[146:149], v[174:177], v[40:43]
	v_mfma_f32_16x16x32_bf16 v[32:35], v[132:135], v[182:185], v[32:35]
	v_mfma_f32_16x16x32_bf16 v[24:27], v[146:149], v[182:185], v[24:27]
	v_mfma_f32_16x16x32_bf16 v[16:19], v[132:135], v[210:213], v[16:19]
	v_mfma_f32_16x16x32_bf16 v[8:11], v[146:149], v[210:213], v[8:11]
	v_mfma_f32_16x16x32_bf16 v[52:55], v[214:217], v[162:165], 0
	v_mfma_f32_16x16x32_bf16 v[44:47], v[222:225], v[162:165], 0
	v_mfma_f32_16x16x32_bf16 v[36:39], v[214:217], v[170:173], 0
	v_mfma_f32_16x16x32_bf16 v[28:31], v[222:225], v[170:173], 0
	v_mfma_f32_16x16x32_bf16 v[20:23], v[214:217], v[178:181], 0
	v_mfma_f32_16x16x32_bf16 v[12:15], v[222:225], v[178:181], 0
	v_mfma_f32_16x16x32_bf16 v[4:7], v[214:217], v[194:197], 0
	v_mfma_f32_16x16x32_bf16 v[0:3], v[222:225], v[194:197], 0
	v_mfma_f32_16x16x32_bf16 v[52:55], v[218:221], v[166:169], v[52:55]
	v_mfma_f32_16x16x32_bf16 v[44:47], v[226:229], v[166:169], v[44:47]
	v_mfma_f32_16x16x32_bf16 v[36:39], v[218:221], v[174:177], v[36:39]
	v_mfma_f32_16x16x32_bf16 v[28:31], v[226:229], v[174:177], v[28:31]
	v_mfma_f32_16x16x32_bf16 v[20:23], v[218:221], v[182:185], v[20:23]
	v_mfma_f32_16x16x32_bf16 v[12:15], v[226:229], v[182:185], v[12:15]
	v_mfma_f32_16x16x32_bf16 v[4:7], v[218:221], v[210:213], v[4:7]
	v_mfma_f32_16x16x32_bf16 v[0:3], v[226:229], v[210:213], v[0:3]
	s_barrier
	s_add_i32 s6, 0, 0x18000
	v_add_u32_e32 v146, s6, v206
	ds_read_b128 v[128:131], v146
	ds_read_b128 v[132:135], v146 offset:1024
	ds_read_b128 v[136:139], v146 offset:2048
	ds_read_b128 v[146:149], v146 offset:3072
	s_add_u32 s58, s58, 0x40000
	s_addc_u32 s59, s59, 0
	s_mov_b32 m0, s70
	v_lshl_add_u64 v[214:215], s[58:59], 0, v[154:155]
	ds_read_b128 v[162:165], v208 offset:32768
	ds_read_b128 v[166:169], v208 offset:33792
	ds_read_b128 v[170:173], v208 offset:34816
	ds_read_b128 v[174:177], v208 offset:35840
	ds_read_b128 v[178:181], v208 offset:36864
	ds_read_b128 v[182:185], v208 offset:37888
	ds_read_b128 v[194:197], v208 offset:38912
	ds_read_b128 v[210:213], v208 offset:39936
	global_load_lds_dwordx4 v[214:215], off
	v_lshl_add_u64 v[214:215], s[58:59], 0, v[152:153]
	s_mov_b32 m0, s71
	s_nop 0
	global_load_lds_dwordx4 v[214:215], off
	s_add_i32 s19, 0, 0x1c000
	v_add_u32_e32 v192, s19, v206
	ds_read_b128 v[214:217], v192
	ds_read_b128 v[218:221], v192 offset:1024
	ds_read_b128 v[222:225], v192 offset:2048
	ds_read_b128 v[226:229], v192 offset:3072
	s_waitcnt vmcnt(8)
	s_waitcnt lgkmcnt(0)
	s_barrier
	v_mfma_f32_16x16x32_bf16 v[124:127], v[128:131], v[162:165], v[124:127]
	v_mfma_f32_16x16x32_bf16 v[120:123], v[136:139], v[162:165], v[120:123]
	v_mfma_f32_16x16x32_bf16 v[108:111], v[128:131], v[170:173], v[108:111]
	v_mfma_f32_16x16x32_bf16 v[104:107], v[136:139], v[170:173], v[104:107]
	v_mfma_f32_16x16x32_bf16 v[96:99], v[128:131], v[178:181], v[96:99]
	v_mfma_f32_16x16x32_bf16 v[88:91], v[136:139], v[178:181], v[88:91]
	v_mfma_f32_16x16x32_bf16 v[84:87], v[128:131], v[194:197], v[84:87]
	v_mfma_f32_16x16x32_bf16 v[80:83], v[136:139], v[194:197], v[80:83]
	v_mfma_f32_16x16x32_bf16 v[124:127], v[132:135], v[166:169], v[124:127]
	v_mfma_f32_16x16x32_bf16 v[120:123], v[146:149], v[166:169], v[120:123]
	v_mfma_f32_16x16x32_bf16 v[108:111], v[132:135], v[174:177], v[108:111]
	v_mfma_f32_16x16x32_bf16 v[104:107], v[146:149], v[174:177], v[104:107]
	v_mfma_f32_16x16x32_bf16 v[96:99], v[132:135], v[182:185], v[96:99]
	v_mfma_f32_16x16x32_bf16 v[88:91], v[146:149], v[182:185], v[88:91]
	v_mfma_f32_16x16x32_bf16 v[84:87], v[132:135], v[210:213], v[84:87]
	v_mfma_f32_16x16x32_bf16 v[80:83], v[146:149], v[210:213], v[80:83]
	v_mfma_f32_16x16x32_bf16 v[116:119], v[214:217], v[162:165], v[116:119]
	v_mfma_f32_16x16x32_bf16 v[112:115], v[222:225], v[162:165], v[112:115]
	v_mfma_f32_16x16x32_bf16 v[100:103], v[214:217], v[170:173], v[100:103]
	v_mfma_f32_16x16x32_bf16 v[92:95], v[222:225], v[170:173], v[92:95]
	v_mfma_f32_16x16x32_bf16 v[76:79], v[214:217], v[178:181], v[76:79]
	v_mfma_f32_16x16x32_bf16 v[72:75], v[222:225], v[178:181], v[72:75]
	v_mfma_f32_16x16x32_bf16 v[68:71], v[214:217], v[194:197], v[68:71]
	v_mfma_f32_16x16x32_bf16 v[64:67], v[222:225], v[194:197], v[64:67]
	v_mfma_f32_16x16x32_bf16 v[116:119], v[218:221], v[166:169], v[116:119]
	v_mfma_f32_16x16x32_bf16 v[112:115], v[226:229], v[166:169], v[112:115]
	v_mfma_f32_16x16x32_bf16 v[100:103], v[218:221], v[174:177], v[100:103]
	v_mfma_f32_16x16x32_bf16 v[92:95], v[226:229], v[174:177], v[92:95]
	v_mfma_f32_16x16x32_bf16 v[76:79], v[218:221], v[182:185], v[76:79]
	v_mfma_f32_16x16x32_bf16 v[72:75], v[226:229], v[182:185], v[72:75]
	v_mfma_f32_16x16x32_bf16 v[68:71], v[218:221], v[210:213], v[68:71]
	v_mfma_f32_16x16x32_bf16 v[64:67], v[226:229], v[210:213], v[64:67]
	s_barrier
	s_add_i32 s6, s6, s57
	v_lshl_add_u64 v[230:231], v[230:231], 0, s[36:37]
	s_mov_b32 m0, s6
	s_nop 0
	global_load_lds_dwordx4 v[230:231], off
	v_lshl_add_u64 v[230:231], v[232:233], 0, s[36:37]
	s_add_i32 m0, s6, 0x2000
	s_nop 0
	global_load_lds_dwordx4 v[230:231], off
	s_mov_b32 m0, s72
	v_lshl_add_u64 v[230:231], v[234:235], 0, s[36:37]
	ds_read_b128 v[162:165], v208 offset:49152
	ds_read_b128 v[166:169], v208 offset:50176
	ds_read_b128 v[170:173], v208 offset:51200
	ds_read_b128 v[174:177], v208 offset:52224
	ds_read_b128 v[178:181], v208 offset:53248
	ds_read_b128 v[182:185], v208 offset:54272
	ds_read_b128 v[194:197], v208 offset:55296
	ds_read_b128 v[210:213], v208 offset:56320
	global_load_lds_dwordx4 v[230:231], off
	v_lshl_add_u64 v[230:231], v[236:237], 0, s[36:37]
	s_mov_b32 m0, s73
	s_nop 0
	global_load_lds_dwordx4 v[230:231], off
	s_add_u32 s54, s54, 0x40080
	s_addc_u32 s55, s55, 0
	s_add_i32 s6, s19, s57
	v_lshl_add_u64 v[250:251], s[54:55], 0, v[140:141]
	s_mov_b32 m0, s6
	s_nop 0
	global_load_lds_dwordx4 v[250:251], off
	v_lshl_add_u64 v[250:251], s[54:55], 0, v[150:151]
	s_add_i32 m0, s6, 0x2000
	s_nop 0
	global_load_lds_dwordx4 v[250:251], off
	s_add_i32 s82, s82, 2
	s_add_u32 s52, s52, 0x100
	s_addc_u32 s53, s53, 0
	s_add_u32 s39, s39, 0x100
	s_addc_u32 s51, s51, 0
	s_cmp_gt_u32 s82, 13
	s_waitcnt vmcnt(8)
	s_waitcnt lgkmcnt(0)
	s_barrier
	v_mfma_f32_16x16x32_bf16 v[60:63], v[128:131], v[162:165], v[60:63]
	v_mfma_f32_16x16x32_bf16 v[56:59], v[136:139], v[162:165], v[56:59]
	v_mfma_f32_16x16x32_bf16 v[48:51], v[128:131], v[170:173], v[48:51]
	v_mfma_f32_16x16x32_bf16 v[40:43], v[136:139], v[170:173], v[40:43]
	v_mfma_f32_16x16x32_bf16 v[32:35], v[128:131], v[178:181], v[32:35]
	v_mfma_f32_16x16x32_bf16 v[24:27], v[136:139], v[178:181], v[24:27]
	v_mfma_f32_16x16x32_bf16 v[16:19], v[128:131], v[194:197], v[16:19]
	v_mfma_f32_16x16x32_bf16 v[8:11], v[136:139], v[194:197], v[8:11]
	v_mfma_f32_16x16x32_bf16 v[60:63], v[132:135], v[166:169], v[60:63]
	v_mfma_f32_16x16x32_bf16 v[56:59], v[146:149], v[166:169], v[56:59]
	v_mfma_f32_16x16x32_bf16 v[48:51], v[132:135], v[174:177], v[48:51]
	v_mfma_f32_16x16x32_bf16 v[40:43], v[146:149], v[174:177], v[40:43]
	v_mfma_f32_16x16x32_bf16 v[32:35], v[132:135], v[182:185], v[32:35]
	v_mfma_f32_16x16x32_bf16 v[24:27], v[146:149], v[182:185], v[24:27]
	v_mfma_f32_16x16x32_bf16 v[16:19], v[132:135], v[210:213], v[16:19]
	v_mfma_f32_16x16x32_bf16 v[8:11], v[146:149], v[210:213], v[8:11]
	v_mfma_f32_16x16x32_bf16 v[52:55], v[214:217], v[162:165], v[52:55]
	v_mfma_f32_16x16x32_bf16 v[44:47], v[222:225], v[162:165], v[44:47]
	v_mfma_f32_16x16x32_bf16 v[36:39], v[214:217], v[170:173], v[36:39]
	v_mfma_f32_16x16x32_bf16 v[28:31], v[222:225], v[170:173], v[28:31]
	v_mfma_f32_16x16x32_bf16 v[20:23], v[214:217], v[178:181], v[20:23]
	v_mfma_f32_16x16x32_bf16 v[12:15], v[222:225], v[178:181], v[12:15]
	v_mfma_f32_16x16x32_bf16 v[4:7], v[214:217], v[194:197], v[4:7]
	v_mfma_f32_16x16x32_bf16 v[0:3], v[222:225], v[194:197], v[0:3]
	v_mfma_f32_16x16x32_bf16 v[52:55], v[218:221], v[166:169], v[52:55]
	v_mfma_f32_16x16x32_bf16 v[44:47], v[226:229], v[166:169], v[44:47]
	v_mfma_f32_16x16x32_bf16 v[36:39], v[218:221], v[174:177], v[36:39]
	v_mfma_f32_16x16x32_bf16 v[28:31], v[226:229], v[174:177], v[28:31]
	v_mfma_f32_16x16x32_bf16 v[20:23], v[218:221], v[182:185], v[20:23]
	v_mfma_f32_16x16x32_bf16 v[12:15], v[226:229], v[182:185], v[12:15]
	v_mfma_f32_16x16x32_bf16 v[4:7], v[218:221], v[210:213], v[4:7]
	v_mfma_f32_16x16x32_bf16 v[0:3], v[226:229], v[210:213], v[0:3]
	s_barrier
.LBB0_248:
	s_add_u32 s6, s52, 0xfffc0080
	s_addc_u32 s19, s53, -1
	s_add_i32 s23, 0, 0x10000
	v_add_u32_e32 v146, s23, v206
	ds_read_b128 v[128:131], v146
	ds_read_b128 v[132:135], v146 offset:1024
	ds_read_b128 v[136:139], v146 offset:2048
	ds_read_b128 v[146:149], v146 offset:3072
	s_cmp_eq_u32 s82, 12
	s_cselect_b32 s59, s10, s19
	s_cselect_b32 s58, s11, s6
	s_cselect_b32 s55, s12, s51
	s_cselect_b32 s54, s35, s39
	v_lshl_add_u64 v[214:215], s[52:53], 0, v[158:159]
	s_add_i32 m0, s68, 0xc000
	ds_read_b128 v[162:165], v208
	ds_read_b128 v[166:169], v208 offset:1024
	ds_read_b128 v[170:173], v208 offset:2048
	ds_read_b128 v[174:177], v208 offset:3072
	ds_read_b128 v[178:181], v208 offset:4096
	ds_read_b128 v[182:185], v208 offset:5120
	ds_read_b128 v[194:197], v208 offset:6144
	ds_read_b128 v[210:213], v208 offset:7168
	global_load_lds_dwordx4 v[214:215], off
	v_lshl_add_u64 v[214:215], s[52:53], 0, v[160:161]
	s_add_i32 m0, s68, 0xe000
	s_nop 0
	global_load_lds_dwordx4 v[214:215], off
	s_add_i32 s6, 0, 0x14000
	v_add_u32_e32 v192, s6, v206
	ds_read_b128 v[214:217], v192
	ds_read_b128 v[218:221], v192 offset:1024
	ds_read_b128 v[222:225], v192 offset:2048
	ds_read_b128 v[226:229], v192 offset:3072
	s_nop 0
	s_waitcnt vmcnt(8)
	s_waitcnt lgkmcnt(0)
	s_barrier
	v_mfma_f32_16x16x32_bf16 v[124:127], v[128:131], v[162:165], v[124:127]
	v_mfma_f32_16x16x32_bf16 v[120:123], v[136:139], v[162:165], v[120:123]
	v_mfma_f32_16x16x32_bf16 v[108:111], v[128:131], v[170:173], v[108:111]
	v_mfma_f32_16x16x32_bf16 v[104:107], v[136:139], v[170:173], v[104:107]
	v_mfma_f32_16x16x32_bf16 v[96:99], v[128:131], v[178:181], v[96:99]
	v_mfma_f32_16x16x32_bf16 v[88:91], v[136:139], v[178:181], v[88:91]
	v_mfma_f32_16x16x32_bf16 v[84:87], v[128:131], v[194:197], v[84:87]
	v_mfma_f32_16x16x32_bf16 v[80:83], v[136:139], v[194:197], v[80:83]
	v_mfma_f32_16x16x32_bf16 v[124:127], v[132:135], v[166:169], v[124:127]
	v_mfma_f32_16x16x32_bf16 v[120:123], v[146:149], v[166:169], v[120:123]
	v_mfma_f32_16x16x32_bf16 v[108:111], v[132:135], v[174:177], v[108:111]
	v_mfma_f32_16x16x32_bf16 v[104:107], v[146:149], v[174:177], v[104:107]
	v_mfma_f32_16x16x32_bf16 v[96:99], v[132:135], v[182:185], v[96:99]
	v_mfma_f32_16x16x32_bf16 v[88:91], v[146:149], v[182:185], v[88:91]
	v_mfma_f32_16x16x32_bf16 v[84:87], v[132:135], v[210:213], v[84:87]
	v_mfma_f32_16x16x32_bf16 v[80:83], v[146:149], v[210:213], v[80:83]
	v_mfma_f32_16x16x32_bf16 v[116:119], v[214:217], v[162:165], v[116:119]
	v_mfma_f32_16x16x32_bf16 v[112:115], v[222:225], v[162:165], v[112:115]
	v_mfma_f32_16x16x32_bf16 v[100:103], v[214:217], v[170:173], v[100:103]
	v_mfma_f32_16x16x32_bf16 v[92:95], v[222:225], v[170:173], v[92:95]
	v_mfma_f32_16x16x32_bf16 v[76:79], v[214:217], v[178:181], v[76:79]
	v_mfma_f32_16x16x32_bf16 v[72:75], v[222:225], v[178:181], v[72:75]
	v_mfma_f32_16x16x32_bf16 v[68:71], v[214:217], v[194:197], v[68:71]
	v_mfma_f32_16x16x32_bf16 v[64:67], v[222:225], v[194:197], v[64:67]
	v_mfma_f32_16x16x32_bf16 v[116:119], v[218:221], v[166:169], v[116:119]
	v_mfma_f32_16x16x32_bf16 v[112:115], v[226:229], v[166:169], v[112:115]
	v_mfma_f32_16x16x32_bf16 v[100:103], v[218:221], v[174:177], v[100:103]
	v_mfma_f32_16x16x32_bf16 v[92:95], v[226:229], v[174:177], v[92:95]
	v_mfma_f32_16x16x32_bf16 v[76:79], v[218:221], v[182:185], v[76:79]
	v_mfma_f32_16x16x32_bf16 v[72:75], v[226:229], v[182:185], v[72:75]
	v_mfma_f32_16x16x32_bf16 v[68:71], v[218:221], v[210:213], v[68:71]
	v_mfma_f32_16x16x32_bf16 v[64:67], v[226:229], v[210:213], v[64:67]
	s_barrier
	s_add_i32 s19, s23, s57
	v_lshl_add_u64 v[230:231], s[54:55], 0, v[140:141]
	s_mov_b32 m0, s19
	s_nop 0
	global_load_lds_dwordx4 v[230:231], off
	v_lshl_add_u64 v[232:233], s[54:55], 0, v[150:151]
	s_add_i32 m0, s19, 0x2000
	s_nop 0
	global_load_lds_dwordx4 v[232:233], off
	s_mov_b32 m0, s68
	v_lshl_add_u64 v[234:235], s[58:59], 0, v[154:155]
	ds_read_b128 v[162:165], v208 offset:16384
	ds_read_b128 v[166:169], v208 offset:17408
	ds_read_b128 v[170:173], v208 offset:18432
	ds_read_b128 v[174:177], v208 offset:19456
	ds_read_b128 v[178:181], v208 offset:20480
	ds_read_b128 v[182:185], v208 offset:21504
	ds_read_b128 v[194:197], v208 offset:22528
	ds_read_b128 v[210:213], v208 offset:23552
	global_load_lds_dwordx4 v[234:235], off
	v_lshl_add_u64 v[236:237], s[58:59], 0, v[152:153]
	s_mov_b32 m0, s69
	s_nop 0
	global_load_lds_dwordx4 v[236:237], off
	s_add_u32 s84, s54, 0x40000
	s_addc_u32 s85, s55, 0
	s_add_i32 s6, s6, s57
	v_lshl_add_u64 v[250:251], s[84:85], 0, v[140:141]
	s_mov_b32 m0, s6
	s_nop 0
	global_load_lds_dwordx4 v[250:251], off
	v_lshl_add_u64 v[250:251], s[84:85], 0, v[150:151]
	s_add_i32 m0, s6, 0x2000
	s_nop 0
	global_load_lds_dwordx4 v[250:251], off
	s_waitcnt vmcnt(8)
	s_waitcnt lgkmcnt(0)
	s_barrier
	v_mfma_f32_16x16x32_bf16 v[60:63], v[128:131], v[162:165], v[60:63]
	v_mfma_f32_16x16x32_bf16 v[56:59], v[136:139], v[162:165], v[56:59]
	v_mfma_f32_16x16x32_bf16 v[48:51], v[128:131], v[170:173], v[48:51]
	v_mfma_f32_16x16x32_bf16 v[40:43], v[136:139], v[170:173], v[40:43]
	v_mfma_f32_16x16x32_bf16 v[32:35], v[128:131], v[178:181], v[32:35]
	v_mfma_f32_16x16x32_bf16 v[24:27], v[136:139], v[178:181], v[24:27]
	v_mfma_f32_16x16x32_bf16 v[16:19], v[128:131], v[194:197], v[16:19]
	v_mfma_f32_16x16x32_bf16 v[8:11], v[136:139], v[194:197], v[8:11]
	v_mfma_f32_16x16x32_bf16 v[60:63], v[132:135], v[166:169], v[60:63]
	v_mfma_f32_16x16x32_bf16 v[56:59], v[146:149], v[166:169], v[56:59]
	v_mfma_f32_16x16x32_bf16 v[48:51], v[132:135], v[174:177], v[48:51]
	v_mfma_f32_16x16x32_bf16 v[40:43], v[146:149], v[174:177], v[40:43]
	v_mfma_f32_16x16x32_bf16 v[32:35], v[132:135], v[182:185], v[32:35]
	v_mfma_f32_16x16x32_bf16 v[24:27], v[146:149], v[182:185], v[24:27]
	v_mfma_f32_16x16x32_bf16 v[16:19], v[132:135], v[210:213], v[16:19]
	v_mfma_f32_16x16x32_bf16 v[8:11], v[146:149], v[210:213], v[8:11]
	v_mfma_f32_16x16x32_bf16 v[52:55], v[214:217], v[162:165], v[52:55]
	v_mfma_f32_16x16x32_bf16 v[44:47], v[222:225], v[162:165], v[44:47]
	v_mfma_f32_16x16x32_bf16 v[36:39], v[214:217], v[170:173], v[36:39]
	v_mfma_f32_16x16x32_bf16 v[28:31], v[222:225], v[170:173], v[28:31]
	v_mfma_f32_16x16x32_bf16 v[20:23], v[214:217], v[178:181], v[20:23]
	v_mfma_f32_16x16x32_bf16 v[12:15], v[222:225], v[178:181], v[12:15]
	v_mfma_f32_16x16x32_bf16 v[4:7], v[214:217], v[194:197], v[4:7]
	v_mfma_f32_16x16x32_bf16 v[0:3], v[222:225], v[194:197], v[0:3]
	v_mfma_f32_16x16x32_bf16 v[52:55], v[218:221], v[166:169], v[52:55]
	v_mfma_f32_16x16x32_bf16 v[44:47], v[226:229], v[166:169], v[44:47]
	v_mfma_f32_16x16x32_bf16 v[36:39], v[218:221], v[174:177], v[36:39]
	v_mfma_f32_16x16x32_bf16 v[28:31], v[226:229], v[174:177], v[28:31]
	v_mfma_f32_16x16x32_bf16 v[20:23], v[218:221], v[182:185], v[20:23]
	v_mfma_f32_16x16x32_bf16 v[12:15], v[226:229], v[182:185], v[12:15]
	v_mfma_f32_16x16x32_bf16 v[4:7], v[218:221], v[210:213], v[4:7]
	v_mfma_f32_16x16x32_bf16 v[0:3], v[226:229], v[210:213], v[0:3]
	s_barrier
	s_add_i32 s6, 0, 0x18000
	v_add_u32_e32 v146, s6, v206
	ds_read_b128 v[128:131], v146
	ds_read_b128 v[132:135], v146 offset:1024
	ds_read_b128 v[136:139], v146 offset:2048
	ds_read_b128 v[146:149], v146 offset:3072
	s_add_u32 s58, s58, 0x40000
	s_addc_u32 s59, s59, 0
	s_mov_b32 m0, s70
	v_lshl_add_u64 v[214:215], s[58:59], 0, v[154:155]
	ds_read_b128 v[162:165], v208 offset:32768
	ds_read_b128 v[166:169], v208 offset:33792
	ds_read_b128 v[170:173], v208 offset:34816
	ds_read_b128 v[174:177], v208 offset:35840
	ds_read_b128 v[178:181], v208 offset:36864
	ds_read_b128 v[182:185], v208 offset:37888
	ds_read_b128 v[194:197], v208 offset:38912
	ds_read_b128 v[210:213], v208 offset:39936
	global_load_lds_dwordx4 v[214:215], off
	v_lshl_add_u64 v[214:215], s[58:59], 0, v[152:153]
	s_mov_b32 m0, s71
	s_nop 0
	global_load_lds_dwordx4 v[214:215], off
	s_add_i32 s19, 0, 0x1c000
	v_add_u32_e32 v192, s19, v206
	ds_read_b128 v[214:217], v192
	ds_read_b128 v[218:221], v192 offset:1024
	ds_read_b128 v[222:225], v192 offset:2048
	ds_read_b128 v[226:229], v192 offset:3072
	s_waitcnt vmcnt(8)
	s_waitcnt lgkmcnt(0)
	s_barrier
	v_mfma_f32_16x16x32_bf16 v[124:127], v[128:131], v[162:165], v[124:127]
	v_mfma_f32_16x16x32_bf16 v[120:123], v[136:139], v[162:165], v[120:123]
	v_mfma_f32_16x16x32_bf16 v[108:111], v[128:131], v[170:173], v[108:111]
	v_mfma_f32_16x16x32_bf16 v[104:107], v[136:139], v[170:173], v[104:107]
	v_mfma_f32_16x16x32_bf16 v[96:99], v[128:131], v[178:181], v[96:99]
	v_mfma_f32_16x16x32_bf16 v[88:91], v[136:139], v[178:181], v[88:91]
	v_mfma_f32_16x16x32_bf16 v[84:87], v[128:131], v[194:197], v[84:87]
	v_mfma_f32_16x16x32_bf16 v[80:83], v[136:139], v[194:197], v[80:83]
	v_mfma_f32_16x16x32_bf16 v[124:127], v[132:135], v[166:169], v[124:127]
	v_mfma_f32_16x16x32_bf16 v[120:123], v[146:149], v[166:169], v[120:123]
	v_mfma_f32_16x16x32_bf16 v[108:111], v[132:135], v[174:177], v[108:111]
	v_mfma_f32_16x16x32_bf16 v[104:107], v[146:149], v[174:177], v[104:107]
	v_mfma_f32_16x16x32_bf16 v[96:99], v[132:135], v[182:185], v[96:99]
	v_mfma_f32_16x16x32_bf16 v[88:91], v[146:149], v[182:185], v[88:91]
	v_mfma_f32_16x16x32_bf16 v[84:87], v[132:135], v[210:213], v[84:87]
	v_mfma_f32_16x16x32_bf16 v[80:83], v[146:149], v[210:213], v[80:83]
	v_mfma_f32_16x16x32_bf16 v[116:119], v[214:217], v[162:165], v[116:119]
	v_mfma_f32_16x16x32_bf16 v[112:115], v[222:225], v[162:165], v[112:115]
	v_mfma_f32_16x16x32_bf16 v[100:103], v[214:217], v[170:173], v[100:103]
	v_mfma_f32_16x16x32_bf16 v[92:95], v[222:225], v[170:173], v[92:95]
	v_mfma_f32_16x16x32_bf16 v[76:79], v[214:217], v[178:181], v[76:79]
	v_mfma_f32_16x16x32_bf16 v[72:75], v[222:225], v[178:181], v[72:75]
	v_mfma_f32_16x16x32_bf16 v[68:71], v[214:217], v[194:197], v[68:71]
	v_mfma_f32_16x16x32_bf16 v[64:67], v[222:225], v[194:197], v[64:67]
	v_mfma_f32_16x16x32_bf16 v[116:119], v[218:221], v[166:169], v[116:119]
	v_mfma_f32_16x16x32_bf16 v[112:115], v[226:229], v[166:169], v[112:115]
	v_mfma_f32_16x16x32_bf16 v[100:103], v[218:221], v[174:177], v[100:103]
	v_mfma_f32_16x16x32_bf16 v[92:95], v[226:229], v[174:177], v[92:95]
	v_mfma_f32_16x16x32_bf16 v[76:79], v[218:221], v[182:185], v[76:79]
	v_mfma_f32_16x16x32_bf16 v[72:75], v[226:229], v[182:185], v[72:75]
	v_mfma_f32_16x16x32_bf16 v[68:71], v[218:221], v[210:213], v[68:71]
	v_mfma_f32_16x16x32_bf16 v[64:67], v[226:229], v[210:213], v[64:67]
	s_barrier
	s_add_i32 s6, s6, s57
	v_lshl_add_u64 v[230:231], v[230:231], 0, s[36:37]
	s_mov_b32 m0, s6
	s_nop 0
	global_load_lds_dwordx4 v[230:231], off
	v_lshl_add_u64 v[230:231], v[232:233], 0, s[36:37]
	s_add_i32 m0, s6, 0x2000
	s_nop 0
	global_load_lds_dwordx4 v[230:231], off
	s_mov_b32 m0, s72
	v_lshl_add_u64 v[230:231], v[234:235], 0, s[36:37]
	ds_read_b128 v[162:165], v208 offset:49152
	ds_read_b128 v[166:169], v208 offset:50176
	ds_read_b128 v[170:173], v208 offset:51200
	ds_read_b128 v[174:177], v208 offset:52224
	ds_read_b128 v[178:181], v208 offset:53248
	ds_read_b128 v[182:185], v208 offset:54272
	ds_read_b128 v[194:197], v208 offset:55296
	ds_read_b128 v[210:213], v208 offset:56320
	global_load_lds_dwordx4 v[230:231], off
	v_lshl_add_u64 v[230:231], v[236:237], 0, s[36:37]
	s_mov_b32 m0, s73
	s_nop 0
	global_load_lds_dwordx4 v[230:231], off
	s_add_u32 s54, s54, 0x40080
	s_addc_u32 s55, s55, 0
	s_add_i32 s6, s19, s57
	v_lshl_add_u64 v[250:251], s[54:55], 0, v[140:141]
	s_mov_b32 m0, s6
	s_nop 0
	global_load_lds_dwordx4 v[250:251], off
	v_lshl_add_u64 v[250:251], s[54:55], 0, v[150:151]
	s_add_i32 m0, s6, 0x2000
	s_nop 0
	global_load_lds_dwordx4 v[250:251], off
	s_add_i32 s82, s82, 2
	s_add_u32 s52, s52, 0x100
	s_addc_u32 s53, s53, 0
	s_add_u32 s39, s39, 0x100
	s_addc_u32 s51, s51, 0
	s_cmp_gt_u32 s82, 13
	s_waitcnt vmcnt(8)
	s_waitcnt lgkmcnt(0)
	s_barrier
	v_mfma_f32_16x16x32_bf16 v[60:63], v[128:131], v[162:165], v[60:63]
	v_mfma_f32_16x16x32_bf16 v[56:59], v[136:139], v[162:165], v[56:59]
	v_mfma_f32_16x16x32_bf16 v[48:51], v[128:131], v[170:173], v[48:51]
	v_mfma_f32_16x16x32_bf16 v[40:43], v[136:139], v[170:173], v[40:43]
	v_mfma_f32_16x16x32_bf16 v[32:35], v[128:131], v[178:181], v[32:35]
	v_mfma_f32_16x16x32_bf16 v[24:27], v[136:139], v[178:181], v[24:27]
	v_mfma_f32_16x16x32_bf16 v[16:19], v[128:131], v[194:197], v[16:19]
	v_mfma_f32_16x16x32_bf16 v[8:11], v[136:139], v[194:197], v[8:11]
	v_mfma_f32_16x16x32_bf16 v[60:63], v[132:135], v[166:169], v[60:63]
	v_mfma_f32_16x16x32_bf16 v[56:59], v[146:149], v[166:169], v[56:59]
	v_mfma_f32_16x16x32_bf16 v[48:51], v[132:135], v[174:177], v[48:51]
	v_mfma_f32_16x16x32_bf16 v[40:43], v[146:149], v[174:177], v[40:43]
	v_mfma_f32_16x16x32_bf16 v[32:35], v[132:135], v[182:185], v[32:35]
	v_mfma_f32_16x16x32_bf16 v[24:27], v[146:149], v[182:185], v[24:27]
	v_mfma_f32_16x16x32_bf16 v[16:19], v[132:135], v[210:213], v[16:19]
	v_mfma_f32_16x16x32_bf16 v[8:11], v[146:149], v[210:213], v[8:11]
	v_mfma_f32_16x16x32_bf16 v[52:55], v[214:217], v[162:165], v[52:55]
	v_mfma_f32_16x16x32_bf16 v[44:47], v[222:225], v[162:165], v[44:47]
	v_mfma_f32_16x16x32_bf16 v[36:39], v[214:217], v[170:173], v[36:39]
	v_mfma_f32_16x16x32_bf16 v[28:31], v[222:225], v[170:173], v[28:31]
	v_mfma_f32_16x16x32_bf16 v[20:23], v[214:217], v[178:181], v[20:23]
	v_mfma_f32_16x16x32_bf16 v[12:15], v[222:225], v[178:181], v[12:15]
	v_mfma_f32_16x16x32_bf16 v[4:7], v[214:217], v[194:197], v[4:7]
	v_mfma_f32_16x16x32_bf16 v[0:3], v[222:225], v[194:197], v[0:3]
	v_mfma_f32_16x16x32_bf16 v[52:55], v[218:221], v[166:169], v[52:55]
	v_mfma_f32_16x16x32_bf16 v[44:47], v[226:229], v[166:169], v[44:47]
	v_mfma_f32_16x16x32_bf16 v[36:39], v[218:221], v[174:177], v[36:39]
	v_mfma_f32_16x16x32_bf16 v[28:31], v[226:229], v[174:177], v[28:31]
	v_mfma_f32_16x16x32_bf16 v[20:23], v[218:221], v[182:185], v[20:23]
	v_mfma_f32_16x16x32_bf16 v[12:15], v[226:229], v[182:185], v[12:15]
	v_mfma_f32_16x16x32_bf16 v[4:7], v[218:221], v[210:213], v[4:7]
	v_mfma_f32_16x16x32_bf16 v[0:3], v[226:229], v[210:213], v[0:3]
	s_barrier
	s_cbranch_scc0 .LBB0_248
	s_mov_b32 s100, 1
	s_ashr_i32 s51, s50, 31
	v_lshl_or_b32 v128, s81, 8, v207
	s_lshl_b64 s[10:11], s[50:51], 8
	v_ashrrev_i32_e32 v129, 31, v128
	v_lshl_add_u64 v[168:169], s[10:11], 0, v[156:157]
	v_lshlrev_b64 v[170:171], 1, v[128:129]
	v_lshl_add_u64 v[174:175], s[28:29], 0, v[170:171]
	v_lshlrev_b64 v[172:173], 11, v[168:169]
	v_lshl_add_u64 v[128:129], v[174:175], 0, v[172:173]
	global_load_dwordx4 v[146:149], v[128:129], off
	global_load_dwordx4 v[182:185], v[128:129], off offset:256
	v_or_b32_e32 v166, 16, v168
	v_mov_b32_e32 v167, v169
	v_lshlrev_b64 v[176:177], 11, v[166:167]
	v_lshl_add_u64 v[128:129], v[174:175], 0, v[176:177]
	global_load_dwordx4 v[194:197], v[128:129], off
	global_load_dwordx4 v[210:213], v[128:129], off offset:256
	v_or_b32_e32 v164, 32, v168
	v_mov_b32_e32 v165, v169
	v_or_b32_e32 v162, 48, v168
	v_mov_b32_e32 v163, v169
	v_lshlrev_b64 v[180:181], 11, v[164:165]
	v_lshlrev_b64 v[178:179], 11, v[162:163]
	v_lshl_add_u64 v[128:129], v[174:175], 0, v[180:181]
	v_lshl_add_u64 v[130:131], v[174:175], 0, v[178:179]
	global_load_dwordx4 v[214:217], v[128:129], off
	global_load_dwordx4 v[136:139], v[128:129], off offset:256
	global_load_dwordx4 v[132:135], v[130:131], off
	s_nop 0
	global_load_dwordx4 v[128:131], v[130:131], off offset:256
	s_mov_b64 s[10:11], 0x90
	v_lshl_add_u64 v[172:173], s[30:31], 0, v[172:173]
	v_lshl_add_u64 v[172:173], v[172:173], 0, v[170:171]
	s_waitcnt vmcnt(0)
	v_lshlrev_b32_e32 v218, 16, v146
	v_and_b32_e32 v219, 0xffff0000, v146
	v_lshlrev_b32_e32 v220, 16, v148
	v_and_b32_e32 v221, 0xffff0000, v148
	v_lshlrev_b32_e32 v146, 16, v147
	v_and_b32_e32 v147, 0xffff0000, v147
	v_lshlrev_b32_e32 v222, 16, v182
	v_and_b32_e32 v223, 0xffff0000, v182
	v_lshlrev_b32_e32 v224, 16, v184
	v_and_b32_e32 v225, 0xffff0000, v184
	v_lshlrev_b32_e32 v182, 16, v183
	v_and_b32_e32 v183, 0xffff0000, v183
	v_pk_add_f32 v[124:125], v[124:125], v[218:219]
	v_pk_add_f32 v[120:121], v[120:121], v[220:221]
	v_pk_add_f32 v[126:127], v[126:127], v[146:147]
	v_pk_add_f32 v[116:117], v[116:117], v[222:223]
	v_pk_add_f32 v[146:147], v[112:113], v[224:225]
	v_pk_add_f32 v[118:119], v[118:119], v[182:183]
	v_pk_mul_f32 v[220:221], v[124:125], v[124:125]
	v_pk_mul_f32 v[222:223], v[126:127], v[126:127]
	v_cvt_pk_bf16_f32 v112, v124, v125
	v_cvt_pk_bf16_f32 v113, v126, v127
	v_pk_mul_f32 v[124:125], v[116:117], v[116:117]
	v_pk_mul_f32 v[126:127], v[118:119], v[118:119]
	v_pk_mul_f32 v[228:229], v[146:147], v[146:147]
	v_cvt_pk_bf16_f32 v116, v116, v117
	v_cvt_pk_bf16_f32 v117, v118, v119
	v_cvt_pk_bf16_f32 v118, v146, v147
	v_add_f32_e32 v146, v220, v221
	v_add_f32_e32 v146, v222, v146
	v_lshlrev_b32_e32 v148, 16, v149
	v_and_b32_e32 v149, 0xffff0000, v149
	v_pk_mul_f32 v[224:225], v[120:121], v[120:121]
	v_add_f32_e32 v146, v223, v146
	v_pk_add_f32 v[122:123], v[122:123], v[148:149]
	v_add_f32_e32 v146, v224, v146
	v_pk_mul_f32 v[226:227], v[122:123], v[122:123]
	v_add_f32_e32 v146, v225, v146
	v_add_f32_e32 v146, v226, v146
	v_add_f32_e32 v146, v227, v146
	v_add_f32_e32 v124, v124, v146
	v_add_f32_e32 v124, v125, v124
	v_add_f32_e32 v124, v126, v124
	v_lshlrev_b32_e32 v184, 16, v185
	v_and_b32_e32 v185, 0xffff0000, v185
	v_add_f32_e32 v124, v127, v124
	v_pk_add_f32 v[148:149], v[114:115], v[184:185]
	v_add_f32_e32 v124, v228, v124
	v_pk_mul_f32 v[230:231], v[148:149], v[148:149]
	v_add_f32_e32 v124, v229, v124
	v_add_f32_e32 v124, v230, v124
	v_add_f32_e32 v209, v231, v124
	v_lshlrev_b32_e32 v124, 16, v212
	v_and_b32_e32 v125, 0xffff0000, v212
	v_pk_add_f32 v[124:125], v[92:93], v[124:125]
	v_lshlrev_b32_e32 v92, 16, v211
	v_and_b32_e32 v93, 0xffff0000, v211
	v_pk_add_f32 v[102:103], v[102:103], v[92:93]
	v_lshlrev_b32_e32 v92, 16, v213
	v_and_b32_e32 v93, 0xffff0000, v213
	v_pk_add_f32 v[126:127], v[94:95], v[92:93]
	v_lshlrev_b32_e32 v92, 16, v214
	v_and_b32_e32 v93, 0xffff0000, v214
	v_pk_add_f32 v[92:93], v[96:97], v[92:93]
	v_lshlrev_b32_e32 v96, 16, v217
	v_and_b32_e32 v97, 0xffff0000, v217
	v_lshlrev_b32_e32 v94, 16, v216
	v_and_b32_e32 v95, 0xffff0000, v216
	v_pk_add_f32 v[90:91], v[90:91], v[96:97]
	v_lshlrev_b32_e32 v96, 16, v136
	v_and_b32_e32 v97, 0xffff0000, v136
	v_lshlrev_b32_e32 v182, 16, v194
	v_and_b32_e32 v183, 0xffff0000, v194
	v_pk_add_f32 v[88:89], v[88:89], v[94:95]
	v_lshlrev_b32_e32 v94, 16, v215
	v_and_b32_e32 v95, 0xffff0000, v215
	v_pk_add_f32 v[96:97], v[76:77], v[96:97]
	v_lshl_add_u64 v[76:77], v[168:169], 0, s[36:37]
	v_lshlrev_b32_e32 v184, 16, v196
	v_and_b32_e32 v185, 0xffff0000, v196
	v_cvt_pk_bf16_f32 v114, v120, v121
	v_pk_add_f32 v[120:121], v[108:109], v[182:183]
	v_pk_add_f32 v[94:95], v[98:99], v[94:95]
	v_lshlrev_b64 v[182:183], 11, v[76:77]
	v_lshlrev_b32_e32 v98, 16, v138
	v_and_b32_e32 v99, 0xffff0000, v138
	v_pk_add_f32 v[108:109], v[104:105], v[184:185]
	v_lshl_add_u64 v[184:185], v[174:175], 0, v[182:183]
	v_pk_add_f32 v[98:99], v[72:73], v[98:99]
	v_lshlrev_b32_e32 v72, 16, v137
	v_and_b32_e32 v73, 0xffff0000, v137
	v_lshlrev_b32_e32 v218, 16, v210
	v_and_b32_e32 v219, 0xffff0000, v210
	global_load_dwordx4 v[210:213], v[184:185], off
	v_pk_add_f32 v[136:137], v[78:79], v[72:73]
	v_lshlrev_b32_e32 v72, 16, v139
	v_and_b32_e32 v73, 0xffff0000, v139
	v_pk_add_f32 v[138:139], v[74:75], v[72:73]
	v_lshlrev_b32_e32 v72, 16, v132
	v_and_b32_e32 v73, 0xffff0000, v132
	v_pk_add_f32 v[74:75], v[84:85], v[72:73]
	v_lshlrev_b32_e32 v72, 16, v134
	v_and_b32_e32 v73, 0xffff0000, v134
	v_pk_add_f32 v[78:79], v[80:81], v[72:73]
	v_lshlrev_b32_e32 v72, 16, v133
	v_and_b32_e32 v73, 0xffff0000, v133
	v_pk_add_f32 v[100:101], v[100:101], v[218:219]
	global_load_dwordx4 v[218:221], v[184:185], off offset:256
	v_pk_add_f32 v[80:81], v[86:87], v[72:73]
	v_lshlrev_b32_e32 v72, 16, v135
	v_and_b32_e32 v73, 0xffff0000, v135
	v_pk_add_f32 v[82:83], v[82:83], v[72:73]
	v_lshl_add_u64 v[72:73], v[168:169], 0, s[10:11]
	v_lshlrev_b64 v[132:133], 11, v[72:73]
	v_lshl_add_u64 v[134:135], v[174:175], 0, v[132:133]
	v_lshlrev_b32_e32 v84, 16, v128
	v_and_b32_e32 v85, 0xffff0000, v128
	global_load_dwordx4 v[226:229], v[134:135], off
	global_load_dwordx4 v[234:237], v[134:135], off offset:256
	v_pk_add_f32 v[84:85], v[68:69], v[84:85]
	v_lshlrev_b32_e32 v68, 16, v130
	v_and_b32_e32 v69, 0xffff0000, v130
	v_pk_add_f32 v[86:87], v[64:65], v[68:69]
	v_lshlrev_b32_e32 v64, 16, v129
	v_and_b32_e32 v65, 0xffff0000, v129
	s_mov_b64 s[10:11], 0xa0
	v_pk_add_f32 v[128:129], v[70:71], v[64:65]
	v_lshl_add_u64 v[70:71], v[168:169], 0, s[10:11]
	s_mov_b64 s[10:11], 0xb0
	v_lshlrev_b32_e32 v64, 16, v131
	v_and_b32_e32 v65, 0xffff0000, v131
	v_lshlrev_b64 v[134:135], 11, v[70:71]
	v_lshl_add_u64 v[68:69], v[168:169], 0, s[10:11]
	v_pk_add_f32 v[130:131], v[66:67], v[64:65]
	v_lshl_add_u64 v[64:65], v[174:175], 0, v[134:135]
	v_lshlrev_b64 v[184:185], 11, v[68:69]
	global_load_dwordx4 v[238:241], v[64:65], off
	global_load_dwordx4 v[242:245], v[64:65], off offset:256
	v_lshl_add_u64 v[64:65], v[174:175], 0, v[184:185]
	global_load_dwordx4 v[246:249], v[64:65], off
	s_nop 0
	global_load_dwordx4 v[64:67], v[64:65], off offset:256
	v_lshlrev_b32_e32 v194, 16, v195
	v_and_b32_e32 v195, 0xffff0000, v195
	v_lshlrev_b32_e32 v196, 16, v197
	v_and_b32_e32 v197, 0xffff0000, v197
	v_cvt_pk_bf16_f32 v115, v122, v123
	v_cvt_pk_bf16_f32 v119, v148, v149
	v_pk_add_f32 v[122:123], v[110:111], v[194:195]
	v_pk_add_f32 v[110:111], v[106:107], v[196:197]
	global_store_dwordx4 v[172:173], v[112:115], off
	global_store_dwordx4 v[172:173], v[116:119], off offset:256
	v_cvt_pk_bf16_f32 v104, v120, v121
	v_lshl_add_u64 v[112:113], s[30:31], 0, v[176:177]
	v_cvt_pk_bf16_f32 v105, v122, v123
	v_cvt_pk_bf16_f32 v106, v108, v109
	v_cvt_pk_bf16_f32 v107, v110, v111
	v_lshl_add_u64 v[112:113], v[112:113], 0, v[170:171]
	v_cvt_pk_bf16_f32 v146, v100, v101
	v_cvt_pk_bf16_f32 v147, v102, v103
	v_cvt_pk_bf16_f32 v148, v124, v125
	v_cvt_pk_bf16_f32 v149, v126, v127
	global_store_dwordx4 v[112:113], v[104:107], off
	global_store_dwordx4 v[112:113], v[146:149], off offset:256
	v_cvt_pk_bf16_f32 v194, v92, v93
	v_lshl_add_u64 v[104:105], s[30:31], 0, v[180:181]
	v_cvt_pk_bf16_f32 v195, v94, v95
	v_cvt_pk_bf16_f32 v196, v88, v89
	v_cvt_pk_bf16_f32 v197, v90, v91
	v_lshl_add_u64 v[104:105], v[104:105], 0, v[170:171]
	v_cvt_pk_bf16_f32 v214, v96, v97
	v_cvt_pk_bf16_f32 v215, v136, v137
	v_cvt_pk_bf16_f32 v216, v98, v99
	v_cvt_pk_bf16_f32 v217, v138, v139
	global_store_dwordx4 v[104:105], v[194:197], off
	global_store_dwordx4 v[104:105], v[214:217], off offset:256
	v_lshl_add_u64 v[104:105], s[30:31], 0, v[178:179]
	v_cvt_pk_bf16_f32 v222, v74, v75
	v_cvt_pk_bf16_f32 v223, v80, v81
	v_cvt_pk_bf16_f32 v224, v78, v79
	v_cvt_pk_bf16_f32 v225, v82, v83
	v_lshl_add_u64 v[104:105], v[104:105], 0, v[170:171]
	v_cvt_pk_bf16_f32 v230, v84, v85
	v_cvt_pk_bf16_f32 v231, v128, v129
	v_cvt_pk_bf16_f32 v232, v86, v87
	v_cvt_pk_bf16_f32 v233, v130, v131
	global_store_dwordx4 v[104:105], v[222:225], off
	global_store_dwordx4 v[104:105], v[230:233], off offset:256
	s_waitcnt vmcnt(0)
	v_lshlrev_b32_e32 v104, 16, v210
	v_and_b32_e32 v105, 0xffff0000, v210
	v_pk_add_f32 v[60:61], v[60:61], v[104:105]
	v_lshlrev_b32_e32 v104, 16, v212
	v_and_b32_e32 v105, 0xffff0000, v212
	v_pk_add_f32 v[56:57], v[56:57], v[104:105]
	v_lshlrev_b32_e32 v104, 16, v211
	v_and_b32_e32 v105, 0xffff0000, v211
	v_pk_add_f32 v[62:63], v[62:63], v[104:105]
	v_lshlrev_b32_e32 v104, 16, v213
	v_and_b32_e32 v105, 0xffff0000, v213
	v_pk_add_f32 v[58:59], v[58:59], v[104:105]
	v_lshlrev_b32_e32 v104, 16, v218
	v_and_b32_e32 v105, 0xffff0000, v218
	v_pk_add_f32 v[52:53], v[52:53], v[104:105]
	v_lshlrev_b32_e32 v104, 16, v220
	v_and_b32_e32 v105, 0xffff0000, v220
	v_pk_add_f32 v[104:105], v[44:45], v[104:105]
	v_lshlrev_b32_e32 v44, 16, v219
	v_and_b32_e32 v45, 0xffff0000, v219
	v_pk_add_f32 v[54:55], v[54:55], v[44:45]
	v_lshlrev_b32_e32 v44, 16, v221
	v_and_b32_e32 v45, 0xffff0000, v221
	v_pk_add_f32 v[106:107], v[46:47], v[44:45]
	v_lshlrev_b32_e32 v44, 16, v226
	v_and_b32_e32 v45, 0xffff0000, v226
	v_pk_add_f32 v[44:45], v[48:49], v[44:45]
	v_lshlrev_b32_e32 v48, 16, v229
	v_and_b32_e32 v49, 0xffff0000, v229
	v_pk_add_f32 v[42:43], v[42:43], v[48:49]
	v_lshlrev_b32_e32 v48, 16, v234
	v_and_b32_e32 v49, 0xffff0000, v234
	v_pk_add_f32 v[36:37], v[36:37], v[48:49]
	v_lshlrev_b32_e32 v48, 16, v236
	v_and_b32_e32 v49, 0xffff0000, v236
	v_lshlrev_b32_e32 v46, 16, v228
	v_and_b32_e32 v47, 0xffff0000, v228
	v_pk_add_f32 v[48:49], v[28:29], v[48:49]
	v_lshlrev_b32_e32 v28, 16, v235
	v_and_b32_e32 v29, 0xffff0000, v235
	v_pk_add_f32 v[40:41], v[40:41], v[46:47]
	v_lshlrev_b32_e32 v46, 16, v227
	v_and_b32_e32 v47, 0xffff0000, v227
	v_pk_add_f32 v[38:39], v[38:39], v[28:29]
	v_lshlrev_b32_e32 v28, 16, v237
	v_and_b32_e32 v29, 0xffff0000, v237
	v_pk_add_f32 v[46:47], v[50:51], v[46:47]
	v_pk_add_f32 v[50:51], v[30:31], v[28:29]
	v_lshlrev_b32_e32 v28, 16, v238
	v_and_b32_e32 v29, 0xffff0000, v238
	v_lshlrev_b32_e32 v180, 16, v64
	v_and_b32_e32 v181, 0xffff0000, v64
	v_pk_add_f32 v[28:29], v[32:33], v[28:29]
	v_lshlrev_b32_e32 v32, 16, v241
	v_and_b32_e32 v33, 0xffff0000, v241
	v_pk_add_f32 v[4:5], v[4:5], v[180:181]
	v_lshlrev_b32_e32 v180, 16, v66
	v_and_b32_e32 v181, 0xffff0000, v66
	v_pk_add_f32 v[26:27], v[26:27], v[32:33]
	v_lshlrev_b32_e32 v32, 16, v242
	v_and_b32_e32 v33, 0xffff0000, v242
	v_pk_add_f32 v[0:1], v[0:1], v[180:181]
	v_lshl_add_u64 v[180:181], s[30:31], 0, v[182:183]
	v_cvt_pk_bf16_f32 v112, v60, v61
	v_cvt_pk_bf16_f32 v113, v62, v63
	v_cvt_pk_bf16_f32 v114, v56, v57
	v_cvt_pk_bf16_f32 v115, v58, v59
	v_pk_add_f32 v[20:21], v[20:21], v[32:33]
	v_lshlrev_b32_e32 v32, 16, v244
	v_and_b32_e32 v33, 0xffff0000, v244
	v_lshl_add_u64 v[180:181], v[180:181], 0, v[170:171]
	v_cvt_pk_bf16_f32 v116, v52, v53
	v_cvt_pk_bf16_f32 v117, v54, v55
	v_cvt_pk_bf16_f32 v118, v104, v105
	v_cvt_pk_bf16_f32 v119, v106, v107
	v_lshlrev_b32_e32 v30, 16, v240
	v_and_b32_e32 v31, 0xffff0000, v240
	v_pk_add_f32 v[32:33], v[12:13], v[32:33]
	v_lshlrev_b32_e32 v12, 16, v243
	v_and_b32_e32 v13, 0xffff0000, v243
	global_store_dwordx4 v[180:181], v[112:115], off
	global_store_dwordx4 v[180:181], v[116:119], off offset:256
	v_cvt_pk_bf16_f32 v146, v44, v45
	v_lshl_add_u64 v[112:113], s[30:31], 0, v[132:133]
	v_cvt_pk_bf16_f32 v147, v46, v47
	v_cvt_pk_bf16_f32 v148, v40, v41
	v_cvt_pk_bf16_f32 v149, v42, v43
	v_pk_add_f32 v[24:25], v[24:25], v[30:31]
	v_lshlrev_b32_e32 v30, 16, v239
	v_and_b32_e32 v31, 0xffff0000, v239
	v_pk_add_f32 v[22:23], v[22:23], v[12:13]
	v_lshlrev_b32_e32 v12, 16, v245
	v_and_b32_e32 v13, 0xffff0000, v245
	v_lshl_add_u64 v[112:113], v[112:113], 0, v[170:171]
	v_cvt_pk_bf16_f32 v172, v36, v37
	v_cvt_pk_bf16_f32 v173, v38, v39
	v_cvt_pk_bf16_f32 v174, v48, v49
	v_cvt_pk_bf16_f32 v175, v50, v51
	v_pk_add_f32 v[30:31], v[34:35], v[30:31]
	v_pk_add_f32 v[34:35], v[14:15], v[12:13]
	v_lshlrev_b32_e32 v12, 16, v246
	v_and_b32_e32 v13, 0xffff0000, v246
	v_lshlrev_b32_e32 v14, 16, v248
	v_and_b32_e32 v15, 0xffff0000, v248
	global_store_dwordx4 v[112:113], v[146:149], off
	global_store_dwordx4 v[112:113], v[172:175], off offset:256
	v_lshl_add_u64 v[112:113], s[30:31], 0, v[134:135]
	v_cvt_pk_bf16_f32 v176, v28, v29
	v_cvt_pk_bf16_f32 v177, v30, v31
	v_cvt_pk_bf16_f32 v178, v24, v25
	v_cvt_pk_bf16_f32 v179, v26, v27
	v_pk_add_f32 v[12:13], v[16:17], v[12:13]
	v_pk_add_f32 v[8:9], v[8:9], v[14:15]
	v_lshlrev_b32_e32 v14, 16, v247
	v_and_b32_e32 v15, 0xffff0000, v247
	v_lshlrev_b32_e32 v16, 16, v249
	v_and_b32_e32 v17, 0xffff0000, v249
	v_lshlrev_b32_e32 v64, 16, v65
	v_and_b32_e32 v65, 0xffff0000, v65
	v_lshl_add_u64 v[112:113], v[112:113], 0, v[170:171]
	v_cvt_pk_bf16_f32 v194, v20, v21
	v_cvt_pk_bf16_f32 v195, v22, v23
	v_cvt_pk_bf16_f32 v196, v32, v33
	v_cvt_pk_bf16_f32 v197, v34, v35
	v_pk_add_f32 v[14:15], v[18:19], v[14:15]
	v_pk_add_f32 v[10:11], v[10:11], v[16:17]
	v_pk_add_f32 v[6:7], v[6:7], v[64:65]
	v_lshlrev_b32_e32 v64, 16, v67
	v_and_b32_e32 v65, 0xffff0000, v67
	global_store_dwordx4 v[112:113], v[176:179], off
	global_store_dwordx4 v[112:113], v[194:197], off offset:256
	v_lshl_add_u64 v[112:113], s[30:31], 0, v[184:185]
	v_cvt_pk_bf16_f32 v16, v12, v13
	v_cvt_pk_bf16_f32 v17, v14, v15
	v_cvt_pk_bf16_f32 v18, v8, v9
	v_cvt_pk_bf16_f32 v19, v10, v11
	v_pk_add_f32 v[2:3], v[2:3], v[64:65]
	v_lshl_add_u64 v[112:113], v[112:113], 0, v[170:171]
	v_cvt_pk_bf16_f32 v64, v4, v5
	v_cvt_pk_bf16_f32 v65, v6, v7
	v_cvt_pk_bf16_f32 v66, v0, v1
	v_cvt_pk_bf16_f32 v67, v2, v3
	global_store_dwordx4 v[112:113], v[16:19], off
	global_store_dwordx4 v[112:113], v[64:67], off offset:256
	s_lshl_b32 s10, s81, 2
	v_and_b32_e32 v17, 64, v188
	v_xor_b32_e32 v16, 16, v188
	v_add_u32_e32 v17, 64, v17
	v_cmp_lt_i32_e32 vcc, v16, v17
	v_xor_b32_e32 v18, 32, v188
	s_ashr_i32 s11, s10, 31
	v_cndmask_b32_e32 v16, v188, v16, vcc
	v_lshlrev_b32_e32 v16, 2, v16
	ds_bpermute_b32 v19, v16, v209
	v_cmp_lt_i32_e32 vcc, v18, v17
	s_lshl_b64 s[10:11], s[10:11], 2
	s_add_u32 s50, s75, s10
	v_cndmask_b32_e32 v17, v188, v18, vcc
	v_lshlrev_b32_e32 v17, 2, v17
	s_waitcnt lgkmcnt(0)
	v_add_f32_e32 v18, v209, v19
	ds_bpermute_b32 v19, v17, v18
	s_addc_u32 s51, s80, s11
	s_and_saveexec_b64 s[52:53], s[42:43]
	s_cbranch_execz .LBB0_251
	s_waitcnt lgkmcnt(0)
	v_add_f32_e32 v64, v18, v19
	v_lshlrev_b64 v[18:19], 6, v[168:169]
	v_lshl_add_u64 v[18:19], s[50:51], 0, v[18:19]
	global_store_dword v[18:19], v64, off

.Lm4bp_295:
	s_waitcnt lgkmcnt(0)
	s_mov_b32 s100, 0
	s_barrier
	v_mfma_f32_16x16x32_bf16 v[60:63], v[146:149], v[170:173], 0
	v_mfma_f32_16x16x32_bf16 v[56:59], v[162:165], v[170:173], 0
	v_mfma_f32_16x16x32_bf16 v[52:55], v[146:149], v[178:181], 0
	v_mfma_f32_16x16x32_bf16 v[48:51], v[162:165], v[178:181], 0
	v_mfma_f32_16x16x32_bf16 v[44:47], v[146:149], v[194:197], 0
	v_mfma_f32_16x16x32_bf16 v[40:43], v[162:165], v[194:197], 0
	v_mfma_f32_16x16x32_bf16 v[36:39], v[146:149], v[210:213], 0
	v_mfma_f32_16x16x32_bf16 v[32:35], v[162:165], v[210:213], 0
	v_mfma_f32_16x16x32_bf16 v[60:63], v[158:161], v[174:177], v[60:63]
	v_mfma_f32_16x16x32_bf16 v[56:59], v[166:169], v[174:177], v[56:59]
	v_mfma_f32_16x16x32_bf16 v[52:55], v[158:161], v[182:185], v[52:55]
	v_mfma_f32_16x16x32_bf16 v[48:51], v[166:169], v[182:185], v[48:51]
	v_mfma_f32_16x16x32_bf16 v[44:47], v[158:161], v[206:209], v[44:47]
	v_mfma_f32_16x16x32_bf16 v[40:43], v[166:169], v[206:209], v[40:43]
	v_mfma_f32_16x16x32_bf16 v[36:39], v[158:161], v[214:217], v[36:39]
	v_mfma_f32_16x16x32_bf16 v[32:35], v[166:169], v[214:217], v[32:35]
	v_mfma_f32_16x16x32_bf16 v[28:31], v[218:221], v[170:173], 0
	v_mfma_f32_16x16x32_bf16 v[24:27], v[226:229], v[170:173], 0
	v_mfma_f32_16x16x32_bf16 v[20:23], v[218:221], v[178:181], 0
	v_mfma_f32_16x16x32_bf16 v[16:19], v[226:229], v[178:181], 0
	v_mfma_f32_16x16x32_bf16 v[12:15], v[218:221], v[194:197], 0
	v_mfma_f32_16x16x32_bf16 v[8:11], v[226:229], v[194:197], 0
	v_mfma_f32_16x16x32_bf16 v[4:7], v[218:221], v[210:213], 0
	v_mfma_f32_16x16x32_bf16 v[0:3], v[226:229], v[210:213], 0
	v_mfma_f32_16x16x32_bf16 v[28:31], v[222:225], v[174:177], v[28:31]
	v_mfma_f32_16x16x32_bf16 v[24:27], v[230:233], v[174:177], v[24:27]
	v_mfma_f32_16x16x32_bf16 v[20:23], v[222:225], v[182:185], v[20:23]
	v_mfma_f32_16x16x32_bf16 v[16:19], v[230:233], v[182:185], v[16:19]
	v_mfma_f32_16x16x32_bf16 v[12:15], v[222:225], v[206:209], v[12:15]
	v_mfma_f32_16x16x32_bf16 v[8:11], v[230:233], v[206:209], v[8:11]
	v_mfma_f32_16x16x32_bf16 v[4:7], v[222:225], v[214:217], v[4:7]
	v_mfma_f32_16x16x32_bf16 v[0:3], v[230:233], v[214:217], v[0:3]
	s_barrier
	s_add_i32 s6, 0, 0x18000
	v_add_u32_e32 v166, s6, v154
	ds_read_b128 v[146:149], v166
	ds_read_b128 v[158:161], v166 offset:1024
	ds_read_b128 v[162:165], v166 offset:2048
	ds_read_b128 v[166:169], v166 offset:3072
	s_add_u32 s52, s52, 0x40000
	s_addc_u32 s53, s53, 0
	s_mov_b32 m0, s68
	v_lshl_add_u64 v[218:219], s[52:53], 0, v[128:129]
	ds_read_b128 v[170:173], v157 offset:32768
	ds_read_b128 v[174:177], v157 offset:33792
	ds_read_b128 v[178:181], v157 offset:34816
	ds_read_b128 v[182:185], v157 offset:35840
	ds_read_b128 v[194:197], v157 offset:36864
	ds_read_b128 v[206:209], v157 offset:37888
	ds_read_b128 v[210:213], v157 offset:38912
	ds_read_b128 v[214:217], v157 offset:39936
	global_load_lds_dwordx4 v[218:219], off
	v_lshl_add_u64 v[218:219], s[52:53], 0, v[130:131]
	s_mov_b32 m0, s69
	s_nop 0
	global_load_lds_dwordx4 v[218:219], off
	s_add_i32 s19, 0, 0x1c000
	v_add_u32_e32 v192, s19, v154
	ds_read_b128 v[218:221], v192
	ds_read_b128 v[222:225], v192 offset:1024
	ds_read_b128 v[226:229], v192 offset:2048
	ds_read_b128 v[230:233], v192 offset:3072
	s_waitcnt vmcnt(8)
	s_waitcnt lgkmcnt(0)
	s_barrier
	v_mfma_f32_16x16x32_bf16 v[124:127], v[146:149], v[170:173], v[124:127]
	v_mfma_f32_16x16x32_bf16 v[120:123], v[162:165], v[170:173], v[120:123]
	v_mfma_f32_16x16x32_bf16 v[116:119], v[146:149], v[178:181], v[116:119]
	v_mfma_f32_16x16x32_bf16 v[112:115], v[162:165], v[178:181], v[112:115]
	v_mfma_f32_16x16x32_bf16 v[108:111], v[146:149], v[194:197], v[108:111]
	v_mfma_f32_16x16x32_bf16 v[104:107], v[162:165], v[194:197], v[104:107]
	v_mfma_f32_16x16x32_bf16 v[100:103], v[146:149], v[210:213], v[100:103]
	v_mfma_f32_16x16x32_bf16 v[96:99], v[162:165], v[210:213], v[96:99]
	v_mfma_f32_16x16x32_bf16 v[124:127], v[158:161], v[174:177], v[124:127]
	v_mfma_f32_16x16x32_bf16 v[120:123], v[166:169], v[174:177], v[120:123]
	v_mfma_f32_16x16x32_bf16 v[116:119], v[158:161], v[182:185], v[116:119]
	v_mfma_f32_16x16x32_bf16 v[112:115], v[166:169], v[182:185], v[112:115]
	v_mfma_f32_16x16x32_bf16 v[108:111], v[158:161], v[206:209], v[108:111]
	v_mfma_f32_16x16x32_bf16 v[104:107], v[166:169], v[206:209], v[104:107]
	v_mfma_f32_16x16x32_bf16 v[100:103], v[158:161], v[214:217], v[100:103]
	v_mfma_f32_16x16x32_bf16 v[96:99], v[166:169], v[214:217], v[96:99]
	v_mfma_f32_16x16x32_bf16 v[92:95], v[218:221], v[170:173], v[92:95]
	v_mfma_f32_16x16x32_bf16 v[88:91], v[226:229], v[170:173], v[88:91]
	v_mfma_f32_16x16x32_bf16 v[84:87], v[218:221], v[178:181], v[84:87]
	v_mfma_f32_16x16x32_bf16 v[80:83], v[226:229], v[178:181], v[80:83]
	v_mfma_f32_16x16x32_bf16 v[76:79], v[218:221], v[194:197], v[76:79]
	v_mfma_f32_16x16x32_bf16 v[72:75], v[226:229], v[194:197], v[72:75]
	v_mfma_f32_16x16x32_bf16 v[68:71], v[218:221], v[210:213], v[68:71]
	v_mfma_f32_16x16x32_bf16 v[64:67], v[226:229], v[210:213], v[64:67]
	v_mfma_f32_16x16x32_bf16 v[92:95], v[222:225], v[174:177], v[92:95]
	v_mfma_f32_16x16x32_bf16 v[88:91], v[230:233], v[174:177], v[88:91]
	v_mfma_f32_16x16x32_bf16 v[84:87], v[222:225], v[182:185], v[84:87]
	v_mfma_f32_16x16x32_bf16 v[80:83], v[230:233], v[182:185], v[80:83]
	v_mfma_f32_16x16x32_bf16 v[76:79], v[222:225], v[206:209], v[76:79]
	v_mfma_f32_16x16x32_bf16 v[72:75], v[230:233], v[206:209], v[72:75]
	v_mfma_f32_16x16x32_bf16 v[68:71], v[222:225], v[214:217], v[68:71]
	v_mfma_f32_16x16x32_bf16 v[64:67], v[230:233], v[214:217], v[64:67]
	s_barrier
	s_add_i32 s6, s6, s57
	v_lshl_add_u64 v[234:235], v[234:235], 0, s[36:37]
	s_mov_b32 m0, s6
	s_nop 0
	global_load_lds_dwordx4 v[234:235], off
	v_lshl_add_u64 v[234:235], v[236:237], 0, s[36:37]
	s_add_i32 m0, s6, 0x2000
	s_nop 0
	global_load_lds_dwordx4 v[234:235], off
	s_mov_b32 m0, s70
	v_lshl_add_u64 v[234:235], v[238:239], 0, s[36:37]
	ds_read_b128 v[170:173], v157 offset:49152
	ds_read_b128 v[174:177], v157 offset:50176
	ds_read_b128 v[178:181], v157 offset:51200
	ds_read_b128 v[182:185], v157 offset:52224
	ds_read_b128 v[194:197], v157 offset:53248
	ds_read_b128 v[206:209], v157 offset:54272
	ds_read_b128 v[210:213], v157 offset:55296
	ds_read_b128 v[214:217], v157 offset:56320
	global_load_lds_dwordx4 v[234:235], off
	v_lshl_add_u64 v[234:235], v[240:241], 0, s[36:37]
	s_mov_b32 m0, s71
	s_nop 0
	global_load_lds_dwordx4 v[234:235], off
	s_add_u32 s50, s50, 0x40080
	s_addc_u32 s51, s51, 0
	s_add_i32 s6, s19, s57
	v_lshl_add_u64 v[250:251], s[50:51], 0, v[140:141]
	s_mov_b32 m0, s6
	s_nop 0
	global_load_lds_dwordx4 v[250:251], off
	v_lshl_add_u64 v[250:251], s[50:51], 0, v[132:133]
	s_add_i32 m0, s6, 0x2000
	s_nop 0
	global_load_lds_dwordx4 v[250:251], off
	s_add_i32 s75, s75, 2
	s_add_u32 s48, s48, 0x100
	s_addc_u32 s49, s49, 0
	s_cmp_gt_u32 s75, 13
	s_nop 0
	s_waitcnt vmcnt(8)
	s_waitcnt lgkmcnt(0)
	s_barrier
	v_mfma_f32_16x16x32_bf16 v[60:63], v[146:149], v[170:173], v[60:63]
	v_mfma_f32_16x16x32_bf16 v[56:59], v[162:165], v[170:173], v[56:59]
	v_mfma_f32_16x16x32_bf16 v[52:55], v[146:149], v[178:181], v[52:55]
	v_mfma_f32_16x16x32_bf16 v[48:51], v[162:165], v[178:181], v[48:51]
	v_mfma_f32_16x16x32_bf16 v[44:47], v[146:149], v[194:197], v[44:47]
	v_mfma_f32_16x16x32_bf16 v[40:43], v[162:165], v[194:197], v[40:43]
	v_mfma_f32_16x16x32_bf16 v[36:39], v[146:149], v[210:213], v[36:39]
	v_mfma_f32_16x16x32_bf16 v[32:35], v[162:165], v[210:213], v[32:35]
	v_mfma_f32_16x16x32_bf16 v[60:63], v[158:161], v[174:177], v[60:63]
	v_mfma_f32_16x16x32_bf16 v[56:59], v[166:169], v[174:177], v[56:59]
	v_mfma_f32_16x16x32_bf16 v[52:55], v[158:161], v[182:185], v[52:55]
	v_mfma_f32_16x16x32_bf16 v[48:51], v[166:169], v[182:185], v[48:51]
	v_mfma_f32_16x16x32_bf16 v[44:47], v[158:161], v[206:209], v[44:47]
	v_mfma_f32_16x16x32_bf16 v[40:43], v[166:169], v[206:209], v[40:43]
	v_mfma_f32_16x16x32_bf16 v[36:39], v[158:161], v[214:217], v[36:39]
	v_mfma_f32_16x16x32_bf16 v[32:35], v[166:169], v[214:217], v[32:35]
	v_mfma_f32_16x16x32_bf16 v[28:31], v[218:221], v[170:173], v[28:31]
	v_mfma_f32_16x16x32_bf16 v[24:27], v[226:229], v[170:173], v[24:27]
	v_mfma_f32_16x16x32_bf16 v[20:23], v[218:221], v[178:181], v[20:23]
	v_mfma_f32_16x16x32_bf16 v[16:19], v[226:229], v[178:181], v[16:19]
	v_mfma_f32_16x16x32_bf16 v[12:15], v[218:221], v[194:197], v[12:15]
	v_mfma_f32_16x16x32_bf16 v[8:11], v[226:229], v[194:197], v[8:11]
	v_mfma_f32_16x16x32_bf16 v[4:7], v[218:221], v[210:213], v[4:7]
	v_mfma_f32_16x16x32_bf16 v[0:3], v[226:229], v[210:213], v[0:3]
	v_mfma_f32_16x16x32_bf16 v[28:31], v[222:225], v[174:177], v[28:31]
	v_mfma_f32_16x16x32_bf16 v[24:27], v[230:233], v[174:177], v[24:27]
	v_mfma_f32_16x16x32_bf16 v[20:23], v[222:225], v[182:185], v[20:23]
	v_mfma_f32_16x16x32_bf16 v[16:19], v[230:233], v[182:185], v[16:19]
	v_mfma_f32_16x16x32_bf16 v[12:15], v[222:225], v[206:209], v[12:15]
	v_mfma_f32_16x16x32_bf16 v[8:11], v[230:233], v[206:209], v[8:11]
	v_mfma_f32_16x16x32_bf16 v[4:7], v[222:225], v[214:217], v[4:7]
	v_mfma_f32_16x16x32_bf16 v[0:3], v[230:233], v[214:217], v[0:3]
	s_barrier
.LBB0_295:
	s_add_u32 s6, s4, s48
	s_addc_u32 s19, s5, s49
	s_add_u32 s6, s6, 0x100
	s_addc_u32 s19, s19, 0
	s_add_u32 s23, s10, s48
	s_addc_u32 s50, s11, s49
	s_add_i32 s80, 0, 0x10000
	v_add_u32_e32 v166, s80, v154
	ds_read_b128 v[146:149], v166
	ds_read_b128 v[158:161], v166 offset:1024
	ds_read_b128 v[162:165], v166 offset:2048
	ds_read_b128 v[166:169], v166 offset:3072
	s_cmpk_eq_i32 s48, 0x700
	s_cselect_b32 s53, s12, s19
	s_cselect_b32 s52, s29, s6
	s_cselect_b32 s51, s31, s50
	s_cselect_b32 s50, s35, s23
	v_lshl_add_u64 v[218:219], v[150:151], 0, s[48:49]
	s_add_i32 m0, s58, 0xc000
	ds_read_b128 v[170:173], v157
	ds_read_b128 v[174:177], v157 offset:1024
	ds_read_b128 v[178:181], v157 offset:2048
	ds_read_b128 v[182:185], v157 offset:3072
	ds_read_b128 v[194:197], v157 offset:4096
	ds_read_b128 v[206:209], v157 offset:5120
	ds_read_b128 v[210:213], v157 offset:6144
	ds_read_b128 v[214:217], v157 offset:7168
	global_load_lds_dwordx4 v[218:219], off
	v_lshl_add_u64 v[218:219], v[152:153], 0, s[48:49]
	s_add_i32 m0, s58, 0xe000
	s_nop 0
	global_load_lds_dwordx4 v[218:219], off
	s_add_i32 s6, 0, 0x14000
	v_add_u32_e32 v192, s6, v154
	ds_read_b128 v[218:221], v192
	ds_read_b128 v[222:225], v192 offset:1024
	ds_read_b128 v[226:229], v192 offset:2048
	ds_read_b128 v[230:233], v192 offset:3072
	s_nop 0
	s_waitcnt vmcnt(8)
	s_waitcnt lgkmcnt(0)
	s_barrier
	v_mfma_f32_16x16x32_bf16 v[124:127], v[146:149], v[170:173], v[124:127]
	v_mfma_f32_16x16x32_bf16 v[120:123], v[162:165], v[170:173], v[120:123]
	v_mfma_f32_16x16x32_bf16 v[116:119], v[146:149], v[178:181], v[116:119]
	v_mfma_f32_16x16x32_bf16 v[112:115], v[162:165], v[178:181], v[112:115]
	v_mfma_f32_16x16x32_bf16 v[108:111], v[146:149], v[194:197], v[108:111]
	v_mfma_f32_16x16x32_bf16 v[104:107], v[162:165], v[194:197], v[104:107]
	v_mfma_f32_16x16x32_bf16 v[100:103], v[146:149], v[210:213], v[100:103]
	v_mfma_f32_16x16x32_bf16 v[96:99], v[162:165], v[210:213], v[96:99]
	v_mfma_f32_16x16x32_bf16 v[124:127], v[158:161], v[174:177], v[124:127]
	v_mfma_f32_16x16x32_bf16 v[120:123], v[166:169], v[174:177], v[120:123]
	v_mfma_f32_16x16x32_bf16 v[116:119], v[158:161], v[182:185], v[116:119]
	v_mfma_f32_16x16x32_bf16 v[112:115], v[166:169], v[182:185], v[112:115]
	v_mfma_f32_16x16x32_bf16 v[108:111], v[158:161], v[206:209], v[108:111]
	v_mfma_f32_16x16x32_bf16 v[104:107], v[166:169], v[206:209], v[104:107]
	v_mfma_f32_16x16x32_bf16 v[100:103], v[158:161], v[214:217], v[100:103]
	v_mfma_f32_16x16x32_bf16 v[96:99], v[166:169], v[214:217], v[96:99]
	v_mfma_f32_16x16x32_bf16 v[92:95], v[218:221], v[170:173], v[92:95]
	v_mfma_f32_16x16x32_bf16 v[88:91], v[226:229], v[170:173], v[88:91]
	v_mfma_f32_16x16x32_bf16 v[84:87], v[218:221], v[178:181], v[84:87]
	v_mfma_f32_16x16x32_bf16 v[80:83], v[226:229], v[178:181], v[80:83]
	v_mfma_f32_16x16x32_bf16 v[76:79], v[218:221], v[194:197], v[76:79]
	v_mfma_f32_16x16x32_bf16 v[72:75], v[226:229], v[194:197], v[72:75]
	v_mfma_f32_16x16x32_bf16 v[68:71], v[218:221], v[210:213], v[68:71]
	v_mfma_f32_16x16x32_bf16 v[64:67], v[226:229], v[210:213], v[64:67]
	v_mfma_f32_16x16x32_bf16 v[92:95], v[222:225], v[174:177], v[92:95]
	v_mfma_f32_16x16x32_bf16 v[88:91], v[230:233], v[174:177], v[88:91]
	v_mfma_f32_16x16x32_bf16 v[84:87], v[222:225], v[182:185], v[84:87]
	v_mfma_f32_16x16x32_bf16 v[80:83], v[230:233], v[182:185], v[80:83]
	v_mfma_f32_16x16x32_bf16 v[76:79], v[222:225], v[206:209], v[76:79]
	v_mfma_f32_16x16x32_bf16 v[72:75], v[230:233], v[206:209], v[72:75]
	v_mfma_f32_16x16x32_bf16 v[68:71], v[222:225], v[214:217], v[68:71]
	v_mfma_f32_16x16x32_bf16 v[64:67], v[230:233], v[214:217], v[64:67]
	s_barrier
	s_add_i32 s19, s80, s57
	v_lshl_add_u64 v[234:235], s[50:51], 0, v[140:141]
	s_mov_b32 m0, s19
	s_nop 0
	global_load_lds_dwordx4 v[234:235], off
	v_lshl_add_u64 v[236:237], s[50:51], 0, v[132:133]
	s_add_i32 m0, s19, 0x2000
	s_nop 0
	global_load_lds_dwordx4 v[236:237], off
	s_mov_b32 m0, s58
	v_lshl_add_u64 v[238:239], s[52:53], 0, v[128:129]
	ds_read_b128 v[170:173], v157 offset:16384
	ds_read_b128 v[174:177], v157 offset:17408
	ds_read_b128 v[178:181], v157 offset:18432
	ds_read_b128 v[182:185], v157 offset:19456
	ds_read_b128 v[194:197], v157 offset:20480
	ds_read_b128 v[206:209], v157 offset:21504
	ds_read_b128 v[210:213], v157 offset:22528
	ds_read_b128 v[214:217], v157 offset:23552
	global_load_lds_dwordx4 v[238:239], off
	v_lshl_add_u64 v[240:241], s[52:53], 0, v[130:131]
	s_mov_b32 m0, s59
	s_nop 0
	global_load_lds_dwordx4 v[240:241], off
	s_add_u32 s80, s50, 0x40000
	s_addc_u32 s81, s51, 0
	s_add_i32 s6, s6, s57
	v_lshl_add_u64 v[250:251], s[80:81], 0, v[140:141]
	s_mov_b32 m0, s6
	s_nop 0
	global_load_lds_dwordx4 v[250:251], off
	v_lshl_add_u64 v[250:251], s[80:81], 0, v[132:133]
	s_add_i32 m0, s6, 0x2000
	s_nop 0
	global_load_lds_dwordx4 v[250:251], off
	s_waitcnt vmcnt(8)
	s_waitcnt lgkmcnt(0)
	s_barrier
	v_mfma_f32_16x16x32_bf16 v[60:63], v[146:149], v[170:173], v[60:63]
	v_mfma_f32_16x16x32_bf16 v[56:59], v[162:165], v[170:173], v[56:59]
	v_mfma_f32_16x16x32_bf16 v[52:55], v[146:149], v[178:181], v[52:55]
	v_mfma_f32_16x16x32_bf16 v[48:51], v[162:165], v[178:181], v[48:51]
	v_mfma_f32_16x16x32_bf16 v[44:47], v[146:149], v[194:197], v[44:47]
	v_mfma_f32_16x16x32_bf16 v[40:43], v[162:165], v[194:197], v[40:43]
	v_mfma_f32_16x16x32_bf16 v[36:39], v[146:149], v[210:213], v[36:39]
	v_mfma_f32_16x16x32_bf16 v[32:35], v[162:165], v[210:213], v[32:35]
	v_mfma_f32_16x16x32_bf16 v[60:63], v[158:161], v[174:177], v[60:63]
	v_mfma_f32_16x16x32_bf16 v[56:59], v[166:169], v[174:177], v[56:59]
	v_mfma_f32_16x16x32_bf16 v[52:55], v[158:161], v[182:185], v[52:55]
	v_mfma_f32_16x16x32_bf16 v[48:51], v[166:169], v[182:185], v[48:51]
	v_mfma_f32_16x16x32_bf16 v[44:47], v[158:161], v[206:209], v[44:47]
	v_mfma_f32_16x16x32_bf16 v[40:43], v[166:169], v[206:209], v[40:43]
	v_mfma_f32_16x16x32_bf16 v[36:39], v[158:161], v[214:217], v[36:39]
	v_mfma_f32_16x16x32_bf16 v[32:35], v[166:169], v[214:217], v[32:35]
	v_mfma_f32_16x16x32_bf16 v[28:31], v[218:221], v[170:173], v[28:31]
	v_mfma_f32_16x16x32_bf16 v[24:27], v[226:229], v[170:173], v[24:27]
	v_mfma_f32_16x16x32_bf16 v[20:23], v[218:221], v[178:181], v[20:23]
	v_mfma_f32_16x16x32_bf16 v[16:19], v[226:229], v[178:181], v[16:19]
	v_mfma_f32_16x16x32_bf16 v[12:15], v[218:221], v[194:197], v[12:15]
	v_mfma_f32_16x16x32_bf16 v[8:11], v[226:229], v[194:197], v[8:11]
	v_mfma_f32_16x16x32_bf16 v[4:7], v[218:221], v[210:213], v[4:7]
	v_mfma_f32_16x16x32_bf16 v[0:3], v[226:229], v[210:213], v[0:3]
	v_mfma_f32_16x16x32_bf16 v[28:31], v[222:225], v[174:177], v[28:31]
	v_mfma_f32_16x16x32_bf16 v[24:27], v[230:233], v[174:177], v[24:27]
	v_mfma_f32_16x16x32_bf16 v[20:23], v[222:225], v[182:185], v[20:23]
	v_mfma_f32_16x16x32_bf16 v[16:19], v[230:233], v[182:185], v[16:19]
	v_mfma_f32_16x16x32_bf16 v[12:15], v[222:225], v[206:209], v[12:15]
	v_mfma_f32_16x16x32_bf16 v[8:11], v[230:233], v[206:209], v[8:11]
	v_mfma_f32_16x16x32_bf16 v[4:7], v[222:225], v[214:217], v[4:7]
	v_mfma_f32_16x16x32_bf16 v[0:3], v[230:233], v[214:217], v[0:3]
	s_barrier
	s_add_i32 s6, 0, 0x18000
	v_add_u32_e32 v166, s6, v154
	ds_read_b128 v[146:149], v166
	ds_read_b128 v[158:161], v166 offset:1024
	ds_read_b128 v[162:165], v166 offset:2048
	ds_read_b128 v[166:169], v166 offset:3072
	s_add_u32 s52, s52, 0x40000
	s_addc_u32 s53, s53, 0
	s_mov_b32 m0, s68
	v_lshl_add_u64 v[218:219], s[52:53], 0, v[128:129]
	ds_read_b128 v[170:173], v157 offset:32768
	ds_read_b128 v[174:177], v157 offset:33792
	ds_read_b128 v[178:181], v157 offset:34816
	ds_read_b128 v[182:185], v157 offset:35840
	ds_read_b128 v[194:197], v157 offset:36864
	ds_read_b128 v[206:209], v157 offset:37888
	ds_read_b128 v[210:213], v157 offset:38912
	ds_read_b128 v[214:217], v157 offset:39936
	global_load_lds_dwordx4 v[218:219], off
	v_lshl_add_u64 v[218:219], s[52:53], 0, v[130:131]
	s_mov_b32 m0, s69
	s_nop 0
	global_load_lds_dwordx4 v[218:219], off
	s_add_i32 s19, 0, 0x1c000
	v_add_u32_e32 v192, s19, v154
	ds_read_b128 v[218:221], v192
	ds_read_b128 v[222:225], v192 offset:1024
	ds_read_b128 v[226:229], v192 offset:2048
	ds_read_b128 v[230:233], v192 offset:3072
	s_waitcnt vmcnt(8)
	s_waitcnt lgkmcnt(0)
	s_barrier
	v_mfma_f32_16x16x32_bf16 v[124:127], v[146:149], v[170:173], v[124:127]
	v_mfma_f32_16x16x32_bf16 v[120:123], v[162:165], v[170:173], v[120:123]
	v_mfma_f32_16x16x32_bf16 v[116:119], v[146:149], v[178:181], v[116:119]
	v_mfma_f32_16x16x32_bf16 v[112:115], v[162:165], v[178:181], v[112:115]
	v_mfma_f32_16x16x32_bf16 v[108:111], v[146:149], v[194:197], v[108:111]
	v_mfma_f32_16x16x32_bf16 v[104:107], v[162:165], v[194:197], v[104:107]
	v_mfma_f32_16x16x32_bf16 v[100:103], v[146:149], v[210:213], v[100:103]
	v_mfma_f32_16x16x32_bf16 v[96:99], v[162:165], v[210:213], v[96:99]
	v_mfma_f32_16x16x32_bf16 v[124:127], v[158:161], v[174:177], v[124:127]
	v_mfma_f32_16x16x32_bf16 v[120:123], v[166:169], v[174:177], v[120:123]
	v_mfma_f32_16x16x32_bf16 v[116:119], v[158:161], v[182:185], v[116:119]
	v_mfma_f32_16x16x32_bf16 v[112:115], v[166:169], v[182:185], v[112:115]
	v_mfma_f32_16x16x32_bf16 v[108:111], v[158:161], v[206:209], v[108:111]
	v_mfma_f32_16x16x32_bf16 v[104:107], v[166:169], v[206:209], v[104:107]
	v_mfma_f32_16x16x32_bf16 v[100:103], v[158:161], v[214:217], v[100:103]
	v_mfma_f32_16x16x32_bf16 v[96:99], v[166:169], v[214:217], v[96:99]
	v_mfma_f32_16x16x32_bf16 v[92:95], v[218:221], v[170:173], v[92:95]
	v_mfma_f32_16x16x32_bf16 v[88:91], v[226:229], v[170:173], v[88:91]
	v_mfma_f32_16x16x32_bf16 v[84:87], v[218:221], v[178:181], v[84:87]
	v_mfma_f32_16x16x32_bf16 v[80:83], v[226:229], v[178:181], v[80:83]
	v_mfma_f32_16x16x32_bf16 v[76:79], v[218:221], v[194:197], v[76:79]
	v_mfma_f32_16x16x32_bf16 v[72:75], v[226:229], v[194:197], v[72:75]
	v_mfma_f32_16x16x32_bf16 v[68:71], v[218:221], v[210:213], v[68:71]
	v_mfma_f32_16x16x32_bf16 v[64:67], v[226:229], v[210:213], v[64:67]
	v_mfma_f32_16x16x32_bf16 v[92:95], v[222:225], v[174:177], v[92:95]
	v_mfma_f32_16x16x32_bf16 v[88:91], v[230:233], v[174:177], v[88:91]
	v_mfma_f32_16x16x32_bf16 v[84:87], v[222:225], v[182:185], v[84:87]
	v_mfma_f32_16x16x32_bf16 v[80:83], v[230:233], v[182:185], v[80:83]
	v_mfma_f32_16x16x32_bf16 v[76:79], v[222:225], v[206:209], v[76:79]
	v_mfma_f32_16x16x32_bf16 v[72:75], v[230:233], v[206:209], v[72:75]
	v_mfma_f32_16x16x32_bf16 v[68:71], v[222:225], v[214:217], v[68:71]
	v_mfma_f32_16x16x32_bf16 v[64:67], v[230:233], v[214:217], v[64:67]
	s_barrier
	s_add_i32 s6, s6, s57
	v_lshl_add_u64 v[234:235], v[234:235], 0, s[36:37]
	s_mov_b32 m0, s6
	s_nop 0
	global_load_lds_dwordx4 v[234:235], off
	v_lshl_add_u64 v[234:235], v[236:237], 0, s[36:37]
	s_add_i32 m0, s6, 0x2000
	s_nop 0
	global_load_lds_dwordx4 v[234:235], off
	s_mov_b32 m0, s70
	v_lshl_add_u64 v[234:235], v[238:239], 0, s[36:37]
	ds_read_b128 v[170:173], v157 offset:49152
	ds_read_b128 v[174:177], v157 offset:50176
	ds_read_b128 v[178:181], v157 offset:51200
	ds_read_b128 v[182:185], v157 offset:52224
	ds_read_b128 v[194:197], v157 offset:53248
	ds_read_b128 v[206:209], v157 offset:54272
	ds_read_b128 v[210:213], v157 offset:55296
	ds_read_b128 v[214:217], v157 offset:56320
	global_load_lds_dwordx4 v[234:235], off
	v_lshl_add_u64 v[234:235], v[240:241], 0, s[36:37]
	s_mov_b32 m0, s71
	s_nop 0
	global_load_lds_dwordx4 v[234:235], off
	s_add_u32 s50, s50, 0x40080
	s_addc_u32 s51, s51, 0
	s_add_i32 s6, s19, s57
	v_lshl_add_u64 v[250:251], s[50:51], 0, v[140:141]
	s_mov_b32 m0, s6
	s_nop 0
	global_load_lds_dwordx4 v[250:251], off
	v_lshl_add_u64 v[250:251], s[50:51], 0, v[132:133]
	s_add_i32 m0, s6, 0x2000
	s_nop 0
	global_load_lds_dwordx4 v[250:251], off
	s_add_i32 s75, s75, 2
	s_add_u32 s48, s48, 0x100
	s_addc_u32 s49, s49, 0
	s_cmp_gt_u32 s75, 13
	s_nop 0
	s_waitcnt vmcnt(8)
	s_waitcnt lgkmcnt(0)
	s_barrier
	v_mfma_f32_16x16x32_bf16 v[60:63], v[146:149], v[170:173], v[60:63]
	v_mfma_f32_16x16x32_bf16 v[56:59], v[162:165], v[170:173], v[56:59]
	v_mfma_f32_16x16x32_bf16 v[52:55], v[146:149], v[178:181], v[52:55]
	v_mfma_f32_16x16x32_bf16 v[48:51], v[162:165], v[178:181], v[48:51]
	v_mfma_f32_16x16x32_bf16 v[44:47], v[146:149], v[194:197], v[44:47]
	v_mfma_f32_16x16x32_bf16 v[40:43], v[162:165], v[194:197], v[40:43]
	v_mfma_f32_16x16x32_bf16 v[36:39], v[146:149], v[210:213], v[36:39]
	v_mfma_f32_16x16x32_bf16 v[32:35], v[162:165], v[210:213], v[32:35]
	v_mfma_f32_16x16x32_bf16 v[60:63], v[158:161], v[174:177], v[60:63]
	v_mfma_f32_16x16x32_bf16 v[56:59], v[166:169], v[174:177], v[56:59]
	v_mfma_f32_16x16x32_bf16 v[52:55], v[158:161], v[182:185], v[52:55]
	v_mfma_f32_16x16x32_bf16 v[48:51], v[166:169], v[182:185], v[48:51]
	v_mfma_f32_16x16x32_bf16 v[44:47], v[158:161], v[206:209], v[44:47]
	v_mfma_f32_16x16x32_bf16 v[40:43], v[166:169], v[206:209], v[40:43]
	v_mfma_f32_16x16x32_bf16 v[36:39], v[158:161], v[214:217], v[36:39]
	v_mfma_f32_16x16x32_bf16 v[32:35], v[166:169], v[214:217], v[32:35]
	v_mfma_f32_16x16x32_bf16 v[28:31], v[218:221], v[170:173], v[28:31]
	v_mfma_f32_16x16x32_bf16 v[24:27], v[226:229], v[170:173], v[24:27]
	v_mfma_f32_16x16x32_bf16 v[20:23], v[218:221], v[178:181], v[20:23]
	v_mfma_f32_16x16x32_bf16 v[16:19], v[226:229], v[178:181], v[16:19]
	v_mfma_f32_16x16x32_bf16 v[12:15], v[218:221], v[194:197], v[12:15]
	v_mfma_f32_16x16x32_bf16 v[8:11], v[226:229], v[194:197], v[8:11]
	v_mfma_f32_16x16x32_bf16 v[4:7], v[218:221], v[210:213], v[4:7]
	v_mfma_f32_16x16x32_bf16 v[0:3], v[226:229], v[210:213], v[0:3]
	v_mfma_f32_16x16x32_bf16 v[28:31], v[222:225], v[174:177], v[28:31]
	v_mfma_f32_16x16x32_bf16 v[24:27], v[230:233], v[174:177], v[24:27]
	v_mfma_f32_16x16x32_bf16 v[20:23], v[222:225], v[182:185], v[20:23]
	v_mfma_f32_16x16x32_bf16 v[16:19], v[230:233], v[182:185], v[16:19]
	v_mfma_f32_16x16x32_bf16 v[12:15], v[222:225], v[206:209], v[12:15]
	v_mfma_f32_16x16x32_bf16 v[8:11], v[230:233], v[206:209], v[8:11]
	v_mfma_f32_16x16x32_bf16 v[4:7], v[222:225], v[214:217], v[4:7]
	v_mfma_f32_16x16x32_bf16 v[0:3], v[230:233], v[214:217], v[0:3]
	s_barrier
	s_cbranch_scc0 .LBB0_295
	s_mov_b32 s100, 1
	s_add_u32 s48, s10, 0xffffff00
	v_lshl_add_u32 v166, s73, 10, v155
	s_addc_u32 s49, s11, -1
	s_ashr_i32 s29, s28, 31
	v_lshl_or_b32 v146, s72, 8, v156
	ds_read2_b32 v[158:159], v166 offset1:16
	s_lshl_b64 s[10:11], s[28:29], 8
	v_ashrrev_i32_e32 v147, 31, v146
	v_lshl_add_u64 v[148:149], s[10:11], 0, v[134:135]
	v_lshl_add_u64 v[146:147], v[146:147], 1, s[26:27]
	v_mad_u64_u32 v[150:151], s[10:11], v148, s13, v[146:147]
	v_mov_b32_e32 v146, v151
	v_mad_u64_u32 v[152:153], s[10:11], v149, s13, v[146:147]
	s_waitcnt lgkmcnt(0)
	v_pk_mul_f32 v[148:149], v[126:127], v[158:159] op_sel_hi:[1,0]
	v_pk_mul_f32 v[146:147], v[124:125], v[158:159] op_sel_hi:[1,0]
	v_pk_mul_f32 v[160:161], v[122:123], v[158:159] op_sel_hi:[1,0]
	v_pk_mul_f32 v[162:163], v[120:121], v[158:159] op_sel_hi:[1,0]
	v_mov_b32_e32 v151, v152
	v_cvt_pk_bf16_f32 v146, v146, v147
	v_cvt_pk_bf16_f32 v147, v148, v149
	v_cvt_pk_bf16_f32 v148, v162, v163
	v_cvt_pk_bf16_f32 v149, v160, v161
	global_store_dwordx4 v[150:151], v[146:149], off
	v_pk_mul_f32 v[160:161], v[90:91], v[158:159] op_sel_hi:[1,0]
	v_pk_mul_f32 v[162:163], v[88:89], v[158:159] op_sel_hi:[1,0]
	v_pk_mul_f32 v[148:149], v[94:95], v[158:159] op_sel_hi:[1,0]
	v_pk_mul_f32 v[146:147], v[92:93], v[158:159] op_sel_hi:[1,0]
	v_mov_b32_e32 v158, v159
	v_cvt_pk_bf16_f32 v146, v146, v147
	v_cvt_pk_bf16_f32 v147, v148, v149
	v_cvt_pk_bf16_f32 v148, v162, v163
	v_cvt_pk_bf16_f32 v149, v160, v161
	global_store_dwordx4 v[150:151], v[146:149], off offset:256
	v_pk_mul_f32 v[160:161], v[114:115], v[158:159] op_sel_hi:[1,0]
	s_mov_b32 s6, 0x1e000
	v_pk_mul_f32 v[148:149], v[118:119], v[158:159] op_sel_hi:[1,0]
	v_pk_mul_f32 v[146:147], v[116:117], v[158:159] op_sel_hi:[1,0]
	ds_read2_b32 v[164:165], v166 offset0:32 offset1:48
	v_pk_mul_f32 v[162:163], v[112:113], v[158:159] op_sel_hi:[1,0]
	v_cvt_pk_bf16_f32 v146, v146, v147
	v_cvt_pk_bf16_f32 v147, v148, v149
	v_cvt_pk_bf16_f32 v149, v160, v161
	v_add_co_u32_e32 v160, vcc, s6, v150
	v_cvt_pk_bf16_f32 v148, v162, v163
	s_nop 0
	v_addc_co_u32_e32 v161, vcc, 0, v152, vcc
	global_store_dwordx4 v[160:161], v[146:149], off
	v_pk_mul_f32 v[162:163], v[82:83], v[158:159] op_sel_hi:[1,0]
	s_mov_b32 s6, 0x3c000
	v_pk_mul_f32 v[148:149], v[86:87], v[158:159] op_sel_hi:[1,0]
	v_pk_mul_f32 v[146:147], v[84:85], v[158:159] op_sel_hi:[1,0]
	v_pk_mul_f32 v[158:159], v[80:81], v[158:159] op_sel_hi:[1,0]
	v_cvt_pk_bf16_f32 v146, v146, v147
	v_cvt_pk_bf16_f32 v147, v148, v149
	v_cvt_pk_bf16_f32 v148, v158, v159
	v_cvt_pk_bf16_f32 v149, v162, v163
	global_store_dwordx4 v[160:161], v[146:149], off offset:256
	s_waitcnt lgkmcnt(0)
	v_pk_mul_f32 v[158:159], v[106:107], v[164:165] op_sel_hi:[1,0]
	v_pk_mul_f32 v[160:161], v[104:105], v[164:165] op_sel_hi:[1,0]
	v_pk_mul_f32 v[148:149], v[110:111], v[164:165] op_sel_hi:[1,0]
	v_pk_mul_f32 v[146:147], v[108:109], v[164:165] op_sel_hi:[1,0]
	v_pk_mul_f32 v[162:163], v[72:73], v[164:165] op_sel_hi:[1,0]
	v_cvt_pk_bf16_f32 v146, v146, v147
	v_cvt_pk_bf16_f32 v147, v148, v149
	v_cvt_pk_bf16_f32 v149, v158, v159
	v_add_co_u32_e32 v158, vcc, s6, v150
	v_cvt_pk_bf16_f32 v148, v160, v161
	s_nop 0
	v_addc_co_u32_e32 v159, vcc, 0, v152, vcc
	global_store_dwordx4 v[158:159], v[146:149], off
	v_pk_mul_f32 v[160:161], v[74:75], v[164:165] op_sel_hi:[1,0]
	s_mov_b32 s6, 0x5a000
	v_pk_mul_f32 v[148:149], v[78:79], v[164:165] op_sel_hi:[1,0]
	v_pk_mul_f32 v[146:147], v[76:77], v[164:165] op_sel_hi:[1,0]
	s_nop 0
	v_cvt_pk_bf16_f32 v146, v146, v147
	v_cvt_pk_bf16_f32 v147, v148, v149
	v_cvt_pk_bf16_f32 v148, v162, v163
	v_cvt_pk_bf16_f32 v149, v160, v161
	global_store_dwordx4 v[158:159], v[146:149], off offset:256
	v_mov_b32_e32 v158, v165
	v_pk_mul_f32 v[160:161], v[98:99], v[158:159] op_sel_hi:[1,0]
	v_pk_mul_f32 v[148:149], v[102:103], v[158:159] op_sel_hi:[1,0]
	v_pk_mul_f32 v[146:147], v[100:101], v[158:159] op_sel_hi:[1,0]
	ds_read2_b32 v[164:165], v166 offset0:128 offset1:144
	v_pk_mul_f32 v[162:163], v[96:97], v[158:159] op_sel_hi:[1,0]
	v_cvt_pk_bf16_f32 v146, v146, v147
	v_cvt_pk_bf16_f32 v147, v148, v149
	v_cvt_pk_bf16_f32 v149, v160, v161
	v_add_co_u32_e32 v160, vcc, s6, v150
	v_cvt_pk_bf16_f32 v148, v162, v163
	s_nop 0
	v_addc_co_u32_e32 v161, vcc, 0, v152, vcc
	global_store_dwordx4 v[160:161], v[146:149], off
	v_pk_mul_f32 v[162:163], v[66:67], v[158:159] op_sel_hi:[1,0]
	s_mov_b32 s6, 0xf0000
	v_pk_mul_f32 v[148:149], v[70:71], v[158:159] op_sel_hi:[1,0]
	v_pk_mul_f32 v[146:147], v[68:69], v[158:159] op_sel_hi:[1,0]
	v_pk_mul_f32 v[158:159], v[64:65], v[158:159] op_sel_hi:[1,0]
	v_cvt_pk_bf16_f32 v146, v146, v147
	v_cvt_pk_bf16_f32 v147, v148, v149
	v_cvt_pk_bf16_f32 v148, v158, v159
	v_cvt_pk_bf16_f32 v149, v162, v163
	global_store_dwordx4 v[160:161], v[146:149], off offset:256
	s_waitcnt lgkmcnt(0)
	v_pk_mul_f32 v[158:159], v[58:59], v[164:165] op_sel_hi:[1,0]
	v_pk_mul_f32 v[160:161], v[56:57], v[164:165] op_sel_hi:[1,0]
	v_pk_mul_f32 v[148:149], v[62:63], v[164:165] op_sel_hi:[1,0]
	v_pk_mul_f32 v[146:147], v[60:61], v[164:165] op_sel_hi:[1,0]
	v_pk_mul_f32 v[162:163], v[24:25], v[164:165] op_sel_hi:[1,0]
	v_cvt_pk_bf16_f32 v146, v146, v147
	v_cvt_pk_bf16_f32 v147, v148, v149
	v_cvt_pk_bf16_f32 v149, v158, v159
	v_add_co_u32_e32 v158, vcc, s6, v150
	v_cvt_pk_bf16_f32 v148, v160, v161
	s_nop 0
	v_addc_co_u32_e32 v159, vcc, 0, v152, vcc
	global_store_dwordx4 v[158:159], v[146:149], off
	v_pk_mul_f32 v[160:161], v[26:27], v[164:165] op_sel_hi:[1,0]
	s_mov_b32 s6, 0x10e000
	v_pk_mul_f32 v[148:149], v[30:31], v[164:165] op_sel_hi:[1,0]
	v_pk_mul_f32 v[146:147], v[28:29], v[164:165] op_sel_hi:[1,0]
	s_nop 0
	v_cvt_pk_bf16_f32 v146, v146, v147
	v_cvt_pk_bf16_f32 v147, v148, v149
	v_cvt_pk_bf16_f32 v148, v162, v163
	v_cvt_pk_bf16_f32 v149, v160, v161
	global_store_dwordx4 v[158:159], v[146:149], off offset:256
	v_mov_b32_e32 v158, v165
	v_pk_mul_f32 v[160:161], v[50:51], v[158:159] op_sel_hi:[1,0]
	v_pk_mul_f32 v[148:149], v[54:55], v[158:159] op_sel_hi:[1,0]
	v_pk_mul_f32 v[146:147], v[52:53], v[158:159] op_sel_hi:[1,0]
	ds_read2_b32 v[164:165], v166 offset0:160 offset1:176
	v_pk_mul_f32 v[162:163], v[48:49], v[158:159] op_sel_hi:[1,0]
	v_cvt_pk_bf16_f32 v146, v146, v147
	v_cvt_pk_bf16_f32 v147, v148, v149
	v_cvt_pk_bf16_f32 v149, v160, v161
	v_add_co_u32_e32 v160, vcc, s6, v150
	v_cvt_pk_bf16_f32 v148, v162, v163
	s_nop 0
	v_addc_co_u32_e32 v161, vcc, 0, v152, vcc
	global_store_dwordx4 v[160:161], v[146:149], off
	v_pk_mul_f32 v[162:163], v[18:19], v[158:159] op_sel_hi:[1,0]
	s_mov_b32 s6, 0x12c000
	v_pk_mul_f32 v[148:149], v[22:23], v[158:159] op_sel_hi:[1,0]
	v_pk_mul_f32 v[146:147], v[20:21], v[158:159] op_sel_hi:[1,0]
	v_pk_mul_f32 v[158:159], v[16:17], v[158:159] op_sel_hi:[1,0]
	v_cvt_pk_bf16_f32 v146, v146, v147
	v_cvt_pk_bf16_f32 v147, v148, v149
	v_cvt_pk_bf16_f32 v148, v158, v159
	v_cvt_pk_bf16_f32 v149, v162, v163
	global_store_dwordx4 v[160:161], v[146:149], off offset:256
	s_waitcnt lgkmcnt(0)
	v_pk_mul_f32 v[158:159], v[42:43], v[164:165] op_sel_hi:[1,0]
	v_pk_mul_f32 v[160:161], v[40:41], v[164:165] op_sel_hi:[1,0]
	v_pk_mul_f32 v[148:149], v[46:47], v[164:165] op_sel_hi:[1,0]
	v_pk_mul_f32 v[146:147], v[44:45], v[164:165] op_sel_hi:[1,0]
	v_pk_mul_f32 v[162:163], v[8:9], v[164:165] op_sel_hi:[1,0]
	v_cvt_pk_bf16_f32 v146, v146, v147
	v_cvt_pk_bf16_f32 v147, v148, v149
	v_cvt_pk_bf16_f32 v149, v158, v159
	v_add_co_u32_e32 v158, vcc, s6, v150
	v_cvt_pk_bf16_f32 v148, v160, v161
	s_nop 0
	v_addc_co_u32_e32 v159, vcc, 0, v152, vcc
	global_store_dwordx4 v[158:159], v[146:149], off
	v_pk_mul_f32 v[160:161], v[10:11], v[164:165] op_sel_hi:[1,0]
	s_mov_b32 s6, 0x14a000
	v_pk_mul_f32 v[148:149], v[14:15], v[164:165] op_sel_hi:[1,0]
	v_pk_mul_f32 v[146:147], v[12:13], v[164:165] op_sel_hi:[1,0]
	v_add_co_u32_e32 v150, vcc, s6, v150
	v_cvt_pk_bf16_f32 v146, v146, v147
	v_cvt_pk_bf16_f32 v147, v148, v149
	v_cvt_pk_bf16_f32 v148, v162, v163
	v_cvt_pk_bf16_f32 v149, v160, v161
	global_store_dwordx4 v[158:159], v[146:149], off offset:256
	v_mov_b32_e32 v158, v165
	v_pk_mul_f32 v[160:161], v[34:35], v[158:159] op_sel_hi:[1,0]
	v_pk_mul_f32 v[148:149], v[38:39], v[158:159] op_sel_hi:[1,0]
	v_pk_mul_f32 v[146:147], v[36:37], v[158:159] op_sel_hi:[1,0]
	v_pk_mul_f32 v[162:163], v[32:33], v[158:159] op_sel_hi:[1,0]
	v_cvt_pk_bf16_f32 v146, v146, v147
	v_cvt_pk_bf16_f32 v147, v148, v149
	v_cvt_pk_bf16_f32 v148, v162, v163
	v_cvt_pk_bf16_f32 v149, v160, v161
	v_addc_co_u32_e32 v151, vcc, 0, v152, vcc
	global_store_dwordx4 v[150:151], v[146:149], off
	v_pk_mul_f32 v[152:153], v[2:3], v[158:159] op_sel_hi:[1,0]
	s_andn2_b64 vcc, exec, s[44:45]
	v_pk_mul_f32 v[148:149], v[6:7], v[158:159] op_sel_hi:[1,0]
	v_pk_mul_f32 v[146:147], v[4:5], v[158:159] op_sel_hi:[1,0]
	v_pk_mul_f32 v[158:159], v[0:1], v[158:159] op_sel_hi:[1,0]
	v_cvt_pk_bf16_f32 v146, v146, v147
	v_cvt_pk_bf16_f32 v147, v148, v149
	v_cvt_pk_bf16_f32 v148, v158, v159
	v_cvt_pk_bf16_f32 v149, v152, v153
	global_store_dwordx4 v[150:151], v[146:149], off offset:256
	s_cbranch_vccz .LBB0_291
	s_mov_b64 s[38:39], s[48:49]
	s_andn2_b64 vcc, exec, s[42:43]
	s_mov_b64 s[48:49], s[38:39]
	s_cbranch_vccnz .LBB0_292

.Lm4ap_315:
	s_waitcnt lgkmcnt(0)
	s_barrier
	s_nop 0
	v_mfma_f32_16x16x32_bf16 v[124:127], v[146:149], v[170:173], 0
	v_mfma_f32_16x16x32_bf16 v[120:123], v[162:165], v[170:173], 0
	v_mfma_f32_16x16x32_bf16 v[116:119], v[146:149], v[178:181], 0
	v_mfma_f32_16x16x32_bf16 v[112:115], v[162:165], v[178:181], 0
	v_mfma_f32_16x16x32_bf16 v[108:111], v[146:149], v[194:197], 0
	v_mfma_f32_16x16x32_bf16 v[104:107], v[162:165], v[194:197], 0
	v_mfma_f32_16x16x32_bf16 v[100:103], v[146:149], v[210:213], 0
	v_mfma_f32_16x16x32_bf16 v[96:99], v[162:165], v[210:213], 0
	v_mfma_f32_16x16x32_bf16 v[124:127], v[158:161], v[174:177], v[124:127]
	v_mfma_f32_16x16x32_bf16 v[120:123], v[166:169], v[174:177], v[120:123]
	v_mfma_f32_16x16x32_bf16 v[116:119], v[158:161], v[182:185], v[116:119]
	v_mfma_f32_16x16x32_bf16 v[112:115], v[166:169], v[182:185], v[112:115]
	v_mfma_f32_16x16x32_bf16 v[108:111], v[158:161], v[206:209], v[108:111]
	v_mfma_f32_16x16x32_bf16 v[104:107], v[166:169], v[206:209], v[104:107]
	v_mfma_f32_16x16x32_bf16 v[100:103], v[158:161], v[214:217], v[100:103]
	v_mfma_f32_16x16x32_bf16 v[96:99], v[166:169], v[214:217], v[96:99]
	v_mfma_f32_16x16x32_bf16 v[92:95], v[218:221], v[170:173], 0
	v_mfma_f32_16x16x32_bf16 v[88:91], v[226:229], v[170:173], 0
	v_mfma_f32_16x16x32_bf16 v[84:87], v[218:221], v[178:181], 0
	v_mfma_f32_16x16x32_bf16 v[80:83], v[226:229], v[178:181], 0
	v_mfma_f32_16x16x32_bf16 v[76:79], v[218:221], v[194:197], 0
	v_mfma_f32_16x16x32_bf16 v[72:75], v[226:229], v[194:197], 0
	v_mfma_f32_16x16x32_bf16 v[68:71], v[218:221], v[210:213], 0
	v_mfma_f32_16x16x32_bf16 v[64:67], v[226:229], v[210:213], 0
	v_mfma_f32_16x16x32_bf16 v[92:95], v[222:225], v[174:177], v[92:95]
	v_mfma_f32_16x16x32_bf16 v[88:91], v[230:233], v[174:177], v[88:91]
	v_mfma_f32_16x16x32_bf16 v[84:87], v[222:225], v[182:185], v[84:87]
	v_mfma_f32_16x16x32_bf16 v[80:83], v[230:233], v[182:185], v[80:83]
	v_mfma_f32_16x16x32_bf16 v[76:79], v[222:225], v[206:209], v[76:79]
	v_mfma_f32_16x16x32_bf16 v[72:75], v[230:233], v[206:209], v[72:75]
	v_mfma_f32_16x16x32_bf16 v[68:71], v[222:225], v[214:217], v[68:71]
	v_mfma_f32_16x16x32_bf16 v[64:67], v[230:233], v[214:217], v[64:67]
	s_barrier
	s_add_i32 s19, s80, s57
	v_lshl_add_u64 v[234:235], s[50:51], 0, v[140:141]
	s_mov_b32 m0, s19
	s_nop 0
	global_load_lds_dwordx4 v[234:235], off
	v_lshl_add_u64 v[236:237], s[50:51], 0, v[132:133]
	s_add_i32 m0, s19, 0x2000
	s_nop 0
	global_load_lds_dwordx4 v[236:237], off
	s_mov_b32 m0, s58
	v_lshl_add_u64 v[238:239], s[52:53], 0, v[128:129]
	ds_read_b128 v[170:173], v156 offset:16384
	ds_read_b128 v[174:177], v156 offset:17408
	ds_read_b128 v[178:181], v156 offset:18432
	ds_read_b128 v[182:185], v156 offset:19456
	ds_read_b128 v[194:197], v156 offset:20480
	ds_read_b128 v[206:209], v156 offset:21504
	ds_read_b128 v[210:213], v156 offset:22528
	ds_read_b128 v[214:217], v156 offset:23552
	global_load_lds_dwordx4 v[238:239], off
	v_lshl_add_u64 v[240:241], s[52:53], 0, v[130:131]
	s_mov_b32 m0, s59
	s_nop 0
	global_load_lds_dwordx4 v[240:241], off
	s_add_u32 s80, s50, 0x40000
	s_addc_u32 s81, s51, 0
	s_add_i32 s6, s6, s57
	v_lshl_add_u64 v[250:251], s[80:81], 0, v[140:141]
	s_mov_b32 m0, s6
	s_nop 0
	global_load_lds_dwordx4 v[250:251], off
	v_lshl_add_u64 v[250:251], s[80:81], 0, v[132:133]
	s_add_i32 m0, s6, 0x2000
	s_nop 0
	global_load_lds_dwordx4 v[250:251], off
	s_waitcnt vmcnt(24)
	s_cmp_lg_u32 s100, 0
	s_cbranch_scc1 .Lm4bp_315
	s_waitcnt vmcnt(8)
.Lm4bp_315:
	s_waitcnt lgkmcnt(0)
	s_mov_b32 s100, 0
	s_barrier
	v_mfma_f32_16x16x32_bf16 v[60:63], v[146:149], v[170:173], 0
	v_mfma_f32_16x16x32_bf16 v[56:59], v[162:165], v[170:173], 0
	v_mfma_f32_16x16x32_bf16 v[52:55], v[146:149], v[178:181], 0
	v_mfma_f32_16x16x32_bf16 v[48:51], v[162:165], v[178:181], 0
	v_mfma_f32_16x16x32_bf16 v[44:47], v[146:149], v[194:197], 0
	v_mfma_f32_16x16x32_bf16 v[40:43], v[162:165], v[194:197], 0
	v_mfma_f32_16x16x32_bf16 v[36:39], v[146:149], v[210:213], 0
	v_mfma_f32_16x16x32_bf16 v[32:35], v[162:165], v[210:213], 0
	v_mfma_f32_16x16x32_bf16 v[60:63], v[158:161], v[174:177], v[60:63]
	v_mfma_f32_16x16x32_bf16 v[56:59], v[166:169], v[174:177], v[56:59]
	v_mfma_f32_16x16x32_bf16 v[52:55], v[158:161], v[182:185], v[52:55]
	v_mfma_f32_16x16x32_bf16 v[48:51], v[166:169], v[182:185], v[48:51]
	v_mfma_f32_16x16x32_bf16 v[44:47], v[158:161], v[206:209], v[44:47]
	v_mfma_f32_16x16x32_bf16 v[40:43], v[166:169], v[206:209], v[40:43]
	v_mfma_f32_16x16x32_bf16 v[36:39], v[158:161], v[214:217], v[36:39]
	v_mfma_f32_16x16x32_bf16 v[32:35], v[166:169], v[214:217], v[32:35]
	v_mfma_f32_16x16x32_bf16 v[28:31], v[218:221], v[170:173], 0
	v_mfma_f32_16x16x32_bf16 v[24:27], v[226:229], v[170:173], 0
	v_mfma_f32_16x16x32_bf16 v[20:23], v[218:221], v[178:181], 0
	v_mfma_f32_16x16x32_bf16 v[16:19], v[226:229], v[178:181], 0
	v_mfma_f32_16x16x32_bf16 v[12:15], v[218:221], v[194:197], 0
	v_mfma_f32_16x16x32_bf16 v[8:11], v[226:229], v[194:197], 0
	v_mfma_f32_16x16x32_bf16 v[4:7], v[218:221], v[210:213], 0
	v_mfma_f32_16x16x32_bf16 v[0:3], v[226:229], v[210:213], 0
	v_mfma_f32_16x16x32_bf16 v[28:31], v[222:225], v[174:177], v[28:31]
	v_mfma_f32_16x16x32_bf16 v[24:27], v[230:233], v[174:177], v[24:27]
	v_mfma_f32_16x16x32_bf16 v[20:23], v[222:225], v[182:185], v[20:23]
	v_mfma_f32_16x16x32_bf16 v[16:19], v[230:233], v[182:185], v[16:19]
	v_mfma_f32_16x16x32_bf16 v[12:15], v[222:225], v[206:209], v[12:15]
	v_mfma_f32_16x16x32_bf16 v[8:11], v[230:233], v[206:209], v[8:11]
	v_mfma_f32_16x16x32_bf16 v[4:7], v[222:225], v[214:217], v[4:7]
	v_mfma_f32_16x16x32_bf16 v[0:3], v[230:233], v[214:217], v[0:3]
	s_barrier
	s_add_i32 s6, 0, 0x18000
	v_add_u32_e32 v157, s6, v154
	ds_read_b128 v[146:149], v157
	ds_read_b128 v[158:161], v157 offset:1024
	ds_read_b128 v[162:165], v157 offset:2048
	ds_read_b128 v[166:169], v157 offset:3072
	s_add_u32 s52, s52, 0x40000
	s_addc_u32 s53, s53, 0
	s_mov_b32 m0, s68
	v_lshl_add_u64 v[218:219], s[52:53], 0, v[128:129]
	ds_read_b128 v[170:173], v156 offset:32768
	ds_read_b128 v[174:177], v156 offset:33792
	ds_read_b128 v[178:181], v156 offset:34816
	ds_read_b128 v[182:185], v156 offset:35840
	ds_read_b128 v[194:197], v156 offset:36864
	ds_read_b128 v[206:209], v156 offset:37888
	ds_read_b128 v[210:213], v156 offset:38912
	ds_read_b128 v[214:217], v156 offset:39936
	global_load_lds_dwordx4 v[218:219], off
	v_lshl_add_u64 v[218:219], s[52:53], 0, v[130:131]
	s_mov_b32 m0, s69
	s_nop 0
	global_load_lds_dwordx4 v[218:219], off
	s_add_i32 s19, 0, 0x1c000
	v_add_u32_e32 v157, s19, v154
	ds_read_b128 v[218:221], v157
	ds_read_b128 v[222:225], v157 offset:1024
	ds_read_b128 v[226:229], v157 offset:2048
	ds_read_b128 v[230:233], v157 offset:3072
	s_waitcnt vmcnt(8)
	s_waitcnt lgkmcnt(0)
	s_barrier
	v_mfma_f32_16x16x32_bf16 v[124:127], v[146:149], v[170:173], v[124:127]
	v_mfma_f32_16x16x32_bf16 v[120:123], v[162:165], v[170:173], v[120:123]
	v_mfma_f32_16x16x32_bf16 v[116:119], v[146:149], v[178:181], v[116:119]
	v_mfma_f32_16x16x32_bf16 v[112:115], v[162:165], v[178:181], v[112:115]
	v_mfma_f32_16x16x32_bf16 v[108:111], v[146:149], v[194:197], v[108:111]
	v_mfma_f32_16x16x32_bf16 v[104:107], v[162:165], v[194:197], v[104:107]
	v_mfma_f32_16x16x32_bf16 v[100:103], v[146:149], v[210:213], v[100:103]
	v_mfma_f32_16x16x32_bf16 v[96:99], v[162:165], v[210:213], v[96:99]
	v_mfma_f32_16x16x32_bf16 v[124:127], v[158:161], v[174:177], v[124:127]
	v_mfma_f32_16x16x32_bf16 v[120:123], v[166:169], v[174:177], v[120:123]
	v_mfma_f32_16x16x32_bf16 v[116:119], v[158:161], v[182:185], v[116:119]
	v_mfma_f32_16x16x32_bf16 v[112:115], v[166:169], v[182:185], v[112:115]
	v_mfma_f32_16x16x32_bf16 v[108:111], v[158:161], v[206:209], v[108:111]
	v_mfma_f32_16x16x32_bf16 v[104:107], v[166:169], v[206:209], v[104:107]
	v_mfma_f32_16x16x32_bf16 v[100:103], v[158:161], v[214:217], v[100:103]
	v_mfma_f32_16x16x32_bf16 v[96:99], v[166:169], v[214:217], v[96:99]
	v_mfma_f32_16x16x32_bf16 v[92:95], v[218:221], v[170:173], v[92:95]
	v_mfma_f32_16x16x32_bf16 v[88:91], v[226:229], v[170:173], v[88:91]
	v_mfma_f32_16x16x32_bf16 v[84:87], v[218:221], v[178:181], v[84:87]
	v_mfma_f32_16x16x32_bf16 v[80:83], v[226:229], v[178:181], v[80:83]
	v_mfma_f32_16x16x32_bf16 v[76:79], v[218:221], v[194:197], v[76:79]
	v_mfma_f32_16x16x32_bf16 v[72:75], v[226:229], v[194:197], v[72:75]
	v_mfma_f32_16x16x32_bf16 v[68:71], v[218:221], v[210:213], v[68:71]
	v_mfma_f32_16x16x32_bf16 v[64:67], v[226:229], v[210:213], v[64:67]
	v_mfma_f32_16x16x32_bf16 v[92:95], v[222:225], v[174:177], v[92:95]
	v_mfma_f32_16x16x32_bf16 v[88:91], v[230:233], v[174:177], v[88:91]
	v_mfma_f32_16x16x32_bf16 v[84:87], v[222:225], v[182:185], v[84:87]
	v_mfma_f32_16x16x32_bf16 v[80:83], v[230:233], v[182:185], v[80:83]
	v_mfma_f32_16x16x32_bf16 v[76:79], v[222:225], v[206:209], v[76:79]
	v_mfma_f32_16x16x32_bf16 v[72:75], v[230:233], v[206:209], v[72:75]
	v_mfma_f32_16x16x32_bf16 v[68:71], v[222:225], v[214:217], v[68:71]
	v_mfma_f32_16x16x32_bf16 v[64:67], v[230:233], v[214:217], v[64:67]
	s_barrier
	s_add_i32 s6, s6, s57
	v_lshl_add_u64 v[234:235], v[234:235], 0, s[36:37]
	s_mov_b32 m0, s6
	s_nop 0
	global_load_lds_dwordx4 v[234:235], off
	v_lshl_add_u64 v[234:235], v[236:237], 0, s[36:37]
	s_add_i32 m0, s6, 0x2000
	s_nop 0
	global_load_lds_dwordx4 v[234:235], off
	s_mov_b32 m0, s71
	v_lshl_add_u64 v[234:235], v[238:239], 0, s[36:37]
	ds_read_b128 v[170:173], v156 offset:49152
	ds_read_b128 v[174:177], v156 offset:50176
	ds_read_b128 v[178:181], v156 offset:51200
	ds_read_b128 v[182:185], v156 offset:52224
	ds_read_b128 v[194:197], v156 offset:53248
	ds_read_b128 v[206:209], v156 offset:54272
	ds_read_b128 v[210:213], v156 offset:55296
	ds_read_b128 v[214:217], v156 offset:56320
	global_load_lds_dwordx4 v[234:235], off
	v_lshl_add_u64 v[234:235], v[240:241], 0, s[36:37]
	s_mov_b32 m0, s72
	s_nop 0
	global_load_lds_dwordx4 v[234:235], off
	s_add_u32 s50, s50, 0x40080
	s_addc_u32 s51, s51, 0
	s_add_i32 s6, s19, s57
	v_lshl_add_u64 v[250:251], s[50:51], 0, v[140:141]
	s_mov_b32 m0, s6
	s_nop 0
	global_load_lds_dwordx4 v[250:251], off
	v_lshl_add_u64 v[250:251], s[50:51], 0, v[132:133]
	s_add_i32 m0, s6, 0x2000
	s_nop 0
	global_load_lds_dwordx4 v[250:251], off
	s_add_i32 s75, s75, 2
	s_add_u32 s48, s48, 0x100
	s_addc_u32 s49, s49, 0
	s_cmp_gt_u32 s75, 13
	s_nop 0
	s_waitcnt vmcnt(8)
	s_waitcnt lgkmcnt(0)
	s_barrier
	v_mfma_f32_16x16x32_bf16 v[60:63], v[146:149], v[170:173], v[60:63]
	v_mfma_f32_16x16x32_bf16 v[56:59], v[162:165], v[170:173], v[56:59]
	v_mfma_f32_16x16x32_bf16 v[52:55], v[146:149], v[178:181], v[52:55]
	v_mfma_f32_16x16x32_bf16 v[48:51], v[162:165], v[178:181], v[48:51]
	v_mfma_f32_16x16x32_bf16 v[44:47], v[146:149], v[194:197], v[44:47]
	v_mfma_f32_16x16x32_bf16 v[40:43], v[162:165], v[194:197], v[40:43]
	v_mfma_f32_16x16x32_bf16 v[36:39], v[146:149], v[210:213], v[36:39]
	v_mfma_f32_16x16x32_bf16 v[32:35], v[162:165], v[210:213], v[32:35]
	v_mfma_f32_16x16x32_bf16 v[60:63], v[158:161], v[174:177], v[60:63]
	v_mfma_f32_16x16x32_bf16 v[56:59], v[166:169], v[174:177], v[56:59]
	v_mfma_f32_16x16x32_bf16 v[52:55], v[158:161], v[182:185], v[52:55]
	v_mfma_f32_16x16x32_bf16 v[48:51], v[166:169], v[182:185], v[48:51]
	v_mfma_f32_16x16x32_bf16 v[44:47], v[158:161], v[206:209], v[44:47]
	v_mfma_f32_16x16x32_bf16 v[40:43], v[166:169], v[206:209], v[40:43]
	v_mfma_f32_16x16x32_bf16 v[36:39], v[158:161], v[214:217], v[36:39]
	v_mfma_f32_16x16x32_bf16 v[32:35], v[166:169], v[214:217], v[32:35]
	v_mfma_f32_16x16x32_bf16 v[28:31], v[218:221], v[170:173], v[28:31]
	v_mfma_f32_16x16x32_bf16 v[24:27], v[226:229], v[170:173], v[24:27]
	v_mfma_f32_16x16x32_bf16 v[20:23], v[218:221], v[178:181], v[20:23]
	v_mfma_f32_16x16x32_bf16 v[16:19], v[226:229], v[178:181], v[16:19]
	v_mfma_f32_16x16x32_bf16 v[12:15], v[218:221], v[194:197], v[12:15]
	v_mfma_f32_16x16x32_bf16 v[8:11], v[226:229], v[194:197], v[8:11]
	v_mfma_f32_16x16x32_bf16 v[4:7], v[218:221], v[210:213], v[4:7]
	v_mfma_f32_16x16x32_bf16 v[0:3], v[226:229], v[210:213], v[0:3]
	v_mfma_f32_16x16x32_bf16 v[28:31], v[222:225], v[174:177], v[28:31]
	v_mfma_f32_16x16x32_bf16 v[24:27], v[230:233], v[174:177], v[24:27]
	v_mfma_f32_16x16x32_bf16 v[20:23], v[222:225], v[182:185], v[20:23]
	v_mfma_f32_16x16x32_bf16 v[16:19], v[230:233], v[182:185], v[16:19]
	v_mfma_f32_16x16x32_bf16 v[12:15], v[222:225], v[206:209], v[12:15]
	v_mfma_f32_16x16x32_bf16 v[8:11], v[230:233], v[206:209], v[8:11]
	v_mfma_f32_16x16x32_bf16 v[4:7], v[222:225], v[214:217], v[4:7]
	v_mfma_f32_16x16x32_bf16 v[0:3], v[230:233], v[214:217], v[0:3]
	s_barrier
.LBB0_315:
	s_add_u32 s6, s4, s48
	s_addc_u32 s19, s5, s49
	s_add_u32 s6, s6, 0x100
	s_addc_u32 s19, s19, 0
	s_add_u32 s23, s11, s48
	s_addc_u32 s50, s12, s49
	s_add_i32 s80, 0, 0x10000
	v_add_u32_e32 v157, s80, v154
	ds_read_b128 v[146:149], v157
	ds_read_b128 v[158:161], v157 offset:1024
	ds_read_b128 v[162:165], v157 offset:2048
	ds_read_b128 v[166:169], v157 offset:3072
	s_cmpk_eq_i32 s48, 0x700
	s_cselect_b32 s53, s29, s19
	s_cselect_b32 s52, s31, s6
	s_cselect_b32 s51, s35, s50
	s_cselect_b32 s50, s74, s23
	v_lshl_add_u64 v[218:219], v[150:151], 0, s[48:49]
	s_add_i32 m0, s58, 0xc000
	ds_read_b128 v[170:173], v156
	ds_read_b128 v[174:177], v156 offset:1024
	ds_read_b128 v[178:181], v156 offset:2048
	ds_read_b128 v[182:185], v156 offset:3072
	ds_read_b128 v[194:197], v156 offset:4096
	ds_read_b128 v[206:209], v156 offset:5120
	ds_read_b128 v[210:213], v156 offset:6144
	ds_read_b128 v[214:217], v156 offset:7168
	global_load_lds_dwordx4 v[218:219], off
	v_lshl_add_u64 v[218:219], v[152:153], 0, s[48:49]
	s_add_i32 m0, s58, 0xe000
	s_nop 0
	global_load_lds_dwordx4 v[218:219], off
	s_add_i32 s6, 0, 0x14000
	v_add_u32_e32 v157, s6, v154
	ds_read_b128 v[218:221], v157
	ds_read_b128 v[222:225], v157 offset:1024
	ds_read_b128 v[226:229], v157 offset:2048
	ds_read_b128 v[230:233], v157 offset:3072
	s_nop 0
	s_waitcnt vmcnt(8)
	s_waitcnt lgkmcnt(0)
	s_barrier
	v_mfma_f32_16x16x32_bf16 v[124:127], v[146:149], v[170:173], v[124:127]
	v_mfma_f32_16x16x32_bf16 v[120:123], v[162:165], v[170:173], v[120:123]
	v_mfma_f32_16x16x32_bf16 v[116:119], v[146:149], v[178:181], v[116:119]
	v_mfma_f32_16x16x32_bf16 v[112:115], v[162:165], v[178:181], v[112:115]
	v_mfma_f32_16x16x32_bf16 v[108:111], v[146:149], v[194:197], v[108:111]
	v_mfma_f32_16x16x32_bf16 v[104:107], v[162:165], v[194:197], v[104:107]
	v_mfma_f32_16x16x32_bf16 v[100:103], v[146:149], v[210:213], v[100:103]
	v_mfma_f32_16x16x32_bf16 v[96:99], v[162:165], v[210:213], v[96:99]
	v_mfma_f32_16x16x32_bf16 v[124:127], v[158:161], v[174:177], v[124:127]
	v_mfma_f32_16x16x32_bf16 v[120:123], v[166:169], v[174:177], v[120:123]
	v_mfma_f32_16x16x32_bf16 v[116:119], v[158:161], v[182:185], v[116:119]
	v_mfma_f32_16x16x32_bf16 v[112:115], v[166:169], v[182:185], v[112:115]
	v_mfma_f32_16x16x32_bf16 v[108:111], v[158:161], v[206:209], v[108:111]
	v_mfma_f32_16x16x32_bf16 v[104:107], v[166:169], v[206:209], v[104:107]
	v_mfma_f32_16x16x32_bf16 v[100:103], v[158:161], v[214:217], v[100:103]
	v_mfma_f32_16x16x32_bf16 v[96:99], v[166:169], v[214:217], v[96:99]
	v_mfma_f32_16x16x32_bf16 v[92:95], v[218:221], v[170:173], v[92:95]
	v_mfma_f32_16x16x32_bf16 v[88:91], v[226:229], v[170:173], v[88:91]
	v_mfma_f32_16x16x32_bf16 v[84:87], v[218:221], v[178:181], v[84:87]
	v_mfma_f32_16x16x32_bf16 v[80:83], v[226:229], v[178:181], v[80:83]
	v_mfma_f32_16x16x32_bf16 v[76:79], v[218:221], v[194:197], v[76:79]
	v_mfma_f32_16x16x32_bf16 v[72:75], v[226:229], v[194:197], v[72:75]
	v_mfma_f32_16x16x32_bf16 v[68:71], v[218:221], v[210:213], v[68:71]
	v_mfma_f32_16x16x32_bf16 v[64:67], v[226:229], v[210:213], v[64:67]
	v_mfma_f32_16x16x32_bf16 v[92:95], v[222:225], v[174:177], v[92:95]
	v_mfma_f32_16x16x32_bf16 v[88:91], v[230:233], v[174:177], v[88:91]
	v_mfma_f32_16x16x32_bf16 v[84:87], v[222:225], v[182:185], v[84:87]
	v_mfma_f32_16x16x32_bf16 v[80:83], v[230:233], v[182:185], v[80:83]
	v_mfma_f32_16x16x32_bf16 v[76:79], v[222:225], v[206:209], v[76:79]
	v_mfma_f32_16x16x32_bf16 v[72:75], v[230:233], v[206:209], v[72:75]
	v_mfma_f32_16x16x32_bf16 v[68:71], v[222:225], v[214:217], v[68:71]
	v_mfma_f32_16x16x32_bf16 v[64:67], v[230:233], v[214:217], v[64:67]
	s_barrier
	s_add_i32 s19, s80, s57
	v_lshl_add_u64 v[234:235], s[50:51], 0, v[140:141]
	s_mov_b32 m0, s19
	s_nop 0
	global_load_lds_dwordx4 v[234:235], off
	v_lshl_add_u64 v[236:237], s[50:51], 0, v[132:133]
	s_add_i32 m0, s19, 0x2000
	s_nop 0
	global_load_lds_dwordx4 v[236:237], off
	s_mov_b32 m0, s58
	v_lshl_add_u64 v[238:239], s[52:53], 0, v[128:129]
	ds_read_b128 v[170:173], v156 offset:16384
	ds_read_b128 v[174:177], v156 offset:17408
	ds_read_b128 v[178:181], v156 offset:18432
	ds_read_b128 v[182:185], v156 offset:19456
	ds_read_b128 v[194:197], v156 offset:20480
	ds_read_b128 v[206:209], v156 offset:21504
	ds_read_b128 v[210:213], v156 offset:22528
	ds_read_b128 v[214:217], v156 offset:23552
	global_load_lds_dwordx4 v[238:239], off
	v_lshl_add_u64 v[240:241], s[52:53], 0, v[130:131]
	s_mov_b32 m0, s59
	s_nop 0
	global_load_lds_dwordx4 v[240:241], off
	s_add_u32 s80, s50, 0x40000
	s_addc_u32 s81, s51, 0
	s_add_i32 s6, s6, s57
	v_lshl_add_u64 v[250:251], s[80:81], 0, v[140:141]
	s_mov_b32 m0, s6
	s_nop 0
	global_load_lds_dwordx4 v[250:251], off
	v_lshl_add_u64 v[250:251], s[80:81], 0, v[132:133]
	s_add_i32 m0, s6, 0x2000
	s_nop 0
	global_load_lds_dwordx4 v[250:251], off
	s_waitcnt vmcnt(8)
	s_waitcnt lgkmcnt(0)
	s_barrier
	v_mfma_f32_16x16x32_bf16 v[60:63], v[146:149], v[170:173], v[60:63]
	v_mfma_f32_16x16x32_bf16 v[56:59], v[162:165], v[170:173], v[56:59]
	v_mfma_f32_16x16x32_bf16 v[52:55], v[146:149], v[178:181], v[52:55]
	v_mfma_f32_16x16x32_bf16 v[48:51], v[162:165], v[178:181], v[48:51]
	v_mfma_f32_16x16x32_bf16 v[44:47], v[146:149], v[194:197], v[44:47]
	v_mfma_f32_16x16x32_bf16 v[40:43], v[162:165], v[194:197], v[40:43]
	v_mfma_f32_16x16x32_bf16 v[36:39], v[146:149], v[210:213], v[36:39]
	v_mfma_f32_16x16x32_bf16 v[32:35], v[162:165], v[210:213], v[32:35]
	v_mfma_f32_16x16x32_bf16 v[60:63], v[158:161], v[174:177], v[60:63]
	v_mfma_f32_16x16x32_bf16 v[56:59], v[166:169], v[174:177], v[56:59]
	v_mfma_f32_16x16x32_bf16 v[52:55], v[158:161], v[182:185], v[52:55]
	v_mfma_f32_16x16x32_bf16 v[48:51], v[166:169], v[182:185], v[48:51]
	v_mfma_f32_16x16x32_bf16 v[44:47], v[158:161], v[206:209], v[44:47]
	v_mfma_f32_16x16x32_bf16 v[40:43], v[166:169], v[206:209], v[40:43]
	v_mfma_f32_16x16x32_bf16 v[36:39], v[158:161], v[214:217], v[36:39]
	v_mfma_f32_16x16x32_bf16 v[32:35], v[166:169], v[214:217], v[32:35]
	v_mfma_f32_16x16x32_bf16 v[28:31], v[218:221], v[170:173], v[28:31]
	v_mfma_f32_16x16x32_bf16 v[24:27], v[226:229], v[170:173], v[24:27]
	v_mfma_f32_16x16x32_bf16 v[20:23], v[218:221], v[178:181], v[20:23]
	v_mfma_f32_16x16x32_bf16 v[16:19], v[226:229], v[178:181], v[16:19]
	v_mfma_f32_16x16x32_bf16 v[12:15], v[218:221], v[194:197], v[12:15]
	v_mfma_f32_16x16x32_bf16 v[8:11], v[226:229], v[194:197], v[8:11]
	v_mfma_f32_16x16x32_bf16 v[4:7], v[218:221], v[210:213], v[4:7]
	v_mfma_f32_16x16x32_bf16 v[0:3], v[226:229], v[210:213], v[0:3]
	v_mfma_f32_16x16x32_bf16 v[28:31], v[222:225], v[174:177], v[28:31]
	v_mfma_f32_16x16x32_bf16 v[24:27], v[230:233], v[174:177], v[24:27]
	v_mfma_f32_16x16x32_bf16 v[20:23], v[222:225], v[182:185], v[20:23]
	v_mfma_f32_16x16x32_bf16 v[16:19], v[230:233], v[182:185], v[16:19]
	v_mfma_f32_16x16x32_bf16 v[12:15], v[222:225], v[206:209], v[12:15]
	v_mfma_f32_16x16x32_bf16 v[8:11], v[230:233], v[206:209], v[8:11]
	v_mfma_f32_16x16x32_bf16 v[4:7], v[222:225], v[214:217], v[4:7]
	v_mfma_f32_16x16x32_bf16 v[0:3], v[230:233], v[214:217], v[0:3]
	s_barrier
	s_add_i32 s6, 0, 0x18000
	v_add_u32_e32 v157, s6, v154
	ds_read_b128 v[146:149], v157
	ds_read_b128 v[158:161], v157 offset:1024
	ds_read_b128 v[162:165], v157 offset:2048
	ds_read_b128 v[166:169], v157 offset:3072
	s_add_u32 s52, s52, 0x40000
	s_addc_u32 s53, s53, 0
	s_mov_b32 m0, s68
	v_lshl_add_u64 v[218:219], s[52:53], 0, v[128:129]
	ds_read_b128 v[170:173], v156 offset:32768
	ds_read_b128 v[174:177], v156 offset:33792
	ds_read_b128 v[178:181], v156 offset:34816
	ds_read_b128 v[182:185], v156 offset:35840
	ds_read_b128 v[194:197], v156 offset:36864
	ds_read_b128 v[206:209], v156 offset:37888
	ds_read_b128 v[210:213], v156 offset:38912
	ds_read_b128 v[214:217], v156 offset:39936
	global_load_lds_dwordx4 v[218:219], off
	v_lshl_add_u64 v[218:219], s[52:53], 0, v[130:131]
	s_mov_b32 m0, s69
	s_nop 0
	global_load_lds_dwordx4 v[218:219], off
	s_add_i32 s19, 0, 0x1c000
	v_add_u32_e32 v157, s19, v154
	ds_read_b128 v[218:221], v157
	ds_read_b128 v[222:225], v157 offset:1024
	ds_read_b128 v[226:229], v157 offset:2048
	ds_read_b128 v[230:233], v157 offset:3072
	s_waitcnt vmcnt(8)
	s_waitcnt lgkmcnt(0)
	s_barrier
	v_mfma_f32_16x16x32_bf16 v[124:127], v[146:149], v[170:173], v[124:127]
	v_mfma_f32_16x16x32_bf16 v[120:123], v[162:165], v[170:173], v[120:123]
	v_mfma_f32_16x16x32_bf16 v[116:119], v[146:149], v[178:181], v[116:119]
	v_mfma_f32_16x16x32_bf16 v[112:115], v[162:165], v[178:181], v[112:115]
	v_mfma_f32_16x16x32_bf16 v[108:111], v[146:149], v[194:197], v[108:111]
	v_mfma_f32_16x16x32_bf16 v[104:107], v[162:165], v[194:197], v[104:107]
	v_mfma_f32_16x16x32_bf16 v[100:103], v[146:149], v[210:213], v[100:103]
	v_mfma_f32_16x16x32_bf16 v[96:99], v[162:165], v[210:213], v[96:99]
	v_mfma_f32_16x16x32_bf16 v[124:127], v[158:161], v[174:177], v[124:127]
	v_mfma_f32_16x16x32_bf16 v[120:123], v[166:169], v[174:177], v[120:123]
	v_mfma_f32_16x16x32_bf16 v[116:119], v[158:161], v[182:185], v[116:119]
	v_mfma_f32_16x16x32_bf16 v[112:115], v[166:169], v[182:185], v[112:115]
	v_mfma_f32_16x16x32_bf16 v[108:111], v[158:161], v[206:209], v[108:111]
	v_mfma_f32_16x16x32_bf16 v[104:107], v[166:169], v[206:209], v[104:107]
	v_mfma_f32_16x16x32_bf16 v[100:103], v[158:161], v[214:217], v[100:103]
	v_mfma_f32_16x16x32_bf16 v[96:99], v[166:169], v[214:217], v[96:99]
	v_mfma_f32_16x16x32_bf16 v[92:95], v[218:221], v[170:173], v[92:95]
	v_mfma_f32_16x16x32_bf16 v[88:91], v[226:229], v[170:173], v[88:91]
	v_mfma_f32_16x16x32_bf16 v[84:87], v[218:221], v[178:181], v[84:87]
	v_mfma_f32_16x16x32_bf16 v[80:83], v[226:229], v[178:181], v[80:83]
	v_mfma_f32_16x16x32_bf16 v[76:79], v[218:221], v[194:197], v[76:79]
	v_mfma_f32_16x16x32_bf16 v[72:75], v[226:229], v[194:197], v[72:75]
	v_mfma_f32_16x16x32_bf16 v[68:71], v[218:221], v[210:213], v[68:71]
	v_mfma_f32_16x16x32_bf16 v[64:67], v[226:229], v[210:213], v[64:67]
	v_mfma_f32_16x16x32_bf16 v[92:95], v[222:225], v[174:177], v[92:95]
	v_mfma_f32_16x16x32_bf16 v[88:91], v[230:233], v[174:177], v[88:91]
	v_mfma_f32_16x16x32_bf16 v[84:87], v[222:225], v[182:185], v[84:87]
	v_mfma_f32_16x16x32_bf16 v[80:83], v[230:233], v[182:185], v[80:83]
	v_mfma_f32_16x16x32_bf16 v[76:79], v[222:225], v[206:209], v[76:79]
	v_mfma_f32_16x16x32_bf16 v[72:75], v[230:233], v[206:209], v[72:75]
	v_mfma_f32_16x16x32_bf16 v[68:71], v[222:225], v[214:217], v[68:71]
	v_mfma_f32_16x16x32_bf16 v[64:67], v[230:233], v[214:217], v[64:67]
	s_barrier
	s_add_i32 s6, s6, s57
	v_lshl_add_u64 v[234:235], v[234:235], 0, s[36:37]
	s_mov_b32 m0, s6
	s_nop 0
	global_load_lds_dwordx4 v[234:235], off
	v_lshl_add_u64 v[234:235], v[236:237], 0, s[36:37]
	s_add_i32 m0, s6, 0x2000
	s_nop 0
	global_load_lds_dwordx4 v[234:235], off
	s_mov_b32 m0, s71
	v_lshl_add_u64 v[234:235], v[238:239], 0, s[36:37]
	ds_read_b128 v[170:173], v156 offset:49152
	ds_read_b128 v[174:177], v156 offset:50176
	ds_read_b128 v[178:181], v156 offset:51200
	ds_read_b128 v[182:185], v156 offset:52224
	ds_read_b128 v[194:197], v156 offset:53248
	ds_read_b128 v[206:209], v156 offset:54272
	ds_read_b128 v[210:213], v156 offset:55296
	ds_read_b128 v[214:217], v156 offset:56320
	global_load_lds_dwordx4 v[234:235], off
	v_lshl_add_u64 v[234:235], v[240:241], 0, s[36:37]
	s_mov_b32 m0, s72
	s_nop 0
	global_load_lds_dwordx4 v[234:235], off
	s_add_u32 s50, s50, 0x40080
	s_addc_u32 s51, s51, 0
	s_add_i32 s6, s19, s57
	v_lshl_add_u64 v[250:251], s[50:51], 0, v[140:141]
	s_mov_b32 m0, s6
	s_nop 0
	global_load_lds_dwordx4 v[250:251], off
	v_lshl_add_u64 v[250:251], s[50:51], 0, v[132:133]
	s_add_i32 m0, s6, 0x2000
	s_nop 0
	global_load_lds_dwordx4 v[250:251], off
	s_add_i32 s75, s75, 2
	s_add_u32 s48, s48, 0x100
	s_addc_u32 s49, s49, 0
	s_cmp_gt_u32 s75, 13
	s_nop 0
	s_waitcnt vmcnt(8)
	s_waitcnt lgkmcnt(0)
	s_barrier
	v_mfma_f32_16x16x32_bf16 v[60:63], v[146:149], v[170:173], v[60:63]
	v_mfma_f32_16x16x32_bf16 v[56:59], v[162:165], v[170:173], v[56:59]
	v_mfma_f32_16x16x32_bf16 v[52:55], v[146:149], v[178:181], v[52:55]
	v_mfma_f32_16x16x32_bf16 v[48:51], v[162:165], v[178:181], v[48:51]
	v_mfma_f32_16x16x32_bf16 v[44:47], v[146:149], v[194:197], v[44:47]
	v_mfma_f32_16x16x32_bf16 v[40:43], v[162:165], v[194:197], v[40:43]
	v_mfma_f32_16x16x32_bf16 v[36:39], v[146:149], v[210:213], v[36:39]
	v_mfma_f32_16x16x32_bf16 v[32:35], v[162:165], v[210:213], v[32:35]
	v_mfma_f32_16x16x32_bf16 v[60:63], v[158:161], v[174:177], v[60:63]
	v_mfma_f32_16x16x32_bf16 v[56:59], v[166:169], v[174:177], v[56:59]
	v_mfma_f32_16x16x32_bf16 v[52:55], v[158:161], v[182:185], v[52:55]
	v_mfma_f32_16x16x32_bf16 v[48:51], v[166:169], v[182:185], v[48:51]
	v_mfma_f32_16x16x32_bf16 v[44:47], v[158:161], v[206:209], v[44:47]
	v_mfma_f32_16x16x32_bf16 v[40:43], v[166:169], v[206:209], v[40:43]
	v_mfma_f32_16x16x32_bf16 v[36:39], v[158:161], v[214:217], v[36:39]
	v_mfma_f32_16x16x32_bf16 v[32:35], v[166:169], v[214:217], v[32:35]
	v_mfma_f32_16x16x32_bf16 v[28:31], v[218:221], v[170:173], v[28:31]
	v_mfma_f32_16x16x32_bf16 v[24:27], v[226:229], v[170:173], v[24:27]
	v_mfma_f32_16x16x32_bf16 v[20:23], v[218:221], v[178:181], v[20:23]
	v_mfma_f32_16x16x32_bf16 v[16:19], v[226:229], v[178:181], v[16:19]
	v_mfma_f32_16x16x32_bf16 v[12:15], v[218:221], v[194:197], v[12:15]
	v_mfma_f32_16x16x32_bf16 v[8:11], v[226:229], v[194:197], v[8:11]
	v_mfma_f32_16x16x32_bf16 v[4:7], v[218:221], v[210:213], v[4:7]
	v_mfma_f32_16x16x32_bf16 v[0:3], v[226:229], v[210:213], v[0:3]
	v_mfma_f32_16x16x32_bf16 v[28:31], v[222:225], v[174:177], v[28:31]
	v_mfma_f32_16x16x32_bf16 v[24:27], v[230:233], v[174:177], v[24:27]
	v_mfma_f32_16x16x32_bf16 v[20:23], v[222:225], v[182:185], v[20:23]
	v_mfma_f32_16x16x32_bf16 v[16:19], v[230:233], v[182:185], v[16:19]
	v_mfma_f32_16x16x32_bf16 v[12:15], v[222:225], v[206:209], v[12:15]
	v_mfma_f32_16x16x32_bf16 v[8:11], v[230:233], v[206:209], v[8:11]
	v_mfma_f32_16x16x32_bf16 v[4:7], v[222:225], v[214:217], v[4:7]
	v_mfma_f32_16x16x32_bf16 v[0:3], v[230:233], v[214:217], v[0:3]
	s_barrier
	s_cbranch_scc0 .LBB0_315
	s_mov_b32 s100, 1
	s_add_u32 s48, s11, 0xffffff00
	v_lshl_or_b32 v146, s70, 8, v155
	s_addc_u32 s49, s12, -1
	s_ashr_i32 s29, s28, 31
	v_ashrrev_i32_e32 v147, 31, v146
	v_lshl_add_u64 v[146:147], v[146:147], 1, s[26:27]
	s_lshl_b64 s[50:51], s[28:29], 20
	v_lshl_add_u64 v[146:147], v[146:147], 0, s[50:51]
	v_lshl_add_u64 v[150:151], v[146:147], 0, v[134:135]
	v_cvt_pk_bf16_f32 v146, v124, v125
	v_cvt_pk_bf16_f32 v147, v126, v127
	v_cvt_pk_bf16_f32 v148, v120, v121
	v_cvt_pk_bf16_f32 v149, v122, v123
	global_store_dwordx4 v[150:151], v[146:149], off
	v_add_co_u32_e32 v152, vcc, s66, v150
	s_nop 0
	v_cvt_pk_bf16_f32 v146, v92, v93
	v_cvt_pk_bf16_f32 v147, v94, v95
	v_cvt_pk_bf16_f32 v148, v88, v89
	v_cvt_pk_bf16_f32 v149, v90, v91
	global_store_dwordx4 v[150:151], v[146:149], off offset:256
	v_addc_co_u32_e32 v153, vcc, 0, v151, vcc
	s_nop 0
	v_cvt_pk_bf16_f32 v146, v116, v117
	v_cvt_pk_bf16_f32 v147, v118, v119
	v_cvt_pk_bf16_f32 v148, v112, v113
	v_cvt_pk_bf16_f32 v149, v114, v115
	global_store_dwordx4 v[152:153], v[146:149], off
	s_mov_b32 s6, 0x20000
	s_nop 0
	v_cvt_pk_bf16_f32 v146, v84, v85
	v_cvt_pk_bf16_f32 v147, v86, v87
	v_cvt_pk_bf16_f32 v148, v80, v81
	v_cvt_pk_bf16_f32 v149, v82, v83
	global_store_dwordx4 v[152:153], v[146:149], off offset:256
	v_add_co_u32_e32 v152, vcc, s6, v150
	s_nop 0
	v_cvt_pk_bf16_f32 v146, v108, v109
	v_cvt_pk_bf16_f32 v147, v110, v111
	v_cvt_pk_bf16_f32 v148, v104, v105
	v_cvt_pk_bf16_f32 v149, v106, v107
	v_addc_co_u32_e32 v153, vcc, 0, v151, vcc
	global_store_dwordx4 v[152:153], v[146:149], off
	s_mov_b32 s6, 0x30000
	s_nop 0
	v_cvt_pk_bf16_f32 v146, v76, v77
	v_cvt_pk_bf16_f32 v147, v78, v79
	v_cvt_pk_bf16_f32 v148, v72, v73
	v_cvt_pk_bf16_f32 v149, v74, v75
	global_store_dwordx4 v[152:153], v[146:149], off offset:256
	v_add_co_u32_e32 v152, vcc, s6, v150
	s_nop 0
	v_cvt_pk_bf16_f32 v146, v100, v101
	v_cvt_pk_bf16_f32 v147, v102, v103
	v_cvt_pk_bf16_f32 v148, v96, v97
	v_cvt_pk_bf16_f32 v149, v98, v99
	v_addc_co_u32_e32 v153, vcc, 0, v151, vcc
	global_store_dwordx4 v[152:153], v[146:149], off
	s_mov_b32 s6, 0x80000
	s_nop 0
	v_cvt_pk_bf16_f32 v146, v68, v69
	v_cvt_pk_bf16_f32 v147, v70, v71
	v_cvt_pk_bf16_f32 v148, v64, v65
	v_cvt_pk_bf16_f32 v149, v66, v67
	global_store_dwordx4 v[152:153], v[146:149], off offset:256
	v_add_co_u32_e32 v152, vcc, s6, v150
	s_nop 0
	v_cvt_pk_bf16_f32 v146, v60, v61
	v_cvt_pk_bf16_f32 v147, v62, v63
	v_cvt_pk_bf16_f32 v148, v56, v57
	v_cvt_pk_bf16_f32 v149, v58, v59
	v_addc_co_u32_e32 v153, vcc, 0, v151, vcc
	global_store_dwordx4 v[152:153], v[146:149], off
	s_mov_b32 s6, 0x90000
	s_nop 0
	v_cvt_pk_bf16_f32 v146, v28, v29
	v_cvt_pk_bf16_f32 v147, v30, v31
	v_cvt_pk_bf16_f32 v148, v24, v25
	v_cvt_pk_bf16_f32 v149, v26, v27
	global_store_dwordx4 v[152:153], v[146:149], off offset:256
	v_add_co_u32_e32 v152, vcc, s6, v150
	s_nop 0
	v_cvt_pk_bf16_f32 v146, v52, v53
	v_cvt_pk_bf16_f32 v147, v54, v55
	v_cvt_pk_bf16_f32 v148, v48, v49
	v_cvt_pk_bf16_f32 v149, v50, v51
	v_addc_co_u32_e32 v153, vcc, 0, v151, vcc
	global_store_dwordx4 v[152:153], v[146:149], off
	s_mov_b32 s6, 0xa0000
	s_nop 0
	v_cvt_pk_bf16_f32 v146, v20, v21
	v_cvt_pk_bf16_f32 v147, v22, v23
	v_cvt_pk_bf16_f32 v148, v16, v17
	v_cvt_pk_bf16_f32 v149, v18, v19
	global_store_dwordx4 v[152:153], v[146:149], off offset:256
	v_add_co_u32_e32 v152, vcc, s6, v150
	s_nop 0
	v_cvt_pk_bf16_f32 v146, v44, v45
	v_cvt_pk_bf16_f32 v147, v46, v47
	v_cvt_pk_bf16_f32 v148, v40, v41
	v_cvt_pk_bf16_f32 v149, v42, v43
	v_addc_co_u32_e32 v153, vcc, 0, v151, vcc
	s_mov_b32 s6, 0xb0000
	global_store_dwordx4 v[152:153], v[146:149], off
	v_add_co_u32_e32 v150, vcc, s6, v150
	s_nop 0
	v_cvt_pk_bf16_f32 v146, v12, v13
	v_cvt_pk_bf16_f32 v147, v14, v15
	v_cvt_pk_bf16_f32 v148, v8, v9
	v_cvt_pk_bf16_f32 v149, v10, v11
	global_store_dwordx4 v[152:153], v[146:149], off offset:256
	v_addc_co_u32_e32 v151, vcc, 0, v151, vcc
	s_nop 0
	v_cvt_pk_bf16_f32 v146, v36, v37
	v_cvt_pk_bf16_f32 v147, v38, v39
	v_cvt_pk_bf16_f32 v148, v32, v33
	v_cvt_pk_bf16_f32 v149, v34, v35
	global_store_dwordx4 v[150:151], v[146:149], off
	s_andn2_b64 vcc, exec, s[44:45]
	s_nop 0
	v_cvt_pk_bf16_f32 v146, v4, v5
	v_cvt_pk_bf16_f32 v147, v6, v7
	v_cvt_pk_bf16_f32 v148, v0, v1
	v_cvt_pk_bf16_f32 v149, v2, v3
	global_store_dwordx4 v[150:151], v[146:149], off offset:256
	s_cbranch_vccz .LBB0_307
	s_mov_b64 s[42:43], s[48:49]
	s_andn2_b64 vcc, exec, s[38:39]
	s_mov_b64 s[48:49], s[42:43]
	s_cbranch_vccnz .LBB0_308

.LBB0_341:
	s_add_u32 s46, s50, 0x100
	s_addc_u32 s47, s51, 0
	s_add_i32 s6, 0, 0x10000
	v_add_u32_e32 v146, s6, v206
	ds_read_b128 v[128:131], v146
	ds_read_b128 v[132:135], v146 offset:1024
	ds_read_b128 v[136:139], v146 offset:2048
	ds_read_b128 v[146:149], v146 offset:3072
	s_cmp_eq_u32 s12, 40
	s_cselect_b32 s53, s31, s47
	s_cselect_b32 s52, s30, s46
	s_cselect_b32 s49, s35, s11
	s_cselect_b32 s48, s34, s10
	v_lshl_add_u64 v[214:215], s[50:51], 0, v[158:159]
	s_add_i32 m0, s58, 0xc000
	ds_read_b128 v[162:165], v208
	ds_read_b128 v[166:169], v208 offset:1024
	ds_read_b128 v[170:173], v208 offset:2048
	ds_read_b128 v[174:177], v208 offset:3072
	ds_read_b128 v[178:181], v208 offset:4096
	ds_read_b128 v[182:185], v208 offset:5120
	ds_read_b128 v[194:197], v208 offset:6144
	ds_read_b128 v[210:213], v208 offset:7168
	global_load_lds_dwordx4 v[214:215], off
	v_lshl_add_u64 v[214:215], s[50:51], 0, v[160:161]
	s_add_i32 m0, s58, 0xe000
	s_nop 0
	global_load_lds_dwordx4 v[214:215], off
	s_add_i32 s19, 0, 0x14000
	v_add_u32_e32 v192, s19, v206
	ds_read_b128 v[214:217], v192
	ds_read_b128 v[218:221], v192 offset:1024
	ds_read_b128 v[222:225], v192 offset:2048
	ds_read_b128 v[226:229], v192 offset:3072
	s_nop 0
	s_waitcnt vmcnt(8)
	s_waitcnt lgkmcnt(0)
	s_barrier
	v_mfma_f32_16x16x32_bf16 v[124:127], v[128:131], v[162:165], v[124:127]
	v_mfma_f32_16x16x32_bf16 v[120:123], v[136:139], v[162:165], v[120:123]
	v_mfma_f32_16x16x32_bf16 v[108:111], v[128:131], v[170:173], v[108:111]
	v_mfma_f32_16x16x32_bf16 v[104:107], v[136:139], v[170:173], v[104:107]
	v_mfma_f32_16x16x32_bf16 v[96:99], v[128:131], v[178:181], v[96:99]
	v_mfma_f32_16x16x32_bf16 v[88:91], v[136:139], v[178:181], v[88:91]
	v_mfma_f32_16x16x32_bf16 v[84:87], v[128:131], v[194:197], v[84:87]
	v_mfma_f32_16x16x32_bf16 v[80:83], v[136:139], v[194:197], v[80:83]
	v_mfma_f32_16x16x32_bf16 v[124:127], v[132:135], v[166:169], v[124:127]
	v_mfma_f32_16x16x32_bf16 v[120:123], v[146:149], v[166:169], v[120:123]
	v_mfma_f32_16x16x32_bf16 v[108:111], v[132:135], v[174:177], v[108:111]
	v_mfma_f32_16x16x32_bf16 v[104:107], v[146:149], v[174:177], v[104:107]
	v_mfma_f32_16x16x32_bf16 v[96:99], v[132:135], v[182:185], v[96:99]
	v_mfma_f32_16x16x32_bf16 v[88:91], v[146:149], v[182:185], v[88:91]
	v_mfma_f32_16x16x32_bf16 v[84:87], v[132:135], v[210:213], v[84:87]
	v_mfma_f32_16x16x32_bf16 v[80:83], v[146:149], v[210:213], v[80:83]
	v_mfma_f32_16x16x32_bf16 v[116:119], v[214:217], v[162:165], v[116:119]
	v_mfma_f32_16x16x32_bf16 v[112:115], v[222:225], v[162:165], v[112:115]
	v_mfma_f32_16x16x32_bf16 v[100:103], v[214:217], v[170:173], v[100:103]
	v_mfma_f32_16x16x32_bf16 v[92:95], v[222:225], v[170:173], v[92:95]
	v_mfma_f32_16x16x32_bf16 v[76:79], v[214:217], v[178:181], v[76:79]
	v_mfma_f32_16x16x32_bf16 v[72:75], v[222:225], v[178:181], v[72:75]
	v_mfma_f32_16x16x32_bf16 v[68:71], v[214:217], v[194:197], v[68:71]
	v_mfma_f32_16x16x32_bf16 v[64:67], v[222:225], v[194:197], v[64:67]
	v_mfma_f32_16x16x32_bf16 v[116:119], v[218:221], v[166:169], v[116:119]
	v_mfma_f32_16x16x32_bf16 v[112:115], v[226:229], v[166:169], v[112:115]
	v_mfma_f32_16x16x32_bf16 v[100:103], v[218:221], v[174:177], v[100:103]
	v_mfma_f32_16x16x32_bf16 v[92:95], v[226:229], v[174:177], v[92:95]
	v_mfma_f32_16x16x32_bf16 v[76:79], v[218:221], v[182:185], v[76:79]
	v_mfma_f32_16x16x32_bf16 v[72:75], v[226:229], v[182:185], v[72:75]
	v_mfma_f32_16x16x32_bf16 v[68:71], v[218:221], v[210:213], v[68:71]
	v_mfma_f32_16x16x32_bf16 v[64:67], v[226:229], v[210:213], v[64:67]
	s_barrier
	s_add_i32 s6, s6, s57
	v_lshl_add_u64 v[230:231], s[48:49], 0, v[140:141]
	s_mov_b32 m0, s6
	s_nop 0
	global_load_lds_dwordx4 v[230:231], off
	v_lshl_add_u64 v[232:233], s[48:49], 0, v[150:151]
	s_add_i32 m0, s6, 0x2000
	s_nop 0
	global_load_lds_dwordx4 v[232:233], off
	s_mov_b32 m0, s58
	v_lshl_add_u64 v[234:235], s[52:53], 0, v[154:155]
	ds_read_b128 v[162:165], v208 offset:16384
	ds_read_b128 v[166:169], v208 offset:17408
	ds_read_b128 v[170:173], v208 offset:18432
	ds_read_b128 v[174:177], v208 offset:19456
	ds_read_b128 v[178:181], v208 offset:20480
	ds_read_b128 v[182:185], v208 offset:21504
	ds_read_b128 v[194:197], v208 offset:22528
	ds_read_b128 v[210:213], v208 offset:23552
	global_load_lds_dwordx4 v[234:235], off
	v_lshl_add_u64 v[236:237], s[52:53], 0, v[152:153]
	s_mov_b32 m0, s59
	s_nop 0
	global_load_lds_dwordx4 v[236:237], off
	s_add_u32 s50, s48, 0xb0000
	s_addc_u32 s51, s49, 0
	s_add_i32 s6, s19, s57
	v_lshl_add_u64 v[250:251], s[50:51], 0, v[140:141]
	s_mov_b32 m0, s6
	s_nop 0
	global_load_lds_dwordx4 v[250:251], off
	v_lshl_add_u64 v[250:251], s[50:51], 0, v[150:151]
	s_add_i32 m0, s6, 0x2000
	s_nop 0
	global_load_lds_dwordx4 v[250:251], off
	s_waitcnt vmcnt(8)
	s_waitcnt lgkmcnt(0)
	s_barrier
	v_mfma_f32_16x16x32_bf16 v[60:63], v[128:131], v[162:165], v[60:63]
	v_mfma_f32_16x16x32_bf16 v[56:59], v[136:139], v[162:165], v[56:59]
	v_mfma_f32_16x16x32_bf16 v[48:51], v[128:131], v[170:173], v[48:51]
	v_mfma_f32_16x16x32_bf16 v[40:43], v[136:139], v[170:173], v[40:43]
	v_mfma_f32_16x16x32_bf16 v[32:35], v[128:131], v[178:181], v[32:35]
	v_mfma_f32_16x16x32_bf16 v[24:27], v[136:139], v[178:181], v[24:27]
	v_mfma_f32_16x16x32_bf16 v[16:19], v[128:131], v[194:197], v[16:19]
	v_mfma_f32_16x16x32_bf16 v[8:11], v[136:139], v[194:197], v[8:11]
	v_mfma_f32_16x16x32_bf16 v[60:63], v[132:135], v[166:169], v[60:63]
	v_mfma_f32_16x16x32_bf16 v[56:59], v[146:149], v[166:169], v[56:59]
	v_mfma_f32_16x16x32_bf16 v[48:51], v[132:135], v[174:177], v[48:51]
	v_mfma_f32_16x16x32_bf16 v[40:43], v[146:149], v[174:177], v[40:43]
	v_mfma_f32_16x16x32_bf16 v[32:35], v[132:135], v[182:185], v[32:35]
	v_mfma_f32_16x16x32_bf16 v[24:27], v[146:149], v[182:185], v[24:27]
	v_mfma_f32_16x16x32_bf16 v[16:19], v[132:135], v[210:213], v[16:19]
	v_mfma_f32_16x16x32_bf16 v[8:11], v[146:149], v[210:213], v[8:11]
	v_mfma_f32_16x16x32_bf16 v[52:55], v[214:217], v[162:165], v[52:55]
	v_mfma_f32_16x16x32_bf16 v[44:47], v[222:225], v[162:165], v[44:47]
	v_mfma_f32_16x16x32_bf16 v[36:39], v[214:217], v[170:173], v[36:39]
	v_mfma_f32_16x16x32_bf16 v[28:31], v[222:225], v[170:173], v[28:31]
	v_mfma_f32_16x16x32_bf16 v[20:23], v[214:217], v[178:181], v[20:23]
	v_mfma_f32_16x16x32_bf16 v[12:15], v[222:225], v[178:181], v[12:15]
	v_mfma_f32_16x16x32_bf16 v[4:7], v[214:217], v[194:197], v[4:7]
	v_mfma_f32_16x16x32_bf16 v[0:3], v[222:225], v[194:197], v[0:3]
	v_mfma_f32_16x16x32_bf16 v[52:55], v[218:221], v[166:169], v[52:55]
	v_mfma_f32_16x16x32_bf16 v[44:47], v[226:229], v[166:169], v[44:47]
	v_mfma_f32_16x16x32_bf16 v[36:39], v[218:221], v[174:177], v[36:39]
	v_mfma_f32_16x16x32_bf16 v[28:31], v[226:229], v[174:177], v[28:31]
	v_mfma_f32_16x16x32_bf16 v[20:23], v[218:221], v[182:185], v[20:23]
	v_mfma_f32_16x16x32_bf16 v[12:15], v[226:229], v[182:185], v[12:15]
	v_mfma_f32_16x16x32_bf16 v[4:7], v[218:221], v[210:213], v[4:7]
	v_mfma_f32_16x16x32_bf16 v[0:3], v[226:229], v[210:213], v[0:3]
	s_barrier
	s_add_i32 s6, 0, 0x18000
	v_add_u32_e32 v146, s6, v206
	ds_read_b128 v[128:131], v146
	ds_read_b128 v[132:135], v146 offset:1024
	ds_read_b128 v[136:139], v146 offset:2048
	ds_read_b128 v[146:149], v146 offset:3072
	s_add_u32 s50, s52, 0xb0000
	s_addc_u32 s51, s53, 0
	s_mov_b32 m0, s68
	v_lshl_add_u64 v[214:215], s[50:51], 0, v[154:155]
	ds_read_b128 v[162:165], v208 offset:32768
	ds_read_b128 v[166:169], v208 offset:33792
	ds_read_b128 v[170:173], v208 offset:34816
	ds_read_b128 v[174:177], v208 offset:35840
	ds_read_b128 v[178:181], v208 offset:36864
	ds_read_b128 v[182:185], v208 offset:37888
	ds_read_b128 v[194:197], v208 offset:38912
	ds_read_b128 v[210:213], v208 offset:39936
	global_load_lds_dwordx4 v[214:215], off
	v_lshl_add_u64 v[214:215], s[50:51], 0, v[152:153]
	s_mov_b32 m0, s69
	s_nop 0
	global_load_lds_dwordx4 v[214:215], off
	s_add_i32 s19, 0, 0x1c000
	v_add_u32_e32 v192, s19, v206
	ds_read_b128 v[214:217], v192
	ds_read_b128 v[218:221], v192 offset:1024
	ds_read_b128 v[222:225], v192 offset:2048
	ds_read_b128 v[226:229], v192 offset:3072
	s_waitcnt vmcnt(8)
	s_waitcnt lgkmcnt(0)
	s_barrier
	v_mfma_f32_16x16x32_bf16 v[124:127], v[128:131], v[162:165], v[124:127]
	v_mfma_f32_16x16x32_bf16 v[120:123], v[136:139], v[162:165], v[120:123]
	v_mfma_f32_16x16x32_bf16 v[108:111], v[128:131], v[170:173], v[108:111]
	v_mfma_f32_16x16x32_bf16 v[104:107], v[136:139], v[170:173], v[104:107]
	v_mfma_f32_16x16x32_bf16 v[96:99], v[128:131], v[178:181], v[96:99]
	v_mfma_f32_16x16x32_bf16 v[88:91], v[136:139], v[178:181], v[88:91]
	v_mfma_f32_16x16x32_bf16 v[84:87], v[128:131], v[194:197], v[84:87]
	v_mfma_f32_16x16x32_bf16 v[80:83], v[136:139], v[194:197], v[80:83]
	v_mfma_f32_16x16x32_bf16 v[124:127], v[132:135], v[166:169], v[124:127]
	v_mfma_f32_16x16x32_bf16 v[120:123], v[146:149], v[166:169], v[120:123]
	v_mfma_f32_16x16x32_bf16 v[108:111], v[132:135], v[174:177], v[108:111]
	v_mfma_f32_16x16x32_bf16 v[104:107], v[146:149], v[174:177], v[104:107]
	v_mfma_f32_16x16x32_bf16 v[96:99], v[132:135], v[182:185], v[96:99]
	v_mfma_f32_16x16x32_bf16 v[88:91], v[146:149], v[182:185], v[88:91]
	v_mfma_f32_16x16x32_bf16 v[84:87], v[132:135], v[210:213], v[84:87]
	v_mfma_f32_16x16x32_bf16 v[80:83], v[146:149], v[210:213], v[80:83]
	v_mfma_f32_16x16x32_bf16 v[116:119], v[214:217], v[162:165], v[116:119]
	v_mfma_f32_16x16x32_bf16 v[112:115], v[222:225], v[162:165], v[112:115]
	v_mfma_f32_16x16x32_bf16 v[100:103], v[214:217], v[170:173], v[100:103]
	v_mfma_f32_16x16x32_bf16 v[92:95], v[222:225], v[170:173], v[92:95]
	v_mfma_f32_16x16x32_bf16 v[76:79], v[214:217], v[178:181], v[76:79]
	v_mfma_f32_16x16x32_bf16 v[72:75], v[222:225], v[178:181], v[72:75]
	v_mfma_f32_16x16x32_bf16 v[68:71], v[214:217], v[194:197], v[68:71]
	v_mfma_f32_16x16x32_bf16 v[64:67], v[222:225], v[194:197], v[64:67]
	v_mfma_f32_16x16x32_bf16 v[116:119], v[218:221], v[166:169], v[116:119]
	v_mfma_f32_16x16x32_bf16 v[112:115], v[226:229], v[166:169], v[112:115]
	v_mfma_f32_16x16x32_bf16 v[100:103], v[218:221], v[174:177], v[100:103]
	v_mfma_f32_16x16x32_bf16 v[92:95], v[226:229], v[174:177], v[92:95]
	v_mfma_f32_16x16x32_bf16 v[76:79], v[218:221], v[182:185], v[76:79]
	v_mfma_f32_16x16x32_bf16 v[72:75], v[226:229], v[182:185], v[72:75]
	v_mfma_f32_16x16x32_bf16 v[68:71], v[218:221], v[210:213], v[68:71]
	v_mfma_f32_16x16x32_bf16 v[64:67], v[226:229], v[210:213], v[64:67]
	s_barrier
	s_add_i32 s6, s6, s57
	v_lshl_add_u64 v[230:231], v[230:231], 0, s[36:37]
	s_mov_b32 m0, s6
	s_nop 0
	global_load_lds_dwordx4 v[230:231], off
	v_lshl_add_u64 v[230:231], v[232:233], 0, s[36:37]
	s_add_i32 m0, s6, 0x2000
	s_nop 0
	global_load_lds_dwordx4 v[230:231], off
	s_mov_b32 m0, s70
	v_lshl_add_u64 v[230:231], v[234:235], 0, s[36:37]
	ds_read_b128 v[162:165], v208 offset:49152
	ds_read_b128 v[166:169], v208 offset:50176
	ds_read_b128 v[170:173], v208 offset:51200
	ds_read_b128 v[174:177], v208 offset:52224
	ds_read_b128 v[178:181], v208 offset:53248
	ds_read_b128 v[182:185], v208 offset:54272
	ds_read_b128 v[194:197], v208 offset:55296
	ds_read_b128 v[210:213], v208 offset:56320
	global_load_lds_dwordx4 v[230:231], off
	v_lshl_add_u64 v[230:231], v[236:237], 0, s[36:37]
	s_mov_b32 m0, s71
	s_nop 0
	global_load_lds_dwordx4 v[230:231], off
	s_add_u32 s48, s48, 0xb0080
	s_addc_u32 s49, s49, 0
	s_add_i32 s6, s19, s57
	v_lshl_add_u64 v[250:251], s[48:49], 0, v[140:141]
	s_mov_b32 m0, s6
	s_nop 0
	global_load_lds_dwordx4 v[250:251], off
	v_lshl_add_u64 v[250:251], s[48:49], 0, v[150:151]
	s_add_i32 m0, s6, 0x2000
	s_nop 0
	global_load_lds_dwordx4 v[250:251], off
	s_add_i32 s12, s12, 2
	s_add_u32 s10, s10, 0x100
	s_addc_u32 s11, s11, 0
	s_cmp_gt_u32 s12, 41
	s_mov_b64 s[50:51], s[46:47]
	s_waitcnt vmcnt(8)
	s_waitcnt lgkmcnt(0)
	s_barrier
	v_mfma_f32_16x16x32_bf16 v[60:63], v[128:131], v[162:165], v[60:63]
	v_mfma_f32_16x16x32_bf16 v[56:59], v[136:139], v[162:165], v[56:59]
	v_mfma_f32_16x16x32_bf16 v[48:51], v[128:131], v[170:173], v[48:51]
	v_mfma_f32_16x16x32_bf16 v[40:43], v[136:139], v[170:173], v[40:43]
	v_mfma_f32_16x16x32_bf16 v[32:35], v[128:131], v[178:181], v[32:35]
	v_mfma_f32_16x16x32_bf16 v[24:27], v[136:139], v[178:181], v[24:27]
	v_mfma_f32_16x16x32_bf16 v[16:19], v[128:131], v[194:197], v[16:19]
	v_mfma_f32_16x16x32_bf16 v[8:11], v[136:139], v[194:197], v[8:11]
	v_mfma_f32_16x16x32_bf16 v[60:63], v[132:135], v[166:169], v[60:63]
	v_mfma_f32_16x16x32_bf16 v[56:59], v[146:149], v[166:169], v[56:59]
	v_mfma_f32_16x16x32_bf16 v[48:51], v[132:135], v[174:177], v[48:51]
	v_mfma_f32_16x16x32_bf16 v[40:43], v[146:149], v[174:177], v[40:43]
	v_mfma_f32_16x16x32_bf16 v[32:35], v[132:135], v[182:185], v[32:35]
	v_mfma_f32_16x16x32_bf16 v[24:27], v[146:149], v[182:185], v[24:27]
	v_mfma_f32_16x16x32_bf16 v[16:19], v[132:135], v[210:213], v[16:19]
	v_mfma_f32_16x16x32_bf16 v[8:11], v[146:149], v[210:213], v[8:11]
	v_mfma_f32_16x16x32_bf16 v[52:55], v[214:217], v[162:165], v[52:55]
	v_mfma_f32_16x16x32_bf16 v[44:47], v[222:225], v[162:165], v[44:47]
	v_mfma_f32_16x16x32_bf16 v[36:39], v[214:217], v[170:173], v[36:39]
	v_mfma_f32_16x16x32_bf16 v[28:31], v[222:225], v[170:173], v[28:31]
	v_mfma_f32_16x16x32_bf16 v[20:23], v[214:217], v[178:181], v[20:23]
	v_mfma_f32_16x16x32_bf16 v[12:15], v[222:225], v[178:181], v[12:15]
	v_mfma_f32_16x16x32_bf16 v[4:7], v[214:217], v[194:197], v[4:7]
	v_mfma_f32_16x16x32_bf16 v[0:3], v[222:225], v[194:197], v[0:3]
	v_mfma_f32_16x16x32_bf16 v[52:55], v[218:221], v[166:169], v[52:55]
	v_mfma_f32_16x16x32_bf16 v[44:47], v[226:229], v[166:169], v[44:47]
	v_mfma_f32_16x16x32_bf16 v[36:39], v[218:221], v[174:177], v[36:39]
	v_mfma_f32_16x16x32_bf16 v[28:31], v[226:229], v[174:177], v[28:31]
	v_mfma_f32_16x16x32_bf16 v[20:23], v[218:221], v[182:185], v[20:23]
	v_mfma_f32_16x16x32_bf16 v[12:15], v[226:229], v[182:185], v[12:15]
	v_mfma_f32_16x16x32_bf16 v[4:7], v[218:221], v[210:213], v[4:7]
	v_mfma_f32_16x16x32_bf16 v[0:3], v[226:229], v[210:213], v[0:3]
	s_barrier
	s_cbranch_scc0 .LBB0_341
	s_mov_b32 s100, 1
	s_ashr_i32 s39, s38, 31
	v_lshl_or_b32 v128, s81, 8, v207
	s_lshl_b64 s[10:11], s[38:39], 8
	v_ashrrev_i32_e32 v129, 31, v128
	v_lshl_add_u64 v[168:169], s[10:11], 0, v[156:157]
	v_lshlrev_b64 v[170:171], 1, v[128:129]
	v_lshl_add_u64 v[174:175], s[26:27], 0, v[170:171]
	v_lshlrev_b64 v[172:173], 11, v[168:169]
	v_lshl_add_u64 v[128:129], v[174:175], 0, v[172:173]
	global_load_dwordx4 v[182:185], v[128:129], off
	global_load_dwordx4 v[210:213], v[128:129], off offset:256
	v_or_b32_e32 v166, 16, v168
	v_mov_b32_e32 v167, v169
	v_lshlrev_b64 v[176:177], 11, v[166:167]
	v_lshl_add_u64 v[128:129], v[174:175], 0, v[176:177]
	global_load_dwordx4 v[214:217], v[128:129], off
	global_load_dwordx4 v[218:221], v[128:129], off offset:256
	v_or_b32_e32 v164, 32, v168
	v_mov_b32_e32 v165, v169
	v_or_b32_e32 v162, 48, v168
	v_mov_b32_e32 v163, v169
	v_lshlrev_b64 v[180:181], 11, v[164:165]
	v_lshlrev_b64 v[178:179], 11, v[162:163]
	v_lshl_add_u64 v[128:129], v[174:175], 0, v[180:181]
	v_lshl_add_u64 v[130:131], v[174:175], 0, v[178:179]
	global_load_dwordx4 v[222:225], v[128:129], off
	global_load_dwordx4 v[136:139], v[128:129], off offset:256
	global_load_dwordx4 v[132:135], v[130:131], off
	s_nop 0
	global_load_dwordx4 v[128:131], v[130:131], off offset:256
	s_mov_b64 s[10:11], 0x90
	v_lshl_add_u64 v[172:173], s[28:29], 0, v[172:173]
	v_lshl_add_u64 v[172:173], v[172:173], 0, v[170:171]
	s_waitcnt vmcnt(0)
	v_lshlrev_b32_e32 v146, 16, v182
	v_and_b32_e32 v147, 0xffff0000, v182
	v_lshlrev_b32_e32 v148, 16, v184
	v_and_b32_e32 v149, 0xffff0000, v184
	v_lshlrev_b32_e32 v182, 16, v183
	v_and_b32_e32 v183, 0xffff0000, v183
	v_lshlrev_b32_e32 v194, 16, v210
	v_and_b32_e32 v195, 0xffff0000, v210
	v_lshlrev_b32_e32 v196, 16, v212
	v_and_b32_e32 v197, 0xffff0000, v212
	v_lshlrev_b32_e32 v210, 16, v211
	v_and_b32_e32 v211, 0xffff0000, v211
	v_lshlrev_b32_e32 v212, 16, v213
	v_and_b32_e32 v213, 0xffff0000, v213
	v_pk_fma_f32 v[124:125], v[124:125], 0.5, v[146:147] op_sel_hi:[1,0,1]
	v_pk_fma_f32 v[120:121], v[120:121], 0.5, v[148:149] op_sel_hi:[1,0,1]
	v_pk_fma_f32 v[126:127], v[126:127], 0.5, v[182:183] op_sel_hi:[1,0,1]
	v_pk_fma_f32 v[116:117], v[116:117], 0.5, v[194:195] op_sel_hi:[1,0,1]
	v_pk_fma_f32 v[146:147], v[112:113], 0.5, v[196:197] op_sel_hi:[1,0,1]
	v_pk_fma_f32 v[118:119], v[118:119], 0.5, v[210:211] op_sel_hi:[1,0,1]
	v_pk_fma_f32 v[148:149], v[114:115], 0.5, v[212:213] op_sel_hi:[1,0,1]
	v_pk_mul_f32 v[212:213], v[124:125], v[124:125]
	v_lshlrev_b32_e32 v182, 16, v214
	v_and_b32_e32 v183, 0xffff0000, v214
	v_lshlrev_b32_e32 v194, 16, v215
	v_and_b32_e32 v195, 0xffff0000, v215
	v_pk_mul_f32 v[214:215], v[126:127], v[126:127]
	v_cvt_pk_bf16_f32 v112, v124, v125
	v_cvt_pk_bf16_f32 v113, v126, v127
	v_pk_mul_f32 v[124:125], v[116:117], v[116:117]
	v_pk_mul_f32 v[126:127], v[118:119], v[118:119]
	v_pk_mul_f32 v[228:229], v[146:147], v[146:147]
	v_cvt_pk_bf16_f32 v116, v116, v117
	v_cvt_pk_bf16_f32 v117, v118, v119
	v_cvt_pk_bf16_f32 v118, v146, v147
	v_add_f32_e32 v146, v212, v213
	v_lshlrev_b32_e32 v184, 16, v185
	v_and_b32_e32 v185, 0xffff0000, v185
	v_add_f32_e32 v146, v214, v146
	v_pk_fma_f32 v[122:123], v[122:123], 0.5, v[184:185] op_sel_hi:[1,0,1]
	v_lshlrev_b32_e32 v184, 16, v216
	v_and_b32_e32 v185, 0xffff0000, v216
	v_lshlrev_b32_e32 v196, 16, v217
	v_and_b32_e32 v197, 0xffff0000, v217
	v_pk_mul_f32 v[216:217], v[120:121], v[120:121]
	v_add_f32_e32 v146, v215, v146
	v_add_f32_e32 v146, v216, v146
	v_pk_mul_f32 v[226:227], v[122:123], v[122:123]
	v_add_f32_e32 v146, v217, v146
	v_add_f32_e32 v146, v226, v146
	v_add_f32_e32 v146, v227, v146
	v_add_f32_e32 v124, v124, v146
	v_add_f32_e32 v124, v125, v124
	v_add_f32_e32 v124, v126, v124
	v_add_f32_e32 v124, v127, v124
	v_add_f32_e32 v124, v228, v124
	v_pk_mul_f32 v[230:231], v[148:149], v[148:149]
	v_add_f32_e32 v124, v229, v124
	v_add_f32_e32 v124, v230, v124
	v_add_f32_e32 v209, v231, v124
	v_lshlrev_b32_e32 v124, 16, v220
	v_and_b32_e32 v125, 0xffff0000, v220
	v_pk_fma_f32 v[124:125], v[92:93], 0.5, v[124:125] op_sel_hi:[1,0,1]
	v_lshlrev_b32_e32 v92, 16, v219
	v_and_b32_e32 v93, 0xffff0000, v219
	v_pk_fma_f32 v[102:103], v[102:103], 0.5, v[92:93] op_sel_hi:[1,0,1]
	v_lshlrev_b32_e32 v92, 16, v221
	v_and_b32_e32 v93, 0xffff0000, v221
	v_pk_fma_f32 v[126:127], v[94:95], 0.5, v[92:93] op_sel_hi:[1,0,1]
	v_lshlrev_b32_e32 v92, 16, v222
	v_and_b32_e32 v93, 0xffff0000, v222
	v_pk_fma_f32 v[92:93], v[96:97], 0.5, v[92:93] op_sel_hi:[1,0,1]
	v_lshlrev_b32_e32 v96, 16, v225
	v_and_b32_e32 v97, 0xffff0000, v225
	v_lshlrev_b32_e32 v94, 16, v224
	v_and_b32_e32 v95, 0xffff0000, v224
	v_pk_fma_f32 v[90:91], v[90:91], 0.5, v[96:97] op_sel_hi:[1,0,1]
	v_lshlrev_b32_e32 v96, 16, v136
	v_and_b32_e32 v97, 0xffff0000, v136
	v_pk_fma_f32 v[88:89], v[88:89], 0.5, v[94:95] op_sel_hi:[1,0,1]
	v_lshlrev_b32_e32 v94, 16, v223
	v_and_b32_e32 v95, 0xffff0000, v223
	v_pk_fma_f32 v[96:97], v[76:77], 0.5, v[96:97] op_sel_hi:[1,0,1]
	v_lshl_add_u64 v[76:77], v[168:169], 0, s[36:37]
	v_cvt_pk_bf16_f32 v114, v120, v121
	v_pk_fma_f32 v[120:121], v[108:109], 0.5, v[182:183] op_sel_hi:[1,0,1]
	v_pk_fma_f32 v[94:95], v[98:99], 0.5, v[94:95] op_sel_hi:[1,0,1]
	v_lshlrev_b64 v[182:183], 11, v[76:77]
	v_lshlrev_b32_e32 v98, 16, v138
	v_and_b32_e32 v99, 0xffff0000, v138
	v_lshl_add_u64 v[146:147], v[174:175], 0, v[182:183]
	v_pk_fma_f32 v[98:99], v[72:73], 0.5, v[98:99] op_sel_hi:[1,0,1]
	v_lshlrev_b32_e32 v72, 16, v137
	v_and_b32_e32 v73, 0xffff0000, v137
	v_lshlrev_b32_e32 v210, 16, v218
	v_and_b32_e32 v211, 0xffff0000, v218
	global_load_dwordx4 v[218:221], v[146:147], off
	global_load_dwordx4 v[226:229], v[146:147], off offset:256
	v_pk_fma_f32 v[136:137], v[78:79], 0.5, v[72:73] op_sel_hi:[1,0,1]
	v_lshlrev_b32_e32 v72, 16, v139
	v_and_b32_e32 v73, 0xffff0000, v139
	v_pk_fma_f32 v[138:139], v[74:75], 0.5, v[72:73] op_sel_hi:[1,0,1]
	v_lshlrev_b32_e32 v72, 16, v132
	v_and_b32_e32 v73, 0xffff0000, v132
	v_pk_fma_f32 v[74:75], v[84:85], 0.5, v[72:73] op_sel_hi:[1,0,1]
	v_lshlrev_b32_e32 v72, 16, v134
	v_and_b32_e32 v73, 0xffff0000, v134
	v_pk_fma_f32 v[78:79], v[80:81], 0.5, v[72:73] op_sel_hi:[1,0,1]
	v_lshlrev_b32_e32 v72, 16, v133
	v_and_b32_e32 v73, 0xffff0000, v133
	v_pk_fma_f32 v[80:81], v[86:87], 0.5, v[72:73] op_sel_hi:[1,0,1]
	v_lshlrev_b32_e32 v72, 16, v135
	v_and_b32_e32 v73, 0xffff0000, v135
	v_pk_fma_f32 v[82:83], v[82:83], 0.5, v[72:73] op_sel_hi:[1,0,1]
	v_lshl_add_u64 v[72:73], v[168:169], 0, s[10:11]
	v_lshlrev_b64 v[132:133], 11, v[72:73]
	v_lshl_add_u64 v[134:135], v[174:175], 0, v[132:133]
	global_load_dwordx4 v[234:237], v[134:135], off
	global_load_dwordx4 v[242:245], v[134:135], off offset:256
	v_lshlrev_b32_e32 v84, 16, v128
	v_and_b32_e32 v85, 0xffff0000, v128
	v_pk_fma_f32 v[84:85], v[68:69], 0.5, v[84:85] op_sel_hi:[1,0,1]
	v_lshlrev_b32_e32 v68, 16, v130
	v_and_b32_e32 v69, 0xffff0000, v130
	v_pk_fma_f32 v[86:87], v[64:65], 0.5, v[68:69] op_sel_hi:[1,0,1]
	v_lshlrev_b32_e32 v64, 16, v129
	v_and_b32_e32 v65, 0xffff0000, v129
	s_mov_b64 s[10:11], 0xa0
	v_pk_fma_f32 v[128:129], v[70:71], 0.5, v[64:65] op_sel_hi:[1,0,1]
	v_lshl_add_u64 v[70:71], v[168:169], 0, s[10:11]
	v_lshlrev_b32_e32 v64, 16, v131
	v_and_b32_e32 v65, 0xffff0000, v131
	v_lshlrev_b64 v[134:135], 11, v[70:71]
	v_pk_fma_f32 v[130:131], v[66:67], 0.5, v[64:65] op_sel_hi:[1,0,1]
	v_lshl_add_u64 v[64:65], v[174:175], 0, v[134:135]
	v_cvt_pk_bf16_f32 v115, v122, v123
	v_pk_fma_f32 v[122:123], v[110:111], 0.5, v[194:195] op_sel_hi:[1,0,1]
	v_pk_fma_f32 v[110:111], v[106:107], 0.5, v[196:197] op_sel_hi:[1,0,1]
	global_load_dwordx4 v[246:249], v[64:65], off
	global_load_dwordx4 v[194:197], v[64:65], off offset:256
	s_mov_b64 s[10:11], 0xb0
	v_lshl_add_u64 v[68:69], v[168:169], 0, s[10:11]
	v_pk_fma_f32 v[108:109], v[104:105], 0.5, v[184:185] op_sel_hi:[1,0,1]
	v_lshlrev_b64 v[184:185], 11, v[68:69]
	v_lshl_add_u64 v[64:65], v[174:175], 0, v[184:185]
	v_cvt_pk_bf16_f32 v119, v148, v149
	global_load_dwordx4 v[146:149], v[64:65], off
	s_nop 0
	global_load_dwordx4 v[64:67], v[64:65], off offset:256
	global_store_dwordx4 v[172:173], v[112:115], off
	global_store_dwordx4 v[172:173], v[116:119], off offset:256
	v_cvt_pk_bf16_f32 v104, v120, v121
	v_lshl_add_u64 v[112:113], s[28:29], 0, v[176:177]
	v_cvt_pk_bf16_f32 v105, v122, v123
	v_cvt_pk_bf16_f32 v106, v108, v109
	v_cvt_pk_bf16_f32 v107, v110, v111
	v_pk_fma_f32 v[100:101], v[100:101], 0.5, v[210:211] op_sel_hi:[1,0,1]
	v_lshl_add_u64 v[112:113], v[112:113], 0, v[170:171]
	v_cvt_pk_bf16_f32 v210, v100, v101
	v_cvt_pk_bf16_f32 v211, v102, v103
	v_cvt_pk_bf16_f32 v212, v124, v125
	v_cvt_pk_bf16_f32 v213, v126, v127
	global_store_dwordx4 v[112:113], v[104:107], off
	global_store_dwordx4 v[112:113], v[210:213], off offset:256
	v_cvt_pk_bf16_f32 v214, v92, v93
	v_lshl_add_u64 v[104:105], s[28:29], 0, v[180:181]
	v_cvt_pk_bf16_f32 v215, v94, v95
	v_cvt_pk_bf16_f32 v216, v88, v89
	v_cvt_pk_bf16_f32 v217, v90, v91
	v_lshl_add_u64 v[104:105], v[104:105], 0, v[170:171]
	v_cvt_pk_bf16_f32 v222, v96, v97
	v_cvt_pk_bf16_f32 v223, v136, v137
	v_cvt_pk_bf16_f32 v224, v98, v99
	v_cvt_pk_bf16_f32 v225, v138, v139
	global_store_dwordx4 v[104:105], v[214:217], off
	global_store_dwordx4 v[104:105], v[222:225], off offset:256
	v_lshl_add_u64 v[104:105], s[28:29], 0, v[178:179]
	v_cvt_pk_bf16_f32 v230, v74, v75
	v_cvt_pk_bf16_f32 v231, v80, v81
	v_cvt_pk_bf16_f32 v232, v78, v79
	v_cvt_pk_bf16_f32 v233, v82, v83
	v_lshl_add_u64 v[104:105], v[104:105], 0, v[170:171]
	v_cvt_pk_bf16_f32 v238, v84, v85
	v_cvt_pk_bf16_f32 v239, v128, v129
	v_cvt_pk_bf16_f32 v240, v86, v87
	v_cvt_pk_bf16_f32 v241, v130, v131
	global_store_dwordx4 v[104:105], v[230:233], off
	global_store_dwordx4 v[104:105], v[238:241], off offset:256
	s_waitcnt vmcnt(0)
	v_lshlrev_b32_e32 v104, 16, v218
	v_and_b32_e32 v105, 0xffff0000, v218
	v_pk_fma_f32 v[60:61], v[60:61], 0.5, v[104:105] op_sel_hi:[1,0,1]
	v_lshlrev_b32_e32 v104, 16, v220
	v_and_b32_e32 v105, 0xffff0000, v220
	v_pk_fma_f32 v[56:57], v[56:57], 0.5, v[104:105] op_sel_hi:[1,0,1]
	v_lshlrev_b32_e32 v104, 16, v219
	v_and_b32_e32 v105, 0xffff0000, v219
	v_pk_fma_f32 v[62:63], v[62:63], 0.5, v[104:105] op_sel_hi:[1,0,1]
	v_lshlrev_b32_e32 v104, 16, v221
	v_and_b32_e32 v105, 0xffff0000, v221
	v_pk_fma_f32 v[58:59], v[58:59], 0.5, v[104:105] op_sel_hi:[1,0,1]
	v_lshlrev_b32_e32 v104, 16, v226
	v_and_b32_e32 v105, 0xffff0000, v226
	v_pk_fma_f32 v[52:53], v[52:53], 0.5, v[104:105] op_sel_hi:[1,0,1]
	v_lshlrev_b32_e32 v104, 16, v228
	v_and_b32_e32 v105, 0xffff0000, v228
	v_pk_fma_f32 v[104:105], v[44:45], 0.5, v[104:105] op_sel_hi:[1,0,1]
	v_lshlrev_b32_e32 v44, 16, v227
	v_and_b32_e32 v45, 0xffff0000, v227
	v_pk_fma_f32 v[54:55], v[54:55], 0.5, v[44:45] op_sel_hi:[1,0,1]
	v_lshlrev_b32_e32 v44, 16, v229
	v_and_b32_e32 v45, 0xffff0000, v229
	v_pk_fma_f32 v[106:107], v[46:47], 0.5, v[44:45] op_sel_hi:[1,0,1]
	v_lshlrev_b32_e32 v44, 16, v234
	v_and_b32_e32 v45, 0xffff0000, v234
	v_pk_fma_f32 v[44:45], v[48:49], 0.5, v[44:45] op_sel_hi:[1,0,1]
	v_lshlrev_b32_e32 v48, 16, v237
	v_and_b32_e32 v49, 0xffff0000, v237
	v_pk_fma_f32 v[42:43], v[42:43], 0.5, v[48:49] op_sel_hi:[1,0,1]
	v_lshlrev_b32_e32 v48, 16, v242
	v_and_b32_e32 v49, 0xffff0000, v242
	v_pk_fma_f32 v[36:37], v[36:37], 0.5, v[48:49] op_sel_hi:[1,0,1]
	v_lshlrev_b32_e32 v48, 16, v244
	v_and_b32_e32 v49, 0xffff0000, v244
	v_lshlrev_b32_e32 v46, 16, v236
	v_and_b32_e32 v47, 0xffff0000, v236
	v_pk_fma_f32 v[48:49], v[28:29], 0.5, v[48:49] op_sel_hi:[1,0,1]
	v_lshlrev_b32_e32 v28, 16, v243
	v_and_b32_e32 v29, 0xffff0000, v243
	v_pk_fma_f32 v[40:41], v[40:41], 0.5, v[46:47] op_sel_hi:[1,0,1]
	v_lshlrev_b32_e32 v46, 16, v235
	v_and_b32_e32 v47, 0xffff0000, v235
	v_pk_fma_f32 v[38:39], v[38:39], 0.5, v[28:29] op_sel_hi:[1,0,1]
	v_lshlrev_b32_e32 v28, 16, v245
	v_and_b32_e32 v29, 0xffff0000, v245
	v_pk_fma_f32 v[46:47], v[50:51], 0.5, v[46:47] op_sel_hi:[1,0,1]
	v_pk_fma_f32 v[50:51], v[30:31], 0.5, v[28:29] op_sel_hi:[1,0,1]
	v_lshlrev_b32_e32 v28, 16, v246
	v_and_b32_e32 v29, 0xffff0000, v246
	v_pk_fma_f32 v[28:29], v[32:33], 0.5, v[28:29] op_sel_hi:[1,0,1]
	v_lshlrev_b32_e32 v32, 16, v249
	v_and_b32_e32 v33, 0xffff0000, v249
	v_pk_fma_f32 v[26:27], v[26:27], 0.5, v[32:33] op_sel_hi:[1,0,1]
	v_lshlrev_b32_e32 v32, 16, v194
	v_and_b32_e32 v33, 0xffff0000, v194
	v_pk_fma_f32 v[20:21], v[20:21], 0.5, v[32:33] op_sel_hi:[1,0,1]
	v_lshlrev_b32_e32 v32, 16, v196
	v_and_b32_e32 v33, 0xffff0000, v196
	v_lshlrev_b32_e32 v30, 16, v248
	v_and_b32_e32 v31, 0xffff0000, v248
	v_pk_fma_f32 v[32:33], v[12:13], 0.5, v[32:33] op_sel_hi:[1,0,1]
	v_lshlrev_b32_e32 v12, 16, v195
	v_and_b32_e32 v13, 0xffff0000, v195
	v_pk_fma_f32 v[24:25], v[24:25], 0.5, v[30:31] op_sel_hi:[1,0,1]
	v_lshlrev_b32_e32 v30, 16, v247
	v_and_b32_e32 v31, 0xffff0000, v247
	v_pk_fma_f32 v[22:23], v[22:23], 0.5, v[12:13] op_sel_hi:[1,0,1]
	v_lshlrev_b32_e32 v12, 16, v197
	v_and_b32_e32 v13, 0xffff0000, v197
	v_pk_fma_f32 v[30:31], v[34:35], 0.5, v[30:31] op_sel_hi:[1,0,1]
	v_pk_fma_f32 v[34:35], v[14:15], 0.5, v[12:13] op_sel_hi:[1,0,1]
	v_lshlrev_b32_e32 v14, 16, v148
	v_and_b32_e32 v15, 0xffff0000, v148
	v_lshlrev_b32_e32 v12, 16, v146
	v_and_b32_e32 v13, 0xffff0000, v146
	v_pk_fma_f32 v[8:9], v[8:9], 0.5, v[14:15] op_sel_hi:[1,0,1]
	v_lshlrev_b32_e32 v14, 16, v147
	v_and_b32_e32 v15, 0xffff0000, v147
	v_lshlrev_b32_e32 v146, 16, v64
	v_and_b32_e32 v147, 0xffff0000, v64
	v_pk_fma_f32 v[4:5], v[4:5], 0.5, v[146:147] op_sel_hi:[1,0,1]
	v_lshlrev_b32_e32 v146, 16, v66
	v_and_b32_e32 v147, 0xffff0000, v66
	v_pk_fma_f32 v[0:1], v[0:1], 0.5, v[146:147] op_sel_hi:[1,0,1]
	v_lshl_add_u64 v[146:147], s[28:29], 0, v[182:183]
	v_cvt_pk_bf16_f32 v112, v60, v61
	v_cvt_pk_bf16_f32 v113, v62, v63
	v_cvt_pk_bf16_f32 v114, v56, v57
	v_cvt_pk_bf16_f32 v115, v58, v59
	v_lshl_add_u64 v[146:147], v[146:147], 0, v[170:171]
	v_cvt_pk_bf16_f32 v116, v52, v53
	v_cvt_pk_bf16_f32 v117, v54, v55
	v_cvt_pk_bf16_f32 v118, v104, v105
	v_cvt_pk_bf16_f32 v119, v106, v107
	global_store_dwordx4 v[146:147], v[112:115], off
	global_store_dwordx4 v[146:147], v[116:119], off offset:256
	v_cvt_pk_bf16_f32 v172, v44, v45
	v_lshl_add_u64 v[112:113], s[28:29], 0, v[132:133]
	v_cvt_pk_bf16_f32 v173, v46, v47
	v_cvt_pk_bf16_f32 v174, v40, v41
	v_cvt_pk_bf16_f32 v175, v42, v43
	v_lshl_add_u64 v[112:113], v[112:113], 0, v[170:171]
	v_cvt_pk_bf16_f32 v176, v36, v37
	v_cvt_pk_bf16_f32 v177, v38, v39
	v_cvt_pk_bf16_f32 v178, v48, v49
	v_cvt_pk_bf16_f32 v179, v50, v51
	global_store_dwordx4 v[112:113], v[172:175], off
	global_store_dwordx4 v[112:113], v[176:179], off offset:256
	v_lshl_add_u64 v[112:113], s[28:29], 0, v[134:135]
	v_cvt_pk_bf16_f32 v210, v28, v29
	v_cvt_pk_bf16_f32 v211, v30, v31
	v_cvt_pk_bf16_f32 v212, v24, v25
	v_cvt_pk_bf16_f32 v213, v26, v27
	v_pk_fma_f32 v[12:13], v[16:17], 0.5, v[12:13] op_sel_hi:[1,0,1]
	v_lshlrev_b32_e32 v16, 16, v149
	v_and_b32_e32 v17, 0xffff0000, v149
	v_lshlrev_b32_e32 v64, 16, v65
	v_and_b32_e32 v65, 0xffff0000, v65
	v_lshl_add_u64 v[112:113], v[112:113], 0, v[170:171]
	v_cvt_pk_bf16_f32 v194, v20, v21
	v_cvt_pk_bf16_f32 v195, v22, v23
	v_cvt_pk_bf16_f32 v196, v32, v33
	v_cvt_pk_bf16_f32 v197, v34, v35
	v_pk_fma_f32 v[14:15], v[18:19], 0.5, v[14:15] op_sel_hi:[1,0,1]
	v_pk_fma_f32 v[10:11], v[10:11], 0.5, v[16:17] op_sel_hi:[1,0,1]
	v_pk_fma_f32 v[6:7], v[6:7], 0.5, v[64:65] op_sel_hi:[1,0,1]
	v_lshlrev_b32_e32 v64, 16, v67
	v_and_b32_e32 v65, 0xffff0000, v67
	global_store_dwordx4 v[112:113], v[210:213], off
	global_store_dwordx4 v[112:113], v[194:197], off offset:256
	v_lshl_add_u64 v[112:113], s[28:29], 0, v[184:185]
	v_cvt_pk_bf16_f32 v16, v12, v13
	v_cvt_pk_bf16_f32 v17, v14, v15
	v_cvt_pk_bf16_f32 v18, v8, v9
	v_cvt_pk_bf16_f32 v19, v10, v11
	v_pk_fma_f32 v[2:3], v[2:3], 0.5, v[64:65] op_sel_hi:[1,0,1]
	v_lshl_add_u64 v[112:113], v[112:113], 0, v[170:171]
	v_cvt_pk_bf16_f32 v64, v4, v5
	v_cvt_pk_bf16_f32 v65, v6, v7
	v_cvt_pk_bf16_f32 v66, v0, v1
	v_cvt_pk_bf16_f32 v67, v2, v3
	global_store_dwordx4 v[112:113], v[16:19], off
	global_store_dwordx4 v[112:113], v[64:67], off offset:256
	s_lshl_b32 s10, s81, 2
	v_and_b32_e32 v17, 64, v188
	v_xor_b32_e32 v16, 16, v188
	v_add_u32_e32 v17, 64, v17
	v_cmp_lt_i32_e32 vcc, v16, v17
	v_xor_b32_e32 v18, 32, v188
	s_ashr_i32 s11, s10, 31
	v_cndmask_b32_e32 v16, v188, v16, vcc
	v_lshlrev_b32_e32 v16, 2, v16
	ds_bpermute_b32 v19, v16, v209
	v_cmp_lt_i32_e32 vcc, v18, v17
	s_lshl_b64 s[10:11], s[10:11], 2
	s_add_u32 s38, s73, s10
	v_cndmask_b32_e32 v17, v188, v18, vcc
	v_lshlrev_b32_e32 v17, 2, v17
	s_waitcnt lgkmcnt(0)
	v_add_f32_e32 v18, v209, v19
	ds_bpermute_b32 v19, v17, v18
	s_addc_u32 s39, s74, s11
	s_and_saveexec_b64 s[46:47], s[42:43]
	s_cbranch_execz .LBB0_344
	s_waitcnt lgkmcnt(0)
	v_add_f32_e32 v64, v18, v19
	v_lshlrev_b64 v[18:19], 6, v[168:169]
	v_lshl_add_u64 v[18:19], s[38:39], 0, v[18:19]
	global_store_dword v[18:19], v64, off

.Lm4bp_386:
	s_waitcnt lgkmcnt(0)
	s_mov_b32 s100, 0
	s_barrier
	s_nop 0
	v_mfma_f32_16x16x32_bf16 v[60:63], v[158:161], v[174:177], 0
	v_mfma_f32_16x16x32_bf16 v[56:59], v[166:169], v[174:177], 0
	v_mfma_f32_16x16x32_bf16 v[52:55], v[158:161], v[182:185], 0
	v_mfma_f32_16x16x32_bf16 v[48:51], v[166:169], v[182:185], 0
	v_mfma_f32_16x16x32_bf16 v[44:47], v[158:161], v[210:213], 0
	v_mfma_f32_16x16x32_bf16 v[40:43], v[166:169], v[210:213], 0
	v_mfma_f32_16x16x32_bf16 v[36:39], v[158:161], v[218:221], 0
	v_mfma_f32_16x16x32_bf16 v[32:35], v[166:169], v[218:221], 0
	v_mfma_f32_16x16x32_bf16 v[60:63], v[162:165], v[178:181], v[60:63]
	v_mfma_f32_16x16x32_bf16 v[56:59], v[170:173], v[178:181], v[56:59]
	v_mfma_f32_16x16x32_bf16 v[52:55], v[162:165], v[206:209], v[52:55]
	v_mfma_f32_16x16x32_bf16 v[48:51], v[170:173], v[206:209], v[48:51]
	v_mfma_f32_16x16x32_bf16 v[44:47], v[162:165], v[214:217], v[44:47]
	v_mfma_f32_16x16x32_bf16 v[40:43], v[170:173], v[214:217], v[40:43]
	v_mfma_f32_16x16x32_bf16 v[36:39], v[162:165], v[222:225], v[36:39]
	v_mfma_f32_16x16x32_bf16 v[32:35], v[170:173], v[222:225], v[32:35]
	v_mfma_f32_16x16x32_bf16 v[28:31], v[226:229], v[174:177], 0
	v_mfma_f32_16x16x32_bf16 v[24:27], v[234:237], v[174:177], 0
	v_mfma_f32_16x16x32_bf16 v[20:23], v[226:229], v[182:185], 0
	v_mfma_f32_16x16x32_bf16 v[16:19], v[234:237], v[182:185], 0
	v_mfma_f32_16x16x32_bf16 v[12:15], v[226:229], v[210:213], 0
	v_mfma_f32_16x16x32_bf16 v[8:11], v[234:237], v[210:213], 0
	v_mfma_f32_16x16x32_bf16 v[4:7], v[226:229], v[218:221], 0
	v_mfma_f32_16x16x32_bf16 v[0:3], v[234:237], v[218:221], 0
	v_mfma_f32_16x16x32_bf16 v[28:31], v[230:233], v[178:181], v[28:31]
	v_mfma_f32_16x16x32_bf16 v[24:27], v[238:241], v[178:181], v[24:27]
	v_mfma_f32_16x16x32_bf16 v[20:23], v[230:233], v[206:209], v[20:23]
	v_mfma_f32_16x16x32_bf16 v[16:19], v[238:241], v[206:209], v[16:19]
	v_mfma_f32_16x16x32_bf16 v[12:15], v[230:233], v[214:217], v[12:15]
	v_mfma_f32_16x16x32_bf16 v[8:11], v[238:241], v[214:217], v[8:11]
	v_mfma_f32_16x16x32_bf16 v[4:7], v[230:233], v[222:225], v[4:7]
	v_mfma_f32_16x16x32_bf16 v[0:3], v[238:241], v[222:225], v[0:3]
	s_barrier
	s_add_i32 s6, 0, 0x18000
	v_add_u32_e32 v170, s6, v154
	ds_read_b128 v[158:161], v170
	ds_read_b128 v[162:165], v170 offset:1024
	ds_read_b128 v[166:169], v170 offset:2048
	ds_read_b128 v[170:173], v170 offset:3072
	s_add_u32 s58, s58, 0x40000
	s_addc_u32 s59, s59, 0
	s_mov_b32 m0, s70
	v_lshl_add_u64 v[226:227], s[58:59], 0, v[128:129]
	ds_read_b128 v[174:177], v157 offset:32768
	ds_read_b128 v[178:181], v157 offset:33792
	ds_read_b128 v[182:185], v157 offset:34816
	ds_read_b128 v[206:209], v157 offset:35840
	ds_read_b128 v[210:213], v157 offset:36864
	ds_read_b128 v[214:217], v157 offset:37888
	ds_read_b128 v[218:221], v157 offset:38912
	ds_read_b128 v[222:225], v157 offset:39936
	global_load_lds_dwordx4 v[226:227], off
	v_lshl_add_u64 v[226:227], s[58:59], 0, v[130:131]
	s_mov_b32 m0, s71
	s_nop 0
	global_load_lds_dwordx4 v[226:227], off
	s_add_i32 s19, 0, 0x1c000
	v_add_u32_e32 v192, s19, v154
	ds_read_b128 v[226:229], v192
	ds_read_b128 v[230:233], v192 offset:1024
	ds_read_b128 v[234:237], v192 offset:2048
	ds_read_b128 v[238:241], v192 offset:3072
	s_waitcnt vmcnt(8)
	s_waitcnt lgkmcnt(0)
	s_barrier
	v_mfma_f32_16x16x32_bf16 v[124:127], v[158:161], v[174:177], v[124:127]
	v_mfma_f32_16x16x32_bf16 v[120:123], v[166:169], v[174:177], v[120:123]
	v_mfma_f32_16x16x32_bf16 v[116:119], v[158:161], v[182:185], v[116:119]
	v_mfma_f32_16x16x32_bf16 v[112:115], v[166:169], v[182:185], v[112:115]
	v_mfma_f32_16x16x32_bf16 v[108:111], v[158:161], v[210:213], v[108:111]
	v_mfma_f32_16x16x32_bf16 v[104:107], v[166:169], v[210:213], v[104:107]
	v_mfma_f32_16x16x32_bf16 v[100:103], v[158:161], v[218:221], v[100:103]
	v_mfma_f32_16x16x32_bf16 v[96:99], v[166:169], v[218:221], v[96:99]
	v_mfma_f32_16x16x32_bf16 v[124:127], v[162:165], v[178:181], v[124:127]
	v_mfma_f32_16x16x32_bf16 v[120:123], v[170:173], v[178:181], v[120:123]
	v_mfma_f32_16x16x32_bf16 v[116:119], v[162:165], v[206:209], v[116:119]
	v_mfma_f32_16x16x32_bf16 v[112:115], v[170:173], v[206:209], v[112:115]
	v_mfma_f32_16x16x32_bf16 v[108:111], v[162:165], v[214:217], v[108:111]
	v_mfma_f32_16x16x32_bf16 v[104:107], v[170:173], v[214:217], v[104:107]
	v_mfma_f32_16x16x32_bf16 v[100:103], v[162:165], v[222:225], v[100:103]
	v_mfma_f32_16x16x32_bf16 v[96:99], v[170:173], v[222:225], v[96:99]
	v_mfma_f32_16x16x32_bf16 v[92:95], v[226:229], v[174:177], v[92:95]
	v_mfma_f32_16x16x32_bf16 v[88:91], v[234:237], v[174:177], v[88:91]
	v_mfma_f32_16x16x32_bf16 v[84:87], v[226:229], v[182:185], v[84:87]
	v_mfma_f32_16x16x32_bf16 v[80:83], v[234:237], v[182:185], v[80:83]
	v_mfma_f32_16x16x32_bf16 v[76:79], v[226:229], v[210:213], v[76:79]
	v_mfma_f32_16x16x32_bf16 v[72:75], v[234:237], v[210:213], v[72:75]
	v_mfma_f32_16x16x32_bf16 v[68:71], v[226:229], v[218:221], v[68:71]
	v_mfma_f32_16x16x32_bf16 v[64:67], v[234:237], v[218:221], v[64:67]
	v_mfma_f32_16x16x32_bf16 v[92:95], v[230:233], v[178:181], v[92:95]
	v_mfma_f32_16x16x32_bf16 v[88:91], v[238:241], v[178:181], v[88:91]
	v_mfma_f32_16x16x32_bf16 v[84:87], v[230:233], v[206:209], v[84:87]
	v_mfma_f32_16x16x32_bf16 v[80:83], v[238:241], v[206:209], v[80:83]
	v_mfma_f32_16x16x32_bf16 v[76:79], v[230:233], v[214:217], v[76:79]
	v_mfma_f32_16x16x32_bf16 v[72:75], v[238:241], v[214:217], v[72:75]
	v_mfma_f32_16x16x32_bf16 v[68:71], v[230:233], v[222:225], v[68:71]
	v_mfma_f32_16x16x32_bf16 v[64:67], v[238:241], v[222:225], v[64:67]
	s_barrier
	s_add_i32 s6, s6, s57
	v_lshl_add_u64 v[146:147], v[146:147], 0, s[36:37]
	s_mov_b32 m0, s6
	s_nop 0
	global_load_lds_dwordx4 v[146:147], off
	v_lshl_add_u64 v[146:147], v[148:149], 0, s[36:37]
	s_add_i32 m0, s6, 0x2000
	s_nop 0
	global_load_lds_dwordx4 v[146:147], off
	s_mov_b32 m0, s72
	v_lshl_add_u64 v[146:147], v[194:195], 0, s[36:37]
	ds_read_b128 v[174:177], v157 offset:49152
	ds_read_b128 v[178:181], v157 offset:50176
	ds_read_b128 v[182:185], v157 offset:51200
	ds_read_b128 v[206:209], v157 offset:52224
	ds_read_b128 v[210:213], v157 offset:53248
	ds_read_b128 v[214:217], v157 offset:54272
	ds_read_b128 v[218:221], v157 offset:55296
	ds_read_b128 v[222:225], v157 offset:56320
	global_load_lds_dwordx4 v[146:147], off
	v_lshl_add_u64 v[146:147], v[196:197], 0, s[36:37]
	s_mov_b32 m0, s73
	s_nop 0
	global_load_lds_dwordx4 v[146:147], off
	s_add_u32 s54, s54, 0x40080
	s_addc_u32 s55, s55, 0
	s_add_i32 s6, s19, s57
	v_lshl_add_u64 v[146:147], s[54:55], 0, v[140:141]
	s_mov_b32 m0, s6
	s_nop 0
	global_load_lds_dwordx4 v[146:147], off
	v_lshl_add_u64 v[146:147], s[54:55], 0, v[132:133]
	s_add_i32 m0, s6, 0x2000
	s_nop 0
	global_load_lds_dwordx4 v[146:147], off
	s_add_i32 s81, s81, 2
	s_add_u32 s52, s52, 0x100
	s_addc_u32 s53, s53, 0
	s_cmp_gt_u32 s81, 13
	s_nop 0
	s_waitcnt vmcnt(8)
	s_waitcnt lgkmcnt(0)
	s_barrier
	v_mfma_f32_16x16x32_bf16 v[60:63], v[158:161], v[174:177], v[60:63]
	v_mfma_f32_16x16x32_bf16 v[56:59], v[166:169], v[174:177], v[56:59]
	v_mfma_f32_16x16x32_bf16 v[52:55], v[158:161], v[182:185], v[52:55]
	v_mfma_f32_16x16x32_bf16 v[48:51], v[166:169], v[182:185], v[48:51]
	v_mfma_f32_16x16x32_bf16 v[44:47], v[158:161], v[210:213], v[44:47]
	v_mfma_f32_16x16x32_bf16 v[40:43], v[166:169], v[210:213], v[40:43]
	v_mfma_f32_16x16x32_bf16 v[36:39], v[158:161], v[218:221], v[36:39]
	v_mfma_f32_16x16x32_bf16 v[32:35], v[166:169], v[218:221], v[32:35]
	v_mfma_f32_16x16x32_bf16 v[60:63], v[162:165], v[178:181], v[60:63]
	v_mfma_f32_16x16x32_bf16 v[56:59], v[170:173], v[178:181], v[56:59]
	v_mfma_f32_16x16x32_bf16 v[52:55], v[162:165], v[206:209], v[52:55]
	v_mfma_f32_16x16x32_bf16 v[48:51], v[170:173], v[206:209], v[48:51]
	v_mfma_f32_16x16x32_bf16 v[44:47], v[162:165], v[214:217], v[44:47]
	v_mfma_f32_16x16x32_bf16 v[40:43], v[170:173], v[214:217], v[40:43]
	v_mfma_f32_16x16x32_bf16 v[36:39], v[162:165], v[222:225], v[36:39]
	v_mfma_f32_16x16x32_bf16 v[32:35], v[170:173], v[222:225], v[32:35]
	v_mfma_f32_16x16x32_bf16 v[28:31], v[226:229], v[174:177], v[28:31]
	v_mfma_f32_16x16x32_bf16 v[24:27], v[234:237], v[174:177], v[24:27]
	v_mfma_f32_16x16x32_bf16 v[20:23], v[226:229], v[182:185], v[20:23]
	v_mfma_f32_16x16x32_bf16 v[16:19], v[234:237], v[182:185], v[16:19]
	v_mfma_f32_16x16x32_bf16 v[12:15], v[226:229], v[210:213], v[12:15]
	v_mfma_f32_16x16x32_bf16 v[8:11], v[234:237], v[210:213], v[8:11]
	v_mfma_f32_16x16x32_bf16 v[4:7], v[226:229], v[218:221], v[4:7]
	v_mfma_f32_16x16x32_bf16 v[0:3], v[234:237], v[218:221], v[0:3]
	v_mfma_f32_16x16x32_bf16 v[28:31], v[230:233], v[178:181], v[28:31]
	v_mfma_f32_16x16x32_bf16 v[24:27], v[238:241], v[178:181], v[24:27]
	v_mfma_f32_16x16x32_bf16 v[20:23], v[230:233], v[206:209], v[20:23]
	v_mfma_f32_16x16x32_bf16 v[16:19], v[238:241], v[206:209], v[16:19]
	v_mfma_f32_16x16x32_bf16 v[12:15], v[230:233], v[214:217], v[12:15]
	v_mfma_f32_16x16x32_bf16 v[8:11], v[238:241], v[214:217], v[8:11]
	v_mfma_f32_16x16x32_bf16 v[4:7], v[230:233], v[222:225], v[4:7]
	v_mfma_f32_16x16x32_bf16 v[0:3], v[238:241], v[222:225], v[0:3]
	s_barrier
.LBB0_386:
	s_add_u32 s6, s28, s52
	s_addc_u32 s19, s29, s53
	s_add_u32 s6, s6, 0x100
	s_addc_u32 s19, s19, 0
	s_add_u32 s23, s10, s52
	s_addc_u32 s54, s11, s53
	s_add_i32 s82, 0, 0x10000
	v_add_u32_e32 v146, s82, v154
	ds_read_b128 v[158:161], v146
	ds_read_b128 v[162:165], v146 offset:1024
	ds_read_b128 v[166:169], v146 offset:2048
	ds_read_b128 v[170:173], v146 offset:3072
	s_cmpk_eq_i32 s52, 0x700
	s_cselect_b32 s59, s12, s19
	s_cselect_b32 s58, s35, s6
	s_cselect_b32 s55, s39, s54
	s_cselect_b32 s54, s47, s23
	v_lshl_add_u64 v[146:147], v[150:151], 0, s[52:53]
	s_add_i32 m0, s68, 0xc000
	ds_read_b128 v[174:177], v157
	ds_read_b128 v[178:181], v157 offset:1024
	ds_read_b128 v[182:185], v157 offset:2048
	ds_read_b128 v[206:209], v157 offset:3072
	ds_read_b128 v[210:213], v157 offset:4096
	ds_read_b128 v[214:217], v157 offset:5120
	ds_read_b128 v[218:221], v157 offset:6144
	ds_read_b128 v[222:225], v157 offset:7168
	global_load_lds_dwordx4 v[146:147], off
	v_lshl_add_u64 v[146:147], v[152:153], 0, s[52:53]
	s_add_i32 m0, s68, 0xe000
	s_nop 0
	global_load_lds_dwordx4 v[146:147], off
	s_add_i32 s6, 0, 0x14000
	v_add_u32_e32 v146, s6, v154
	ds_read_b128 v[226:229], v146
	ds_read_b128 v[230:233], v146 offset:1024
	ds_read_b128 v[234:237], v146 offset:2048
	ds_read_b128 v[238:241], v146 offset:3072
	s_nop 0
	s_waitcnt vmcnt(8)
	s_waitcnt lgkmcnt(0)
	s_barrier
	v_mfma_f32_16x16x32_bf16 v[124:127], v[158:161], v[174:177], v[124:127]
	v_mfma_f32_16x16x32_bf16 v[120:123], v[166:169], v[174:177], v[120:123]
	v_mfma_f32_16x16x32_bf16 v[116:119], v[158:161], v[182:185], v[116:119]
	v_mfma_f32_16x16x32_bf16 v[112:115], v[166:169], v[182:185], v[112:115]
	v_mfma_f32_16x16x32_bf16 v[108:111], v[158:161], v[210:213], v[108:111]
	v_mfma_f32_16x16x32_bf16 v[104:107], v[166:169], v[210:213], v[104:107]
	v_mfma_f32_16x16x32_bf16 v[100:103], v[158:161], v[218:221], v[100:103]
	v_mfma_f32_16x16x32_bf16 v[96:99], v[166:169], v[218:221], v[96:99]
	v_mfma_f32_16x16x32_bf16 v[124:127], v[162:165], v[178:181], v[124:127]
	v_mfma_f32_16x16x32_bf16 v[120:123], v[170:173], v[178:181], v[120:123]
	v_mfma_f32_16x16x32_bf16 v[116:119], v[162:165], v[206:209], v[116:119]
	v_mfma_f32_16x16x32_bf16 v[112:115], v[170:173], v[206:209], v[112:115]
	v_mfma_f32_16x16x32_bf16 v[108:111], v[162:165], v[214:217], v[108:111]
	v_mfma_f32_16x16x32_bf16 v[104:107], v[170:173], v[214:217], v[104:107]
	v_mfma_f32_16x16x32_bf16 v[100:103], v[162:165], v[222:225], v[100:103]
	v_mfma_f32_16x16x32_bf16 v[96:99], v[170:173], v[222:225], v[96:99]
	v_mfma_f32_16x16x32_bf16 v[92:95], v[226:229], v[174:177], v[92:95]
	v_mfma_f32_16x16x32_bf16 v[88:91], v[234:237], v[174:177], v[88:91]
	v_mfma_f32_16x16x32_bf16 v[84:87], v[226:229], v[182:185], v[84:87]
	v_mfma_f32_16x16x32_bf16 v[80:83], v[234:237], v[182:185], v[80:83]
	v_mfma_f32_16x16x32_bf16 v[76:79], v[226:229], v[210:213], v[76:79]
	v_mfma_f32_16x16x32_bf16 v[72:75], v[234:237], v[210:213], v[72:75]
	v_mfma_f32_16x16x32_bf16 v[68:71], v[226:229], v[218:221], v[68:71]
	v_mfma_f32_16x16x32_bf16 v[64:67], v[234:237], v[218:221], v[64:67]
	v_mfma_f32_16x16x32_bf16 v[92:95], v[230:233], v[178:181], v[92:95]
	v_mfma_f32_16x16x32_bf16 v[88:91], v[238:241], v[178:181], v[88:91]
	v_mfma_f32_16x16x32_bf16 v[84:87], v[230:233], v[206:209], v[84:87]
	v_mfma_f32_16x16x32_bf16 v[80:83], v[238:241], v[206:209], v[80:83]
	v_mfma_f32_16x16x32_bf16 v[76:79], v[230:233], v[214:217], v[76:79]
	v_mfma_f32_16x16x32_bf16 v[72:75], v[238:241], v[214:217], v[72:75]
	v_mfma_f32_16x16x32_bf16 v[68:71], v[230:233], v[222:225], v[68:71]
	v_mfma_f32_16x16x32_bf16 v[64:67], v[238:241], v[222:225], v[64:67]
	s_barrier
	s_add_i32 s19, s82, s57
	v_lshl_add_u64 v[146:147], s[54:55], 0, v[140:141]
	s_mov_b32 m0, s19
	v_lshl_add_u64 v[148:149], s[54:55], 0, v[132:133]
	global_load_lds_dwordx4 v[146:147], off
	s_add_i32 m0, s19, 0x2000
	s_nop 0
	global_load_lds_dwordx4 v[148:149], off
	s_mov_b32 m0, s68
	v_lshl_add_u64 v[194:195], s[58:59], 0, v[128:129]
	ds_read_b128 v[174:177], v157 offset:16384
	ds_read_b128 v[178:181], v157 offset:17408
	ds_read_b128 v[182:185], v157 offset:18432
	ds_read_b128 v[206:209], v157 offset:19456
	ds_read_b128 v[210:213], v157 offset:20480
	ds_read_b128 v[214:217], v157 offset:21504
	ds_read_b128 v[218:221], v157 offset:22528
	ds_read_b128 v[222:225], v157 offset:23552
	global_load_lds_dwordx4 v[194:195], off
	v_lshl_add_u64 v[196:197], s[58:59], 0, v[130:131]
	s_mov_b32 m0, s69
	s_nop 0
	global_load_lds_dwordx4 v[196:197], off
	s_add_u32 s82, s54, 0x40000
	s_addc_u32 s83, s55, 0
	s_add_i32 s6, s6, s57
	v_lshl_add_u64 v[250:251], s[82:83], 0, v[140:141]
	s_mov_b32 m0, s6
	s_nop 0
	global_load_lds_dwordx4 v[250:251], off
	v_lshl_add_u64 v[250:251], s[82:83], 0, v[132:133]
	s_add_i32 m0, s6, 0x2000
	s_nop 0
	global_load_lds_dwordx4 v[250:251], off
	s_nop 0
	s_waitcnt vmcnt(8)
	s_waitcnt lgkmcnt(0)
	s_barrier
	v_mfma_f32_16x16x32_bf16 v[60:63], v[158:161], v[174:177], v[60:63]
	v_mfma_f32_16x16x32_bf16 v[56:59], v[166:169], v[174:177], v[56:59]
	v_mfma_f32_16x16x32_bf16 v[52:55], v[158:161], v[182:185], v[52:55]
	v_mfma_f32_16x16x32_bf16 v[48:51], v[166:169], v[182:185], v[48:51]
	v_mfma_f32_16x16x32_bf16 v[44:47], v[158:161], v[210:213], v[44:47]
	v_mfma_f32_16x16x32_bf16 v[40:43], v[166:169], v[210:213], v[40:43]
	v_mfma_f32_16x16x32_bf16 v[36:39], v[158:161], v[218:221], v[36:39]
	v_mfma_f32_16x16x32_bf16 v[32:35], v[166:169], v[218:221], v[32:35]
	v_mfma_f32_16x16x32_bf16 v[60:63], v[162:165], v[178:181], v[60:63]
	v_mfma_f32_16x16x32_bf16 v[56:59], v[170:173], v[178:181], v[56:59]
	v_mfma_f32_16x16x32_bf16 v[52:55], v[162:165], v[206:209], v[52:55]
	v_mfma_f32_16x16x32_bf16 v[48:51], v[170:173], v[206:209], v[48:51]
	v_mfma_f32_16x16x32_bf16 v[44:47], v[162:165], v[214:217], v[44:47]
	v_mfma_f32_16x16x32_bf16 v[40:43], v[170:173], v[214:217], v[40:43]
	v_mfma_f32_16x16x32_bf16 v[36:39], v[162:165], v[222:225], v[36:39]
	v_mfma_f32_16x16x32_bf16 v[32:35], v[170:173], v[222:225], v[32:35]
	v_mfma_f32_16x16x32_bf16 v[28:31], v[226:229], v[174:177], v[28:31]
	v_mfma_f32_16x16x32_bf16 v[24:27], v[234:237], v[174:177], v[24:27]
	v_mfma_f32_16x16x32_bf16 v[20:23], v[226:229], v[182:185], v[20:23]
	v_mfma_f32_16x16x32_bf16 v[16:19], v[234:237], v[182:185], v[16:19]
	v_mfma_f32_16x16x32_bf16 v[12:15], v[226:229], v[210:213], v[12:15]
	v_mfma_f32_16x16x32_bf16 v[8:11], v[234:237], v[210:213], v[8:11]
	v_mfma_f32_16x16x32_bf16 v[4:7], v[226:229], v[218:221], v[4:7]
	v_mfma_f32_16x16x32_bf16 v[0:3], v[234:237], v[218:221], v[0:3]
	v_mfma_f32_16x16x32_bf16 v[28:31], v[230:233], v[178:181], v[28:31]
	v_mfma_f32_16x16x32_bf16 v[24:27], v[238:241], v[178:181], v[24:27]
	v_mfma_f32_16x16x32_bf16 v[20:23], v[230:233], v[206:209], v[20:23]
	v_mfma_f32_16x16x32_bf16 v[16:19], v[238:241], v[206:209], v[16:19]
	v_mfma_f32_16x16x32_bf16 v[12:15], v[230:233], v[214:217], v[12:15]
	v_mfma_f32_16x16x32_bf16 v[8:11], v[238:241], v[214:217], v[8:11]
	v_mfma_f32_16x16x32_bf16 v[4:7], v[230:233], v[222:225], v[4:7]
	v_mfma_f32_16x16x32_bf16 v[0:3], v[238:241], v[222:225], v[0:3]
	s_barrier
	s_add_i32 s6, 0, 0x18000
	v_add_u32_e32 v170, s6, v154
	ds_read_b128 v[158:161], v170
	ds_read_b128 v[162:165], v170 offset:1024
	ds_read_b128 v[166:169], v170 offset:2048
	ds_read_b128 v[170:173], v170 offset:3072
	s_add_u32 s58, s58, 0x40000
	s_addc_u32 s59, s59, 0
	s_mov_b32 m0, s70
	v_lshl_add_u64 v[226:227], s[58:59], 0, v[128:129]
	ds_read_b128 v[174:177], v157 offset:32768
	ds_read_b128 v[178:181], v157 offset:33792
	ds_read_b128 v[182:185], v157 offset:34816
	ds_read_b128 v[206:209], v157 offset:35840
	ds_read_b128 v[210:213], v157 offset:36864
	ds_read_b128 v[214:217], v157 offset:37888
	ds_read_b128 v[218:221], v157 offset:38912
	ds_read_b128 v[222:225], v157 offset:39936
	global_load_lds_dwordx4 v[226:227], off
	v_lshl_add_u64 v[226:227], s[58:59], 0, v[130:131]
	s_mov_b32 m0, s71
	s_nop 0
	global_load_lds_dwordx4 v[226:227], off
	s_add_i32 s19, 0, 0x1c000
	v_add_u32_e32 v192, s19, v154
	ds_read_b128 v[226:229], v192
	ds_read_b128 v[230:233], v192 offset:1024
	ds_read_b128 v[234:237], v192 offset:2048
	ds_read_b128 v[238:241], v192 offset:3072
	s_waitcnt vmcnt(8)
	s_waitcnt lgkmcnt(0)
	s_barrier
	v_mfma_f32_16x16x32_bf16 v[124:127], v[158:161], v[174:177], v[124:127]
	v_mfma_f32_16x16x32_bf16 v[120:123], v[166:169], v[174:177], v[120:123]
	v_mfma_f32_16x16x32_bf16 v[116:119], v[158:161], v[182:185], v[116:119]
	v_mfma_f32_16x16x32_bf16 v[112:115], v[166:169], v[182:185], v[112:115]
	v_mfma_f32_16x16x32_bf16 v[108:111], v[158:161], v[210:213], v[108:111]
	v_mfma_f32_16x16x32_bf16 v[104:107], v[166:169], v[210:213], v[104:107]
	v_mfma_f32_16x16x32_bf16 v[100:103], v[158:161], v[218:221], v[100:103]
	v_mfma_f32_16x16x32_bf16 v[96:99], v[166:169], v[218:221], v[96:99]
	v_mfma_f32_16x16x32_bf16 v[124:127], v[162:165], v[178:181], v[124:127]
	v_mfma_f32_16x16x32_bf16 v[120:123], v[170:173], v[178:181], v[120:123]
	v_mfma_f32_16x16x32_bf16 v[116:119], v[162:165], v[206:209], v[116:119]
	v_mfma_f32_16x16x32_bf16 v[112:115], v[170:173], v[206:209], v[112:115]
	v_mfma_f32_16x16x32_bf16 v[108:111], v[162:165], v[214:217], v[108:111]
	v_mfma_f32_16x16x32_bf16 v[104:107], v[170:173], v[214:217], v[104:107]
	v_mfma_f32_16x16x32_bf16 v[100:103], v[162:165], v[222:225], v[100:103]
	v_mfma_f32_16x16x32_bf16 v[96:99], v[170:173], v[222:225], v[96:99]
	v_mfma_f32_16x16x32_bf16 v[92:95], v[226:229], v[174:177], v[92:95]
	v_mfma_f32_16x16x32_bf16 v[88:91], v[234:237], v[174:177], v[88:91]
	v_mfma_f32_16x16x32_bf16 v[84:87], v[226:229], v[182:185], v[84:87]
	v_mfma_f32_16x16x32_bf16 v[80:83], v[234:237], v[182:185], v[80:83]
	v_mfma_f32_16x16x32_bf16 v[76:79], v[226:229], v[210:213], v[76:79]
	v_mfma_f32_16x16x32_bf16 v[72:75], v[234:237], v[210:213], v[72:75]
	v_mfma_f32_16x16x32_bf16 v[68:71], v[226:229], v[218:221], v[68:71]
	v_mfma_f32_16x16x32_bf16 v[64:67], v[234:237], v[218:221], v[64:67]
	v_mfma_f32_16x16x32_bf16 v[92:95], v[230:233], v[178:181], v[92:95]
	v_mfma_f32_16x16x32_bf16 v[88:91], v[238:241], v[178:181], v[88:91]
	v_mfma_f32_16x16x32_bf16 v[84:87], v[230:233], v[206:209], v[84:87]
	v_mfma_f32_16x16x32_bf16 v[80:83], v[238:241], v[206:209], v[80:83]
	v_mfma_f32_16x16x32_bf16 v[76:79], v[230:233], v[214:217], v[76:79]
	v_mfma_f32_16x16x32_bf16 v[72:75], v[238:241], v[214:217], v[72:75]
	v_mfma_f32_16x16x32_bf16 v[68:71], v[230:233], v[222:225], v[68:71]
	v_mfma_f32_16x16x32_bf16 v[64:67], v[238:241], v[222:225], v[64:67]
	s_barrier
	s_add_i32 s6, s6, s57
	v_lshl_add_u64 v[146:147], v[146:147], 0, s[36:37]
	s_mov_b32 m0, s6
	s_nop 0
	global_load_lds_dwordx4 v[146:147], off
	v_lshl_add_u64 v[146:147], v[148:149], 0, s[36:37]
	s_add_i32 m0, s6, 0x2000
	s_nop 0
	global_load_lds_dwordx4 v[146:147], off
	s_mov_b32 m0, s72
	v_lshl_add_u64 v[146:147], v[194:195], 0, s[36:37]
	ds_read_b128 v[174:177], v157 offset:49152
	ds_read_b128 v[178:181], v157 offset:50176
	ds_read_b128 v[182:185], v157 offset:51200
	ds_read_b128 v[206:209], v157 offset:52224
	ds_read_b128 v[210:213], v157 offset:53248
	ds_read_b128 v[214:217], v157 offset:54272
	ds_read_b128 v[218:221], v157 offset:55296
	ds_read_b128 v[222:225], v157 offset:56320
	global_load_lds_dwordx4 v[146:147], off
	v_lshl_add_u64 v[146:147], v[196:197], 0, s[36:37]
	s_mov_b32 m0, s73
	s_nop 0
	global_load_lds_dwordx4 v[146:147], off
	s_add_u32 s54, s54, 0x40080
	s_addc_u32 s55, s55, 0
	s_add_i32 s6, s19, s57
	v_lshl_add_u64 v[146:147], s[54:55], 0, v[140:141]
	s_mov_b32 m0, s6
	s_nop 0
	global_load_lds_dwordx4 v[146:147], off
	v_lshl_add_u64 v[146:147], s[54:55], 0, v[132:133]
	s_add_i32 m0, s6, 0x2000
	s_nop 0
	global_load_lds_dwordx4 v[146:147], off
	s_add_i32 s81, s81, 2
	s_add_u32 s52, s52, 0x100
	s_addc_u32 s53, s53, 0
	s_cmp_gt_u32 s81, 13
	s_nop 0
	s_waitcnt vmcnt(8)
	s_waitcnt lgkmcnt(0)
	s_barrier
	v_mfma_f32_16x16x32_bf16 v[60:63], v[158:161], v[174:177], v[60:63]
	v_mfma_f32_16x16x32_bf16 v[56:59], v[166:169], v[174:177], v[56:59]
	v_mfma_f32_16x16x32_bf16 v[52:55], v[158:161], v[182:185], v[52:55]
	v_mfma_f32_16x16x32_bf16 v[48:51], v[166:169], v[182:185], v[48:51]
	v_mfma_f32_16x16x32_bf16 v[44:47], v[158:161], v[210:213], v[44:47]
	v_mfma_f32_16x16x32_bf16 v[40:43], v[166:169], v[210:213], v[40:43]
	v_mfma_f32_16x16x32_bf16 v[36:39], v[158:161], v[218:221], v[36:39]
	v_mfma_f32_16x16x32_bf16 v[32:35], v[166:169], v[218:221], v[32:35]
	v_mfma_f32_16x16x32_bf16 v[60:63], v[162:165], v[178:181], v[60:63]
	v_mfma_f32_16x16x32_bf16 v[56:59], v[170:173], v[178:181], v[56:59]
	v_mfma_f32_16x16x32_bf16 v[52:55], v[162:165], v[206:209], v[52:55]
	v_mfma_f32_16x16x32_bf16 v[48:51], v[170:173], v[206:209], v[48:51]
	v_mfma_f32_16x16x32_bf16 v[44:47], v[162:165], v[214:217], v[44:47]
	v_mfma_f32_16x16x32_bf16 v[40:43], v[170:173], v[214:217], v[40:43]
	v_mfma_f32_16x16x32_bf16 v[36:39], v[162:165], v[222:225], v[36:39]
	v_mfma_f32_16x16x32_bf16 v[32:35], v[170:173], v[222:225], v[32:35]
	v_mfma_f32_16x16x32_bf16 v[28:31], v[226:229], v[174:177], v[28:31]
	v_mfma_f32_16x16x32_bf16 v[24:27], v[234:237], v[174:177], v[24:27]
	v_mfma_f32_16x16x32_bf16 v[20:23], v[226:229], v[182:185], v[20:23]
	v_mfma_f32_16x16x32_bf16 v[16:19], v[234:237], v[182:185], v[16:19]
	v_mfma_f32_16x16x32_bf16 v[12:15], v[226:229], v[210:213], v[12:15]
	v_mfma_f32_16x16x32_bf16 v[8:11], v[234:237], v[210:213], v[8:11]
	v_mfma_f32_16x16x32_bf16 v[4:7], v[226:229], v[218:221], v[4:7]
	v_mfma_f32_16x16x32_bf16 v[0:3], v[234:237], v[218:221], v[0:3]
	v_mfma_f32_16x16x32_bf16 v[28:31], v[230:233], v[178:181], v[28:31]
	v_mfma_f32_16x16x32_bf16 v[24:27], v[238:241], v[178:181], v[24:27]
	v_mfma_f32_16x16x32_bf16 v[20:23], v[230:233], v[206:209], v[20:23]
	v_mfma_f32_16x16x32_bf16 v[16:19], v[238:241], v[206:209], v[16:19]
	v_mfma_f32_16x16x32_bf16 v[12:15], v[230:233], v[214:217], v[12:15]
	v_mfma_f32_16x16x32_bf16 v[8:11], v[238:241], v[214:217], v[8:11]
	v_mfma_f32_16x16x32_bf16 v[4:7], v[230:233], v[222:225], v[4:7]
	v_mfma_f32_16x16x32_bf16 v[0:3], v[238:241], v[222:225], v[0:3]
	s_barrier
	s_cbranch_scc0 .LBB0_386
	s_mov_b32 s100, 1
	v_lshl_add_u32 v158, s75, 10, v155
	ds_read2_b32 v[146:147], v158 offset1:16
	s_add_u32 s52, s10, 0xffffff00
	s_addc_u32 s53, s11, -1
	s_ashr_i32 s35, s34, 31
	s_lshl_b64 s[10:11], s[34:35], 8
	s_waitcnt lgkmcnt(0)
	v_mul_f32_e32 v184, 0xbfb8aa3b, v146
	v_mul_f32_e32 v206, v146, v146
	v_pk_mul_f32 v[168:169], v[124:125], v[184:185] op_sel_hi:[1,0]
	v_pk_mul_f32 v[170:171], v[126:127], v[184:185] op_sel_hi:[1,0]
	v_pk_mul_f32 v[172:173], v[120:121], v[184:185] op_sel_hi:[1,0]
	v_pk_mul_f32 v[174:175], v[122:123], v[184:185] op_sel_hi:[1,0]
	v_exp_f32_e32 v168, v168
	v_exp_f32_e32 v169, v169
	v_exp_f32_e32 v170, v170
	v_exp_f32_e32 v171, v171
	v_exp_f32_e32 v172, v172
	v_exp_f32_e32 v173, v173
	v_exp_f32_e32 v174, v174
	v_exp_f32_e32 v175, v175
	v_pk_mul_f32 v[176:177], v[124:125], v[92:93]
	v_pk_mul_f32 v[178:179], v[126:127], v[94:95]
	v_pk_mul_f32 v[180:181], v[120:121], v[88:89]
	v_pk_mul_f32 v[182:183], v[122:123], v[90:91]
	v_pk_add_f32 v[168:169], v[168:169], 1.0 op_sel_hi:[1,0]
	v_pk_add_f32 v[170:171], v[170:171], 1.0 op_sel_hi:[1,0]
	v_pk_add_f32 v[172:173], v[172:173], 1.0 op_sel_hi:[1,0]
	v_pk_add_f32 v[174:175], v[174:175], 1.0 op_sel_hi:[1,0]
	v_rcp_f32_e32 v168, v168
	v_rcp_f32_e32 v169, v169
	v_rcp_f32_e32 v170, v170
	v_rcp_f32_e32 v171, v171
	v_rcp_f32_e32 v172, v172
	v_rcp_f32_e32 v173, v173
	v_rcp_f32_e32 v174, v174
	v_rcp_f32_e32 v175, v175
	v_pk_mul_f32 v[176:177], v[176:177], v[206:207] op_sel_hi:[1,0]
	v_pk_mul_f32 v[178:179], v[178:179], v[206:207] op_sel_hi:[1,0]
	v_pk_mul_f32 v[180:181], v[180:181], v[206:207] op_sel_hi:[1,0]
	v_pk_mul_f32 v[182:183], v[182:183], v[206:207] op_sel_hi:[1,0]
	v_pk_mul_f32 v[176:177], v[176:177], v[168:169]
	v_pk_mul_f32 v[178:179], v[178:179], v[170:171]
	v_pk_mul_f32 v[180:181], v[180:181], v[172:173]
	v_pk_mul_f32 v[182:183], v[182:183], v[174:175]
	v_cvt_pk_bf16_f32 v160, v176, v177
	v_cvt_pk_bf16_f32 v161, v178, v179
	v_cvt_pk_bf16_f32 v162, v180, v181
	v_cvt_pk_bf16_f32 v163, v182, v183
	v_lshl_add_u64 v[152:153], v[134:135], 0, s[10:11]
	s_movk_i32 s6, 0x1600
	v_lshl_or_b32 v150, s74, 7, v156
	v_ashrrev_i32_e32 v151, 31, v150
	s_nop 1
	v_mov_b64_e32 v[148:149], s[30:31]
	v_mad_u64_u32 v[148:149], s[10:11], v152, s6, v[148:149]
	v_mov_b32_e32 v146, v149
	v_mad_u64_u32 v[152:153], s[10:11], v153, s6, v[146:147]
	v_mov_b32_e32 v149, v152
	v_mov_b32_e32 v146, v147
	v_lshl_add_u64 v[150:151], v[150:151], 1, v[148:149]
	global_store_dwordx4 v[150:151], v[160:163], off
	v_mul_f32_e32 v184, 0xbfb8aa3b, v146
	v_mul_f32_e32 v206, v146, v146
	v_pk_mul_f32 v[168:169], v[116:117], v[184:185] op_sel_hi:[1,0]
	v_pk_mul_f32 v[170:171], v[118:119], v[184:185] op_sel_hi:[1,0]
	v_pk_mul_f32 v[172:173], v[112:113], v[184:185] op_sel_hi:[1,0]
	v_pk_mul_f32 v[174:175], v[114:115], v[184:185] op_sel_hi:[1,0]
	v_exp_f32_e32 v168, v168
	v_exp_f32_e32 v169, v169
	v_exp_f32_e32 v170, v170
	v_exp_f32_e32 v171, v171
	v_exp_f32_e32 v172, v172
	v_exp_f32_e32 v173, v173
	v_exp_f32_e32 v174, v174
	v_exp_f32_e32 v175, v175
	v_pk_mul_f32 v[176:177], v[116:117], v[84:85]
	v_pk_mul_f32 v[178:179], v[118:119], v[86:87]
	v_pk_mul_f32 v[180:181], v[112:113], v[80:81]
	v_pk_mul_f32 v[182:183], v[114:115], v[82:83]
	v_pk_add_f32 v[168:169], v[168:169], 1.0 op_sel_hi:[1,0]
	v_pk_add_f32 v[170:171], v[170:171], 1.0 op_sel_hi:[1,0]
	v_pk_add_f32 v[172:173], v[172:173], 1.0 op_sel_hi:[1,0]
	v_pk_add_f32 v[174:175], v[174:175], 1.0 op_sel_hi:[1,0]
	v_rcp_f32_e32 v168, v168
	v_rcp_f32_e32 v169, v169
	v_rcp_f32_e32 v170, v170
	v_rcp_f32_e32 v171, v171
	v_rcp_f32_e32 v172, v172
	v_rcp_f32_e32 v173, v173
	v_rcp_f32_e32 v174, v174
	v_rcp_f32_e32 v175, v175
	v_pk_mul_f32 v[176:177], v[176:177], v[206:207] op_sel_hi:[1,0]
	v_pk_mul_f32 v[178:179], v[178:179], v[206:207] op_sel_hi:[1,0]
	v_pk_mul_f32 v[180:181], v[180:181], v[206:207] op_sel_hi:[1,0]
	v_pk_mul_f32 v[182:183], v[182:183], v[206:207] op_sel_hi:[1,0]
	v_pk_mul_f32 v[176:177], v[176:177], v[168:169]
	v_pk_mul_f32 v[178:179], v[178:179], v[170:171]
	v_pk_mul_f32 v[180:181], v[180:181], v[172:173]
	v_pk_mul_f32 v[182:183], v[182:183], v[174:175]
	v_cvt_pk_bf16_f32 v160, v176, v177
	v_cvt_pk_bf16_f32 v161, v178, v179
	v_cvt_pk_bf16_f32 v162, v180, v181
	v_cvt_pk_bf16_f32 v163, v182, v183
	s_mov_b32 s6, 0x16000
	s_nop 1
	v_add_co_u32_e32 v146, vcc, s6, v150
	s_nop 0
	v_addc_co_u32_e32 v147, vcc, 0, v151, vcc
	global_store_dwordx4 v[146:147], v[160:163], off
	ds_read2_b32 v[146:147], v158 offset0:32 offset1:48
	s_mov_b32 s6, 0x2c000
	s_waitcnt lgkmcnt(0)
	v_mul_f32_e32 v184, 0xbfb8aa3b, v146
	v_mul_f32_e32 v206, v146, v146
	v_pk_mul_f32 v[168:169], v[108:109], v[184:185] op_sel_hi:[1,0]
	v_pk_mul_f32 v[170:171], v[110:111], v[184:185] op_sel_hi:[1,0]
	v_pk_mul_f32 v[172:173], v[104:105], v[184:185] op_sel_hi:[1,0]
	v_pk_mul_f32 v[174:175], v[106:107], v[184:185] op_sel_hi:[1,0]
	v_exp_f32_e32 v168, v168
	v_exp_f32_e32 v169, v169
	v_exp_f32_e32 v170, v170
	v_exp_f32_e32 v171, v171
	v_exp_f32_e32 v172, v172
	v_exp_f32_e32 v173, v173
	v_exp_f32_e32 v174, v174
	v_exp_f32_e32 v175, v175
	v_pk_mul_f32 v[176:177], v[108:109], v[76:77]
	v_pk_mul_f32 v[178:179], v[110:111], v[78:79]
	v_pk_mul_f32 v[180:181], v[104:105], v[72:73]
	v_pk_mul_f32 v[182:183], v[106:107], v[74:75]
	v_pk_add_f32 v[168:169], v[168:169], 1.0 op_sel_hi:[1,0]
	v_pk_add_f32 v[170:171], v[170:171], 1.0 op_sel_hi:[1,0]
	v_pk_add_f32 v[172:173], v[172:173], 1.0 op_sel_hi:[1,0]
	v_pk_add_f32 v[174:175], v[174:175], 1.0 op_sel_hi:[1,0]
	v_rcp_f32_e32 v168, v168
	v_rcp_f32_e32 v169, v169
	v_rcp_f32_e32 v170, v170
	v_rcp_f32_e32 v171, v171
	v_rcp_f32_e32 v172, v172
	v_rcp_f32_e32 v173, v173
	v_rcp_f32_e32 v174, v174
	v_rcp_f32_e32 v175, v175
	v_pk_mul_f32 v[176:177], v[176:177], v[206:207] op_sel_hi:[1,0]
	v_pk_mul_f32 v[178:179], v[178:179], v[206:207] op_sel_hi:[1,0]
	v_pk_mul_f32 v[180:181], v[180:181], v[206:207] op_sel_hi:[1,0]
	v_pk_mul_f32 v[182:183], v[182:183], v[206:207] op_sel_hi:[1,0]
	v_pk_mul_f32 v[176:177], v[176:177], v[168:169]
	v_pk_mul_f32 v[178:179], v[178:179], v[170:171]
	v_pk_mul_f32 v[180:181], v[180:181], v[172:173]
	v_pk_mul_f32 v[182:183], v[182:183], v[174:175]
	v_cvt_pk_bf16_f32 v160, v176, v177
	v_cvt_pk_bf16_f32 v161, v178, v179
	v_cvt_pk_bf16_f32 v162, v180, v181
	v_cvt_pk_bf16_f32 v163, v182, v183
	s_nop 1
	v_mov_b32_e32 v146, v147
	v_add_co_u32_e32 v148, vcc, s6, v150
	v_addc_co_u32_e32 v149, vcc, 0, v151, vcc
	global_store_dwordx4 v[148:149], v[160:163], off
	v_mul_f32_e32 v184, 0xbfb8aa3b, v146
	v_mul_f32_e32 v206, v146, v146
	v_pk_mul_f32 v[168:169], v[100:101], v[184:185] op_sel_hi:[1,0]
	v_pk_mul_f32 v[170:171], v[102:103], v[184:185] op_sel_hi:[1,0]
	v_pk_mul_f32 v[172:173], v[96:97], v[184:185] op_sel_hi:[1,0]
	v_pk_mul_f32 v[174:175], v[98:99], v[184:185] op_sel_hi:[1,0]
	v_exp_f32_e32 v168, v168
	v_exp_f32_e32 v169, v169
	v_exp_f32_e32 v170, v170
	v_exp_f32_e32 v171, v171
	v_exp_f32_e32 v172, v172
	v_exp_f32_e32 v173, v173
	v_exp_f32_e32 v174, v174
	v_exp_f32_e32 v175, v175
	v_pk_mul_f32 v[176:177], v[100:101], v[68:69]
	v_pk_mul_f32 v[178:179], v[102:103], v[70:71]
	v_pk_mul_f32 v[180:181], v[96:97], v[64:65]
	v_pk_mul_f32 v[182:183], v[98:99], v[66:67]
	v_pk_add_f32 v[168:169], v[168:169], 1.0 op_sel_hi:[1,0]
	v_pk_add_f32 v[170:171], v[170:171], 1.0 op_sel_hi:[1,0]
	v_pk_add_f32 v[172:173], v[172:173], 1.0 op_sel_hi:[1,0]
	v_pk_add_f32 v[174:175], v[174:175], 1.0 op_sel_hi:[1,0]
	v_rcp_f32_e32 v168, v168
	v_rcp_f32_e32 v169, v169
	v_rcp_f32_e32 v170, v170
	v_rcp_f32_e32 v171, v171
	v_rcp_f32_e32 v172, v172
	v_rcp_f32_e32 v173, v173
	v_rcp_f32_e32 v174, v174
	v_rcp_f32_e32 v175, v175
	v_pk_mul_f32 v[176:177], v[176:177], v[206:207] op_sel_hi:[1,0]
	v_pk_mul_f32 v[178:179], v[178:179], v[206:207] op_sel_hi:[1,0]
	v_pk_mul_f32 v[180:181], v[180:181], v[206:207] op_sel_hi:[1,0]
	v_pk_mul_f32 v[182:183], v[182:183], v[206:207] op_sel_hi:[1,0]
	v_pk_mul_f32 v[176:177], v[176:177], v[168:169]
	v_pk_mul_f32 v[178:179], v[178:179], v[170:171]
	v_pk_mul_f32 v[180:181], v[180:181], v[172:173]
	v_pk_mul_f32 v[182:183], v[182:183], v[174:175]
	v_cvt_pk_bf16_f32 v160, v176, v177
	v_cvt_pk_bf16_f32 v161, v178, v179
	v_cvt_pk_bf16_f32 v162, v180, v181
	v_cvt_pk_bf16_f32 v163, v182, v183
	s_mov_b32 s6, 0x42000
	s_nop 1
	v_add_co_u32_e32 v146, vcc, s6, v150
	s_nop 0
	v_addc_co_u32_e32 v147, vcc, 0, v151, vcc
	global_store_dwordx4 v[146:147], v[160:163], off
	ds_read2_b32 v[146:147], v158 offset0:128 offset1:144
	s_mov_b32 s6, 0xb0000
	s_waitcnt lgkmcnt(0)
	v_mul_f32_e32 v184, 0xbfb8aa3b, v146
	v_mul_f32_e32 v206, v146, v146
	v_pk_mul_f32 v[168:169], v[60:61], v[184:185] op_sel_hi:[1,0]
	v_pk_mul_f32 v[170:171], v[62:63], v[184:185] op_sel_hi:[1,0]
	v_pk_mul_f32 v[172:173], v[56:57], v[184:185] op_sel_hi:[1,0]
	v_pk_mul_f32 v[174:175], v[58:59], v[184:185] op_sel_hi:[1,0]
	v_exp_f32_e32 v168, v168
	v_exp_f32_e32 v169, v169
	v_exp_f32_e32 v170, v170
	v_exp_f32_e32 v171, v171
	v_exp_f32_e32 v172, v172
	v_exp_f32_e32 v173, v173
	v_exp_f32_e32 v174, v174
	v_exp_f32_e32 v175, v175
	v_pk_mul_f32 v[176:177], v[60:61], v[28:29]
	v_pk_mul_f32 v[178:179], v[62:63], v[30:31]
	v_pk_mul_f32 v[180:181], v[56:57], v[24:25]
	v_pk_mul_f32 v[182:183], v[58:59], v[26:27]
	v_pk_add_f32 v[168:169], v[168:169], 1.0 op_sel_hi:[1,0]
	v_pk_add_f32 v[170:171], v[170:171], 1.0 op_sel_hi:[1,0]
	v_pk_add_f32 v[172:173], v[172:173], 1.0 op_sel_hi:[1,0]
	v_pk_add_f32 v[174:175], v[174:175], 1.0 op_sel_hi:[1,0]
	v_rcp_f32_e32 v168, v168
	v_rcp_f32_e32 v169, v169
	v_rcp_f32_e32 v170, v170
	v_rcp_f32_e32 v171, v171
	v_rcp_f32_e32 v172, v172
	v_rcp_f32_e32 v173, v173
	v_rcp_f32_e32 v174, v174
	v_rcp_f32_e32 v175, v175
	v_pk_mul_f32 v[176:177], v[176:177], v[206:207] op_sel_hi:[1,0]
	v_pk_mul_f32 v[178:179], v[178:179], v[206:207] op_sel_hi:[1,0]
	v_pk_mul_f32 v[180:181], v[180:181], v[206:207] op_sel_hi:[1,0]
	v_pk_mul_f32 v[182:183], v[182:183], v[206:207] op_sel_hi:[1,0]
	v_pk_mul_f32 v[176:177], v[176:177], v[168:169]
	v_pk_mul_f32 v[178:179], v[178:179], v[170:171]
	v_pk_mul_f32 v[180:181], v[180:181], v[172:173]
	v_pk_mul_f32 v[182:183], v[182:183], v[174:175]
	v_cvt_pk_bf16_f32 v160, v176, v177
	v_cvt_pk_bf16_f32 v161, v178, v179
	v_cvt_pk_bf16_f32 v162, v180, v181
	v_cvt_pk_bf16_f32 v163, v182, v183
	s_nop 1
	v_mov_b32_e32 v146, v147
	v_add_co_u32_e32 v148, vcc, s6, v150
	v_addc_co_u32_e32 v149, vcc, 0, v151, vcc
	global_store_dwordx4 v[148:149], v[160:163], off
	v_mul_f32_e32 v184, 0xbfb8aa3b, v146
	v_mul_f32_e32 v206, v146, v146
	v_pk_mul_f32 v[168:169], v[52:53], v[184:185] op_sel_hi:[1,0]
	v_pk_mul_f32 v[170:171], v[54:55], v[184:185] op_sel_hi:[1,0]
	v_pk_mul_f32 v[172:173], v[48:49], v[184:185] op_sel_hi:[1,0]
	v_pk_mul_f32 v[174:175], v[50:51], v[184:185] op_sel_hi:[1,0]
	v_exp_f32_e32 v168, v168
	v_exp_f32_e32 v169, v169
	v_exp_f32_e32 v170, v170
	v_exp_f32_e32 v171, v171
	v_exp_f32_e32 v172, v172
	v_exp_f32_e32 v173, v173
	v_exp_f32_e32 v174, v174
	v_exp_f32_e32 v175, v175
	v_pk_mul_f32 v[176:177], v[52:53], v[20:21]
	v_pk_mul_f32 v[178:179], v[54:55], v[22:23]
	v_pk_mul_f32 v[180:181], v[48:49], v[16:17]
	v_pk_mul_f32 v[182:183], v[50:51], v[18:19]
	v_pk_add_f32 v[168:169], v[168:169], 1.0 op_sel_hi:[1,0]
	v_pk_add_f32 v[170:171], v[170:171], 1.0 op_sel_hi:[1,0]
	v_pk_add_f32 v[172:173], v[172:173], 1.0 op_sel_hi:[1,0]
	v_pk_add_f32 v[174:175], v[174:175], 1.0 op_sel_hi:[1,0]
	v_rcp_f32_e32 v168, v168
	v_rcp_f32_e32 v169, v169
	v_rcp_f32_e32 v170, v170
	v_rcp_f32_e32 v171, v171
	v_rcp_f32_e32 v172, v172
	v_rcp_f32_e32 v173, v173
	v_rcp_f32_e32 v174, v174
	v_rcp_f32_e32 v175, v175
	v_pk_mul_f32 v[176:177], v[176:177], v[206:207] op_sel_hi:[1,0]
	v_pk_mul_f32 v[178:179], v[178:179], v[206:207] op_sel_hi:[1,0]
	v_pk_mul_f32 v[180:181], v[180:181], v[206:207] op_sel_hi:[1,0]
	v_pk_mul_f32 v[182:183], v[182:183], v[206:207] op_sel_hi:[1,0]
	v_pk_mul_f32 v[176:177], v[176:177], v[168:169]
	v_pk_mul_f32 v[178:179], v[178:179], v[170:171]
	v_pk_mul_f32 v[180:181], v[180:181], v[172:173]
	v_pk_mul_f32 v[182:183], v[182:183], v[174:175]
	v_cvt_pk_bf16_f32 v160, v176, v177
	v_cvt_pk_bf16_f32 v161, v178, v179
	v_cvt_pk_bf16_f32 v162, v180, v181
	v_cvt_pk_bf16_f32 v163, v182, v183
	s_mov_b32 s6, 0xc6000
	s_nop 1
	v_add_co_u32_e32 v146, vcc, s6, v150
	s_nop 0
	v_addc_co_u32_e32 v147, vcc, 0, v151, vcc
	global_store_dwordx4 v[146:147], v[160:163], off
	ds_read2_b32 v[146:147], v158 offset0:160 offset1:176
	s_mov_b32 s6, 0xdc000
	s_waitcnt lgkmcnt(0)
	v_mul_f32_e32 v184, 0xbfb8aa3b, v146
	v_mul_f32_e32 v206, v146, v146
	v_pk_mul_f32 v[168:169], v[44:45], v[184:185] op_sel_hi:[1,0]
	v_pk_mul_f32 v[170:171], v[46:47], v[184:185] op_sel_hi:[1,0]
	v_pk_mul_f32 v[172:173], v[40:41], v[184:185] op_sel_hi:[1,0]
	v_pk_mul_f32 v[174:175], v[42:43], v[184:185] op_sel_hi:[1,0]
	v_exp_f32_e32 v168, v168
	v_exp_f32_e32 v169, v169
	v_exp_f32_e32 v170, v170
	v_exp_f32_e32 v171, v171
	v_exp_f32_e32 v172, v172
	v_exp_f32_e32 v173, v173
	v_exp_f32_e32 v174, v174
	v_exp_f32_e32 v175, v175
	v_pk_mul_f32 v[176:177], v[44:45], v[12:13]
	v_pk_mul_f32 v[178:179], v[46:47], v[14:15]
	v_pk_mul_f32 v[180:181], v[40:41], v[8:9]
	v_pk_mul_f32 v[182:183], v[42:43], v[10:11]
	v_pk_add_f32 v[168:169], v[168:169], 1.0 op_sel_hi:[1,0]
	v_pk_add_f32 v[170:171], v[170:171], 1.0 op_sel_hi:[1,0]
	v_pk_add_f32 v[172:173], v[172:173], 1.0 op_sel_hi:[1,0]
	v_pk_add_f32 v[174:175], v[174:175], 1.0 op_sel_hi:[1,0]
	v_rcp_f32_e32 v168, v168
	v_rcp_f32_e32 v169, v169
	v_rcp_f32_e32 v170, v170
	v_rcp_f32_e32 v171, v171
	v_rcp_f32_e32 v172, v172
	v_rcp_f32_e32 v173, v173
	v_rcp_f32_e32 v174, v174
	v_rcp_f32_e32 v175, v175
	v_pk_mul_f32 v[176:177], v[176:177], v[206:207] op_sel_hi:[1,0]
	v_pk_mul_f32 v[178:179], v[178:179], v[206:207] op_sel_hi:[1,0]
	v_pk_mul_f32 v[180:181], v[180:181], v[206:207] op_sel_hi:[1,0]
	v_pk_mul_f32 v[182:183], v[182:183], v[206:207] op_sel_hi:[1,0]
	v_pk_mul_f32 v[176:177], v[176:177], v[168:169]
	v_pk_mul_f32 v[178:179], v[178:179], v[170:171]
	v_pk_mul_f32 v[180:181], v[180:181], v[172:173]
	v_pk_mul_f32 v[182:183], v[182:183], v[174:175]
	v_cvt_pk_bf16_f32 v158, v176, v177
	v_cvt_pk_bf16_f32 v159, v178, v179
	v_cvt_pk_bf16_f32 v160, v180, v181
	v_cvt_pk_bf16_f32 v161, v182, v183
	s_nop 1
	v_mov_b32_e32 v146, v147
	v_add_co_u32_e32 v148, vcc, s6, v150
	v_addc_co_u32_e32 v149, vcc, 0, v151, vcc
	global_store_dwordx4 v[148:149], v[158:161], off
	v_mul_f32_e32 v184, 0xbfb8aa3b, v146
	v_mul_f32_e32 v206, v146, v146
	v_pk_mul_f32 v[168:169], v[36:37], v[184:185] op_sel_hi:[1,0]
	v_pk_mul_f32 v[170:171], v[38:39], v[184:185] op_sel_hi:[1,0]
	v_pk_mul_f32 v[172:173], v[32:33], v[184:185] op_sel_hi:[1,0]
	v_pk_mul_f32 v[174:175], v[34:35], v[184:185] op_sel_hi:[1,0]
	v_exp_f32_e32 v168, v168
	v_exp_f32_e32 v169, v169
	v_exp_f32_e32 v170, v170
	v_exp_f32_e32 v171, v171
	v_exp_f32_e32 v172, v172
	v_exp_f32_e32 v173, v173
	v_exp_f32_e32 v174, v174
	v_exp_f32_e32 v175, v175
	v_pk_mul_f32 v[176:177], v[36:37], v[4:5]
	v_pk_mul_f32 v[178:179], v[38:39], v[6:7]
	v_pk_mul_f32 v[180:181], v[32:33], v[0:1]
	v_pk_mul_f32 v[182:183], v[34:35], v[2:3]
	v_pk_add_f32 v[168:169], v[168:169], 1.0 op_sel_hi:[1,0]
	v_pk_add_f32 v[170:171], v[170:171], 1.0 op_sel_hi:[1,0]
	v_pk_add_f32 v[172:173], v[172:173], 1.0 op_sel_hi:[1,0]
	v_pk_add_f32 v[174:175], v[174:175], 1.0 op_sel_hi:[1,0]
	v_rcp_f32_e32 v168, v168
	v_rcp_f32_e32 v169, v169
	v_rcp_f32_e32 v170, v170
	v_rcp_f32_e32 v171, v171
	v_rcp_f32_e32 v172, v172
	v_rcp_f32_e32 v173, v173
	v_rcp_f32_e32 v174, v174
	v_rcp_f32_e32 v175, v175
	v_pk_mul_f32 v[176:177], v[176:177], v[206:207] op_sel_hi:[1,0]
	v_pk_mul_f32 v[178:179], v[178:179], v[206:207] op_sel_hi:[1,0]
	v_pk_mul_f32 v[180:181], v[180:181], v[206:207] op_sel_hi:[1,0]
	v_pk_mul_f32 v[182:183], v[182:183], v[206:207] op_sel_hi:[1,0]
	v_pk_mul_f32 v[176:177], v[176:177], v[168:169]
	v_pk_mul_f32 v[178:179], v[178:179], v[170:171]
	v_pk_mul_f32 v[180:181], v[180:181], v[172:173]
	v_pk_mul_f32 v[182:183], v[182:183], v[174:175]
	v_cvt_pk_bf16_f32 v158, v176, v177
	v_cvt_pk_bf16_f32 v159, v178, v179
	v_cvt_pk_bf16_f32 v160, v180, v181
	v_cvt_pk_bf16_f32 v161, v182, v183
	s_nop 1
	v_add_co_u32_e32 v146, vcc, 0xf2000, v150
	s_nop 0
	v_addc_co_u32_e32 v147, vcc, 0, v151, vcc
	s_andn2_b64 vcc, exec, s[44:45]
	global_store_dwordx4 v[146:147], v[158:161], off
	s_cbranch_vccz .LBB0_382
	s_mov_b64 s[48:49], s[52:53]
	s_andn2_b64 vcc, exec, s[42:43]
	s_mov_b64 s[52:53], s[48:49]
	s_cbranch_vccnz .LBB0_383
